# E20: MFMA order per 32-segment: the two k-steps of each accumulator issued back to back (accumulate chain, D->C forwarding), snake over (weight fragment, activation fragment); bitwise same math; on N5
# speedup vs baseline: 1.0285x; 1.0141x over previous
.LBB0_303:
	s_lshl_b32 s18, s91, 20
	s_and_b64 s[8:9], s[34:35], exec
	s_cselect_b32 s8, s18, s94
	s_lshl_b32 s19, s90, 20
	s_and_b64 s[42:43], s[34:35], exec
	s_cselect_b32 s9, s19, s95
	s_add_i32 s94, s94, 0x80080
	s_addk_i32 s95, 0x100
	s_mov_b32 vcc_lo, -2
	ds_read_b128 v[142:145], v136
	ds_read_b128 v[170:173], v136 offset:1024
	ds_read_b128 v[174:177], v136 offset:2048
	ds_read_b128 v[178:181], v136 offset:3072
	ds_read_b128 v[182:185], v137
	ds_read_b128 v[186:189], v137 offset:1024
	ds_read_b128 v[190:193], v137 offset:2048
	ds_read_b128 v[194:197], v137 offset:3072
	s_add_i32 s42, s94, 0xfff80080
	s_cmp_eq_u32 vcc_lo, 28
	s_cselect_b32 s97, s8, s42
	s_cselect_b32 s52, s9, s95
	s_or_b32 vcc_hi, s97, 0x80
	s_mov_b32 m0, s72
	ds_read_b128 v[198:201], v138
	ds_read_b128 v[202:205], v138 offset:1024
	ds_read_b128 v[228:231], v138 offset:2048
	ds_read_b128 v[232:235], v138 offset:3072
	ds_read_b128 v[236:239], v138 offset:4096
	ds_read_b128 v[240:243], v138 offset:5120
	ds_read_b128 v[244:247], v138 offset:6144
	ds_read_b128 v[248:251], v138 offset:7168
	buffer_load_dwordx4 v132, s[60:63], s94 offen lds
	s_mov_b32 m0, s47
	s_nop 0
	buffer_load_dwordx4 v134, s[60:63], s94 offen lds
	s_waitcnt vmcnt(8)
	s_waitcnt lgkmcnt(0)
	s_setprio 1
	s_barrier
	v_mfma_f32_16x16x32_bf16 v[114:117], v[142:145], v[198:201], 0
	v_mfma_f32_16x16x32_bf16 v[114:117], v[170:173], v[202:205], v[114:117]
	v_mfma_f32_16x16x32_bf16 v[110:113], v[174:177], v[198:201], 0
	v_mfma_f32_16x16x32_bf16 v[110:113], v[178:181], v[202:205], v[110:113]
	v_mfma_f32_16x16x32_bf16 v[122:125], v[190:193], v[198:201], 0
	v_mfma_f32_16x16x32_bf16 v[122:125], v[194:197], v[202:205], v[122:125]
	v_mfma_f32_16x16x32_bf16 v[126:129], v[182:185], v[198:201], 0
	v_mfma_f32_16x16x32_bf16 v[126:129], v[186:189], v[202:205], v[126:129]
	v_mfma_f32_16x16x32_bf16 v[118:121], v[182:185], v[228:231], 0
	v_mfma_f32_16x16x32_bf16 v[118:121], v[186:189], v[232:235], v[118:121]
	v_mfma_f32_16x16x32_bf16 v[98:101], v[190:193], v[228:231], 0
	v_mfma_f32_16x16x32_bf16 v[98:101], v[194:197], v[232:235], v[98:101]
	v_mfma_f32_16x16x32_bf16 v[102:105], v[174:177], v[228:231], 0
	v_mfma_f32_16x16x32_bf16 v[102:105], v[178:181], v[232:235], v[102:105]
	v_mfma_f32_16x16x32_bf16 v[106:109], v[142:145], v[228:231], 0
	v_mfma_f32_16x16x32_bf16 v[106:109], v[170:173], v[232:235], v[106:109]
	v_mfma_f32_16x16x32_bf16 v[94:97], v[142:145], v[236:239], 0
	v_mfma_f32_16x16x32_bf16 v[94:97], v[170:173], v[240:243], v[94:97]
	v_mfma_f32_16x16x32_bf16 v[86:89], v[174:177], v[236:239], 0
	v_mfma_f32_16x16x32_bf16 v[86:89], v[178:181], v[240:243], v[86:89]
	v_mfma_f32_16x16x32_bf16 v[82:85], v[190:193], v[236:239], 0
	v_mfma_f32_16x16x32_bf16 v[82:85], v[194:197], v[240:243], v[82:85]
	v_mfma_f32_16x16x32_bf16 v[90:93], v[182:185], v[236:239], 0
	v_mfma_f32_16x16x32_bf16 v[90:93], v[186:189], v[240:243], v[90:93]
	v_mfma_f32_16x16x32_bf16 v[74:77], v[182:185], v[244:247], 0
	v_mfma_f32_16x16x32_bf16 v[74:77], v[186:189], v[248:251], v[74:77]
	v_mfma_f32_16x16x32_bf16 v[66:69], v[190:193], v[244:247], 0
	v_mfma_f32_16x16x32_bf16 v[66:69], v[194:197], v[248:251], v[66:69]
	v_mfma_f32_16x16x32_bf16 v[70:73], v[174:177], v[244:247], 0
	v_mfma_f32_16x16x32_bf16 v[70:73], v[178:181], v[248:251], v[70:73]
	v_mfma_f32_16x16x32_bf16 v[78:81], v[142:145], v[244:247], 0
	v_mfma_f32_16x16x32_bf16 v[78:81], v[170:173], v[248:251], v[78:81]
	s_barrier
	s_setprio 0
	s_mov_b32 m0, s13
	s_mov_b32 s42, s62
	s_mov_b32 s43, s63
	ds_read_b128 v[198:201], v138 offset:16384
	ds_read_b128 v[202:205], v138 offset:17408
	ds_read_b128 v[228:231], v138 offset:18432
	ds_read_b128 v[232:235], v138 offset:19456
	ds_read_b128 v[236:239], v138 offset:20480
	ds_read_b128 v[240:243], v138 offset:21504
	ds_read_b128 v[244:247], v138 offset:22528
	ds_read_b128 v[248:251], v138 offset:23552
	buffer_load_dwordx4 v133, s[40:43], s52 offen lds
	s_mov_b32 m0, s14
	s_add_i32 s96, s52, 0x80000
	buffer_load_dwordx4 v135, s[40:43], s52 offen lds
	s_mov_b32 m0, s15
	s_nop 0
	buffer_load_dwordx4 v133, s[40:43], s96 offen lds
	s_mov_b32 m0, s16
	s_nop 0
	buffer_load_dwordx4 v135, s[40:43], s96 offen lds
	s_mov_b32 m0, s2
	s_nop 0
	buffer_load_dwordx4 v132, s[60:63], s97 offen lds
	s_mov_b32 m0, s21
	s_nop 0
	buffer_load_dwordx4 v134, s[60:63], s97 offen lds
	s_waitcnt vmcnt(8)
	s_waitcnt lgkmcnt(0)
	s_setprio 1
	s_barrier
	v_mfma_f32_16x16x32_bf16 v[62:65], v[142:145], v[198:201], 0
	v_mfma_f32_16x16x32_bf16 v[62:65], v[170:173], v[202:205], v[62:65]
	v_mfma_f32_16x16x32_bf16 v[54:57], v[174:177], v[198:201], 0
	v_mfma_f32_16x16x32_bf16 v[54:57], v[178:181], v[202:205], v[54:57]
	v_mfma_f32_16x16x32_bf16 v[50:53], v[190:193], v[198:201], 0
	v_mfma_f32_16x16x32_bf16 v[50:53], v[194:197], v[202:205], v[50:53]
	v_mfma_f32_16x16x32_bf16 v[58:61], v[182:185], v[198:201], 0
	v_mfma_f32_16x16x32_bf16 v[58:61], v[186:189], v[202:205], v[58:61]
	v_mfma_f32_16x16x32_bf16 v[42:45], v[182:185], v[228:231], 0
	v_mfma_f32_16x16x32_bf16 v[42:45], v[186:189], v[232:235], v[42:45]
	v_mfma_f32_16x16x32_bf16 v[34:37], v[190:193], v[228:231], 0
	v_mfma_f32_16x16x32_bf16 v[34:37], v[194:197], v[232:235], v[34:37]
	v_mfma_f32_16x16x32_bf16 v[38:41], v[174:177], v[228:231], 0
	v_mfma_f32_16x16x32_bf16 v[38:41], v[178:181], v[232:235], v[38:41]
	v_mfma_f32_16x16x32_bf16 v[46:49], v[142:145], v[228:231], 0
	v_mfma_f32_16x16x32_bf16 v[46:49], v[170:173], v[232:235], v[46:49]
	v_mfma_f32_16x16x32_bf16 v[30:33], v[142:145], v[236:239], 0
	v_mfma_f32_16x16x32_bf16 v[30:33], v[170:173], v[240:243], v[30:33]
	v_mfma_f32_16x16x32_bf16 v[22:25], v[174:177], v[236:239], 0
	v_mfma_f32_16x16x32_bf16 v[22:25], v[178:181], v[240:243], v[22:25]
	v_mfma_f32_16x16x32_bf16 v[18:21], v[190:193], v[236:239], 0
	v_mfma_f32_16x16x32_bf16 v[18:21], v[194:197], v[240:243], v[18:21]
	v_mfma_f32_16x16x32_bf16 v[26:29], v[182:185], v[236:239], 0
	v_mfma_f32_16x16x32_bf16 v[26:29], v[186:189], v[240:243], v[26:29]
	v_mfma_f32_16x16x32_bf16 v[10:13], v[182:185], v[244:247], 0
	v_mfma_f32_16x16x32_bf16 v[10:13], v[186:189], v[248:251], v[10:13]
	v_mfma_f32_16x16x32_bf16 v[2:5], v[190:193], v[244:247], 0
	v_mfma_f32_16x16x32_bf16 v[2:5], v[194:197], v[248:251], v[2:5]
	v_mfma_f32_16x16x32_bf16 v[6:9], v[174:177], v[244:247], 0
	v_mfma_f32_16x16x32_bf16 v[6:9], v[178:181], v[248:251], v[6:9]
	v_mfma_f32_16x16x32_bf16 v[14:17], v[142:145], v[244:247], 0
	v_mfma_f32_16x16x32_bf16 v[14:17], v[170:173], v[248:251], v[14:17]
	s_barrier
	s_setprio 0
	ds_read_b128 v[142:145], v139
	ds_read_b128 v[170:173], v139 offset:1024
	ds_read_b128 v[174:177], v139 offset:2048
	ds_read_b128 v[178:181], v139 offset:3072
	ds_read_b128 v[182:185], v140
	ds_read_b128 v[186:189], v140 offset:1024
	ds_read_b128 v[190:193], v140 offset:2048
	ds_read_b128 v[194:197], v140 offset:3072
	s_add_i32 s97, s97, 0x80000
	s_mov_b32 m0, s23
	ds_read_b128 v[198:201], v138 offset:32768
	ds_read_b128 v[202:205], v138 offset:33792
	ds_read_b128 v[228:231], v138 offset:34816
	ds_read_b128 v[232:235], v138 offset:35840
	ds_read_b128 v[236:239], v138 offset:36864
	ds_read_b128 v[240:243], v138 offset:37888
	ds_read_b128 v[244:247], v138 offset:38912
	ds_read_b128 v[248:251], v138 offset:39936
	buffer_load_dwordx4 v132, s[60:63], s97 offen lds
	s_mov_b32 m0, s24
	s_nop 0
	buffer_load_dwordx4 v134, s[60:63], s97 offen lds
	s_waitcnt vmcnt(8)
	s_waitcnt lgkmcnt(0)
	s_setprio 1
	s_barrier
	v_mfma_f32_16x16x32_bf16 v[114:117], v[142:145], v[198:201], v[114:117]
	v_mfma_f32_16x16x32_bf16 v[114:117], v[170:173], v[202:205], v[114:117]
	v_mfma_f32_16x16x32_bf16 v[110:113], v[174:177], v[198:201], v[110:113]
	v_mfma_f32_16x16x32_bf16 v[110:113], v[178:181], v[202:205], v[110:113]
	v_mfma_f32_16x16x32_bf16 v[122:125], v[190:193], v[198:201], v[122:125]
	v_mfma_f32_16x16x32_bf16 v[122:125], v[194:197], v[202:205], v[122:125]
	v_mfma_f32_16x16x32_bf16 v[126:129], v[182:185], v[198:201], v[126:129]
	v_mfma_f32_16x16x32_bf16 v[126:129], v[186:189], v[202:205], v[126:129]
	v_mfma_f32_16x16x32_bf16 v[118:121], v[182:185], v[228:231], v[118:121]
	v_mfma_f32_16x16x32_bf16 v[118:121], v[186:189], v[232:235], v[118:121]
	v_mfma_f32_16x16x32_bf16 v[98:101], v[190:193], v[228:231], v[98:101]
	v_mfma_f32_16x16x32_bf16 v[98:101], v[194:197], v[232:235], v[98:101]
	v_mfma_f32_16x16x32_bf16 v[102:105], v[174:177], v[228:231], v[102:105]
	v_mfma_f32_16x16x32_bf16 v[102:105], v[178:181], v[232:235], v[102:105]
	v_mfma_f32_16x16x32_bf16 v[106:109], v[142:145], v[228:231], v[106:109]
	v_mfma_f32_16x16x32_bf16 v[106:109], v[170:173], v[232:235], v[106:109]
	v_mfma_f32_16x16x32_bf16 v[94:97], v[142:145], v[236:239], v[94:97]
	v_mfma_f32_16x16x32_bf16 v[94:97], v[170:173], v[240:243], v[94:97]
	v_mfma_f32_16x16x32_bf16 v[86:89], v[174:177], v[236:239], v[86:89]
	v_mfma_f32_16x16x32_bf16 v[86:89], v[178:181], v[240:243], v[86:89]
	v_mfma_f32_16x16x32_bf16 v[82:85], v[190:193], v[236:239], v[82:85]
	v_mfma_f32_16x16x32_bf16 v[82:85], v[194:197], v[240:243], v[82:85]
	v_mfma_f32_16x16x32_bf16 v[90:93], v[182:185], v[236:239], v[90:93]
	v_mfma_f32_16x16x32_bf16 v[90:93], v[186:189], v[240:243], v[90:93]
	v_mfma_f32_16x16x32_bf16 v[74:77], v[182:185], v[244:247], v[74:77]
	v_mfma_f32_16x16x32_bf16 v[74:77], v[186:189], v[248:251], v[74:77]
	v_mfma_f32_16x16x32_bf16 v[66:69], v[190:193], v[244:247], v[66:69]
	v_mfma_f32_16x16x32_bf16 v[66:69], v[194:197], v[248:251], v[66:69]
	v_mfma_f32_16x16x32_bf16 v[70:73], v[174:177], v[244:247], v[70:73]
	v_mfma_f32_16x16x32_bf16 v[70:73], v[178:181], v[248:251], v[70:73]
	v_mfma_f32_16x16x32_bf16 v[78:81], v[142:145], v[244:247], v[78:81]
	v_mfma_f32_16x16x32_bf16 v[78:81], v[170:173], v[248:251], v[78:81]
	s_barrier
	s_setprio 0
	s_mov_b32 m0, s31
	s_or_b32 s53, s52, 0x80
	ds_read_b128 v[198:201], v138 offset:49152
	ds_read_b128 v[202:205], v138 offset:50176
	ds_read_b128 v[228:231], v138 offset:51200
	ds_read_b128 v[232:235], v138 offset:52224
	ds_read_b128 v[236:239], v138 offset:53248
	ds_read_b128 v[240:243], v138 offset:54272
	ds_read_b128 v[244:247], v138 offset:55296
	ds_read_b128 v[248:251], v138 offset:56320
	buffer_load_dwordx4 v133, s[40:43], s53 offen lds
	s_mov_b32 m0, s33
	s_add_i32 s52, s52, 0x80080
	buffer_load_dwordx4 v135, s[40:43], s53 offen lds
	s_mov_b32 m0, s68
	s_nop 0
	buffer_load_dwordx4 v133, s[40:43], s52 offen lds
	s_mov_b32 m0, s69
	s_nop 0
	buffer_load_dwordx4 v135, s[40:43], s52 offen lds
	s_mov_b32 m0, s36
	s_nop 0
	buffer_load_dwordx4 v132, s[60:63], vcc_hi offen lds
	s_mov_b32 m0, s37
	s_nop 0
	buffer_load_dwordx4 v134, s[60:63], vcc_hi offen lds
	s_waitcnt vmcnt(8)
	s_waitcnt lgkmcnt(0)
	s_setprio 1
	s_barrier
	v_mfma_f32_16x16x32_bf16 v[62:65], v[142:145], v[198:201], v[62:65]
	v_mfma_f32_16x16x32_bf16 v[62:65], v[170:173], v[202:205], v[62:65]
	v_mfma_f32_16x16x32_bf16 v[54:57], v[174:177], v[198:201], v[54:57]
	v_mfma_f32_16x16x32_bf16 v[54:57], v[178:181], v[202:205], v[54:57]
	v_mfma_f32_16x16x32_bf16 v[50:53], v[190:193], v[198:201], v[50:53]
	v_mfma_f32_16x16x32_bf16 v[50:53], v[194:197], v[202:205], v[50:53]
	v_mfma_f32_16x16x32_bf16 v[58:61], v[182:185], v[198:201], v[58:61]
	v_mfma_f32_16x16x32_bf16 v[58:61], v[186:189], v[202:205], v[58:61]
	v_mfma_f32_16x16x32_bf16 v[42:45], v[182:185], v[228:231], v[42:45]
	v_mfma_f32_16x16x32_bf16 v[42:45], v[186:189], v[232:235], v[42:45]
	v_mfma_f32_16x16x32_bf16 v[34:37], v[190:193], v[228:231], v[34:37]
	v_mfma_f32_16x16x32_bf16 v[34:37], v[194:197], v[232:235], v[34:37]
	v_mfma_f32_16x16x32_bf16 v[38:41], v[174:177], v[228:231], v[38:41]
	v_mfma_f32_16x16x32_bf16 v[38:41], v[178:181], v[232:235], v[38:41]
	v_mfma_f32_16x16x32_bf16 v[46:49], v[142:145], v[228:231], v[46:49]
	v_mfma_f32_16x16x32_bf16 v[46:49], v[170:173], v[232:235], v[46:49]
	v_mfma_f32_16x16x32_bf16 v[30:33], v[142:145], v[236:239], v[30:33]
	v_mfma_f32_16x16x32_bf16 v[30:33], v[170:173], v[240:243], v[30:33]
	v_mfma_f32_16x16x32_bf16 v[22:25], v[174:177], v[236:239], v[22:25]
	v_mfma_f32_16x16x32_bf16 v[22:25], v[178:181], v[240:243], v[22:25]
	v_mfma_f32_16x16x32_bf16 v[18:21], v[190:193], v[236:239], v[18:21]
	v_mfma_f32_16x16x32_bf16 v[18:21], v[194:197], v[240:243], v[18:21]
	v_mfma_f32_16x16x32_bf16 v[26:29], v[182:185], v[236:239], v[26:29]
	v_mfma_f32_16x16x32_bf16 v[26:29], v[186:189], v[240:243], v[26:29]
	v_mfma_f32_16x16x32_bf16 v[10:13], v[182:185], v[244:247], v[10:13]
	v_mfma_f32_16x16x32_bf16 v[10:13], v[186:189], v[248:251], v[10:13]
	v_mfma_f32_16x16x32_bf16 v[2:5], v[190:193], v[244:247], v[2:5]
	v_mfma_f32_16x16x32_bf16 v[2:5], v[194:197], v[248:251], v[2:5]
	v_mfma_f32_16x16x32_bf16 v[6:9], v[174:177], v[244:247], v[6:9]
	v_mfma_f32_16x16x32_bf16 v[6:9], v[178:181], v[248:251], v[6:9]
	v_mfma_f32_16x16x32_bf16 v[14:17], v[142:145], v[244:247], v[14:17]
	v_mfma_f32_16x16x32_bf16 v[14:17], v[170:173], v[248:251], v[14:17]
	s_barrier
	s_setprio 0
	s_add_i32 vcc_lo, vcc_lo, 2
	s_addk_i32 s94, 0x100
	s_addk_i32 s95, 0x100
	s_cmp_gt_u32 vcc_lo, 29
.LBB0_304:
	ds_read_b128 v[142:145], v136
	ds_read_b128 v[170:173], v136 offset:1024
	ds_read_b128 v[174:177], v136 offset:2048
	ds_read_b128 v[178:181], v136 offset:3072
	ds_read_b128 v[182:185], v137
	ds_read_b128 v[186:189], v137 offset:1024
	ds_read_b128 v[190:193], v137 offset:2048
	ds_read_b128 v[194:197], v137 offset:3072
	s_add_i32 s42, s94, 0xfff80080
	s_cmp_eq_u32 vcc_lo, 28
	s_cselect_b32 s97, s8, s42
	s_cselect_b32 s52, s9, s95
	s_or_b32 vcc_hi, s97, 0x80
	s_mov_b32 m0, s72
	ds_read_b128 v[198:201], v138
	ds_read_b128 v[202:205], v138 offset:1024
	ds_read_b128 v[228:231], v138 offset:2048
	ds_read_b128 v[232:235], v138 offset:3072
	ds_read_b128 v[236:239], v138 offset:4096
	ds_read_b128 v[240:243], v138 offset:5120
	ds_read_b128 v[244:247], v138 offset:6144
	ds_read_b128 v[248:251], v138 offset:7168
	buffer_load_dwordx4 v132, s[60:63], s94 offen lds
	s_mov_b32 m0, s47
	s_nop 0
	buffer_load_dwordx4 v134, s[60:63], s94 offen lds
	s_waitcnt vmcnt(8)
	s_waitcnt lgkmcnt(0)
	s_setprio 1
	s_barrier
	v_mfma_f32_16x16x32_bf16 v[114:117], v[142:145], v[198:201], v[114:117]
	v_mfma_f32_16x16x32_bf16 v[114:117], v[170:173], v[202:205], v[114:117]
	v_mfma_f32_16x16x32_bf16 v[110:113], v[174:177], v[198:201], v[110:113]
	v_mfma_f32_16x16x32_bf16 v[110:113], v[178:181], v[202:205], v[110:113]
	v_mfma_f32_16x16x32_bf16 v[122:125], v[190:193], v[198:201], v[122:125]
	v_mfma_f32_16x16x32_bf16 v[122:125], v[194:197], v[202:205], v[122:125]
	v_mfma_f32_16x16x32_bf16 v[126:129], v[182:185], v[198:201], v[126:129]
	v_mfma_f32_16x16x32_bf16 v[126:129], v[186:189], v[202:205], v[126:129]
	v_mfma_f32_16x16x32_bf16 v[118:121], v[182:185], v[228:231], v[118:121]
	v_mfma_f32_16x16x32_bf16 v[118:121], v[186:189], v[232:235], v[118:121]
	v_mfma_f32_16x16x32_bf16 v[98:101], v[190:193], v[228:231], v[98:101]
	v_mfma_f32_16x16x32_bf16 v[98:101], v[194:197], v[232:235], v[98:101]
	v_mfma_f32_16x16x32_bf16 v[102:105], v[174:177], v[228:231], v[102:105]
	v_mfma_f32_16x16x32_bf16 v[102:105], v[178:181], v[232:235], v[102:105]
	v_mfma_f32_16x16x32_bf16 v[106:109], v[142:145], v[228:231], v[106:109]
	v_mfma_f32_16x16x32_bf16 v[106:109], v[170:173], v[232:235], v[106:109]
	v_mfma_f32_16x16x32_bf16 v[94:97], v[142:145], v[236:239], v[94:97]
	v_mfma_f32_16x16x32_bf16 v[94:97], v[170:173], v[240:243], v[94:97]
	v_mfma_f32_16x16x32_bf16 v[86:89], v[174:177], v[236:239], v[86:89]
	v_mfma_f32_16x16x32_bf16 v[86:89], v[178:181], v[240:243], v[86:89]
	v_mfma_f32_16x16x32_bf16 v[82:85], v[190:193], v[236:239], v[82:85]
	v_mfma_f32_16x16x32_bf16 v[82:85], v[194:197], v[240:243], v[82:85]
	v_mfma_f32_16x16x32_bf16 v[90:93], v[182:185], v[236:239], v[90:93]
	v_mfma_f32_16x16x32_bf16 v[90:93], v[186:189], v[240:243], v[90:93]
	v_mfma_f32_16x16x32_bf16 v[74:77], v[182:185], v[244:247], v[74:77]
	v_mfma_f32_16x16x32_bf16 v[74:77], v[186:189], v[248:251], v[74:77]
	v_mfma_f32_16x16x32_bf16 v[66:69], v[190:193], v[244:247], v[66:69]
	v_mfma_f32_16x16x32_bf16 v[66:69], v[194:197], v[248:251], v[66:69]
	v_mfma_f32_16x16x32_bf16 v[70:73], v[174:177], v[244:247], v[70:73]
	v_mfma_f32_16x16x32_bf16 v[70:73], v[178:181], v[248:251], v[70:73]
	v_mfma_f32_16x16x32_bf16 v[78:81], v[142:145], v[244:247], v[78:81]
	v_mfma_f32_16x16x32_bf16 v[78:81], v[170:173], v[248:251], v[78:81]
	s_barrier
	s_setprio 0
	s_mov_b32 m0, s13
	s_mov_b32 s42, s62
	s_mov_b32 s43, s63
	ds_read_b128 v[198:201], v138 offset:16384
	ds_read_b128 v[202:205], v138 offset:17408
	ds_read_b128 v[228:231], v138 offset:18432
	ds_read_b128 v[232:235], v138 offset:19456
	ds_read_b128 v[236:239], v138 offset:20480
	ds_read_b128 v[240:243], v138 offset:21504
	ds_read_b128 v[244:247], v138 offset:22528
	ds_read_b128 v[248:251], v138 offset:23552
	buffer_load_dwordx4 v133, s[40:43], s52 offen lds
	s_mov_b32 m0, s14
	s_add_i32 s96, s52, 0x80000
	buffer_load_dwordx4 v135, s[40:43], s52 offen lds
	s_mov_b32 m0, s15
	s_nop 0
	buffer_load_dwordx4 v133, s[40:43], s96 offen lds
	s_mov_b32 m0, s16
	s_nop 0
	buffer_load_dwordx4 v135, s[40:43], s96 offen lds
	s_mov_b32 m0, s2
	s_nop 0
	buffer_load_dwordx4 v132, s[60:63], s97 offen lds
	s_mov_b32 m0, s21
	s_nop 0
	buffer_load_dwordx4 v134, s[60:63], s97 offen lds
	s_waitcnt vmcnt(8)
	s_waitcnt lgkmcnt(0)
	s_setprio 1
	s_barrier
	v_mfma_f32_16x16x32_bf16 v[62:65], v[142:145], v[198:201], v[62:65]
	v_mfma_f32_16x16x32_bf16 v[62:65], v[170:173], v[202:205], v[62:65]
	v_mfma_f32_16x16x32_bf16 v[54:57], v[174:177], v[198:201], v[54:57]
	v_mfma_f32_16x16x32_bf16 v[54:57], v[178:181], v[202:205], v[54:57]
	v_mfma_f32_16x16x32_bf16 v[50:53], v[190:193], v[198:201], v[50:53]
	v_mfma_f32_16x16x32_bf16 v[50:53], v[194:197], v[202:205], v[50:53]
	v_mfma_f32_16x16x32_bf16 v[58:61], v[182:185], v[198:201], v[58:61]
	v_mfma_f32_16x16x32_bf16 v[58:61], v[186:189], v[202:205], v[58:61]
	v_mfma_f32_16x16x32_bf16 v[42:45], v[182:185], v[228:231], v[42:45]
	v_mfma_f32_16x16x32_bf16 v[42:45], v[186:189], v[232:235], v[42:45]
	v_mfma_f32_16x16x32_bf16 v[34:37], v[190:193], v[228:231], v[34:37]
	v_mfma_f32_16x16x32_bf16 v[34:37], v[194:197], v[232:235], v[34:37]
	v_mfma_f32_16x16x32_bf16 v[38:41], v[174:177], v[228:231], v[38:41]
	v_mfma_f32_16x16x32_bf16 v[38:41], v[178:181], v[232:235], v[38:41]
	v_mfma_f32_16x16x32_bf16 v[46:49], v[142:145], v[228:231], v[46:49]
	v_mfma_f32_16x16x32_bf16 v[46:49], v[170:173], v[232:235], v[46:49]
	v_mfma_f32_16x16x32_bf16 v[30:33], v[142:145], v[236:239], v[30:33]
	v_mfma_f32_16x16x32_bf16 v[30:33], v[170:173], v[240:243], v[30:33]
	v_mfma_f32_16x16x32_bf16 v[22:25], v[174:177], v[236:239], v[22:25]
	v_mfma_f32_16x16x32_bf16 v[22:25], v[178:181], v[240:243], v[22:25]
	v_mfma_f32_16x16x32_bf16 v[18:21], v[190:193], v[236:239], v[18:21]
	v_mfma_f32_16x16x32_bf16 v[18:21], v[194:197], v[240:243], v[18:21]
	v_mfma_f32_16x16x32_bf16 v[26:29], v[182:185], v[236:239], v[26:29]
	v_mfma_f32_16x16x32_bf16 v[26:29], v[186:189], v[240:243], v[26:29]
	v_mfma_f32_16x16x32_bf16 v[10:13], v[182:185], v[244:247], v[10:13]
	v_mfma_f32_16x16x32_bf16 v[10:13], v[186:189], v[248:251], v[10:13]
	v_mfma_f32_16x16x32_bf16 v[2:5], v[190:193], v[244:247], v[2:5]
	v_mfma_f32_16x16x32_bf16 v[2:5], v[194:197], v[248:251], v[2:5]
	v_mfma_f32_16x16x32_bf16 v[6:9], v[174:177], v[244:247], v[6:9]
	v_mfma_f32_16x16x32_bf16 v[6:9], v[178:181], v[248:251], v[6:9]
	v_mfma_f32_16x16x32_bf16 v[14:17], v[142:145], v[244:247], v[14:17]
	v_mfma_f32_16x16x32_bf16 v[14:17], v[170:173], v[248:251], v[14:17]
	s_barrier
	s_setprio 0
	ds_read_b128 v[142:145], v139
	ds_read_b128 v[170:173], v139 offset:1024
	ds_read_b128 v[174:177], v139 offset:2048
	ds_read_b128 v[178:181], v139 offset:3072
	ds_read_b128 v[182:185], v140
	ds_read_b128 v[186:189], v140 offset:1024
	ds_read_b128 v[190:193], v140 offset:2048
	ds_read_b128 v[194:197], v140 offset:3072
	s_add_i32 s97, s97, 0x80000
	s_mov_b32 m0, s23
	ds_read_b128 v[198:201], v138 offset:32768
	ds_read_b128 v[202:205], v138 offset:33792
	ds_read_b128 v[228:231], v138 offset:34816
	ds_read_b128 v[232:235], v138 offset:35840
	ds_read_b128 v[236:239], v138 offset:36864
	ds_read_b128 v[240:243], v138 offset:37888
	ds_read_b128 v[244:247], v138 offset:38912
	ds_read_b128 v[248:251], v138 offset:39936
	buffer_load_dwordx4 v132, s[60:63], s97 offen lds
	s_mov_b32 m0, s24
	s_nop 0
	buffer_load_dwordx4 v134, s[60:63], s97 offen lds
	s_waitcnt vmcnt(8)
	s_waitcnt lgkmcnt(0)
	s_setprio 1
	s_barrier
	v_mfma_f32_16x16x32_bf16 v[114:117], v[142:145], v[198:201], v[114:117]
	v_mfma_f32_16x16x32_bf16 v[114:117], v[170:173], v[202:205], v[114:117]
	v_mfma_f32_16x16x32_bf16 v[110:113], v[174:177], v[198:201], v[110:113]
	v_mfma_f32_16x16x32_bf16 v[110:113], v[178:181], v[202:205], v[110:113]
	v_mfma_f32_16x16x32_bf16 v[122:125], v[190:193], v[198:201], v[122:125]
	v_mfma_f32_16x16x32_bf16 v[122:125], v[194:197], v[202:205], v[122:125]
	v_mfma_f32_16x16x32_bf16 v[126:129], v[182:185], v[198:201], v[126:129]
	v_mfma_f32_16x16x32_bf16 v[126:129], v[186:189], v[202:205], v[126:129]
	v_mfma_f32_16x16x32_bf16 v[118:121], v[182:185], v[228:231], v[118:121]
	v_mfma_f32_16x16x32_bf16 v[118:121], v[186:189], v[232:235], v[118:121]
	v_mfma_f32_16x16x32_bf16 v[98:101], v[190:193], v[228:231], v[98:101]
	v_mfma_f32_16x16x32_bf16 v[98:101], v[194:197], v[232:235], v[98:101]
	v_mfma_f32_16x16x32_bf16 v[102:105], v[174:177], v[228:231], v[102:105]
	v_mfma_f32_16x16x32_bf16 v[102:105], v[178:181], v[232:235], v[102:105]
	v_mfma_f32_16x16x32_bf16 v[106:109], v[142:145], v[228:231], v[106:109]
	v_mfma_f32_16x16x32_bf16 v[106:109], v[170:173], v[232:235], v[106:109]
	v_mfma_f32_16x16x32_bf16 v[94:97], v[142:145], v[236:239], v[94:97]
	v_mfma_f32_16x16x32_bf16 v[94:97], v[170:173], v[240:243], v[94:97]
	v_mfma_f32_16x16x32_bf16 v[86:89], v[174:177], v[236:239], v[86:89]
	v_mfma_f32_16x16x32_bf16 v[86:89], v[178:181], v[240:243], v[86:89]
	v_mfma_f32_16x16x32_bf16 v[82:85], v[190:193], v[236:239], v[82:85]
	v_mfma_f32_16x16x32_bf16 v[82:85], v[194:197], v[240:243], v[82:85]
	v_mfma_f32_16x16x32_bf16 v[90:93], v[182:185], v[236:239], v[90:93]
	v_mfma_f32_16x16x32_bf16 v[90:93], v[186:189], v[240:243], v[90:93]
	v_mfma_f32_16x16x32_bf16 v[74:77], v[182:185], v[244:247], v[74:77]
	v_mfma_f32_16x16x32_bf16 v[74:77], v[186:189], v[248:251], v[74:77]
	v_mfma_f32_16x16x32_bf16 v[66:69], v[190:193], v[244:247], v[66:69]
	v_mfma_f32_16x16x32_bf16 v[66:69], v[194:197], v[248:251], v[66:69]
	v_mfma_f32_16x16x32_bf16 v[70:73], v[174:177], v[244:247], v[70:73]
	v_mfma_f32_16x16x32_bf16 v[70:73], v[178:181], v[248:251], v[70:73]
	v_mfma_f32_16x16x32_bf16 v[78:81], v[142:145], v[244:247], v[78:81]
	v_mfma_f32_16x16x32_bf16 v[78:81], v[170:173], v[248:251], v[78:81]
	s_barrier
	s_setprio 0
	s_mov_b32 m0, s31
	s_or_b32 s53, s52, 0x80
	ds_read_b128 v[198:201], v138 offset:49152
	ds_read_b128 v[202:205], v138 offset:50176
	ds_read_b128 v[228:231], v138 offset:51200
	ds_read_b128 v[232:235], v138 offset:52224
	ds_read_b128 v[236:239], v138 offset:53248
	ds_read_b128 v[240:243], v138 offset:54272
	ds_read_b128 v[244:247], v138 offset:55296
	ds_read_b128 v[248:251], v138 offset:56320
	buffer_load_dwordx4 v133, s[40:43], s53 offen lds
	s_mov_b32 m0, s33
	s_add_i32 s52, s52, 0x80080
	buffer_load_dwordx4 v135, s[40:43], s53 offen lds
	s_mov_b32 m0, s68
	s_nop 0
	buffer_load_dwordx4 v133, s[40:43], s52 offen lds
	s_mov_b32 m0, s69
	s_nop 0
	buffer_load_dwordx4 v135, s[40:43], s52 offen lds
	s_mov_b32 m0, s36
	s_nop 0
	buffer_load_dwordx4 v132, s[60:63], vcc_hi offen lds
	s_mov_b32 m0, s37
	s_nop 0
	buffer_load_dwordx4 v134, s[60:63], vcc_hi offen lds
	s_waitcnt vmcnt(8)
	s_waitcnt lgkmcnt(0)
	s_setprio 1
	s_barrier
	v_mfma_f32_16x16x32_bf16 v[62:65], v[142:145], v[198:201], v[62:65]
	v_mfma_f32_16x16x32_bf16 v[62:65], v[170:173], v[202:205], v[62:65]
	v_mfma_f32_16x16x32_bf16 v[54:57], v[174:177], v[198:201], v[54:57]
	v_mfma_f32_16x16x32_bf16 v[54:57], v[178:181], v[202:205], v[54:57]
	v_mfma_f32_16x16x32_bf16 v[50:53], v[190:193], v[198:201], v[50:53]
	v_mfma_f32_16x16x32_bf16 v[50:53], v[194:197], v[202:205], v[50:53]
	v_mfma_f32_16x16x32_bf16 v[58:61], v[182:185], v[198:201], v[58:61]
	v_mfma_f32_16x16x32_bf16 v[58:61], v[186:189], v[202:205], v[58:61]
	v_mfma_f32_16x16x32_bf16 v[42:45], v[182:185], v[228:231], v[42:45]
	v_mfma_f32_16x16x32_bf16 v[42:45], v[186:189], v[232:235], v[42:45]
	v_mfma_f32_16x16x32_bf16 v[34:37], v[190:193], v[228:231], v[34:37]
	v_mfma_f32_16x16x32_bf16 v[34:37], v[194:197], v[232:235], v[34:37]
	v_mfma_f32_16x16x32_bf16 v[38:41], v[174:177], v[228:231], v[38:41]
	v_mfma_f32_16x16x32_bf16 v[38:41], v[178:181], v[232:235], v[38:41]
	v_mfma_f32_16x16x32_bf16 v[46:49], v[142:145], v[228:231], v[46:49]
	v_mfma_f32_16x16x32_bf16 v[46:49], v[170:173], v[232:235], v[46:49]
	v_mfma_f32_16x16x32_bf16 v[30:33], v[142:145], v[236:239], v[30:33]
	v_mfma_f32_16x16x32_bf16 v[30:33], v[170:173], v[240:243], v[30:33]
	v_mfma_f32_16x16x32_bf16 v[22:25], v[174:177], v[236:239], v[22:25]
	v_mfma_f32_16x16x32_bf16 v[22:25], v[178:181], v[240:243], v[22:25]
	v_mfma_f32_16x16x32_bf16 v[18:21], v[190:193], v[236:239], v[18:21]
	v_mfma_f32_16x16x32_bf16 v[18:21], v[194:197], v[240:243], v[18:21]
	v_mfma_f32_16x16x32_bf16 v[26:29], v[182:185], v[236:239], v[26:29]
	v_mfma_f32_16x16x32_bf16 v[26:29], v[186:189], v[240:243], v[26:29]
	v_mfma_f32_16x16x32_bf16 v[10:13], v[182:185], v[244:247], v[10:13]
	v_mfma_f32_16x16x32_bf16 v[10:13], v[186:189], v[248:251], v[10:13]
	v_mfma_f32_16x16x32_bf16 v[2:5], v[190:193], v[244:247], v[2:5]
	v_mfma_f32_16x16x32_bf16 v[2:5], v[194:197], v[248:251], v[2:5]
	v_mfma_f32_16x16x32_bf16 v[6:9], v[174:177], v[244:247], v[6:9]
	v_mfma_f32_16x16x32_bf16 v[6:9], v[178:181], v[248:251], v[6:9]
	v_mfma_f32_16x16x32_bf16 v[14:17], v[142:145], v[244:247], v[14:17]
	v_mfma_f32_16x16x32_bf16 v[14:17], v[170:173], v[248:251], v[14:17]
	s_barrier
	s_setprio 0
	s_add_i32 vcc_lo, vcc_lo, 2
	s_addk_i32 s94, 0x100
	s_addk_i32 s95, 0x100
	s_cmp_gt_u32 vcc_lo, 29
	s_cbranch_scc0 .LBB0_304
	s_and_b64 vcc, exec, s[48:49]
	s_cbranch_vccz .LBB0_307
	s_barrier

.LBB0_579:
	s_mul_i32 s73, s72, 0x2c0000
	s_and_b64 s[8:9], s[42:43], exec
	s_mul_i32 s84, s71, 0x2c0000
	s_cselect_b32 s8, s73, s21
	s_cselect_b32 s9, s84, s13
	s_addk_i32 s13, 0x100
	s_add_i32 s21, s21, 0xc000
	s_mov_b32 s22, -2
	s_waitcnt lgkmcnt(0)
	v_add_u32_e32 v154, 0x10000, v140
	ds_read_b128 v[132:135], v154
	ds_read_b128 v[142:145], v154 offset:1024
	ds_read_b128 v[170:173], v154 offset:2048
	ds_read_b128 v[174:177], v154 offset:3072
	v_add_u32_e32 v154, 0x14000, v140
	ds_read_b128 v[178:181], v154
	ds_read_b128 v[182:185], v154 offset:1024
	ds_read_b128 v[186:189], v154 offset:2048
	ds_read_b128 v[190:193], v154 offset:3072
	s_add_i32 s23, s21, 0x4000
	s_cmpk_eq_i32 s22, 0x54
	s_cselect_b32 s27, s8, s23
	s_cselect_b32 s26, s9, s13
	s_or_b32 s23, s27, 0x8000
	s_mov_b32 m0, s68
	ds_read_b128 v[194:197], v141
	ds_read_b128 v[198:201], v141 offset:1024
	ds_read_b128 v[202:205], v141 offset:2048
	ds_read_b128 v[228:231], v141 offset:3072
	ds_read_b128 v[232:235], v141 offset:4096
	ds_read_b128 v[236:239], v141 offset:5120
	ds_read_b128 v[240:243], v141 offset:6144
	ds_read_b128 v[244:247], v141 offset:7168
	buffer_load_dwordx4 v136, s[60:63], s21 offen lds
	s_mov_b32 m0, s70
	s_nop 0
	buffer_load_dwordx4 v138, s[60:63], s21 offen lds
	s_waitcnt vmcnt(8)
	s_waitcnt lgkmcnt(0)
	s_setprio 1
	s_barrier
	v_mfma_f32_16x16x32_bf16 v[126:129], v[132:135], v[194:197], 0
	v_mfma_f32_16x16x32_bf16 v[126:129], v[142:145], v[198:201], v[126:129]
	v_mfma_f32_16x16x32_bf16 v[106:109], v[170:173], v[194:197], 0
	v_mfma_f32_16x16x32_bf16 v[106:109], v[174:177], v[198:201], v[106:109]
	v_mfma_f32_16x16x32_bf16 v[110:113], v[186:189], v[194:197], 0
	v_mfma_f32_16x16x32_bf16 v[110:113], v[190:193], v[198:201], v[110:113]
	v_mfma_f32_16x16x32_bf16 v[122:125], v[178:181], v[194:197], 0
	v_mfma_f32_16x16x32_bf16 v[122:125], v[182:185], v[198:201], v[122:125]
	v_mfma_f32_16x16x32_bf16 v[102:105], v[178:181], v[202:205], 0
	v_mfma_f32_16x16x32_bf16 v[102:105], v[182:185], v[228:231], v[102:105]
	v_mfma_f32_16x16x32_bf16 v[98:101], v[186:189], v[202:205], 0
	v_mfma_f32_16x16x32_bf16 v[98:101], v[190:193], v[228:231], v[98:101]
	v_mfma_f32_16x16x32_bf16 v[114:117], v[170:173], v[202:205], 0
	v_mfma_f32_16x16x32_bf16 v[114:117], v[174:177], v[228:231], v[114:117]
	v_mfma_f32_16x16x32_bf16 v[118:121], v[132:135], v[202:205], 0
	v_mfma_f32_16x16x32_bf16 v[118:121], v[142:145], v[228:231], v[118:121]
	v_mfma_f32_16x16x32_bf16 v[94:97], v[132:135], v[232:235], 0
	v_mfma_f32_16x16x32_bf16 v[94:97], v[142:145], v[236:239], v[94:97]
	v_mfma_f32_16x16x32_bf16 v[90:93], v[170:173], v[232:235], 0
	v_mfma_f32_16x16x32_bf16 v[90:93], v[174:177], v[236:239], v[90:93]
	v_mfma_f32_16x16x32_bf16 v[82:85], v[186:189], v[232:235], 0
	v_mfma_f32_16x16x32_bf16 v[82:85], v[190:193], v[236:239], v[82:85]
	v_mfma_f32_16x16x32_bf16 v[86:89], v[178:181], v[232:235], 0
	v_mfma_f32_16x16x32_bf16 v[86:89], v[182:185], v[236:239], v[86:89]
	v_mfma_f32_16x16x32_bf16 v[70:73], v[178:181], v[240:243], 0
	v_mfma_f32_16x16x32_bf16 v[70:73], v[182:185], v[244:247], v[70:73]
	v_mfma_f32_16x16x32_bf16 v[66:69], v[186:189], v[240:243], 0
	v_mfma_f32_16x16x32_bf16 v[66:69], v[190:193], v[244:247], v[66:69]
	v_mfma_f32_16x16x32_bf16 v[74:77], v[170:173], v[240:243], 0
	v_mfma_f32_16x16x32_bf16 v[74:77], v[174:177], v[244:247], v[74:77]
	v_mfma_f32_16x16x32_bf16 v[78:81], v[132:135], v[240:243], 0
	v_mfma_f32_16x16x32_bf16 v[78:81], v[142:145], v[244:247], v[78:81]
	s_barrier
	s_setprio 0
	s_mov_b32 m0, s15
	s_mov_b32 s46, s62
	s_mov_b32 s47, s63
	ds_read_b128 v[194:197], v141 offset:16384
	ds_read_b128 v[198:201], v141 offset:17408
	ds_read_b128 v[202:205], v141 offset:18432
	ds_read_b128 v[228:231], v141 offset:19456
	ds_read_b128 v[232:235], v141 offset:20480
	ds_read_b128 v[236:239], v141 offset:21504
	ds_read_b128 v[240:243], v141 offset:22528
	ds_read_b128 v[244:247], v141 offset:23552
	buffer_load_dwordx4 v137, s[44:47], s26 offen lds
	s_mov_b32 m0, s16
	s_add_i32 s52, s26, 0x160000
	buffer_load_dwordx4 v139, s[44:47], s26 offen lds
	s_mov_b32 m0, s18
	s_nop 0
	buffer_load_dwordx4 v137, s[44:47], s52 offen lds
	s_mov_b32 m0, s19
	s_nop 0
	buffer_load_dwordx4 v139, s[44:47], s52 offen lds
	s_mov_b32 m0, s14
	s_nop 0
	buffer_load_dwordx4 v136, s[60:63], s27 offen lds
	s_mov_b32 m0, s24
	s_nop 0
	buffer_load_dwordx4 v138, s[60:63], s27 offen lds
	s_waitcnt vmcnt(8)
	s_waitcnt lgkmcnt(0)
	s_setprio 1
	s_barrier
	v_mfma_f32_16x16x32_bf16 v[62:65], v[132:135], v[194:197], 0
	v_mfma_f32_16x16x32_bf16 v[62:65], v[142:145], v[198:201], v[62:65]
	v_mfma_f32_16x16x32_bf16 v[58:61], v[170:173], v[194:197], 0
	v_mfma_f32_16x16x32_bf16 v[58:61], v[174:177], v[198:201], v[58:61]
	v_mfma_f32_16x16x32_bf16 v[50:53], v[186:189], v[194:197], 0
	v_mfma_f32_16x16x32_bf16 v[50:53], v[190:193], v[198:201], v[50:53]
	v_mfma_f32_16x16x32_bf16 v[54:57], v[178:181], v[194:197], 0
	v_mfma_f32_16x16x32_bf16 v[54:57], v[182:185], v[198:201], v[54:57]
	v_mfma_f32_16x16x32_bf16 v[38:41], v[178:181], v[202:205], 0
	v_mfma_f32_16x16x32_bf16 v[38:41], v[182:185], v[228:231], v[38:41]
	v_mfma_f32_16x16x32_bf16 v[34:37], v[186:189], v[202:205], 0
	v_mfma_f32_16x16x32_bf16 v[34:37], v[190:193], v[228:231], v[34:37]
	v_mfma_f32_16x16x32_bf16 v[42:45], v[170:173], v[202:205], 0
	v_mfma_f32_16x16x32_bf16 v[42:45], v[174:177], v[228:231], v[42:45]
	v_mfma_f32_16x16x32_bf16 v[46:49], v[132:135], v[202:205], 0
	v_mfma_f32_16x16x32_bf16 v[46:49], v[142:145], v[228:231], v[46:49]
	v_mfma_f32_16x16x32_bf16 v[30:33], v[132:135], v[232:235], 0
	v_mfma_f32_16x16x32_bf16 v[30:33], v[142:145], v[236:239], v[30:33]
	v_mfma_f32_16x16x32_bf16 v[26:29], v[170:173], v[232:235], 0
	v_mfma_f32_16x16x32_bf16 v[26:29], v[174:177], v[236:239], v[26:29]
	v_mfma_f32_16x16x32_bf16 v[18:21], v[186:189], v[232:235], 0
	v_mfma_f32_16x16x32_bf16 v[18:21], v[190:193], v[236:239], v[18:21]
	v_mfma_f32_16x16x32_bf16 v[22:25], v[178:181], v[232:235], 0
	v_mfma_f32_16x16x32_bf16 v[22:25], v[182:185], v[236:239], v[22:25]
	v_mfma_f32_16x16x32_bf16 v[6:9], v[178:181], v[240:243], 0
	v_mfma_f32_16x16x32_bf16 v[6:9], v[182:185], v[244:247], v[6:9]
	v_mfma_f32_16x16x32_bf16 v[2:5], v[186:189], v[240:243], 0
	v_mfma_f32_16x16x32_bf16 v[2:5], v[190:193], v[244:247], v[2:5]
	v_mfma_f32_16x16x32_bf16 v[10:13], v[170:173], v[240:243], 0
	v_mfma_f32_16x16x32_bf16 v[10:13], v[174:177], v[244:247], v[10:13]
	v_mfma_f32_16x16x32_bf16 v[14:17], v[132:135], v[240:243], 0
	v_mfma_f32_16x16x32_bf16 v[14:17], v[142:145], v[244:247], v[14:17]
	s_barrier
	s_setprio 0
	v_add_u32_e32 v154, 0x18000, v140
	ds_read_b128 v[132:135], v154
	ds_read_b128 v[142:145], v154 offset:1024
	ds_read_b128 v[170:173], v154 offset:2048
	ds_read_b128 v[174:177], v154 offset:3072
	v_add_u32_e32 v154, 0x1c000, v140
	ds_read_b128 v[178:181], v154
	ds_read_b128 v[182:185], v154 offset:1024
	ds_read_b128 v[186:189], v154 offset:2048
	ds_read_b128 v[190:193], v154 offset:3072
	s_bitset1_b32 s27, 14
	s_mov_b32 m0, s25
	ds_read_b128 v[194:197], v141 offset:32768
	ds_read_b128 v[198:201], v141 offset:33792
	ds_read_b128 v[202:205], v141 offset:34816
	ds_read_b128 v[228:231], v141 offset:35840
	ds_read_b128 v[232:235], v141 offset:36864
	ds_read_b128 v[236:239], v141 offset:37888
	ds_read_b128 v[240:243], v141 offset:38912
	ds_read_b128 v[244:247], v141 offset:39936
	buffer_load_dwordx4 v136, s[60:63], s27 offen lds
	s_mov_b32 m0, s30
	s_nop 0
	buffer_load_dwordx4 v138, s[60:63], s27 offen lds
	s_waitcnt vmcnt(8)
	s_waitcnt lgkmcnt(0)
	s_setprio 1
	s_barrier
	v_mfma_f32_16x16x32_bf16 v[126:129], v[132:135], v[194:197], v[126:129]
	v_mfma_f32_16x16x32_bf16 v[126:129], v[142:145], v[198:201], v[126:129]
	v_mfma_f32_16x16x32_bf16 v[106:109], v[170:173], v[194:197], v[106:109]
	v_mfma_f32_16x16x32_bf16 v[106:109], v[174:177], v[198:201], v[106:109]
	v_mfma_f32_16x16x32_bf16 v[110:113], v[186:189], v[194:197], v[110:113]
	v_mfma_f32_16x16x32_bf16 v[110:113], v[190:193], v[198:201], v[110:113]
	v_mfma_f32_16x16x32_bf16 v[122:125], v[178:181], v[194:197], v[122:125]
	v_mfma_f32_16x16x32_bf16 v[122:125], v[182:185], v[198:201], v[122:125]
	v_mfma_f32_16x16x32_bf16 v[102:105], v[178:181], v[202:205], v[102:105]
	v_mfma_f32_16x16x32_bf16 v[102:105], v[182:185], v[228:231], v[102:105]
	v_mfma_f32_16x16x32_bf16 v[98:101], v[186:189], v[202:205], v[98:101]
	v_mfma_f32_16x16x32_bf16 v[98:101], v[190:193], v[228:231], v[98:101]
	v_mfma_f32_16x16x32_bf16 v[114:117], v[170:173], v[202:205], v[114:117]
	v_mfma_f32_16x16x32_bf16 v[114:117], v[174:177], v[228:231], v[114:117]
	v_mfma_f32_16x16x32_bf16 v[118:121], v[132:135], v[202:205], v[118:121]
	v_mfma_f32_16x16x32_bf16 v[118:121], v[142:145], v[228:231], v[118:121]
	v_mfma_f32_16x16x32_bf16 v[94:97], v[132:135], v[232:235], v[94:97]
	v_mfma_f32_16x16x32_bf16 v[94:97], v[142:145], v[236:239], v[94:97]
	v_mfma_f32_16x16x32_bf16 v[90:93], v[170:173], v[232:235], v[90:93]
	v_mfma_f32_16x16x32_bf16 v[90:93], v[174:177], v[236:239], v[90:93]
	v_mfma_f32_16x16x32_bf16 v[82:85], v[186:189], v[232:235], v[82:85]
	v_mfma_f32_16x16x32_bf16 v[82:85], v[190:193], v[236:239], v[82:85]
	v_mfma_f32_16x16x32_bf16 v[86:89], v[178:181], v[232:235], v[86:89]
	v_mfma_f32_16x16x32_bf16 v[86:89], v[182:185], v[236:239], v[86:89]
	v_mfma_f32_16x16x32_bf16 v[70:73], v[178:181], v[240:243], v[70:73]
	v_mfma_f32_16x16x32_bf16 v[70:73], v[182:185], v[244:247], v[70:73]
	v_mfma_f32_16x16x32_bf16 v[66:69], v[186:189], v[240:243], v[66:69]
	v_mfma_f32_16x16x32_bf16 v[66:69], v[190:193], v[244:247], v[66:69]
	v_mfma_f32_16x16x32_bf16 v[74:77], v[170:173], v[240:243], v[74:77]
	v_mfma_f32_16x16x32_bf16 v[74:77], v[174:177], v[244:247], v[74:77]
	v_mfma_f32_16x16x32_bf16 v[78:81], v[132:135], v[240:243], v[78:81]
	v_mfma_f32_16x16x32_bf16 v[78:81], v[142:145], v[244:247], v[78:81]
	s_barrier
	s_setprio 0
	s_mov_b32 m0, s36
	s_or_b32 s27, s26, 0x80
	ds_read_b128 v[194:197], v141 offset:49152
	ds_read_b128 v[198:201], v141 offset:50176
	ds_read_b128 v[202:205], v141 offset:51200
	ds_read_b128 v[228:231], v141 offset:52224
	ds_read_b128 v[232:235], v141 offset:53248
	ds_read_b128 v[236:239], v141 offset:54272
	ds_read_b128 v[240:243], v141 offset:55296
	ds_read_b128 v[244:247], v141 offset:56320
	buffer_load_dwordx4 v137, s[44:47], s27 offen lds
	s_mov_b32 m0, s37
	s_add_i32 s26, s26, 0x160080
	buffer_load_dwordx4 v139, s[44:47], s27 offen lds
	s_mov_b32 m0, s66
	s_nop 0
	buffer_load_dwordx4 v137, s[44:47], s26 offen lds
	s_mov_b32 m0, s67
	s_nop 0
	buffer_load_dwordx4 v139, s[44:47], s26 offen lds
	s_mov_b32 m0, s48
	s_nop 0
	buffer_load_dwordx4 v136, s[60:63], s23 offen lds
	s_mov_b32 m0, s49
	s_nop 0
	buffer_load_dwordx4 v138, s[60:63], s23 offen lds
	s_waitcnt vmcnt(8)
	s_waitcnt lgkmcnt(0)
	s_setprio 1
	s_barrier
	v_mfma_f32_16x16x32_bf16 v[62:65], v[132:135], v[194:197], v[62:65]
	v_mfma_f32_16x16x32_bf16 v[62:65], v[142:145], v[198:201], v[62:65]
	v_mfma_f32_16x16x32_bf16 v[58:61], v[170:173], v[194:197], v[58:61]
	v_mfma_f32_16x16x32_bf16 v[58:61], v[174:177], v[198:201], v[58:61]
	v_mfma_f32_16x16x32_bf16 v[50:53], v[186:189], v[194:197], v[50:53]
	v_mfma_f32_16x16x32_bf16 v[50:53], v[190:193], v[198:201], v[50:53]
	v_mfma_f32_16x16x32_bf16 v[54:57], v[178:181], v[194:197], v[54:57]
	v_mfma_f32_16x16x32_bf16 v[54:57], v[182:185], v[198:201], v[54:57]
	v_mfma_f32_16x16x32_bf16 v[38:41], v[178:181], v[202:205], v[38:41]
	v_mfma_f32_16x16x32_bf16 v[38:41], v[182:185], v[228:231], v[38:41]
	v_mfma_f32_16x16x32_bf16 v[34:37], v[186:189], v[202:205], v[34:37]
	v_mfma_f32_16x16x32_bf16 v[34:37], v[190:193], v[228:231], v[34:37]
	v_mfma_f32_16x16x32_bf16 v[42:45], v[170:173], v[202:205], v[42:45]
	v_mfma_f32_16x16x32_bf16 v[42:45], v[174:177], v[228:231], v[42:45]
	v_mfma_f32_16x16x32_bf16 v[46:49], v[132:135], v[202:205], v[46:49]
	v_mfma_f32_16x16x32_bf16 v[46:49], v[142:145], v[228:231], v[46:49]
	v_mfma_f32_16x16x32_bf16 v[30:33], v[132:135], v[232:235], v[30:33]
	v_mfma_f32_16x16x32_bf16 v[30:33], v[142:145], v[236:239], v[30:33]
	v_mfma_f32_16x16x32_bf16 v[26:29], v[170:173], v[232:235], v[26:29]
	v_mfma_f32_16x16x32_bf16 v[26:29], v[174:177], v[236:239], v[26:29]
	v_mfma_f32_16x16x32_bf16 v[18:21], v[186:189], v[232:235], v[18:21]
	v_mfma_f32_16x16x32_bf16 v[18:21], v[190:193], v[236:239], v[18:21]
	v_mfma_f32_16x16x32_bf16 v[22:25], v[178:181], v[232:235], v[22:25]
	v_mfma_f32_16x16x32_bf16 v[22:25], v[182:185], v[236:239], v[22:25]
	v_mfma_f32_16x16x32_bf16 v[6:9], v[178:181], v[240:243], v[6:9]
	v_mfma_f32_16x16x32_bf16 v[6:9], v[182:185], v[244:247], v[6:9]
	v_mfma_f32_16x16x32_bf16 v[2:5], v[186:189], v[240:243], v[2:5]
	v_mfma_f32_16x16x32_bf16 v[2:5], v[190:193], v[244:247], v[2:5]
	v_mfma_f32_16x16x32_bf16 v[10:13], v[170:173], v[240:243], v[10:13]
	v_mfma_f32_16x16x32_bf16 v[10:13], v[174:177], v[244:247], v[10:13]
	v_mfma_f32_16x16x32_bf16 v[14:17], v[132:135], v[240:243], v[14:17]
	v_mfma_f32_16x16x32_bf16 v[14:17], v[142:145], v[244:247], v[14:17]
	s_barrier
	s_setprio 0
	s_addk_i32 s13, 0x100
	s_add_i32 s22, s22, 2
	s_add_i32 s21, s21, 0x10000
	s_cmpk_gt_u32 s22, 0x55
.LBB0_580:
	v_add_u32_e32 v154, 0x10000, v140
	ds_read_b128 v[132:135], v154
	ds_read_b128 v[142:145], v154 offset:1024
	ds_read_b128 v[170:173], v154 offset:2048
	ds_read_b128 v[174:177], v154 offset:3072
	v_add_u32_e32 v154, 0x14000, v140
	ds_read_b128 v[178:181], v154
	ds_read_b128 v[182:185], v154 offset:1024
	ds_read_b128 v[186:189], v154 offset:2048
	ds_read_b128 v[190:193], v154 offset:3072
	s_add_i32 s23, s21, 0x4000
	s_cmpk_eq_i32 s22, 0x54
	s_cselect_b32 s27, s8, s23
	s_cselect_b32 s26, s9, s13
	s_or_b32 s23, s27, 0x8000
	s_mov_b32 m0, s68
	ds_read_b128 v[194:197], v141
	ds_read_b128 v[198:201], v141 offset:1024
	ds_read_b128 v[202:205], v141 offset:2048
	ds_read_b128 v[228:231], v141 offset:3072
	ds_read_b128 v[232:235], v141 offset:4096
	ds_read_b128 v[236:239], v141 offset:5120
	ds_read_b128 v[240:243], v141 offset:6144
	ds_read_b128 v[244:247], v141 offset:7168
	buffer_load_dwordx4 v136, s[60:63], s21 offen lds
	s_mov_b32 m0, s70
	s_nop 0
	buffer_load_dwordx4 v138, s[60:63], s21 offen lds
	s_waitcnt vmcnt(8)
	s_waitcnt lgkmcnt(0)
	s_setprio 1
	s_barrier
	v_mfma_f32_16x16x32_bf16 v[126:129], v[132:135], v[194:197], v[126:129]
	v_mfma_f32_16x16x32_bf16 v[126:129], v[142:145], v[198:201], v[126:129]
	v_mfma_f32_16x16x32_bf16 v[106:109], v[170:173], v[194:197], v[106:109]
	v_mfma_f32_16x16x32_bf16 v[106:109], v[174:177], v[198:201], v[106:109]
	v_mfma_f32_16x16x32_bf16 v[110:113], v[186:189], v[194:197], v[110:113]
	v_mfma_f32_16x16x32_bf16 v[110:113], v[190:193], v[198:201], v[110:113]
	v_mfma_f32_16x16x32_bf16 v[122:125], v[178:181], v[194:197], v[122:125]
	v_mfma_f32_16x16x32_bf16 v[122:125], v[182:185], v[198:201], v[122:125]
	v_mfma_f32_16x16x32_bf16 v[102:105], v[178:181], v[202:205], v[102:105]
	v_mfma_f32_16x16x32_bf16 v[102:105], v[182:185], v[228:231], v[102:105]
	v_mfma_f32_16x16x32_bf16 v[98:101], v[186:189], v[202:205], v[98:101]
	v_mfma_f32_16x16x32_bf16 v[98:101], v[190:193], v[228:231], v[98:101]
	v_mfma_f32_16x16x32_bf16 v[114:117], v[170:173], v[202:205], v[114:117]
	v_mfma_f32_16x16x32_bf16 v[114:117], v[174:177], v[228:231], v[114:117]
	v_mfma_f32_16x16x32_bf16 v[118:121], v[132:135], v[202:205], v[118:121]
	v_mfma_f32_16x16x32_bf16 v[118:121], v[142:145], v[228:231], v[118:121]
	v_mfma_f32_16x16x32_bf16 v[94:97], v[132:135], v[232:235], v[94:97]
	v_mfma_f32_16x16x32_bf16 v[94:97], v[142:145], v[236:239], v[94:97]
	v_mfma_f32_16x16x32_bf16 v[90:93], v[170:173], v[232:235], v[90:93]
	v_mfma_f32_16x16x32_bf16 v[90:93], v[174:177], v[236:239], v[90:93]
	v_mfma_f32_16x16x32_bf16 v[82:85], v[186:189], v[232:235], v[82:85]
	v_mfma_f32_16x16x32_bf16 v[82:85], v[190:193], v[236:239], v[82:85]
	v_mfma_f32_16x16x32_bf16 v[86:89], v[178:181], v[232:235], v[86:89]
	v_mfma_f32_16x16x32_bf16 v[86:89], v[182:185], v[236:239], v[86:89]
	v_mfma_f32_16x16x32_bf16 v[70:73], v[178:181], v[240:243], v[70:73]
	v_mfma_f32_16x16x32_bf16 v[70:73], v[182:185], v[244:247], v[70:73]
	v_mfma_f32_16x16x32_bf16 v[66:69], v[186:189], v[240:243], v[66:69]
	v_mfma_f32_16x16x32_bf16 v[66:69], v[190:193], v[244:247], v[66:69]
	v_mfma_f32_16x16x32_bf16 v[74:77], v[170:173], v[240:243], v[74:77]
	v_mfma_f32_16x16x32_bf16 v[74:77], v[174:177], v[244:247], v[74:77]
	v_mfma_f32_16x16x32_bf16 v[78:81], v[132:135], v[240:243], v[78:81]
	v_mfma_f32_16x16x32_bf16 v[78:81], v[142:145], v[244:247], v[78:81]
	s_barrier
	s_setprio 0
	s_mov_b32 m0, s15
	s_mov_b32 s46, s62
	s_mov_b32 s47, s63
	ds_read_b128 v[194:197], v141 offset:16384
	ds_read_b128 v[198:201], v141 offset:17408
	ds_read_b128 v[202:205], v141 offset:18432
	ds_read_b128 v[228:231], v141 offset:19456
	ds_read_b128 v[232:235], v141 offset:20480
	ds_read_b128 v[236:239], v141 offset:21504
	ds_read_b128 v[240:243], v141 offset:22528
	ds_read_b128 v[244:247], v141 offset:23552
	buffer_load_dwordx4 v137, s[44:47], s26 offen lds
	s_mov_b32 m0, s16
	s_add_i32 s52, s26, 0x160000
	buffer_load_dwordx4 v139, s[44:47], s26 offen lds
	s_mov_b32 m0, s18
	s_nop 0
	buffer_load_dwordx4 v137, s[44:47], s52 offen lds
	s_mov_b32 m0, s19
	s_nop 0
	buffer_load_dwordx4 v139, s[44:47], s52 offen lds
	s_mov_b32 m0, s14
	s_nop 0
	buffer_load_dwordx4 v136, s[60:63], s27 offen lds
	s_mov_b32 m0, s24
	s_nop 0
	buffer_load_dwordx4 v138, s[60:63], s27 offen lds
	s_waitcnt vmcnt(8)
	s_waitcnt lgkmcnt(0)
	s_setprio 1
	s_barrier
	v_mfma_f32_16x16x32_bf16 v[62:65], v[132:135], v[194:197], v[62:65]
	v_mfma_f32_16x16x32_bf16 v[62:65], v[142:145], v[198:201], v[62:65]
	v_mfma_f32_16x16x32_bf16 v[58:61], v[170:173], v[194:197], v[58:61]
	v_mfma_f32_16x16x32_bf16 v[58:61], v[174:177], v[198:201], v[58:61]
	v_mfma_f32_16x16x32_bf16 v[50:53], v[186:189], v[194:197], v[50:53]
	v_mfma_f32_16x16x32_bf16 v[50:53], v[190:193], v[198:201], v[50:53]
	v_mfma_f32_16x16x32_bf16 v[54:57], v[178:181], v[194:197], v[54:57]
	v_mfma_f32_16x16x32_bf16 v[54:57], v[182:185], v[198:201], v[54:57]
	v_mfma_f32_16x16x32_bf16 v[38:41], v[178:181], v[202:205], v[38:41]
	v_mfma_f32_16x16x32_bf16 v[38:41], v[182:185], v[228:231], v[38:41]
	v_mfma_f32_16x16x32_bf16 v[34:37], v[186:189], v[202:205], v[34:37]
	v_mfma_f32_16x16x32_bf16 v[34:37], v[190:193], v[228:231], v[34:37]
	v_mfma_f32_16x16x32_bf16 v[42:45], v[170:173], v[202:205], v[42:45]
	v_mfma_f32_16x16x32_bf16 v[42:45], v[174:177], v[228:231], v[42:45]
	v_mfma_f32_16x16x32_bf16 v[46:49], v[132:135], v[202:205], v[46:49]
	v_mfma_f32_16x16x32_bf16 v[46:49], v[142:145], v[228:231], v[46:49]
	v_mfma_f32_16x16x32_bf16 v[30:33], v[132:135], v[232:235], v[30:33]
	v_mfma_f32_16x16x32_bf16 v[30:33], v[142:145], v[236:239], v[30:33]
	v_mfma_f32_16x16x32_bf16 v[26:29], v[170:173], v[232:235], v[26:29]
	v_mfma_f32_16x16x32_bf16 v[26:29], v[174:177], v[236:239], v[26:29]
	v_mfma_f32_16x16x32_bf16 v[18:21], v[186:189], v[232:235], v[18:21]
	v_mfma_f32_16x16x32_bf16 v[18:21], v[190:193], v[236:239], v[18:21]
	v_mfma_f32_16x16x32_bf16 v[22:25], v[178:181], v[232:235], v[22:25]
	v_mfma_f32_16x16x32_bf16 v[22:25], v[182:185], v[236:239], v[22:25]
	v_mfma_f32_16x16x32_bf16 v[6:9], v[178:181], v[240:243], v[6:9]
	v_mfma_f32_16x16x32_bf16 v[6:9], v[182:185], v[244:247], v[6:9]
	v_mfma_f32_16x16x32_bf16 v[2:5], v[186:189], v[240:243], v[2:5]
	v_mfma_f32_16x16x32_bf16 v[2:5], v[190:193], v[244:247], v[2:5]
	v_mfma_f32_16x16x32_bf16 v[10:13], v[170:173], v[240:243], v[10:13]
	v_mfma_f32_16x16x32_bf16 v[10:13], v[174:177], v[244:247], v[10:13]
	v_mfma_f32_16x16x32_bf16 v[14:17], v[132:135], v[240:243], v[14:17]
	v_mfma_f32_16x16x32_bf16 v[14:17], v[142:145], v[244:247], v[14:17]
	s_barrier
	s_setprio 0
	v_add_u32_e32 v154, 0x18000, v140
	ds_read_b128 v[132:135], v154
	ds_read_b128 v[142:145], v154 offset:1024
	ds_read_b128 v[170:173], v154 offset:2048
	ds_read_b128 v[174:177], v154 offset:3072
	v_add_u32_e32 v154, 0x1c000, v140
	ds_read_b128 v[178:181], v154
	ds_read_b128 v[182:185], v154 offset:1024
	ds_read_b128 v[186:189], v154 offset:2048
	ds_read_b128 v[190:193], v154 offset:3072
	s_bitset1_b32 s27, 14
	s_mov_b32 m0, s25
	ds_read_b128 v[194:197], v141 offset:32768
	ds_read_b128 v[198:201], v141 offset:33792
	ds_read_b128 v[202:205], v141 offset:34816
	ds_read_b128 v[228:231], v141 offset:35840
	ds_read_b128 v[232:235], v141 offset:36864
	ds_read_b128 v[236:239], v141 offset:37888
	ds_read_b128 v[240:243], v141 offset:38912
	ds_read_b128 v[244:247], v141 offset:39936
	buffer_load_dwordx4 v136, s[60:63], s27 offen lds
	s_mov_b32 m0, s30
	s_nop 0
	buffer_load_dwordx4 v138, s[60:63], s27 offen lds
	s_waitcnt vmcnt(8)
	s_waitcnt lgkmcnt(0)
	s_setprio 1
	s_barrier
	v_mfma_f32_16x16x32_bf16 v[126:129], v[132:135], v[194:197], v[126:129]
	v_mfma_f32_16x16x32_bf16 v[126:129], v[142:145], v[198:201], v[126:129]
	v_mfma_f32_16x16x32_bf16 v[106:109], v[170:173], v[194:197], v[106:109]
	v_mfma_f32_16x16x32_bf16 v[106:109], v[174:177], v[198:201], v[106:109]
	v_mfma_f32_16x16x32_bf16 v[110:113], v[186:189], v[194:197], v[110:113]
	v_mfma_f32_16x16x32_bf16 v[110:113], v[190:193], v[198:201], v[110:113]
	v_mfma_f32_16x16x32_bf16 v[122:125], v[178:181], v[194:197], v[122:125]
	v_mfma_f32_16x16x32_bf16 v[122:125], v[182:185], v[198:201], v[122:125]
	v_mfma_f32_16x16x32_bf16 v[102:105], v[178:181], v[202:205], v[102:105]
	v_mfma_f32_16x16x32_bf16 v[102:105], v[182:185], v[228:231], v[102:105]
	v_mfma_f32_16x16x32_bf16 v[98:101], v[186:189], v[202:205], v[98:101]
	v_mfma_f32_16x16x32_bf16 v[98:101], v[190:193], v[228:231], v[98:101]
	v_mfma_f32_16x16x32_bf16 v[114:117], v[170:173], v[202:205], v[114:117]
	v_mfma_f32_16x16x32_bf16 v[114:117], v[174:177], v[228:231], v[114:117]
	v_mfma_f32_16x16x32_bf16 v[118:121], v[132:135], v[202:205], v[118:121]
	v_mfma_f32_16x16x32_bf16 v[118:121], v[142:145], v[228:231], v[118:121]
	v_mfma_f32_16x16x32_bf16 v[94:97], v[132:135], v[232:235], v[94:97]
	v_mfma_f32_16x16x32_bf16 v[94:97], v[142:145], v[236:239], v[94:97]
	v_mfma_f32_16x16x32_bf16 v[90:93], v[170:173], v[232:235], v[90:93]
	v_mfma_f32_16x16x32_bf16 v[90:93], v[174:177], v[236:239], v[90:93]
	v_mfma_f32_16x16x32_bf16 v[82:85], v[186:189], v[232:235], v[82:85]
	v_mfma_f32_16x16x32_bf16 v[82:85], v[190:193], v[236:239], v[82:85]
	v_mfma_f32_16x16x32_bf16 v[86:89], v[178:181], v[232:235], v[86:89]
	v_mfma_f32_16x16x32_bf16 v[86:89], v[182:185], v[236:239], v[86:89]
	v_mfma_f32_16x16x32_bf16 v[70:73], v[178:181], v[240:243], v[70:73]
	v_mfma_f32_16x16x32_bf16 v[70:73], v[182:185], v[244:247], v[70:73]
	v_mfma_f32_16x16x32_bf16 v[66:69], v[186:189], v[240:243], v[66:69]
	v_mfma_f32_16x16x32_bf16 v[66:69], v[190:193], v[244:247], v[66:69]
	v_mfma_f32_16x16x32_bf16 v[74:77], v[170:173], v[240:243], v[74:77]
	v_mfma_f32_16x16x32_bf16 v[74:77], v[174:177], v[244:247], v[74:77]
	v_mfma_f32_16x16x32_bf16 v[78:81], v[132:135], v[240:243], v[78:81]
	v_mfma_f32_16x16x32_bf16 v[78:81], v[142:145], v[244:247], v[78:81]
	s_barrier
	s_setprio 0
	s_mov_b32 m0, s36
	s_or_b32 s27, s26, 0x80
	ds_read_b128 v[194:197], v141 offset:49152
	ds_read_b128 v[198:201], v141 offset:50176
	ds_read_b128 v[202:205], v141 offset:51200
	ds_read_b128 v[228:231], v141 offset:52224
	ds_read_b128 v[232:235], v141 offset:53248
	ds_read_b128 v[236:239], v141 offset:54272
	ds_read_b128 v[240:243], v141 offset:55296
	ds_read_b128 v[244:247], v141 offset:56320
	buffer_load_dwordx4 v137, s[44:47], s27 offen lds
	s_mov_b32 m0, s37
	s_add_i32 s26, s26, 0x160080
	buffer_load_dwordx4 v139, s[44:47], s27 offen lds
	s_mov_b32 m0, s66
	s_nop 0
	buffer_load_dwordx4 v137, s[44:47], s26 offen lds
	s_mov_b32 m0, s67
	s_nop 0
	buffer_load_dwordx4 v139, s[44:47], s26 offen lds
	s_mov_b32 m0, s48
	s_nop 0
	buffer_load_dwordx4 v136, s[60:63], s23 offen lds
	s_mov_b32 m0, s49
	s_nop 0
	buffer_load_dwordx4 v138, s[60:63], s23 offen lds
	s_waitcnt vmcnt(8)
	s_waitcnt lgkmcnt(0)
	s_setprio 1
	s_barrier
	v_mfma_f32_16x16x32_bf16 v[62:65], v[132:135], v[194:197], v[62:65]
	v_mfma_f32_16x16x32_bf16 v[62:65], v[142:145], v[198:201], v[62:65]
	v_mfma_f32_16x16x32_bf16 v[58:61], v[170:173], v[194:197], v[58:61]
	v_mfma_f32_16x16x32_bf16 v[58:61], v[174:177], v[198:201], v[58:61]
	v_mfma_f32_16x16x32_bf16 v[50:53], v[186:189], v[194:197], v[50:53]
	v_mfma_f32_16x16x32_bf16 v[50:53], v[190:193], v[198:201], v[50:53]
	v_mfma_f32_16x16x32_bf16 v[54:57], v[178:181], v[194:197], v[54:57]
	v_mfma_f32_16x16x32_bf16 v[54:57], v[182:185], v[198:201], v[54:57]
	v_mfma_f32_16x16x32_bf16 v[38:41], v[178:181], v[202:205], v[38:41]
	v_mfma_f32_16x16x32_bf16 v[38:41], v[182:185], v[228:231], v[38:41]
	v_mfma_f32_16x16x32_bf16 v[34:37], v[186:189], v[202:205], v[34:37]
	v_mfma_f32_16x16x32_bf16 v[34:37], v[190:193], v[228:231], v[34:37]
	v_mfma_f32_16x16x32_bf16 v[42:45], v[170:173], v[202:205], v[42:45]
	v_mfma_f32_16x16x32_bf16 v[42:45], v[174:177], v[228:231], v[42:45]
	v_mfma_f32_16x16x32_bf16 v[46:49], v[132:135], v[202:205], v[46:49]
	v_mfma_f32_16x16x32_bf16 v[46:49], v[142:145], v[228:231], v[46:49]
	v_mfma_f32_16x16x32_bf16 v[30:33], v[132:135], v[232:235], v[30:33]
	v_mfma_f32_16x16x32_bf16 v[30:33], v[142:145], v[236:239], v[30:33]
	v_mfma_f32_16x16x32_bf16 v[26:29], v[170:173], v[232:235], v[26:29]
	v_mfma_f32_16x16x32_bf16 v[26:29], v[174:177], v[236:239], v[26:29]
	v_mfma_f32_16x16x32_bf16 v[18:21], v[186:189], v[232:235], v[18:21]
	v_mfma_f32_16x16x32_bf16 v[18:21], v[190:193], v[236:239], v[18:21]
	v_mfma_f32_16x16x32_bf16 v[22:25], v[178:181], v[232:235], v[22:25]
	v_mfma_f32_16x16x32_bf16 v[22:25], v[182:185], v[236:239], v[22:25]
	v_mfma_f32_16x16x32_bf16 v[6:9], v[178:181], v[240:243], v[6:9]
	v_mfma_f32_16x16x32_bf16 v[6:9], v[182:185], v[244:247], v[6:9]
	v_mfma_f32_16x16x32_bf16 v[2:5], v[186:189], v[240:243], v[2:5]
	v_mfma_f32_16x16x32_bf16 v[2:5], v[190:193], v[244:247], v[2:5]
	v_mfma_f32_16x16x32_bf16 v[10:13], v[170:173], v[240:243], v[10:13]
	v_mfma_f32_16x16x32_bf16 v[10:13], v[174:177], v[244:247], v[10:13]
	v_mfma_f32_16x16x32_bf16 v[14:17], v[132:135], v[240:243], v[14:17]
	v_mfma_f32_16x16x32_bf16 v[14:17], v[142:145], v[244:247], v[14:17]
	s_barrier
	s_setprio 0
	s_addk_i32 s13, 0x100
	s_add_i32 s22, s22, 2
	s_add_i32 s21, s21, 0x10000
	s_cmpk_gt_u32 s22, 0x55
	s_cbranch_scc0 .LBB0_580
	s_and_b64 vcc, exec, s[64:65]
	s_cbranch_vccz .LBB0_583
	s_barrier

.LBB0_858:
	s_lshl_b32 s2, s21, 20
	s_and_b64 s[8:9], s[42:43], exec
	s_cselect_b32 s8, s2, s18
	s_lshl_b32 s82, s71, 20
	s_and_b64 s[26:27], s[42:43], exec
	s_cselect_b32 s9, s82, s19
	s_add_i32 s18, s18, 0x80080
	s_addk_i32 s19, 0x100
	s_mov_b32 s22, -2
	v_add_u32_e32 v146, 0x10000, v195
	ds_read_b128 v[130:133], v146
	ds_read_b128 v[138:141], v146 offset:1024
	ds_read_b128 v[142:145], v146 offset:2048
	ds_read_b128 v[154:157], v146 offset:3072
	v_add_u32_e32 v146, 0x14000, v195
	ds_read_b128 v[170:173], v146
	ds_read_b128 v[174:177], v146 offset:1024
	ds_read_b128 v[178:181], v146 offset:2048
	ds_read_b128 v[182:185], v146 offset:3072
	s_add_i32 s26, s18, 0xfff80080
	s_cmp_eq_u32 s22, 28
	s_cselect_b32 s52, s8, s26
	s_cselect_b32 s27, s9, s19
	s_or_b32 s26, s52, 0x80
	s_mov_b32 m0, s85
	ds_read_b128 v[186:189], v196
	ds_read_b128 v[198:201], v196 offset:1024
	ds_read_b128 v[202:205], v196 offset:2048
	ds_read_b128 v[228:231], v196 offset:3072
	ds_read_b128 v[232:235], v196 offset:4096
	ds_read_b128 v[236:239], v196 offset:5120
	ds_read_b128 v[240:243], v196 offset:6144
	ds_read_b128 v[244:247], v196 offset:7168
	buffer_load_dwordx4 v135, s[44:47], s18 offen lds
	s_mov_b32 m0, s15
	s_nop 0
	buffer_load_dwordx4 v193, s[44:47], s18 offen lds
	s_waitcnt vmcnt(8)
	s_waitcnt lgkmcnt(0)
	s_setprio 1
	s_barrier
	v_mfma_f32_16x16x32_bf16 v[126:129], v[130:133], v[186:189], 0
	v_mfma_f32_16x16x32_bf16 v[126:129], v[138:141], v[198:201], v[126:129]
	v_mfma_f32_16x16x32_bf16 v[122:125], v[142:145], v[186:189], 0
	v_mfma_f32_16x16x32_bf16 v[122:125], v[154:157], v[198:201], v[122:125]
	v_mfma_f32_16x16x32_bf16 v[114:117], v[178:181], v[186:189], 0
	v_mfma_f32_16x16x32_bf16 v[114:117], v[182:185], v[198:201], v[114:117]
	v_mfma_f32_16x16x32_bf16 v[118:121], v[170:173], v[186:189], 0
	v_mfma_f32_16x16x32_bf16 v[118:121], v[174:177], v[198:201], v[118:121]
	v_mfma_f32_16x16x32_bf16 v[102:105], v[170:173], v[202:205], 0
	v_mfma_f32_16x16x32_bf16 v[102:105], v[174:177], v[228:231], v[102:105]
	v_mfma_f32_16x16x32_bf16 v[98:101], v[178:181], v[202:205], 0
	v_mfma_f32_16x16x32_bf16 v[98:101], v[182:185], v[228:231], v[98:101]
	v_mfma_f32_16x16x32_bf16 v[106:109], v[142:145], v[202:205], 0
	v_mfma_f32_16x16x32_bf16 v[106:109], v[154:157], v[228:231], v[106:109]
	v_mfma_f32_16x16x32_bf16 v[110:113], v[130:133], v[202:205], 0
	v_mfma_f32_16x16x32_bf16 v[110:113], v[138:141], v[228:231], v[110:113]
	v_mfma_f32_16x16x32_bf16 v[94:97], v[130:133], v[232:235], 0
	v_mfma_f32_16x16x32_bf16 v[94:97], v[138:141], v[236:239], v[94:97]
	v_mfma_f32_16x16x32_bf16 v[90:93], v[142:145], v[232:235], 0
	v_mfma_f32_16x16x32_bf16 v[90:93], v[154:157], v[236:239], v[90:93]
	v_mfma_f32_16x16x32_bf16 v[82:85], v[178:181], v[232:235], 0
	v_mfma_f32_16x16x32_bf16 v[82:85], v[182:185], v[236:239], v[82:85]
	v_mfma_f32_16x16x32_bf16 v[86:89], v[170:173], v[232:235], 0
	v_mfma_f32_16x16x32_bf16 v[86:89], v[174:177], v[236:239], v[86:89]
	v_mfma_f32_16x16x32_bf16 v[70:73], v[170:173], v[240:243], 0
	v_mfma_f32_16x16x32_bf16 v[70:73], v[174:177], v[244:247], v[70:73]
	v_mfma_f32_16x16x32_bf16 v[66:69], v[178:181], v[240:243], 0
	v_mfma_f32_16x16x32_bf16 v[66:69], v[182:185], v[244:247], v[66:69]
	v_mfma_f32_16x16x32_bf16 v[74:77], v[142:145], v[240:243], 0
	v_mfma_f32_16x16x32_bf16 v[74:77], v[154:157], v[244:247], v[74:77]
	v_mfma_f32_16x16x32_bf16 v[78:81], v[130:133], v[240:243], 0
	v_mfma_f32_16x16x32_bf16 v[78:81], v[138:141], v[244:247], v[78:81]
	s_barrier
	s_setprio 0
	s_mov_b32 m0, s23
	s_mov_b32 s66, s46
	s_mov_b32 s67, s47
	ds_read_b128 v[186:189], v196 offset:16384
	ds_read_b128 v[198:201], v196 offset:17408
	ds_read_b128 v[202:205], v196 offset:18432
	ds_read_b128 v[228:231], v196 offset:19456
	ds_read_b128 v[232:235], v196 offset:20480
	ds_read_b128 v[236:239], v196 offset:21504
	ds_read_b128 v[240:243], v196 offset:22528
	ds_read_b128 v[244:247], v196 offset:23552
	buffer_load_dwordx4 v192, s[64:67], s27 offen lds
	s_mov_b32 m0, s24
	s_add_i32 s53, s27, 0x80000
	buffer_load_dwordx4 v194, s[64:67], s27 offen lds
	s_mov_b32 m0, s25
	s_nop 0
	buffer_load_dwordx4 v192, s[64:67], s53 offen lds
	s_mov_b32 m0, s33
	s_nop 0
	buffer_load_dwordx4 v194, s[64:67], s53 offen lds
	s_mov_b32 m0, s13
	s_nop 0
	buffer_load_dwordx4 v135, s[44:47], s52 offen lds
	s_mov_b32 m0, s34
	s_nop 0
	buffer_load_dwordx4 v193, s[44:47], s52 offen lds
	s_waitcnt vmcnt(8)
	s_waitcnt lgkmcnt(0)
	s_setprio 1
	s_barrier
	v_mfma_f32_16x16x32_bf16 v[62:65], v[130:133], v[186:189], 0
	v_mfma_f32_16x16x32_bf16 v[62:65], v[138:141], v[198:201], v[62:65]
	v_mfma_f32_16x16x32_bf16 v[58:61], v[142:145], v[186:189], 0
	v_mfma_f32_16x16x32_bf16 v[58:61], v[154:157], v[198:201], v[58:61]
	v_mfma_f32_16x16x32_bf16 v[50:53], v[178:181], v[186:189], 0
	v_mfma_f32_16x16x32_bf16 v[50:53], v[182:185], v[198:201], v[50:53]
	v_mfma_f32_16x16x32_bf16 v[54:57], v[170:173], v[186:189], 0
	v_mfma_f32_16x16x32_bf16 v[54:57], v[174:177], v[198:201], v[54:57]
	v_mfma_f32_16x16x32_bf16 v[38:41], v[170:173], v[202:205], 0
	v_mfma_f32_16x16x32_bf16 v[38:41], v[174:177], v[228:231], v[38:41]
	v_mfma_f32_16x16x32_bf16 v[34:37], v[178:181], v[202:205], 0
	v_mfma_f32_16x16x32_bf16 v[34:37], v[182:185], v[228:231], v[34:37]
	v_mfma_f32_16x16x32_bf16 v[42:45], v[142:145], v[202:205], 0
	v_mfma_f32_16x16x32_bf16 v[42:45], v[154:157], v[228:231], v[42:45]
	v_mfma_f32_16x16x32_bf16 v[46:49], v[130:133], v[202:205], 0
	v_mfma_f32_16x16x32_bf16 v[46:49], v[138:141], v[228:231], v[46:49]
	v_mfma_f32_16x16x32_bf16 v[30:33], v[130:133], v[232:235], 0
	v_mfma_f32_16x16x32_bf16 v[30:33], v[138:141], v[236:239], v[30:33]
	v_mfma_f32_16x16x32_bf16 v[26:29], v[142:145], v[232:235], 0
	v_mfma_f32_16x16x32_bf16 v[26:29], v[154:157], v[236:239], v[26:29]
	v_mfma_f32_16x16x32_bf16 v[18:21], v[178:181], v[232:235], 0
	v_mfma_f32_16x16x32_bf16 v[18:21], v[182:185], v[236:239], v[18:21]
	v_mfma_f32_16x16x32_bf16 v[22:25], v[170:173], v[232:235], 0
	v_mfma_f32_16x16x32_bf16 v[22:25], v[174:177], v[236:239], v[22:25]
	v_mfma_f32_16x16x32_bf16 v[6:9], v[170:173], v[240:243], 0
	v_mfma_f32_16x16x32_bf16 v[6:9], v[174:177], v[244:247], v[6:9]
	v_mfma_f32_16x16x32_bf16 v[2:5], v[178:181], v[240:243], 0
	v_mfma_f32_16x16x32_bf16 v[2:5], v[182:185], v[244:247], v[2:5]
	v_mfma_f32_16x16x32_bf16 v[10:13], v[142:145], v[240:243], 0
	v_mfma_f32_16x16x32_bf16 v[10:13], v[154:157], v[244:247], v[10:13]
	v_mfma_f32_16x16x32_bf16 v[14:17], v[130:133], v[240:243], 0
	v_mfma_f32_16x16x32_bf16 v[14:17], v[138:141], v[244:247], v[14:17]
	s_barrier
	s_setprio 0
	v_add_u32_e32 v146, 0x18000, v195
	ds_read_b128 v[130:133], v146
	ds_read_b128 v[138:141], v146 offset:1024
	ds_read_b128 v[142:145], v146 offset:2048
	ds_read_b128 v[154:157], v146 offset:3072
	v_add_u32_e32 v146, 0x1c000, v195
	ds_read_b128 v[170:173], v146
	ds_read_b128 v[174:177], v146 offset:1024
	ds_read_b128 v[178:181], v146 offset:2048
	ds_read_b128 v[182:185], v146 offset:3072
	s_add_i32 s52, s52, 0x80000
	s_mov_b32 m0, s35
	ds_read_b128 v[186:189], v196 offset:32768
	ds_read_b128 v[198:201], v196 offset:33792
	ds_read_b128 v[202:205], v196 offset:34816
	ds_read_b128 v[228:231], v196 offset:35840
	ds_read_b128 v[232:235], v196 offset:36864
	ds_read_b128 v[236:239], v196 offset:37888
	ds_read_b128 v[240:243], v196 offset:38912
	ds_read_b128 v[244:247], v196 offset:39936
	buffer_load_dwordx4 v135, s[44:47], s52 offen lds
	s_mov_b32 m0, s36
	s_nop 0
	buffer_load_dwordx4 v193, s[44:47], s52 offen lds
	s_waitcnt vmcnt(8)
	s_waitcnt lgkmcnt(0)
	s_setprio 1
	s_barrier
	v_mfma_f32_16x16x32_bf16 v[126:129], v[130:133], v[186:189], v[126:129]
	v_mfma_f32_16x16x32_bf16 v[126:129], v[138:141], v[198:201], v[126:129]
	v_mfma_f32_16x16x32_bf16 v[122:125], v[142:145], v[186:189], v[122:125]
	v_mfma_f32_16x16x32_bf16 v[122:125], v[154:157], v[198:201], v[122:125]
	v_mfma_f32_16x16x32_bf16 v[114:117], v[178:181], v[186:189], v[114:117]
	v_mfma_f32_16x16x32_bf16 v[114:117], v[182:185], v[198:201], v[114:117]
	v_mfma_f32_16x16x32_bf16 v[118:121], v[170:173], v[186:189], v[118:121]
	v_mfma_f32_16x16x32_bf16 v[118:121], v[174:177], v[198:201], v[118:121]
	v_mfma_f32_16x16x32_bf16 v[102:105], v[170:173], v[202:205], v[102:105]
	v_mfma_f32_16x16x32_bf16 v[102:105], v[174:177], v[228:231], v[102:105]
	v_mfma_f32_16x16x32_bf16 v[98:101], v[178:181], v[202:205], v[98:101]
	v_mfma_f32_16x16x32_bf16 v[98:101], v[182:185], v[228:231], v[98:101]
	v_mfma_f32_16x16x32_bf16 v[106:109], v[142:145], v[202:205], v[106:109]
	v_mfma_f32_16x16x32_bf16 v[106:109], v[154:157], v[228:231], v[106:109]
	v_mfma_f32_16x16x32_bf16 v[110:113], v[130:133], v[202:205], v[110:113]
	v_mfma_f32_16x16x32_bf16 v[110:113], v[138:141], v[228:231], v[110:113]
	v_mfma_f32_16x16x32_bf16 v[94:97], v[130:133], v[232:235], v[94:97]
	v_mfma_f32_16x16x32_bf16 v[94:97], v[138:141], v[236:239], v[94:97]
	v_mfma_f32_16x16x32_bf16 v[90:93], v[142:145], v[232:235], v[90:93]
	v_mfma_f32_16x16x32_bf16 v[90:93], v[154:157], v[236:239], v[90:93]
	v_mfma_f32_16x16x32_bf16 v[82:85], v[178:181], v[232:235], v[82:85]
	v_mfma_f32_16x16x32_bf16 v[82:85], v[182:185], v[236:239], v[82:85]
	v_mfma_f32_16x16x32_bf16 v[86:89], v[170:173], v[232:235], v[86:89]
	v_mfma_f32_16x16x32_bf16 v[86:89], v[174:177], v[236:239], v[86:89]
	v_mfma_f32_16x16x32_bf16 v[70:73], v[170:173], v[240:243], v[70:73]
	v_mfma_f32_16x16x32_bf16 v[70:73], v[174:177], v[244:247], v[70:73]
	v_mfma_f32_16x16x32_bf16 v[66:69], v[178:181], v[240:243], v[66:69]
	v_mfma_f32_16x16x32_bf16 v[66:69], v[182:185], v[244:247], v[66:69]
	v_mfma_f32_16x16x32_bf16 v[74:77], v[142:145], v[240:243], v[74:77]
	v_mfma_f32_16x16x32_bf16 v[74:77], v[154:157], v[244:247], v[74:77]
	v_mfma_f32_16x16x32_bf16 v[78:81], v[130:133], v[240:243], v[78:81]
	v_mfma_f32_16x16x32_bf16 v[78:81], v[138:141], v[244:247], v[78:81]
	s_barrier
	s_setprio 0
	s_mov_b32 m0, s41
	s_or_b32 s52, s27, 0x80
	ds_read_b128 v[186:189], v196 offset:49152
	ds_read_b128 v[198:201], v196 offset:50176
	ds_read_b128 v[202:205], v196 offset:51200
	ds_read_b128 v[228:231], v196 offset:52224
	ds_read_b128 v[232:235], v196 offset:53248
	ds_read_b128 v[236:239], v196 offset:54272
	ds_read_b128 v[240:243], v196 offset:55296
	ds_read_b128 v[244:247], v196 offset:56320
	buffer_load_dwordx4 v192, s[64:67], s52 offen lds
	s_mov_b32 m0, s48
	s_add_i32 s27, s27, 0x80080
	buffer_load_dwordx4 v194, s[64:67], s52 offen lds
	s_mov_b32 m0, s69
	s_nop 0
	buffer_load_dwordx4 v192, s[64:67], s27 offen lds
	s_mov_b32 m0, s72
	s_nop 0
	buffer_load_dwordx4 v194, s[64:67], s27 offen lds
	s_mov_b32 m0, s49
	s_nop 0
	buffer_load_dwordx4 v135, s[44:47], s26 offen lds
	s_mov_b32 m0, s68
	s_nop 0
	buffer_load_dwordx4 v193, s[44:47], s26 offen lds
	s_waitcnt vmcnt(8)
	s_waitcnt lgkmcnt(0)
	s_setprio 1
	s_barrier
	v_mfma_f32_16x16x32_bf16 v[62:65], v[130:133], v[186:189], v[62:65]
	v_mfma_f32_16x16x32_bf16 v[62:65], v[138:141], v[198:201], v[62:65]
	v_mfma_f32_16x16x32_bf16 v[58:61], v[142:145], v[186:189], v[58:61]
	v_mfma_f32_16x16x32_bf16 v[58:61], v[154:157], v[198:201], v[58:61]
	v_mfma_f32_16x16x32_bf16 v[50:53], v[178:181], v[186:189], v[50:53]
	v_mfma_f32_16x16x32_bf16 v[50:53], v[182:185], v[198:201], v[50:53]
	v_mfma_f32_16x16x32_bf16 v[54:57], v[170:173], v[186:189], v[54:57]
	v_mfma_f32_16x16x32_bf16 v[54:57], v[174:177], v[198:201], v[54:57]
	v_mfma_f32_16x16x32_bf16 v[38:41], v[170:173], v[202:205], v[38:41]
	v_mfma_f32_16x16x32_bf16 v[38:41], v[174:177], v[228:231], v[38:41]
	v_mfma_f32_16x16x32_bf16 v[34:37], v[178:181], v[202:205], v[34:37]
	v_mfma_f32_16x16x32_bf16 v[34:37], v[182:185], v[228:231], v[34:37]
	v_mfma_f32_16x16x32_bf16 v[42:45], v[142:145], v[202:205], v[42:45]
	v_mfma_f32_16x16x32_bf16 v[42:45], v[154:157], v[228:231], v[42:45]
	v_mfma_f32_16x16x32_bf16 v[46:49], v[130:133], v[202:205], v[46:49]
	v_mfma_f32_16x16x32_bf16 v[46:49], v[138:141], v[228:231], v[46:49]
	v_mfma_f32_16x16x32_bf16 v[30:33], v[130:133], v[232:235], v[30:33]
	v_mfma_f32_16x16x32_bf16 v[30:33], v[138:141], v[236:239], v[30:33]
	v_mfma_f32_16x16x32_bf16 v[26:29], v[142:145], v[232:235], v[26:29]
	v_mfma_f32_16x16x32_bf16 v[26:29], v[154:157], v[236:239], v[26:29]
	v_mfma_f32_16x16x32_bf16 v[18:21], v[178:181], v[232:235], v[18:21]
	v_mfma_f32_16x16x32_bf16 v[18:21], v[182:185], v[236:239], v[18:21]
	v_mfma_f32_16x16x32_bf16 v[22:25], v[170:173], v[232:235], v[22:25]
	v_mfma_f32_16x16x32_bf16 v[22:25], v[174:177], v[236:239], v[22:25]
	v_mfma_f32_16x16x32_bf16 v[6:9], v[170:173], v[240:243], v[6:9]
	v_mfma_f32_16x16x32_bf16 v[6:9], v[174:177], v[244:247], v[6:9]
	v_mfma_f32_16x16x32_bf16 v[2:5], v[178:181], v[240:243], v[2:5]
	v_mfma_f32_16x16x32_bf16 v[2:5], v[182:185], v[244:247], v[2:5]
	v_mfma_f32_16x16x32_bf16 v[10:13], v[142:145], v[240:243], v[10:13]
	v_mfma_f32_16x16x32_bf16 v[10:13], v[154:157], v[244:247], v[10:13]
	v_mfma_f32_16x16x32_bf16 v[14:17], v[130:133], v[240:243], v[14:17]
	v_mfma_f32_16x16x32_bf16 v[14:17], v[138:141], v[244:247], v[14:17]
	s_barrier
	s_setprio 0
	s_add_i32 s22, s22, 2
	s_addk_i32 s18, 0x100
	s_addk_i32 s19, 0x100
	s_cmp_gt_u32 s22, 29
.LBB0_859:
	v_add_u32_e32 v146, 0x10000, v195
	ds_read_b128 v[130:133], v146
	ds_read_b128 v[138:141], v146 offset:1024
	ds_read_b128 v[142:145], v146 offset:2048
	ds_read_b128 v[154:157], v146 offset:3072
	v_add_u32_e32 v146, 0x14000, v195
	ds_read_b128 v[170:173], v146
	ds_read_b128 v[174:177], v146 offset:1024
	ds_read_b128 v[178:181], v146 offset:2048
	ds_read_b128 v[182:185], v146 offset:3072
	s_add_i32 s26, s18, 0xfff80080
	s_cmp_eq_u32 s22, 28
	s_cselect_b32 s52, s8, s26
	s_cselect_b32 s27, s9, s19
	s_or_b32 s26, s52, 0x80
	s_mov_b32 m0, s85
	ds_read_b128 v[186:189], v196
	ds_read_b128 v[198:201], v196 offset:1024
	ds_read_b128 v[202:205], v196 offset:2048
	ds_read_b128 v[228:231], v196 offset:3072
	ds_read_b128 v[232:235], v196 offset:4096
	ds_read_b128 v[236:239], v196 offset:5120
	ds_read_b128 v[240:243], v196 offset:6144
	ds_read_b128 v[244:247], v196 offset:7168
	buffer_load_dwordx4 v135, s[44:47], s18 offen lds
	s_mov_b32 m0, s15
	s_nop 0
	buffer_load_dwordx4 v193, s[44:47], s18 offen lds
	s_waitcnt vmcnt(8)
	s_waitcnt lgkmcnt(0)
	s_setprio 1
	s_barrier
	v_mfma_f32_16x16x32_bf16 v[126:129], v[130:133], v[186:189], v[126:129]
	v_mfma_f32_16x16x32_bf16 v[126:129], v[138:141], v[198:201], v[126:129]
	v_mfma_f32_16x16x32_bf16 v[122:125], v[142:145], v[186:189], v[122:125]
	v_mfma_f32_16x16x32_bf16 v[122:125], v[154:157], v[198:201], v[122:125]
	v_mfma_f32_16x16x32_bf16 v[114:117], v[178:181], v[186:189], v[114:117]
	v_mfma_f32_16x16x32_bf16 v[114:117], v[182:185], v[198:201], v[114:117]
	v_mfma_f32_16x16x32_bf16 v[118:121], v[170:173], v[186:189], v[118:121]
	v_mfma_f32_16x16x32_bf16 v[118:121], v[174:177], v[198:201], v[118:121]
	v_mfma_f32_16x16x32_bf16 v[102:105], v[170:173], v[202:205], v[102:105]
	v_mfma_f32_16x16x32_bf16 v[102:105], v[174:177], v[228:231], v[102:105]
	v_mfma_f32_16x16x32_bf16 v[98:101], v[178:181], v[202:205], v[98:101]
	v_mfma_f32_16x16x32_bf16 v[98:101], v[182:185], v[228:231], v[98:101]
	v_mfma_f32_16x16x32_bf16 v[106:109], v[142:145], v[202:205], v[106:109]
	v_mfma_f32_16x16x32_bf16 v[106:109], v[154:157], v[228:231], v[106:109]
	v_mfma_f32_16x16x32_bf16 v[110:113], v[130:133], v[202:205], v[110:113]
	v_mfma_f32_16x16x32_bf16 v[110:113], v[138:141], v[228:231], v[110:113]
	v_mfma_f32_16x16x32_bf16 v[94:97], v[130:133], v[232:235], v[94:97]
	v_mfma_f32_16x16x32_bf16 v[94:97], v[138:141], v[236:239], v[94:97]
	v_mfma_f32_16x16x32_bf16 v[90:93], v[142:145], v[232:235], v[90:93]
	v_mfma_f32_16x16x32_bf16 v[90:93], v[154:157], v[236:239], v[90:93]
	v_mfma_f32_16x16x32_bf16 v[82:85], v[178:181], v[232:235], v[82:85]
	v_mfma_f32_16x16x32_bf16 v[82:85], v[182:185], v[236:239], v[82:85]
	v_mfma_f32_16x16x32_bf16 v[86:89], v[170:173], v[232:235], v[86:89]
	v_mfma_f32_16x16x32_bf16 v[86:89], v[174:177], v[236:239], v[86:89]
	v_mfma_f32_16x16x32_bf16 v[70:73], v[170:173], v[240:243], v[70:73]
	v_mfma_f32_16x16x32_bf16 v[70:73], v[174:177], v[244:247], v[70:73]
	v_mfma_f32_16x16x32_bf16 v[66:69], v[178:181], v[240:243], v[66:69]
	v_mfma_f32_16x16x32_bf16 v[66:69], v[182:185], v[244:247], v[66:69]
	v_mfma_f32_16x16x32_bf16 v[74:77], v[142:145], v[240:243], v[74:77]
	v_mfma_f32_16x16x32_bf16 v[74:77], v[154:157], v[244:247], v[74:77]
	v_mfma_f32_16x16x32_bf16 v[78:81], v[130:133], v[240:243], v[78:81]
	v_mfma_f32_16x16x32_bf16 v[78:81], v[138:141], v[244:247], v[78:81]
	s_barrier
	s_setprio 0
	s_mov_b32 m0, s23
	s_mov_b32 s66, s46
	s_mov_b32 s67, s47
	ds_read_b128 v[186:189], v196 offset:16384
	ds_read_b128 v[198:201], v196 offset:17408
	ds_read_b128 v[202:205], v196 offset:18432
	ds_read_b128 v[228:231], v196 offset:19456
	ds_read_b128 v[232:235], v196 offset:20480
	ds_read_b128 v[236:239], v196 offset:21504
	ds_read_b128 v[240:243], v196 offset:22528
	ds_read_b128 v[244:247], v196 offset:23552
	buffer_load_dwordx4 v192, s[64:67], s27 offen lds
	s_mov_b32 m0, s24
	s_add_i32 s53, s27, 0x80000
	buffer_load_dwordx4 v194, s[64:67], s27 offen lds
	s_mov_b32 m0, s25
	s_nop 0
	buffer_load_dwordx4 v192, s[64:67], s53 offen lds
	s_mov_b32 m0, s33
	s_nop 0
	buffer_load_dwordx4 v194, s[64:67], s53 offen lds
	s_mov_b32 m0, s13
	s_nop 0
	buffer_load_dwordx4 v135, s[44:47], s52 offen lds
	s_mov_b32 m0, s34
	s_nop 0
	buffer_load_dwordx4 v193, s[44:47], s52 offen lds
	s_waitcnt vmcnt(8)
	s_waitcnt lgkmcnt(0)
	s_setprio 1
	s_barrier
	v_mfma_f32_16x16x32_bf16 v[62:65], v[130:133], v[186:189], v[62:65]
	v_mfma_f32_16x16x32_bf16 v[62:65], v[138:141], v[198:201], v[62:65]
	v_mfma_f32_16x16x32_bf16 v[58:61], v[142:145], v[186:189], v[58:61]
	v_mfma_f32_16x16x32_bf16 v[58:61], v[154:157], v[198:201], v[58:61]
	v_mfma_f32_16x16x32_bf16 v[50:53], v[178:181], v[186:189], v[50:53]
	v_mfma_f32_16x16x32_bf16 v[50:53], v[182:185], v[198:201], v[50:53]
	v_mfma_f32_16x16x32_bf16 v[54:57], v[170:173], v[186:189], v[54:57]
	v_mfma_f32_16x16x32_bf16 v[54:57], v[174:177], v[198:201], v[54:57]
	v_mfma_f32_16x16x32_bf16 v[38:41], v[170:173], v[202:205], v[38:41]
	v_mfma_f32_16x16x32_bf16 v[38:41], v[174:177], v[228:231], v[38:41]
	v_mfma_f32_16x16x32_bf16 v[34:37], v[178:181], v[202:205], v[34:37]
	v_mfma_f32_16x16x32_bf16 v[34:37], v[182:185], v[228:231], v[34:37]
	v_mfma_f32_16x16x32_bf16 v[42:45], v[142:145], v[202:205], v[42:45]
	v_mfma_f32_16x16x32_bf16 v[42:45], v[154:157], v[228:231], v[42:45]
	v_mfma_f32_16x16x32_bf16 v[46:49], v[130:133], v[202:205], v[46:49]
	v_mfma_f32_16x16x32_bf16 v[46:49], v[138:141], v[228:231], v[46:49]
	v_mfma_f32_16x16x32_bf16 v[30:33], v[130:133], v[232:235], v[30:33]
	v_mfma_f32_16x16x32_bf16 v[30:33], v[138:141], v[236:239], v[30:33]
	v_mfma_f32_16x16x32_bf16 v[26:29], v[142:145], v[232:235], v[26:29]
	v_mfma_f32_16x16x32_bf16 v[26:29], v[154:157], v[236:239], v[26:29]
	v_mfma_f32_16x16x32_bf16 v[18:21], v[178:181], v[232:235], v[18:21]
	v_mfma_f32_16x16x32_bf16 v[18:21], v[182:185], v[236:239], v[18:21]
	v_mfma_f32_16x16x32_bf16 v[22:25], v[170:173], v[232:235], v[22:25]
	v_mfma_f32_16x16x32_bf16 v[22:25], v[174:177], v[236:239], v[22:25]
	v_mfma_f32_16x16x32_bf16 v[6:9], v[170:173], v[240:243], v[6:9]
	v_mfma_f32_16x16x32_bf16 v[6:9], v[174:177], v[244:247], v[6:9]
	v_mfma_f32_16x16x32_bf16 v[2:5], v[178:181], v[240:243], v[2:5]
	v_mfma_f32_16x16x32_bf16 v[2:5], v[182:185], v[244:247], v[2:5]
	v_mfma_f32_16x16x32_bf16 v[10:13], v[142:145], v[240:243], v[10:13]
	v_mfma_f32_16x16x32_bf16 v[10:13], v[154:157], v[244:247], v[10:13]
	v_mfma_f32_16x16x32_bf16 v[14:17], v[130:133], v[240:243], v[14:17]
	v_mfma_f32_16x16x32_bf16 v[14:17], v[138:141], v[244:247], v[14:17]
	s_barrier
	s_setprio 0
	v_add_u32_e32 v146, 0x18000, v195
	ds_read_b128 v[130:133], v146
	ds_read_b128 v[138:141], v146 offset:1024
	ds_read_b128 v[142:145], v146 offset:2048
	ds_read_b128 v[154:157], v146 offset:3072
	v_add_u32_e32 v146, 0x1c000, v195
	ds_read_b128 v[170:173], v146
	ds_read_b128 v[174:177], v146 offset:1024
	ds_read_b128 v[178:181], v146 offset:2048
	ds_read_b128 v[182:185], v146 offset:3072
	s_add_i32 s52, s52, 0x80000
	s_mov_b32 m0, s35
	ds_read_b128 v[186:189], v196 offset:32768
	ds_read_b128 v[198:201], v196 offset:33792
	ds_read_b128 v[202:205], v196 offset:34816
	ds_read_b128 v[228:231], v196 offset:35840
	ds_read_b128 v[232:235], v196 offset:36864
	ds_read_b128 v[236:239], v196 offset:37888
	ds_read_b128 v[240:243], v196 offset:38912
	ds_read_b128 v[244:247], v196 offset:39936
	buffer_load_dwordx4 v135, s[44:47], s52 offen lds
	s_mov_b32 m0, s36
	s_nop 0
	buffer_load_dwordx4 v193, s[44:47], s52 offen lds
	s_waitcnt vmcnt(8)
	s_waitcnt lgkmcnt(0)
	s_setprio 1
	s_barrier
	v_mfma_f32_16x16x32_bf16 v[126:129], v[130:133], v[186:189], v[126:129]
	v_mfma_f32_16x16x32_bf16 v[126:129], v[138:141], v[198:201], v[126:129]
	v_mfma_f32_16x16x32_bf16 v[122:125], v[142:145], v[186:189], v[122:125]
	v_mfma_f32_16x16x32_bf16 v[122:125], v[154:157], v[198:201], v[122:125]
	v_mfma_f32_16x16x32_bf16 v[114:117], v[178:181], v[186:189], v[114:117]
	v_mfma_f32_16x16x32_bf16 v[114:117], v[182:185], v[198:201], v[114:117]
	v_mfma_f32_16x16x32_bf16 v[118:121], v[170:173], v[186:189], v[118:121]
	v_mfma_f32_16x16x32_bf16 v[118:121], v[174:177], v[198:201], v[118:121]
	v_mfma_f32_16x16x32_bf16 v[102:105], v[170:173], v[202:205], v[102:105]
	v_mfma_f32_16x16x32_bf16 v[102:105], v[174:177], v[228:231], v[102:105]
	v_mfma_f32_16x16x32_bf16 v[98:101], v[178:181], v[202:205], v[98:101]
	v_mfma_f32_16x16x32_bf16 v[98:101], v[182:185], v[228:231], v[98:101]
	v_mfma_f32_16x16x32_bf16 v[106:109], v[142:145], v[202:205], v[106:109]
	v_mfma_f32_16x16x32_bf16 v[106:109], v[154:157], v[228:231], v[106:109]
	v_mfma_f32_16x16x32_bf16 v[110:113], v[130:133], v[202:205], v[110:113]
	v_mfma_f32_16x16x32_bf16 v[110:113], v[138:141], v[228:231], v[110:113]
	v_mfma_f32_16x16x32_bf16 v[94:97], v[130:133], v[232:235], v[94:97]
	v_mfma_f32_16x16x32_bf16 v[94:97], v[138:141], v[236:239], v[94:97]
	v_mfma_f32_16x16x32_bf16 v[90:93], v[142:145], v[232:235], v[90:93]
	v_mfma_f32_16x16x32_bf16 v[90:93], v[154:157], v[236:239], v[90:93]
	v_mfma_f32_16x16x32_bf16 v[82:85], v[178:181], v[232:235], v[82:85]
	v_mfma_f32_16x16x32_bf16 v[82:85], v[182:185], v[236:239], v[82:85]
	v_mfma_f32_16x16x32_bf16 v[86:89], v[170:173], v[232:235], v[86:89]
	v_mfma_f32_16x16x32_bf16 v[86:89], v[174:177], v[236:239], v[86:89]
	v_mfma_f32_16x16x32_bf16 v[70:73], v[170:173], v[240:243], v[70:73]
	v_mfma_f32_16x16x32_bf16 v[70:73], v[174:177], v[244:247], v[70:73]
	v_mfma_f32_16x16x32_bf16 v[66:69], v[178:181], v[240:243], v[66:69]
	v_mfma_f32_16x16x32_bf16 v[66:69], v[182:185], v[244:247], v[66:69]
	v_mfma_f32_16x16x32_bf16 v[74:77], v[142:145], v[240:243], v[74:77]
	v_mfma_f32_16x16x32_bf16 v[74:77], v[154:157], v[244:247], v[74:77]
	v_mfma_f32_16x16x32_bf16 v[78:81], v[130:133], v[240:243], v[78:81]
	v_mfma_f32_16x16x32_bf16 v[78:81], v[138:141], v[244:247], v[78:81]
	s_barrier
	s_setprio 0
	s_mov_b32 m0, s41
	s_or_b32 s52, s27, 0x80
	ds_read_b128 v[186:189], v196 offset:49152
	ds_read_b128 v[198:201], v196 offset:50176
	ds_read_b128 v[202:205], v196 offset:51200
	ds_read_b128 v[228:231], v196 offset:52224
	ds_read_b128 v[232:235], v196 offset:53248
	ds_read_b128 v[236:239], v196 offset:54272
	ds_read_b128 v[240:243], v196 offset:55296
	ds_read_b128 v[244:247], v196 offset:56320
	buffer_load_dwordx4 v192, s[64:67], s52 offen lds
	s_mov_b32 m0, s48
	s_add_i32 s27, s27, 0x80080
	buffer_load_dwordx4 v194, s[64:67], s52 offen lds
	s_mov_b32 m0, s69
	s_nop 0
	buffer_load_dwordx4 v192, s[64:67], s27 offen lds
	s_mov_b32 m0, s72
	s_nop 0
	buffer_load_dwordx4 v194, s[64:67], s27 offen lds
	s_mov_b32 m0, s49
	s_nop 0
	buffer_load_dwordx4 v135, s[44:47], s26 offen lds
	s_mov_b32 m0, s68
	s_nop 0
	buffer_load_dwordx4 v193, s[44:47], s26 offen lds
	s_waitcnt vmcnt(8)
	s_waitcnt lgkmcnt(0)
	s_setprio 1
	s_barrier
	v_mfma_f32_16x16x32_bf16 v[62:65], v[130:133], v[186:189], v[62:65]
	v_mfma_f32_16x16x32_bf16 v[62:65], v[138:141], v[198:201], v[62:65]
	v_mfma_f32_16x16x32_bf16 v[58:61], v[142:145], v[186:189], v[58:61]
	v_mfma_f32_16x16x32_bf16 v[58:61], v[154:157], v[198:201], v[58:61]
	v_mfma_f32_16x16x32_bf16 v[50:53], v[178:181], v[186:189], v[50:53]
	v_mfma_f32_16x16x32_bf16 v[50:53], v[182:185], v[198:201], v[50:53]
	v_mfma_f32_16x16x32_bf16 v[54:57], v[170:173], v[186:189], v[54:57]
	v_mfma_f32_16x16x32_bf16 v[54:57], v[174:177], v[198:201], v[54:57]
	v_mfma_f32_16x16x32_bf16 v[38:41], v[170:173], v[202:205], v[38:41]
	v_mfma_f32_16x16x32_bf16 v[38:41], v[174:177], v[228:231], v[38:41]
	v_mfma_f32_16x16x32_bf16 v[34:37], v[178:181], v[202:205], v[34:37]
	v_mfma_f32_16x16x32_bf16 v[34:37], v[182:185], v[228:231], v[34:37]
	v_mfma_f32_16x16x32_bf16 v[42:45], v[142:145], v[202:205], v[42:45]
	v_mfma_f32_16x16x32_bf16 v[42:45], v[154:157], v[228:231], v[42:45]
	v_mfma_f32_16x16x32_bf16 v[46:49], v[130:133], v[202:205], v[46:49]
	v_mfma_f32_16x16x32_bf16 v[46:49], v[138:141], v[228:231], v[46:49]
	v_mfma_f32_16x16x32_bf16 v[30:33], v[130:133], v[232:235], v[30:33]
	v_mfma_f32_16x16x32_bf16 v[30:33], v[138:141], v[236:239], v[30:33]
	v_mfma_f32_16x16x32_bf16 v[26:29], v[142:145], v[232:235], v[26:29]
	v_mfma_f32_16x16x32_bf16 v[26:29], v[154:157], v[236:239], v[26:29]
	v_mfma_f32_16x16x32_bf16 v[18:21], v[178:181], v[232:235], v[18:21]
	v_mfma_f32_16x16x32_bf16 v[18:21], v[182:185], v[236:239], v[18:21]
	v_mfma_f32_16x16x32_bf16 v[22:25], v[170:173], v[232:235], v[22:25]
	v_mfma_f32_16x16x32_bf16 v[22:25], v[174:177], v[236:239], v[22:25]
	v_mfma_f32_16x16x32_bf16 v[6:9], v[170:173], v[240:243], v[6:9]
	v_mfma_f32_16x16x32_bf16 v[6:9], v[174:177], v[244:247], v[6:9]
	v_mfma_f32_16x16x32_bf16 v[2:5], v[178:181], v[240:243], v[2:5]
	v_mfma_f32_16x16x32_bf16 v[2:5], v[182:185], v[244:247], v[2:5]
	v_mfma_f32_16x16x32_bf16 v[10:13], v[142:145], v[240:243], v[10:13]
	v_mfma_f32_16x16x32_bf16 v[10:13], v[154:157], v[244:247], v[10:13]
	v_mfma_f32_16x16x32_bf16 v[14:17], v[130:133], v[240:243], v[14:17]
	v_mfma_f32_16x16x32_bf16 v[14:17], v[138:141], v[244:247], v[14:17]
	s_barrier
	s_setprio 0
	s_add_i32 s22, s22, 2
	s_addk_i32 s18, 0x100
	s_addk_i32 s19, 0x100
	s_cmp_gt_u32 s22, 29
	s_cbranch_scc0 .LBB0_859
	s_and_b64 vcc, exec, s[60:61]
	s_cbranch_vccz .LBB0_862
	s_barrier

.LBB0_880:
	s_lshl_b32 s14, s85, 20
	s_and_b64 s[8:9], s[42:43], exec
	s_cselect_b32 s8, s14, s12
	s_lshl_b32 s15, s66, 20
	s_and_b64 s[22:23], s[42:43], exec
	s_cselect_b32 s9, s15, s13
	s_add_i32 s12, s12, 0x80080
	s_addk_i32 s13, 0x100
	s_mov_b32 s16, -2
	v_add_u32_e32 v139, 0x10000, v234
	ds_read_b128 v[130:133], v139
	ds_read_b128 v[140:143], v139 offset:1024
	ds_read_b128 v[170:173], v139 offset:2048
	ds_read_b128 v[174:177], v139 offset:3072
	v_add_u32_e32 v139, 0x14000, v234
	ds_read_b128 v[178:181], v139
	ds_read_b128 v[182:185], v139 offset:1024
	ds_read_b128 v[186:189], v139 offset:2048
	ds_read_b128 v[190:193], v139 offset:3072
	s_add_i32 s21, s12, 0xfff80080
	s_cmp_eq_u32 s16, 28
	s_cselect_b32 s23, s8, s21
	s_cselect_b32 s22, s9, s13
	s_or_b32 s21, s23, 0x80
	s_mov_b32 m0, s72
	ds_read_b128 v[194:197], v235
	ds_read_b128 v[198:201], v235 offset:1024
	ds_read_b128 v[202:205], v235 offset:2048
	ds_read_b128 v[236:239], v235 offset:3072
	ds_read_b128 v[240:243], v235 offset:4096
	ds_read_b128 v[244:247], v235 offset:5120
	ds_read_b128 v[248:251], v235 offset:6144
	ds_read_b128 v[154:157], v235 offset:7168
	buffer_load_dwordx4 v228, s[60:63], s12 offen lds
	s_mov_b32 m0, s73
	s_nop 0
	buffer_load_dwordx4 v230, s[60:63], s12 offen lds
	s_waitcnt vmcnt(8)
	s_waitcnt lgkmcnt(0)
	s_setprio 1
	s_barrier
	v_mfma_f32_16x16x32_bf16 v[126:129], v[130:133], v[194:197], 0
	v_mfma_f32_16x16x32_bf16 v[126:129], v[140:143], v[198:201], v[126:129]
	v_mfma_f32_16x16x32_bf16 v[122:125], v[170:173], v[194:197], 0
	v_mfma_f32_16x16x32_bf16 v[122:125], v[174:177], v[198:201], v[122:125]
	v_mfma_f32_16x16x32_bf16 v[110:113], v[186:189], v[194:197], 0
	v_mfma_f32_16x16x32_bf16 v[110:113], v[190:193], v[198:201], v[110:113]
	v_mfma_f32_16x16x32_bf16 v[118:121], v[178:181], v[194:197], 0
	v_mfma_f32_16x16x32_bf16 v[118:121], v[182:185], v[198:201], v[118:121]
	v_mfma_f32_16x16x32_bf16 v[102:105], v[178:181], v[202:205], 0
	v_mfma_f32_16x16x32_bf16 v[102:105], v[182:185], v[236:239], v[102:105]
	v_mfma_f32_16x16x32_bf16 v[94:97], v[186:189], v[202:205], 0
	v_mfma_f32_16x16x32_bf16 v[94:97], v[190:193], v[236:239], v[94:97]
	v_mfma_f32_16x16x32_bf16 v[106:109], v[170:173], v[202:205], 0
	v_mfma_f32_16x16x32_bf16 v[106:109], v[174:177], v[236:239], v[106:109]
	v_mfma_f32_16x16x32_bf16 v[114:117], v[130:133], v[202:205], 0
	v_mfma_f32_16x16x32_bf16 v[114:117], v[140:143], v[236:239], v[114:117]
	v_mfma_f32_16x16x32_bf16 v[98:101], v[130:133], v[240:243], 0
	v_mfma_f32_16x16x32_bf16 v[98:101], v[140:143], v[244:247], v[98:101]
	v_mfma_f32_16x16x32_bf16 v[90:93], v[170:173], v[240:243], 0
	v_mfma_f32_16x16x32_bf16 v[90:93], v[174:177], v[244:247], v[90:93]
	v_mfma_f32_16x16x32_bf16 v[78:81], v[186:189], v[240:243], 0
	v_mfma_f32_16x16x32_bf16 v[78:81], v[190:193], v[244:247], v[78:81]
	v_mfma_f32_16x16x32_bf16 v[86:89], v[178:181], v[240:243], 0
	v_mfma_f32_16x16x32_bf16 v[86:89], v[182:185], v[244:247], v[86:89]
	v_mfma_f32_16x16x32_bf16 v[70:73], v[178:181], v[248:251], 0
	v_mfma_f32_16x16x32_bf16 v[70:73], v[182:185], v[154:157], v[70:73]
	v_mfma_f32_16x16x32_bf16 v[66:69], v[186:189], v[248:251], 0
	v_mfma_f32_16x16x32_bf16 v[66:69], v[190:193], v[154:157], v[66:69]
	v_mfma_f32_16x16x32_bf16 v[74:77], v[170:173], v[248:251], 0
	v_mfma_f32_16x16x32_bf16 v[74:77], v[174:177], v[154:157], v[74:77]
	v_mfma_f32_16x16x32_bf16 v[82:85], v[130:133], v[248:251], 0
	v_mfma_f32_16x16x32_bf16 v[82:85], v[140:143], v[154:157], v[82:85]
	s_barrier
	s_setprio 0
	s_mov_b32 m0, s26
	s_mov_b32 s46, s62
	s_mov_b32 s47, s63
	ds_read_b128 v[154:157], v235 offset:16384
	ds_read_b128 v[194:197], v235 offset:17408
	ds_read_b128 v[198:201], v235 offset:18432
	ds_read_b128 v[202:205], v235 offset:19456
	ds_read_b128 v[236:239], v235 offset:20480
	ds_read_b128 v[240:243], v235 offset:21504
	ds_read_b128 v[244:247], v235 offset:22528
	ds_read_b128 v[248:251], v235 offset:23552
	buffer_load_dwordx4 v229, s[44:47], s22 offen lds
	s_mov_b32 m0, s27
	s_add_i32 s38, s22, 0x80000
	buffer_load_dwordx4 v231, s[44:47], s22 offen lds
	s_mov_b32 m0, s34
	s_nop 0
	buffer_load_dwordx4 v229, s[44:47], s38 offen lds
	s_mov_b32 m0, s35
	s_nop 0
	buffer_load_dwordx4 v231, s[44:47], s38 offen lds
	s_mov_b32 m0, s19
	s_nop 0
	buffer_load_dwordx4 v228, s[60:63], s23 offen lds
	s_mov_b32 m0, s36
	s_nop 0
	buffer_load_dwordx4 v230, s[60:63], s23 offen lds
	s_waitcnt vmcnt(8)
	s_waitcnt lgkmcnt(0)
	s_setprio 1
	s_barrier
	v_mfma_f32_16x16x32_bf16 v[62:65], v[130:133], v[154:157], 0
	v_mfma_f32_16x16x32_bf16 v[62:65], v[140:143], v[194:197], v[62:65]
	v_mfma_f32_16x16x32_bf16 v[58:61], v[170:173], v[154:157], 0
	v_mfma_f32_16x16x32_bf16 v[58:61], v[174:177], v[194:197], v[58:61]
	v_mfma_f32_16x16x32_bf16 v[46:49], v[186:189], v[154:157], 0
	v_mfma_f32_16x16x32_bf16 v[46:49], v[190:193], v[194:197], v[46:49]
	v_mfma_f32_16x16x32_bf16 v[54:57], v[178:181], v[154:157], 0
	v_mfma_f32_16x16x32_bf16 v[54:57], v[182:185], v[194:197], v[54:57]
	v_mfma_f32_16x16x32_bf16 v[38:41], v[178:181], v[198:201], 0
	v_mfma_f32_16x16x32_bf16 v[38:41], v[182:185], v[202:205], v[38:41]
	v_mfma_f32_16x16x32_bf16 v[30:33], v[186:189], v[198:201], 0
	v_mfma_f32_16x16x32_bf16 v[30:33], v[190:193], v[202:205], v[30:33]
	v_mfma_f32_16x16x32_bf16 v[42:45], v[170:173], v[198:201], 0
	v_mfma_f32_16x16x32_bf16 v[42:45], v[174:177], v[202:205], v[42:45]
	v_mfma_f32_16x16x32_bf16 v[50:53], v[130:133], v[198:201], 0
	v_mfma_f32_16x16x32_bf16 v[50:53], v[140:143], v[202:205], v[50:53]
	v_mfma_f32_16x16x32_bf16 v[34:37], v[130:133], v[236:239], 0
	v_mfma_f32_16x16x32_bf16 v[34:37], v[140:143], v[240:243], v[34:37]
	v_mfma_f32_16x16x32_bf16 v[26:29], v[170:173], v[236:239], 0
	v_mfma_f32_16x16x32_bf16 v[26:29], v[174:177], v[240:243], v[26:29]
	v_mfma_f32_16x16x32_bf16 v[14:17], v[186:189], v[236:239], 0
	v_mfma_f32_16x16x32_bf16 v[14:17], v[190:193], v[240:243], v[14:17]
	v_mfma_f32_16x16x32_bf16 v[22:25], v[178:181], v[236:239], 0
	v_mfma_f32_16x16x32_bf16 v[22:25], v[182:185], v[240:243], v[22:25]
	v_mfma_f32_16x16x32_bf16 v[6:9], v[178:181], v[244:247], 0
	v_mfma_f32_16x16x32_bf16 v[6:9], v[182:185], v[248:251], v[6:9]
	v_mfma_f32_16x16x32_bf16 v[2:5], v[186:189], v[244:247], 0
	v_mfma_f32_16x16x32_bf16 v[2:5], v[190:193], v[248:251], v[2:5]
	v_mfma_f32_16x16x32_bf16 v[10:13], v[170:173], v[244:247], 0
	v_mfma_f32_16x16x32_bf16 v[10:13], v[174:177], v[248:251], v[10:13]
	v_mfma_f32_16x16x32_bf16 v[18:21], v[130:133], v[244:247], 0
	v_mfma_f32_16x16x32_bf16 v[18:21], v[140:143], v[248:251], v[18:21]
	s_barrier
	s_setprio 0
	v_add_u32_e32 v139, 0x18000, v234
	ds_read_b128 v[130:133], v139
	ds_read_b128 v[140:143], v139 offset:1024
	ds_read_b128 v[154:157], v139 offset:2048
	ds_read_b128 v[170:173], v139 offset:3072
	v_add_u32_e32 v139, 0x1c000, v234
	ds_read_b128 v[174:177], v139
	ds_read_b128 v[178:181], v139 offset:1024
	ds_read_b128 v[182:185], v139 offset:2048
	ds_read_b128 v[186:189], v139 offset:3072
	s_add_i32 s23, s23, 0x80000
	s_mov_b32 m0, s37
	ds_read_b128 v[190:193], v235 offset:32768
	ds_read_b128 v[194:197], v235 offset:33792
	ds_read_b128 v[198:201], v235 offset:34816
	ds_read_b128 v[202:205], v235 offset:35840
	ds_read_b128 v[236:239], v235 offset:36864
	ds_read_b128 v[240:243], v235 offset:37888
	ds_read_b128 v[244:247], v235 offset:38912
	ds_read_b128 v[248:251], v235 offset:39936
	buffer_load_dwordx4 v228, s[60:63], s23 offen lds
	s_mov_b32 m0, s18
	s_nop 0
	buffer_load_dwordx4 v230, s[60:63], s23 offen lds
	s_waitcnt vmcnt(8)
	s_waitcnt lgkmcnt(0)
	s_setprio 1
	s_barrier
	v_mfma_f32_16x16x32_bf16 v[126:129], v[130:133], v[190:193], v[126:129]
	v_mfma_f32_16x16x32_bf16 v[126:129], v[140:143], v[194:197], v[126:129]
	v_mfma_f32_16x16x32_bf16 v[122:125], v[154:157], v[190:193], v[122:125]
	v_mfma_f32_16x16x32_bf16 v[122:125], v[170:173], v[194:197], v[122:125]
	v_mfma_f32_16x16x32_bf16 v[110:113], v[182:185], v[190:193], v[110:113]
	v_mfma_f32_16x16x32_bf16 v[110:113], v[186:189], v[194:197], v[110:113]
	v_mfma_f32_16x16x32_bf16 v[118:121], v[174:177], v[190:193], v[118:121]
	v_mfma_f32_16x16x32_bf16 v[118:121], v[178:181], v[194:197], v[118:121]
	v_mfma_f32_16x16x32_bf16 v[102:105], v[174:177], v[198:201], v[102:105]
	v_mfma_f32_16x16x32_bf16 v[102:105], v[178:181], v[202:205], v[102:105]
	v_mfma_f32_16x16x32_bf16 v[94:97], v[182:185], v[198:201], v[94:97]
	v_mfma_f32_16x16x32_bf16 v[94:97], v[186:189], v[202:205], v[94:97]
	v_mfma_f32_16x16x32_bf16 v[106:109], v[154:157], v[198:201], v[106:109]
	v_mfma_f32_16x16x32_bf16 v[106:109], v[170:173], v[202:205], v[106:109]
	v_mfma_f32_16x16x32_bf16 v[114:117], v[130:133], v[198:201], v[114:117]
	v_mfma_f32_16x16x32_bf16 v[114:117], v[140:143], v[202:205], v[114:117]
	v_mfma_f32_16x16x32_bf16 v[98:101], v[130:133], v[236:239], v[98:101]
	v_mfma_f32_16x16x32_bf16 v[98:101], v[140:143], v[240:243], v[98:101]
	v_mfma_f32_16x16x32_bf16 v[90:93], v[154:157], v[236:239], v[90:93]
	v_mfma_f32_16x16x32_bf16 v[90:93], v[170:173], v[240:243], v[90:93]
	v_mfma_f32_16x16x32_bf16 v[78:81], v[182:185], v[236:239], v[78:81]
	v_mfma_f32_16x16x32_bf16 v[78:81], v[186:189], v[240:243], v[78:81]
	v_mfma_f32_16x16x32_bf16 v[86:89], v[174:177], v[236:239], v[86:89]
	v_mfma_f32_16x16x32_bf16 v[86:89], v[178:181], v[240:243], v[86:89]
	v_mfma_f32_16x16x32_bf16 v[70:73], v[174:177], v[244:247], v[70:73]
	v_mfma_f32_16x16x32_bf16 v[70:73], v[178:181], v[248:251], v[70:73]
	v_mfma_f32_16x16x32_bf16 v[66:69], v[182:185], v[244:247], v[66:69]
	v_mfma_f32_16x16x32_bf16 v[66:69], v[186:189], v[248:251], v[66:69]
	v_mfma_f32_16x16x32_bf16 v[74:77], v[154:157], v[244:247], v[74:77]
	v_mfma_f32_16x16x32_bf16 v[74:77], v[170:173], v[248:251], v[74:77]
	v_mfma_f32_16x16x32_bf16 v[82:85], v[130:133], v[244:247], v[82:85]
	v_mfma_f32_16x16x32_bf16 v[82:85], v[140:143], v[248:251], v[82:85]
	s_barrier
	s_setprio 0
	s_mov_b32 m0, s24
	s_or_b32 s23, s22, 0x80
	ds_read_b128 v[190:193], v235 offset:49152
	ds_read_b128 v[194:197], v235 offset:50176
	ds_read_b128 v[198:201], v235 offset:51200
	ds_read_b128 v[202:205], v235 offset:52224
	ds_read_b128 v[236:239], v235 offset:53248
	ds_read_b128 v[240:243], v235 offset:54272
	ds_read_b128 v[244:247], v235 offset:55296
	ds_read_b128 v[248:251], v235 offset:56320
	buffer_load_dwordx4 v229, s[44:47], s23 offen lds
	s_mov_b32 m0, s25
	s_add_i32 s22, s22, 0x80080
	buffer_load_dwordx4 v231, s[44:47], s23 offen lds
	s_mov_b32 m0, s64
	s_nop 0
	buffer_load_dwordx4 v229, s[44:47], s22 offen lds
	s_mov_b32 m0, s65
	s_nop 0
	buffer_load_dwordx4 v231, s[44:47], s22 offen lds
	s_mov_b32 m0, s48
	s_nop 0
	buffer_load_dwordx4 v228, s[60:63], s21 offen lds
	s_mov_b32 m0, s49
	s_nop 0
	buffer_load_dwordx4 v230, s[60:63], s21 offen lds
	s_waitcnt vmcnt(8)
	s_waitcnt lgkmcnt(0)
	s_setprio 1
	s_barrier
	v_mfma_f32_16x16x32_bf16 v[62:65], v[130:133], v[190:193], v[62:65]
	v_mfma_f32_16x16x32_bf16 v[62:65], v[140:143], v[194:197], v[62:65]
	v_mfma_f32_16x16x32_bf16 v[58:61], v[154:157], v[190:193], v[58:61]
	v_mfma_f32_16x16x32_bf16 v[58:61], v[170:173], v[194:197], v[58:61]
	v_mfma_f32_16x16x32_bf16 v[46:49], v[182:185], v[190:193], v[46:49]
	v_mfma_f32_16x16x32_bf16 v[46:49], v[186:189], v[194:197], v[46:49]
	v_mfma_f32_16x16x32_bf16 v[54:57], v[174:177], v[190:193], v[54:57]
	v_mfma_f32_16x16x32_bf16 v[54:57], v[178:181], v[194:197], v[54:57]
	v_mfma_f32_16x16x32_bf16 v[38:41], v[174:177], v[198:201], v[38:41]
	v_mfma_f32_16x16x32_bf16 v[38:41], v[178:181], v[202:205], v[38:41]
	v_mfma_f32_16x16x32_bf16 v[30:33], v[182:185], v[198:201], v[30:33]
	v_mfma_f32_16x16x32_bf16 v[30:33], v[186:189], v[202:205], v[30:33]
	v_mfma_f32_16x16x32_bf16 v[42:45], v[154:157], v[198:201], v[42:45]
	v_mfma_f32_16x16x32_bf16 v[42:45], v[170:173], v[202:205], v[42:45]
	v_mfma_f32_16x16x32_bf16 v[50:53], v[130:133], v[198:201], v[50:53]
	v_mfma_f32_16x16x32_bf16 v[50:53], v[140:143], v[202:205], v[50:53]
	v_mfma_f32_16x16x32_bf16 v[34:37], v[130:133], v[236:239], v[34:37]
	v_mfma_f32_16x16x32_bf16 v[34:37], v[140:143], v[240:243], v[34:37]
	v_mfma_f32_16x16x32_bf16 v[26:29], v[154:157], v[236:239], v[26:29]
	v_mfma_f32_16x16x32_bf16 v[26:29], v[170:173], v[240:243], v[26:29]
	v_mfma_f32_16x16x32_bf16 v[14:17], v[182:185], v[236:239], v[14:17]
	v_mfma_f32_16x16x32_bf16 v[14:17], v[186:189], v[240:243], v[14:17]
	v_mfma_f32_16x16x32_bf16 v[22:25], v[174:177], v[236:239], v[22:25]
	v_mfma_f32_16x16x32_bf16 v[22:25], v[178:181], v[240:243], v[22:25]
	v_mfma_f32_16x16x32_bf16 v[6:9], v[174:177], v[244:247], v[6:9]
	v_mfma_f32_16x16x32_bf16 v[6:9], v[178:181], v[248:251], v[6:9]
	v_mfma_f32_16x16x32_bf16 v[2:5], v[182:185], v[244:247], v[2:5]
	v_mfma_f32_16x16x32_bf16 v[2:5], v[186:189], v[248:251], v[2:5]
	v_mfma_f32_16x16x32_bf16 v[10:13], v[154:157], v[244:247], v[10:13]
	v_mfma_f32_16x16x32_bf16 v[10:13], v[170:173], v[248:251], v[10:13]
	v_mfma_f32_16x16x32_bf16 v[18:21], v[130:133], v[244:247], v[18:21]
	v_mfma_f32_16x16x32_bf16 v[18:21], v[140:143], v[248:251], v[18:21]
	s_barrier
	s_setprio 0
	s_add_i32 s16, s16, 2
	s_addk_i32 s12, 0x100
	s_addk_i32 s13, 0x100
	s_cmp_gt_u32 s16, 29
.LBB0_881:
	v_add_u32_e32 v139, 0x10000, v234
	ds_read_b128 v[130:133], v139
	ds_read_b128 v[140:143], v139 offset:1024
	ds_read_b128 v[170:173], v139 offset:2048
	ds_read_b128 v[174:177], v139 offset:3072
	v_add_u32_e32 v139, 0x14000, v234
	ds_read_b128 v[178:181], v139
	ds_read_b128 v[182:185], v139 offset:1024
	ds_read_b128 v[186:189], v139 offset:2048
	ds_read_b128 v[190:193], v139 offset:3072
	s_add_i32 s21, s12, 0xfff80080
	s_cmp_eq_u32 s16, 28
	s_cselect_b32 s23, s8, s21
	s_cselect_b32 s22, s9, s13
	s_or_b32 s21, s23, 0x80
	s_mov_b32 m0, s72
	ds_read_b128 v[194:197], v235
	ds_read_b128 v[198:201], v235 offset:1024
	ds_read_b128 v[202:205], v235 offset:2048
	ds_read_b128 v[236:239], v235 offset:3072
	ds_read_b128 v[240:243], v235 offset:4096
	ds_read_b128 v[244:247], v235 offset:5120
	ds_read_b128 v[248:251], v235 offset:6144
	ds_read_b128 v[154:157], v235 offset:7168
	buffer_load_dwordx4 v228, s[60:63], s12 offen lds
	s_mov_b32 m0, s73
	s_nop 0
	buffer_load_dwordx4 v230, s[60:63], s12 offen lds
	s_waitcnt vmcnt(8)
	s_waitcnt lgkmcnt(0)
	s_setprio 1
	s_barrier
	v_mfma_f32_16x16x32_bf16 v[126:129], v[130:133], v[194:197], v[126:129]
	v_mfma_f32_16x16x32_bf16 v[126:129], v[140:143], v[198:201], v[126:129]
	v_mfma_f32_16x16x32_bf16 v[122:125], v[170:173], v[194:197], v[122:125]
	v_mfma_f32_16x16x32_bf16 v[122:125], v[174:177], v[198:201], v[122:125]
	v_mfma_f32_16x16x32_bf16 v[110:113], v[186:189], v[194:197], v[110:113]
	v_mfma_f32_16x16x32_bf16 v[110:113], v[190:193], v[198:201], v[110:113]
	v_mfma_f32_16x16x32_bf16 v[118:121], v[178:181], v[194:197], v[118:121]
	v_mfma_f32_16x16x32_bf16 v[118:121], v[182:185], v[198:201], v[118:121]
	v_mfma_f32_16x16x32_bf16 v[102:105], v[178:181], v[202:205], v[102:105]
	v_mfma_f32_16x16x32_bf16 v[102:105], v[182:185], v[236:239], v[102:105]
	v_mfma_f32_16x16x32_bf16 v[94:97], v[186:189], v[202:205], v[94:97]
	v_mfma_f32_16x16x32_bf16 v[94:97], v[190:193], v[236:239], v[94:97]
	v_mfma_f32_16x16x32_bf16 v[106:109], v[170:173], v[202:205], v[106:109]
	v_mfma_f32_16x16x32_bf16 v[106:109], v[174:177], v[236:239], v[106:109]
	v_mfma_f32_16x16x32_bf16 v[114:117], v[130:133], v[202:205], v[114:117]
	v_mfma_f32_16x16x32_bf16 v[114:117], v[140:143], v[236:239], v[114:117]
	v_mfma_f32_16x16x32_bf16 v[98:101], v[130:133], v[240:243], v[98:101]
	v_mfma_f32_16x16x32_bf16 v[98:101], v[140:143], v[244:247], v[98:101]
	v_mfma_f32_16x16x32_bf16 v[90:93], v[170:173], v[240:243], v[90:93]
	v_mfma_f32_16x16x32_bf16 v[90:93], v[174:177], v[244:247], v[90:93]
	v_mfma_f32_16x16x32_bf16 v[78:81], v[186:189], v[240:243], v[78:81]
	v_mfma_f32_16x16x32_bf16 v[78:81], v[190:193], v[244:247], v[78:81]
	v_mfma_f32_16x16x32_bf16 v[86:89], v[178:181], v[240:243], v[86:89]
	v_mfma_f32_16x16x32_bf16 v[86:89], v[182:185], v[244:247], v[86:89]
	v_mfma_f32_16x16x32_bf16 v[70:73], v[178:181], v[248:251], v[70:73]
	v_mfma_f32_16x16x32_bf16 v[70:73], v[182:185], v[154:157], v[70:73]
	v_mfma_f32_16x16x32_bf16 v[66:69], v[186:189], v[248:251], v[66:69]
	v_mfma_f32_16x16x32_bf16 v[66:69], v[190:193], v[154:157], v[66:69]
	v_mfma_f32_16x16x32_bf16 v[74:77], v[170:173], v[248:251], v[74:77]
	v_mfma_f32_16x16x32_bf16 v[74:77], v[174:177], v[154:157], v[74:77]
	v_mfma_f32_16x16x32_bf16 v[82:85], v[130:133], v[248:251], v[82:85]
	v_mfma_f32_16x16x32_bf16 v[82:85], v[140:143], v[154:157], v[82:85]
	s_barrier
	s_setprio 0
	s_mov_b32 m0, s26
	s_mov_b32 s46, s62
	s_mov_b32 s47, s63
	ds_read_b128 v[154:157], v235 offset:16384
	ds_read_b128 v[194:197], v235 offset:17408
	ds_read_b128 v[198:201], v235 offset:18432
	ds_read_b128 v[202:205], v235 offset:19456
	ds_read_b128 v[236:239], v235 offset:20480
	ds_read_b128 v[240:243], v235 offset:21504
	ds_read_b128 v[244:247], v235 offset:22528
	ds_read_b128 v[248:251], v235 offset:23552
	buffer_load_dwordx4 v229, s[44:47], s22 offen lds
	s_mov_b32 m0, s27
	s_add_i32 s38, s22, 0x80000
	buffer_load_dwordx4 v231, s[44:47], s22 offen lds
	s_mov_b32 m0, s34
	s_nop 0
	buffer_load_dwordx4 v229, s[44:47], s38 offen lds
	s_mov_b32 m0, s35
	s_nop 0
	buffer_load_dwordx4 v231, s[44:47], s38 offen lds
	s_mov_b32 m0, s19
	s_nop 0
	buffer_load_dwordx4 v228, s[60:63], s23 offen lds
	s_mov_b32 m0, s36
	s_nop 0
	buffer_load_dwordx4 v230, s[60:63], s23 offen lds
	s_waitcnt vmcnt(8)
	s_waitcnt lgkmcnt(0)
	s_setprio 1
	s_barrier
	v_mfma_f32_16x16x32_bf16 v[62:65], v[130:133], v[154:157], v[62:65]
	v_mfma_f32_16x16x32_bf16 v[62:65], v[140:143], v[194:197], v[62:65]
	v_mfma_f32_16x16x32_bf16 v[58:61], v[170:173], v[154:157], v[58:61]
	v_mfma_f32_16x16x32_bf16 v[58:61], v[174:177], v[194:197], v[58:61]
	v_mfma_f32_16x16x32_bf16 v[46:49], v[186:189], v[154:157], v[46:49]
	v_mfma_f32_16x16x32_bf16 v[46:49], v[190:193], v[194:197], v[46:49]
	v_mfma_f32_16x16x32_bf16 v[54:57], v[178:181], v[154:157], v[54:57]
	v_mfma_f32_16x16x32_bf16 v[54:57], v[182:185], v[194:197], v[54:57]
	v_mfma_f32_16x16x32_bf16 v[38:41], v[178:181], v[198:201], v[38:41]
	v_mfma_f32_16x16x32_bf16 v[38:41], v[182:185], v[202:205], v[38:41]
	v_mfma_f32_16x16x32_bf16 v[30:33], v[186:189], v[198:201], v[30:33]
	v_mfma_f32_16x16x32_bf16 v[30:33], v[190:193], v[202:205], v[30:33]
	v_mfma_f32_16x16x32_bf16 v[42:45], v[170:173], v[198:201], v[42:45]
	v_mfma_f32_16x16x32_bf16 v[42:45], v[174:177], v[202:205], v[42:45]
	v_mfma_f32_16x16x32_bf16 v[50:53], v[130:133], v[198:201], v[50:53]
	v_mfma_f32_16x16x32_bf16 v[50:53], v[140:143], v[202:205], v[50:53]
	v_mfma_f32_16x16x32_bf16 v[34:37], v[130:133], v[236:239], v[34:37]
	v_mfma_f32_16x16x32_bf16 v[34:37], v[140:143], v[240:243], v[34:37]
	v_mfma_f32_16x16x32_bf16 v[26:29], v[170:173], v[236:239], v[26:29]
	v_mfma_f32_16x16x32_bf16 v[26:29], v[174:177], v[240:243], v[26:29]
	v_mfma_f32_16x16x32_bf16 v[14:17], v[186:189], v[236:239], v[14:17]
	v_mfma_f32_16x16x32_bf16 v[14:17], v[190:193], v[240:243], v[14:17]
	v_mfma_f32_16x16x32_bf16 v[22:25], v[178:181], v[236:239], v[22:25]
	v_mfma_f32_16x16x32_bf16 v[22:25], v[182:185], v[240:243], v[22:25]
	v_mfma_f32_16x16x32_bf16 v[6:9], v[178:181], v[244:247], v[6:9]
	v_mfma_f32_16x16x32_bf16 v[6:9], v[182:185], v[248:251], v[6:9]
	v_mfma_f32_16x16x32_bf16 v[2:5], v[186:189], v[244:247], v[2:5]
	v_mfma_f32_16x16x32_bf16 v[2:5], v[190:193], v[248:251], v[2:5]
	v_mfma_f32_16x16x32_bf16 v[10:13], v[170:173], v[244:247], v[10:13]
	v_mfma_f32_16x16x32_bf16 v[10:13], v[174:177], v[248:251], v[10:13]
	v_mfma_f32_16x16x32_bf16 v[18:21], v[130:133], v[244:247], v[18:21]
	v_mfma_f32_16x16x32_bf16 v[18:21], v[140:143], v[248:251], v[18:21]
	s_barrier
	s_setprio 0
	v_add_u32_e32 v139, 0x18000, v234
	ds_read_b128 v[130:133], v139
	ds_read_b128 v[140:143], v139 offset:1024
	ds_read_b128 v[154:157], v139 offset:2048
	ds_read_b128 v[170:173], v139 offset:3072
	v_add_u32_e32 v139, 0x1c000, v234
	ds_read_b128 v[174:177], v139
	ds_read_b128 v[178:181], v139 offset:1024
	ds_read_b128 v[182:185], v139 offset:2048
	ds_read_b128 v[186:189], v139 offset:3072
	s_add_i32 s23, s23, 0x80000
	s_mov_b32 m0, s37
	ds_read_b128 v[190:193], v235 offset:32768
	ds_read_b128 v[194:197], v235 offset:33792
	ds_read_b128 v[198:201], v235 offset:34816
	ds_read_b128 v[202:205], v235 offset:35840
	ds_read_b128 v[236:239], v235 offset:36864
	ds_read_b128 v[240:243], v235 offset:37888
	ds_read_b128 v[244:247], v235 offset:38912
	ds_read_b128 v[248:251], v235 offset:39936
	buffer_load_dwordx4 v228, s[60:63], s23 offen lds
	s_mov_b32 m0, s18
	s_nop 0
	buffer_load_dwordx4 v230, s[60:63], s23 offen lds
	s_waitcnt vmcnt(8)
	s_waitcnt lgkmcnt(0)
	s_setprio 1
	s_barrier
	v_mfma_f32_16x16x32_bf16 v[126:129], v[130:133], v[190:193], v[126:129]
	v_mfma_f32_16x16x32_bf16 v[126:129], v[140:143], v[194:197], v[126:129]
	v_mfma_f32_16x16x32_bf16 v[122:125], v[154:157], v[190:193], v[122:125]
	v_mfma_f32_16x16x32_bf16 v[122:125], v[170:173], v[194:197], v[122:125]
	v_mfma_f32_16x16x32_bf16 v[110:113], v[182:185], v[190:193], v[110:113]
	v_mfma_f32_16x16x32_bf16 v[110:113], v[186:189], v[194:197], v[110:113]
	v_mfma_f32_16x16x32_bf16 v[118:121], v[174:177], v[190:193], v[118:121]
	v_mfma_f32_16x16x32_bf16 v[118:121], v[178:181], v[194:197], v[118:121]
	v_mfma_f32_16x16x32_bf16 v[102:105], v[174:177], v[198:201], v[102:105]
	v_mfma_f32_16x16x32_bf16 v[102:105], v[178:181], v[202:205], v[102:105]
	v_mfma_f32_16x16x32_bf16 v[94:97], v[182:185], v[198:201], v[94:97]
	v_mfma_f32_16x16x32_bf16 v[94:97], v[186:189], v[202:205], v[94:97]
	v_mfma_f32_16x16x32_bf16 v[106:109], v[154:157], v[198:201], v[106:109]
	v_mfma_f32_16x16x32_bf16 v[106:109], v[170:173], v[202:205], v[106:109]
	v_mfma_f32_16x16x32_bf16 v[114:117], v[130:133], v[198:201], v[114:117]
	v_mfma_f32_16x16x32_bf16 v[114:117], v[140:143], v[202:205], v[114:117]
	v_mfma_f32_16x16x32_bf16 v[98:101], v[130:133], v[236:239], v[98:101]
	v_mfma_f32_16x16x32_bf16 v[98:101], v[140:143], v[240:243], v[98:101]
	v_mfma_f32_16x16x32_bf16 v[90:93], v[154:157], v[236:239], v[90:93]
	v_mfma_f32_16x16x32_bf16 v[90:93], v[170:173], v[240:243], v[90:93]
	v_mfma_f32_16x16x32_bf16 v[78:81], v[182:185], v[236:239], v[78:81]
	v_mfma_f32_16x16x32_bf16 v[78:81], v[186:189], v[240:243], v[78:81]
	v_mfma_f32_16x16x32_bf16 v[86:89], v[174:177], v[236:239], v[86:89]
	v_mfma_f32_16x16x32_bf16 v[86:89], v[178:181], v[240:243], v[86:89]
	v_mfma_f32_16x16x32_bf16 v[70:73], v[174:177], v[244:247], v[70:73]
	v_mfma_f32_16x16x32_bf16 v[70:73], v[178:181], v[248:251], v[70:73]
	v_mfma_f32_16x16x32_bf16 v[66:69], v[182:185], v[244:247], v[66:69]
	v_mfma_f32_16x16x32_bf16 v[66:69], v[186:189], v[248:251], v[66:69]
	v_mfma_f32_16x16x32_bf16 v[74:77], v[154:157], v[244:247], v[74:77]
	v_mfma_f32_16x16x32_bf16 v[74:77], v[170:173], v[248:251], v[74:77]
	v_mfma_f32_16x16x32_bf16 v[82:85], v[130:133], v[244:247], v[82:85]
	v_mfma_f32_16x16x32_bf16 v[82:85], v[140:143], v[248:251], v[82:85]
	s_barrier
	s_setprio 0
	s_mov_b32 m0, s24
	s_or_b32 s23, s22, 0x80
	ds_read_b128 v[190:193], v235 offset:49152
	ds_read_b128 v[194:197], v235 offset:50176
	ds_read_b128 v[198:201], v235 offset:51200
	ds_read_b128 v[202:205], v235 offset:52224
	ds_read_b128 v[236:239], v235 offset:53248
	ds_read_b128 v[240:243], v235 offset:54272
	ds_read_b128 v[244:247], v235 offset:55296
	ds_read_b128 v[248:251], v235 offset:56320
	buffer_load_dwordx4 v229, s[44:47], s23 offen lds
	s_mov_b32 m0, s25
	s_add_i32 s22, s22, 0x80080
	buffer_load_dwordx4 v231, s[44:47], s23 offen lds
	s_mov_b32 m0, s64
	s_nop 0
	buffer_load_dwordx4 v229, s[44:47], s22 offen lds
	s_mov_b32 m0, s65
	s_nop 0
	buffer_load_dwordx4 v231, s[44:47], s22 offen lds
	s_mov_b32 m0, s48
	s_nop 0
	buffer_load_dwordx4 v228, s[60:63], s21 offen lds
	s_mov_b32 m0, s49
	s_nop 0
	buffer_load_dwordx4 v230, s[60:63], s21 offen lds
	s_waitcnt vmcnt(8)
	s_waitcnt lgkmcnt(0)
	s_setprio 1
	s_barrier
	v_mfma_f32_16x16x32_bf16 v[62:65], v[130:133], v[190:193], v[62:65]
	v_mfma_f32_16x16x32_bf16 v[62:65], v[140:143], v[194:197], v[62:65]
	v_mfma_f32_16x16x32_bf16 v[58:61], v[154:157], v[190:193], v[58:61]
	v_mfma_f32_16x16x32_bf16 v[58:61], v[170:173], v[194:197], v[58:61]
	v_mfma_f32_16x16x32_bf16 v[46:49], v[182:185], v[190:193], v[46:49]
	v_mfma_f32_16x16x32_bf16 v[46:49], v[186:189], v[194:197], v[46:49]
	v_mfma_f32_16x16x32_bf16 v[54:57], v[174:177], v[190:193], v[54:57]
	v_mfma_f32_16x16x32_bf16 v[54:57], v[178:181], v[194:197], v[54:57]
	v_mfma_f32_16x16x32_bf16 v[38:41], v[174:177], v[198:201], v[38:41]
	v_mfma_f32_16x16x32_bf16 v[38:41], v[178:181], v[202:205], v[38:41]
	v_mfma_f32_16x16x32_bf16 v[30:33], v[182:185], v[198:201], v[30:33]
	v_mfma_f32_16x16x32_bf16 v[30:33], v[186:189], v[202:205], v[30:33]
	v_mfma_f32_16x16x32_bf16 v[42:45], v[154:157], v[198:201], v[42:45]
	v_mfma_f32_16x16x32_bf16 v[42:45], v[170:173], v[202:205], v[42:45]
	v_mfma_f32_16x16x32_bf16 v[50:53], v[130:133], v[198:201], v[50:53]
	v_mfma_f32_16x16x32_bf16 v[50:53], v[140:143], v[202:205], v[50:53]
	v_mfma_f32_16x16x32_bf16 v[34:37], v[130:133], v[236:239], v[34:37]
	v_mfma_f32_16x16x32_bf16 v[34:37], v[140:143], v[240:243], v[34:37]
	v_mfma_f32_16x16x32_bf16 v[26:29], v[154:157], v[236:239], v[26:29]
	v_mfma_f32_16x16x32_bf16 v[26:29], v[170:173], v[240:243], v[26:29]
	v_mfma_f32_16x16x32_bf16 v[14:17], v[182:185], v[236:239], v[14:17]
	v_mfma_f32_16x16x32_bf16 v[14:17], v[186:189], v[240:243], v[14:17]
	v_mfma_f32_16x16x32_bf16 v[22:25], v[174:177], v[236:239], v[22:25]
	v_mfma_f32_16x16x32_bf16 v[22:25], v[178:181], v[240:243], v[22:25]
	v_mfma_f32_16x16x32_bf16 v[6:9], v[174:177], v[244:247], v[6:9]
	v_mfma_f32_16x16x32_bf16 v[6:9], v[178:181], v[248:251], v[6:9]
	v_mfma_f32_16x16x32_bf16 v[2:5], v[182:185], v[244:247], v[2:5]
	v_mfma_f32_16x16x32_bf16 v[2:5], v[186:189], v[248:251], v[2:5]
	v_mfma_f32_16x16x32_bf16 v[10:13], v[154:157], v[244:247], v[10:13]
	v_mfma_f32_16x16x32_bf16 v[10:13], v[170:173], v[248:251], v[10:13]
	v_mfma_f32_16x16x32_bf16 v[18:21], v[130:133], v[244:247], v[18:21]
	v_mfma_f32_16x16x32_bf16 v[18:21], v[140:143], v[248:251], v[18:21]
	s_barrier
	s_setprio 0
	s_add_i32 s16, s16, 2
	s_addk_i32 s12, 0x100
	s_addk_i32 s13, 0x100
	s_cmp_gt_u32 s16, 29
	s_cbranch_scc0 .LBB0_881
	v_readlane_b32 s8, v255, 44
	v_readlane_b32 s9, v255, 45
	s_and_b64 vcc, exec, s[8:9]
	s_cbranch_vccz .LBB0_884
	s_barrier

.LBB0_904:
	s_lshl_b32 s73, s72, 20
	s_and_b64 s[8:9], s[42:43], exec
	s_cselect_b32 s8, s73, s13
	s_lshl_b32 s84, s71, 20
	s_and_b64 s[22:23], s[42:43], exec
	s_cselect_b32 s9, s84, s21
	s_add_i32 s13, s13, 0x80080
	s_addk_i32 s21, 0x100
	s_mov_b32 s22, -2
	v_add_u32_e32 v133, 0x10000, v178
	ds_read_b128 v[134:137], v133
	ds_read_b128 v[138:141], v133 offset:1024
	ds_read_b128 v[142:145], v133 offset:2048
	ds_read_b128 v[154:157], v133 offset:3072
	v_add_u32_e32 v133, 0x14000, v178
	ds_read_b128 v[170:173], v133
	ds_read_b128 v[180:183], v133 offset:1024
	ds_read_b128 v[184:187], v133 offset:2048
	ds_read_b128 v[188:191], v133 offset:3072
	s_add_i32 s23, s13, 0xfff80080
	s_cmp_eq_u32 s22, 28
	s_cselect_b32 s27, s8, s23
	s_cselect_b32 s26, s9, s21
	s_or_b32 s23, s27, 0x80
	s_mov_b32 s46, s62
	s_mov_b32 s47, s63
	s_mov_b32 m0, s68
	ds_read_b128 v[192:195], v179
	ds_read_b128 v[196:199], v179 offset:1024
	ds_read_b128 v[200:203], v179 offset:2048
	ds_read_b128 v[204:207], v179 offset:3072
	ds_read_b128 v[228:231], v179 offset:4096
	ds_read_b128 v[232:235], v179 offset:5120
	ds_read_b128 v[236:239], v179 offset:6144
	ds_read_b128 v[240:243], v179 offset:7168
	buffer_load_dwordx4 v174, s[44:47], s13 offen lds
	s_mov_b32 m0, s69
	s_nop 0
	buffer_load_dwordx4 v176, s[44:47], s13 offen lds
	s_waitcnt vmcnt(8)
	s_waitcnt lgkmcnt(0)
	s_setprio 1
	s_barrier
	v_mfma_f32_16x16x32_bf16 v[126:129], v[134:137], v[192:195], 0
	v_mfma_f32_16x16x32_bf16 v[126:129], v[138:141], v[196:199], v[126:129]
	v_mfma_f32_16x16x32_bf16 v[122:125], v[142:145], v[192:195], 0
	v_mfma_f32_16x16x32_bf16 v[122:125], v[154:157], v[196:199], v[122:125]
	v_mfma_f32_16x16x32_bf16 v[114:117], v[184:187], v[192:195], 0
	v_mfma_f32_16x16x32_bf16 v[114:117], v[188:191], v[196:199], v[114:117]
	v_mfma_f32_16x16x32_bf16 v[118:121], v[170:173], v[192:195], 0
	v_mfma_f32_16x16x32_bf16 v[118:121], v[180:183], v[196:199], v[118:121]
	v_mfma_f32_16x16x32_bf16 v[102:105], v[170:173], v[200:203], 0
	v_mfma_f32_16x16x32_bf16 v[102:105], v[180:183], v[204:207], v[102:105]
	v_mfma_f32_16x16x32_bf16 v[98:101], v[184:187], v[200:203], 0
	v_mfma_f32_16x16x32_bf16 v[98:101], v[188:191], v[204:207], v[98:101]
	v_mfma_f32_16x16x32_bf16 v[106:109], v[142:145], v[200:203], 0
	v_mfma_f32_16x16x32_bf16 v[106:109], v[154:157], v[204:207], v[106:109]
	v_mfma_f32_16x16x32_bf16 v[110:113], v[134:137], v[200:203], 0
	v_mfma_f32_16x16x32_bf16 v[110:113], v[138:141], v[204:207], v[110:113]
	v_mfma_f32_16x16x32_bf16 v[94:97], v[134:137], v[228:231], 0
	v_mfma_f32_16x16x32_bf16 v[94:97], v[138:141], v[232:235], v[94:97]
	v_mfma_f32_16x16x32_bf16 v[90:93], v[142:145], v[228:231], 0
	v_mfma_f32_16x16x32_bf16 v[90:93], v[154:157], v[232:235], v[90:93]
	v_mfma_f32_16x16x32_bf16 v[82:85], v[184:187], v[228:231], 0
	v_mfma_f32_16x16x32_bf16 v[82:85], v[188:191], v[232:235], v[82:85]
	v_mfma_f32_16x16x32_bf16 v[86:89], v[170:173], v[228:231], 0
	v_mfma_f32_16x16x32_bf16 v[86:89], v[180:183], v[232:235], v[86:89]
	v_mfma_f32_16x16x32_bf16 v[70:73], v[170:173], v[236:239], 0
	v_mfma_f32_16x16x32_bf16 v[70:73], v[180:183], v[240:243], v[70:73]
	v_mfma_f32_16x16x32_bf16 v[66:69], v[184:187], v[236:239], 0
	v_mfma_f32_16x16x32_bf16 v[66:69], v[188:191], v[240:243], v[66:69]
	v_mfma_f32_16x16x32_bf16 v[74:77], v[142:145], v[236:239], 0
	v_mfma_f32_16x16x32_bf16 v[74:77], v[154:157], v[240:243], v[74:77]
	v_mfma_f32_16x16x32_bf16 v[78:81], v[134:137], v[236:239], 0
	v_mfma_f32_16x16x32_bf16 v[78:81], v[138:141], v[240:243], v[78:81]
	s_barrier
	s_setprio 0
	s_mov_b32 m0, s15
	ds_read_b128 v[192:195], v179 offset:16384
	ds_read_b128 v[196:199], v179 offset:17408
	ds_read_b128 v[200:203], v179 offset:18432
	ds_read_b128 v[204:207], v179 offset:19456
	ds_read_b128 v[228:231], v179 offset:20480
	ds_read_b128 v[232:235], v179 offset:21504
	ds_read_b128 v[236:239], v179 offset:22528
	ds_read_b128 v[240:243], v179 offset:23552
	buffer_load_dwordx4 v175, s[60:63], s26 offen lds
	s_mov_b32 m0, s16
	s_add_i32 s34, s26, 0x80000
	buffer_load_dwordx4 v177, s[60:63], s26 offen lds
	s_mov_b32 m0, s18
	s_nop 0
	buffer_load_dwordx4 v175, s[60:63], s34 offen lds
	s_mov_b32 m0, s19
	s_nop 0
	buffer_load_dwordx4 v177, s[60:63], s34 offen lds
	s_mov_b32 m0, s14
	s_nop 0
	buffer_load_dwordx4 v174, s[44:47], s27 offen lds
	s_mov_b32 m0, s24
	s_nop 0
	buffer_load_dwordx4 v176, s[44:47], s27 offen lds
	s_waitcnt vmcnt(8)
	s_waitcnt lgkmcnt(0)
	s_setprio 1
	s_barrier
	v_mfma_f32_16x16x32_bf16 v[62:65], v[134:137], v[192:195], 0
	v_mfma_f32_16x16x32_bf16 v[62:65], v[138:141], v[196:199], v[62:65]
	v_mfma_f32_16x16x32_bf16 v[58:61], v[142:145], v[192:195], 0
	v_mfma_f32_16x16x32_bf16 v[58:61], v[154:157], v[196:199], v[58:61]
	v_mfma_f32_16x16x32_bf16 v[50:53], v[184:187], v[192:195], 0
	v_mfma_f32_16x16x32_bf16 v[50:53], v[188:191], v[196:199], v[50:53]
	v_mfma_f32_16x16x32_bf16 v[54:57], v[170:173], v[192:195], 0
	v_mfma_f32_16x16x32_bf16 v[54:57], v[180:183], v[196:199], v[54:57]
	v_mfma_f32_16x16x32_bf16 v[38:41], v[170:173], v[200:203], 0
	v_mfma_f32_16x16x32_bf16 v[38:41], v[180:183], v[204:207], v[38:41]
	v_mfma_f32_16x16x32_bf16 v[34:37], v[184:187], v[200:203], 0
	v_mfma_f32_16x16x32_bf16 v[34:37], v[188:191], v[204:207], v[34:37]
	v_mfma_f32_16x16x32_bf16 v[42:45], v[142:145], v[200:203], 0
	v_mfma_f32_16x16x32_bf16 v[42:45], v[154:157], v[204:207], v[42:45]
	v_mfma_f32_16x16x32_bf16 v[46:49], v[134:137], v[200:203], 0
	v_mfma_f32_16x16x32_bf16 v[46:49], v[138:141], v[204:207], v[46:49]
	v_mfma_f32_16x16x32_bf16 v[30:33], v[134:137], v[228:231], 0
	v_mfma_f32_16x16x32_bf16 v[30:33], v[138:141], v[232:235], v[30:33]
	v_mfma_f32_16x16x32_bf16 v[26:29], v[142:145], v[228:231], 0
	v_mfma_f32_16x16x32_bf16 v[26:29], v[154:157], v[232:235], v[26:29]
	v_mfma_f32_16x16x32_bf16 v[18:21], v[184:187], v[228:231], 0
	v_mfma_f32_16x16x32_bf16 v[18:21], v[188:191], v[232:235], v[18:21]
	v_mfma_f32_16x16x32_bf16 v[22:25], v[170:173], v[228:231], 0
	v_mfma_f32_16x16x32_bf16 v[22:25], v[180:183], v[232:235], v[22:25]
	v_mfma_f32_16x16x32_bf16 v[6:9], v[170:173], v[236:239], 0
	v_mfma_f32_16x16x32_bf16 v[6:9], v[180:183], v[240:243], v[6:9]
	v_mfma_f32_16x16x32_bf16 v[2:5], v[184:187], v[236:239], 0
	v_mfma_f32_16x16x32_bf16 v[2:5], v[188:191], v[240:243], v[2:5]
	v_mfma_f32_16x16x32_bf16 v[10:13], v[142:145], v[236:239], 0
	v_mfma_f32_16x16x32_bf16 v[10:13], v[154:157], v[240:243], v[10:13]
	v_mfma_f32_16x16x32_bf16 v[14:17], v[134:137], v[236:239], 0
	v_mfma_f32_16x16x32_bf16 v[14:17], v[138:141], v[240:243], v[14:17]
	s_barrier
	s_setprio 0
	v_add_u32_e32 v133, 0x18000, v178
	ds_read_b128 v[134:137], v133
	ds_read_b128 v[138:141], v133 offset:1024
	ds_read_b128 v[142:145], v133 offset:2048
	ds_read_b128 v[154:157], v133 offset:3072
	v_add_u32_e32 v133, 0x1c000, v178
	ds_read_b128 v[170:173], v133
	ds_read_b128 v[180:183], v133 offset:1024
	ds_read_b128 v[184:187], v133 offset:2048
	ds_read_b128 v[188:191], v133 offset:3072
	s_add_i32 s27, s27, 0x80000
	s_mov_b32 m0, s25
	ds_read_b128 v[192:195], v179 offset:32768
	ds_read_b128 v[196:199], v179 offset:33792
	ds_read_b128 v[200:203], v179 offset:34816
	ds_read_b128 v[204:207], v179 offset:35840
	ds_read_b128 v[228:231], v179 offset:36864
	ds_read_b128 v[232:235], v179 offset:37888
	ds_read_b128 v[236:239], v179 offset:38912
	ds_read_b128 v[240:243], v179 offset:39936
	buffer_load_dwordx4 v174, s[44:47], s27 offen lds
	s_mov_b32 m0, s30
	s_nop 0
	buffer_load_dwordx4 v176, s[44:47], s27 offen lds
	s_waitcnt vmcnt(8)
	s_waitcnt lgkmcnt(0)
	s_setprio 1
	s_barrier
	v_mfma_f32_16x16x32_bf16 v[126:129], v[134:137], v[192:195], v[126:129]
	v_mfma_f32_16x16x32_bf16 v[126:129], v[138:141], v[196:199], v[126:129]
	v_mfma_f32_16x16x32_bf16 v[122:125], v[142:145], v[192:195], v[122:125]
	v_mfma_f32_16x16x32_bf16 v[122:125], v[154:157], v[196:199], v[122:125]
	v_mfma_f32_16x16x32_bf16 v[114:117], v[184:187], v[192:195], v[114:117]
	v_mfma_f32_16x16x32_bf16 v[114:117], v[188:191], v[196:199], v[114:117]
	v_mfma_f32_16x16x32_bf16 v[118:121], v[170:173], v[192:195], v[118:121]
	v_mfma_f32_16x16x32_bf16 v[118:121], v[180:183], v[196:199], v[118:121]
	v_mfma_f32_16x16x32_bf16 v[102:105], v[170:173], v[200:203], v[102:105]
	v_mfma_f32_16x16x32_bf16 v[102:105], v[180:183], v[204:207], v[102:105]
	v_mfma_f32_16x16x32_bf16 v[98:101], v[184:187], v[200:203], v[98:101]
	v_mfma_f32_16x16x32_bf16 v[98:101], v[188:191], v[204:207], v[98:101]
	v_mfma_f32_16x16x32_bf16 v[106:109], v[142:145], v[200:203], v[106:109]
	v_mfma_f32_16x16x32_bf16 v[106:109], v[154:157], v[204:207], v[106:109]
	v_mfma_f32_16x16x32_bf16 v[110:113], v[134:137], v[200:203], v[110:113]
	v_mfma_f32_16x16x32_bf16 v[110:113], v[138:141], v[204:207], v[110:113]
	v_mfma_f32_16x16x32_bf16 v[94:97], v[134:137], v[228:231], v[94:97]
	v_mfma_f32_16x16x32_bf16 v[94:97], v[138:141], v[232:235], v[94:97]
	v_mfma_f32_16x16x32_bf16 v[90:93], v[142:145], v[228:231], v[90:93]
	v_mfma_f32_16x16x32_bf16 v[90:93], v[154:157], v[232:235], v[90:93]
	v_mfma_f32_16x16x32_bf16 v[82:85], v[184:187], v[228:231], v[82:85]
	v_mfma_f32_16x16x32_bf16 v[82:85], v[188:191], v[232:235], v[82:85]
	v_mfma_f32_16x16x32_bf16 v[86:89], v[170:173], v[228:231], v[86:89]
	v_mfma_f32_16x16x32_bf16 v[86:89], v[180:183], v[232:235], v[86:89]
	v_mfma_f32_16x16x32_bf16 v[70:73], v[170:173], v[236:239], v[70:73]
	v_mfma_f32_16x16x32_bf16 v[70:73], v[180:183], v[240:243], v[70:73]
	v_mfma_f32_16x16x32_bf16 v[66:69], v[184:187], v[236:239], v[66:69]
	v_mfma_f32_16x16x32_bf16 v[66:69], v[188:191], v[240:243], v[66:69]
	v_mfma_f32_16x16x32_bf16 v[74:77], v[142:145], v[236:239], v[74:77]
	v_mfma_f32_16x16x32_bf16 v[74:77], v[154:157], v[240:243], v[74:77]
	v_mfma_f32_16x16x32_bf16 v[78:81], v[134:137], v[236:239], v[78:81]
	v_mfma_f32_16x16x32_bf16 v[78:81], v[138:141], v[240:243], v[78:81]
	s_barrier
	s_setprio 0
	s_mov_b32 m0, s36
	s_or_b32 s27, s26, 0x80
	ds_read_b128 v[192:195], v179 offset:49152
	ds_read_b128 v[196:199], v179 offset:50176
	ds_read_b128 v[200:203], v179 offset:51200
	ds_read_b128 v[204:207], v179 offset:52224
	ds_read_b128 v[228:231], v179 offset:53248
	ds_read_b128 v[232:235], v179 offset:54272
	ds_read_b128 v[236:239], v179 offset:55296
	ds_read_b128 v[240:243], v179 offset:56320
	buffer_load_dwordx4 v175, s[60:63], s27 offen lds
	s_mov_b32 m0, s37
	s_add_i32 s26, s26, 0x80080
	buffer_load_dwordx4 v177, s[60:63], s27 offen lds
	s_mov_b32 m0, s48
	s_nop 0
	buffer_load_dwordx4 v175, s[60:63], s26 offen lds
	s_mov_b32 m0, s49
	s_nop 0
	buffer_load_dwordx4 v177, s[60:63], s26 offen lds
	s_mov_b32 m0, s40
	s_nop 0
	buffer_load_dwordx4 v174, s[44:47], s23 offen lds
	s_mov_b32 m0, s41
	s_nop 0
	buffer_load_dwordx4 v176, s[44:47], s23 offen lds
	s_waitcnt vmcnt(8)
	s_waitcnt lgkmcnt(0)
	s_setprio 1
	s_barrier
	v_mfma_f32_16x16x32_bf16 v[62:65], v[134:137], v[192:195], v[62:65]
	v_mfma_f32_16x16x32_bf16 v[62:65], v[138:141], v[196:199], v[62:65]
	v_mfma_f32_16x16x32_bf16 v[58:61], v[142:145], v[192:195], v[58:61]
	v_mfma_f32_16x16x32_bf16 v[58:61], v[154:157], v[196:199], v[58:61]
	v_mfma_f32_16x16x32_bf16 v[50:53], v[184:187], v[192:195], v[50:53]
	v_mfma_f32_16x16x32_bf16 v[50:53], v[188:191], v[196:199], v[50:53]
	v_mfma_f32_16x16x32_bf16 v[54:57], v[170:173], v[192:195], v[54:57]
	v_mfma_f32_16x16x32_bf16 v[54:57], v[180:183], v[196:199], v[54:57]
	v_mfma_f32_16x16x32_bf16 v[38:41], v[170:173], v[200:203], v[38:41]
	v_mfma_f32_16x16x32_bf16 v[38:41], v[180:183], v[204:207], v[38:41]
	v_mfma_f32_16x16x32_bf16 v[34:37], v[184:187], v[200:203], v[34:37]
	v_mfma_f32_16x16x32_bf16 v[34:37], v[188:191], v[204:207], v[34:37]
	v_mfma_f32_16x16x32_bf16 v[42:45], v[142:145], v[200:203], v[42:45]
	v_mfma_f32_16x16x32_bf16 v[42:45], v[154:157], v[204:207], v[42:45]
	v_mfma_f32_16x16x32_bf16 v[46:49], v[134:137], v[200:203], v[46:49]
	v_mfma_f32_16x16x32_bf16 v[46:49], v[138:141], v[204:207], v[46:49]
	v_mfma_f32_16x16x32_bf16 v[30:33], v[134:137], v[228:231], v[30:33]
	v_mfma_f32_16x16x32_bf16 v[30:33], v[138:141], v[232:235], v[30:33]
	v_mfma_f32_16x16x32_bf16 v[26:29], v[142:145], v[228:231], v[26:29]
	v_mfma_f32_16x16x32_bf16 v[26:29], v[154:157], v[232:235], v[26:29]
	v_mfma_f32_16x16x32_bf16 v[18:21], v[184:187], v[228:231], v[18:21]
	v_mfma_f32_16x16x32_bf16 v[18:21], v[188:191], v[232:235], v[18:21]
	v_mfma_f32_16x16x32_bf16 v[22:25], v[170:173], v[228:231], v[22:25]
	v_mfma_f32_16x16x32_bf16 v[22:25], v[180:183], v[232:235], v[22:25]
	v_mfma_f32_16x16x32_bf16 v[6:9], v[170:173], v[236:239], v[6:9]
	v_mfma_f32_16x16x32_bf16 v[6:9], v[180:183], v[240:243], v[6:9]
	v_mfma_f32_16x16x32_bf16 v[2:5], v[184:187], v[236:239], v[2:5]
	v_mfma_f32_16x16x32_bf16 v[2:5], v[188:191], v[240:243], v[2:5]
	v_mfma_f32_16x16x32_bf16 v[10:13], v[142:145], v[236:239], v[10:13]
	v_mfma_f32_16x16x32_bf16 v[10:13], v[154:157], v[240:243], v[10:13]
	v_mfma_f32_16x16x32_bf16 v[14:17], v[134:137], v[236:239], v[14:17]
	v_mfma_f32_16x16x32_bf16 v[14:17], v[138:141], v[240:243], v[14:17]
	s_barrier
	s_setprio 0
	s_add_i32 s22, s22, 2
	s_addk_i32 s13, 0x100
	s_addk_i32 s21, 0x100
	s_cmp_gt_u32 s22, 29
.LBB0_905:
	v_add_u32_e32 v133, 0x10000, v178
	ds_read_b128 v[134:137], v133
	ds_read_b128 v[138:141], v133 offset:1024
	ds_read_b128 v[142:145], v133 offset:2048
	ds_read_b128 v[154:157], v133 offset:3072
	v_add_u32_e32 v133, 0x14000, v178
	ds_read_b128 v[170:173], v133
	ds_read_b128 v[180:183], v133 offset:1024
	ds_read_b128 v[184:187], v133 offset:2048
	ds_read_b128 v[188:191], v133 offset:3072
	s_add_i32 s23, s13, 0xfff80080
	s_cmp_eq_u32 s22, 28
	s_cselect_b32 s27, s8, s23
	s_cselect_b32 s26, s9, s21
	s_or_b32 s23, s27, 0x80
	s_mov_b32 s46, s62
	s_mov_b32 s47, s63
	s_mov_b32 m0, s68
	ds_read_b128 v[192:195], v179
	ds_read_b128 v[196:199], v179 offset:1024
	ds_read_b128 v[200:203], v179 offset:2048
	ds_read_b128 v[204:207], v179 offset:3072
	ds_read_b128 v[228:231], v179 offset:4096
	ds_read_b128 v[232:235], v179 offset:5120
	ds_read_b128 v[236:239], v179 offset:6144
	ds_read_b128 v[240:243], v179 offset:7168
	buffer_load_dwordx4 v174, s[44:47], s13 offen lds
	s_mov_b32 m0, s69
	s_nop 0
	buffer_load_dwordx4 v176, s[44:47], s13 offen lds
	s_waitcnt vmcnt(8)
	s_waitcnt lgkmcnt(0)
	s_setprio 1
	s_barrier
	v_mfma_f32_16x16x32_bf16 v[126:129], v[134:137], v[192:195], v[126:129]
	v_mfma_f32_16x16x32_bf16 v[126:129], v[138:141], v[196:199], v[126:129]
	v_mfma_f32_16x16x32_bf16 v[122:125], v[142:145], v[192:195], v[122:125]
	v_mfma_f32_16x16x32_bf16 v[122:125], v[154:157], v[196:199], v[122:125]
	v_mfma_f32_16x16x32_bf16 v[114:117], v[184:187], v[192:195], v[114:117]
	v_mfma_f32_16x16x32_bf16 v[114:117], v[188:191], v[196:199], v[114:117]
	v_mfma_f32_16x16x32_bf16 v[118:121], v[170:173], v[192:195], v[118:121]
	v_mfma_f32_16x16x32_bf16 v[118:121], v[180:183], v[196:199], v[118:121]
	v_mfma_f32_16x16x32_bf16 v[102:105], v[170:173], v[200:203], v[102:105]
	v_mfma_f32_16x16x32_bf16 v[102:105], v[180:183], v[204:207], v[102:105]
	v_mfma_f32_16x16x32_bf16 v[98:101], v[184:187], v[200:203], v[98:101]
	v_mfma_f32_16x16x32_bf16 v[98:101], v[188:191], v[204:207], v[98:101]
	v_mfma_f32_16x16x32_bf16 v[106:109], v[142:145], v[200:203], v[106:109]
	v_mfma_f32_16x16x32_bf16 v[106:109], v[154:157], v[204:207], v[106:109]
	v_mfma_f32_16x16x32_bf16 v[110:113], v[134:137], v[200:203], v[110:113]
	v_mfma_f32_16x16x32_bf16 v[110:113], v[138:141], v[204:207], v[110:113]
	v_mfma_f32_16x16x32_bf16 v[94:97], v[134:137], v[228:231], v[94:97]
	v_mfma_f32_16x16x32_bf16 v[94:97], v[138:141], v[232:235], v[94:97]
	v_mfma_f32_16x16x32_bf16 v[90:93], v[142:145], v[228:231], v[90:93]
	v_mfma_f32_16x16x32_bf16 v[90:93], v[154:157], v[232:235], v[90:93]
	v_mfma_f32_16x16x32_bf16 v[82:85], v[184:187], v[228:231], v[82:85]
	v_mfma_f32_16x16x32_bf16 v[82:85], v[188:191], v[232:235], v[82:85]
	v_mfma_f32_16x16x32_bf16 v[86:89], v[170:173], v[228:231], v[86:89]
	v_mfma_f32_16x16x32_bf16 v[86:89], v[180:183], v[232:235], v[86:89]
	v_mfma_f32_16x16x32_bf16 v[70:73], v[170:173], v[236:239], v[70:73]
	v_mfma_f32_16x16x32_bf16 v[70:73], v[180:183], v[240:243], v[70:73]
	v_mfma_f32_16x16x32_bf16 v[66:69], v[184:187], v[236:239], v[66:69]
	v_mfma_f32_16x16x32_bf16 v[66:69], v[188:191], v[240:243], v[66:69]
	v_mfma_f32_16x16x32_bf16 v[74:77], v[142:145], v[236:239], v[74:77]
	v_mfma_f32_16x16x32_bf16 v[74:77], v[154:157], v[240:243], v[74:77]
	v_mfma_f32_16x16x32_bf16 v[78:81], v[134:137], v[236:239], v[78:81]
	v_mfma_f32_16x16x32_bf16 v[78:81], v[138:141], v[240:243], v[78:81]
	s_barrier
	s_setprio 0
	s_mov_b32 m0, s15
	ds_read_b128 v[192:195], v179 offset:16384
	ds_read_b128 v[196:199], v179 offset:17408
	ds_read_b128 v[200:203], v179 offset:18432
	ds_read_b128 v[204:207], v179 offset:19456
	ds_read_b128 v[228:231], v179 offset:20480
	ds_read_b128 v[232:235], v179 offset:21504
	ds_read_b128 v[236:239], v179 offset:22528
	ds_read_b128 v[240:243], v179 offset:23552
	buffer_load_dwordx4 v175, s[60:63], s26 offen lds
	s_mov_b32 m0, s16
	s_add_i32 s34, s26, 0x80000
	buffer_load_dwordx4 v177, s[60:63], s26 offen lds
	s_mov_b32 m0, s18
	s_nop 0
	buffer_load_dwordx4 v175, s[60:63], s34 offen lds
	s_mov_b32 m0, s19
	s_nop 0
	buffer_load_dwordx4 v177, s[60:63], s34 offen lds
	s_mov_b32 m0, s14
	s_nop 0
	buffer_load_dwordx4 v174, s[44:47], s27 offen lds
	s_mov_b32 m0, s24
	s_nop 0
	buffer_load_dwordx4 v176, s[44:47], s27 offen lds
	s_waitcnt vmcnt(8)
	s_waitcnt lgkmcnt(0)
	s_setprio 1
	s_barrier
	v_mfma_f32_16x16x32_bf16 v[62:65], v[134:137], v[192:195], v[62:65]
	v_mfma_f32_16x16x32_bf16 v[62:65], v[138:141], v[196:199], v[62:65]
	v_mfma_f32_16x16x32_bf16 v[58:61], v[142:145], v[192:195], v[58:61]
	v_mfma_f32_16x16x32_bf16 v[58:61], v[154:157], v[196:199], v[58:61]
	v_mfma_f32_16x16x32_bf16 v[50:53], v[184:187], v[192:195], v[50:53]
	v_mfma_f32_16x16x32_bf16 v[50:53], v[188:191], v[196:199], v[50:53]
	v_mfma_f32_16x16x32_bf16 v[54:57], v[170:173], v[192:195], v[54:57]
	v_mfma_f32_16x16x32_bf16 v[54:57], v[180:183], v[196:199], v[54:57]
	v_mfma_f32_16x16x32_bf16 v[38:41], v[170:173], v[200:203], v[38:41]
	v_mfma_f32_16x16x32_bf16 v[38:41], v[180:183], v[204:207], v[38:41]
	v_mfma_f32_16x16x32_bf16 v[34:37], v[184:187], v[200:203], v[34:37]
	v_mfma_f32_16x16x32_bf16 v[34:37], v[188:191], v[204:207], v[34:37]
	v_mfma_f32_16x16x32_bf16 v[42:45], v[142:145], v[200:203], v[42:45]
	v_mfma_f32_16x16x32_bf16 v[42:45], v[154:157], v[204:207], v[42:45]
	v_mfma_f32_16x16x32_bf16 v[46:49], v[134:137], v[200:203], v[46:49]
	v_mfma_f32_16x16x32_bf16 v[46:49], v[138:141], v[204:207], v[46:49]
	v_mfma_f32_16x16x32_bf16 v[30:33], v[134:137], v[228:231], v[30:33]
	v_mfma_f32_16x16x32_bf16 v[30:33], v[138:141], v[232:235], v[30:33]
	v_mfma_f32_16x16x32_bf16 v[26:29], v[142:145], v[228:231], v[26:29]
	v_mfma_f32_16x16x32_bf16 v[26:29], v[154:157], v[232:235], v[26:29]
	v_mfma_f32_16x16x32_bf16 v[18:21], v[184:187], v[228:231], v[18:21]
	v_mfma_f32_16x16x32_bf16 v[18:21], v[188:191], v[232:235], v[18:21]
	v_mfma_f32_16x16x32_bf16 v[22:25], v[170:173], v[228:231], v[22:25]
	v_mfma_f32_16x16x32_bf16 v[22:25], v[180:183], v[232:235], v[22:25]
	v_mfma_f32_16x16x32_bf16 v[6:9], v[170:173], v[236:239], v[6:9]
	v_mfma_f32_16x16x32_bf16 v[6:9], v[180:183], v[240:243], v[6:9]
	v_mfma_f32_16x16x32_bf16 v[2:5], v[184:187], v[236:239], v[2:5]
	v_mfma_f32_16x16x32_bf16 v[2:5], v[188:191], v[240:243], v[2:5]
	v_mfma_f32_16x16x32_bf16 v[10:13], v[142:145], v[236:239], v[10:13]
	v_mfma_f32_16x16x32_bf16 v[10:13], v[154:157], v[240:243], v[10:13]
	v_mfma_f32_16x16x32_bf16 v[14:17], v[134:137], v[236:239], v[14:17]
	v_mfma_f32_16x16x32_bf16 v[14:17], v[138:141], v[240:243], v[14:17]
	s_barrier
	s_setprio 0
	v_add_u32_e32 v133, 0x18000, v178
	ds_read_b128 v[134:137], v133
	ds_read_b128 v[138:141], v133 offset:1024
	ds_read_b128 v[142:145], v133 offset:2048
	ds_read_b128 v[154:157], v133 offset:3072
	v_add_u32_e32 v133, 0x1c000, v178
	ds_read_b128 v[170:173], v133
	ds_read_b128 v[180:183], v133 offset:1024
	ds_read_b128 v[184:187], v133 offset:2048
	ds_read_b128 v[188:191], v133 offset:3072
	s_add_i32 s27, s27, 0x80000
	s_mov_b32 m0, s25
	ds_read_b128 v[192:195], v179 offset:32768
	ds_read_b128 v[196:199], v179 offset:33792
	ds_read_b128 v[200:203], v179 offset:34816
	ds_read_b128 v[204:207], v179 offset:35840
	ds_read_b128 v[228:231], v179 offset:36864
	ds_read_b128 v[232:235], v179 offset:37888
	ds_read_b128 v[236:239], v179 offset:38912
	ds_read_b128 v[240:243], v179 offset:39936
	buffer_load_dwordx4 v174, s[44:47], s27 offen lds
	s_mov_b32 m0, s30
	s_nop 0
	buffer_load_dwordx4 v176, s[44:47], s27 offen lds
	s_waitcnt vmcnt(8)
	s_waitcnt lgkmcnt(0)
	s_setprio 1
	s_barrier
	v_mfma_f32_16x16x32_bf16 v[126:129], v[134:137], v[192:195], v[126:129]
	v_mfma_f32_16x16x32_bf16 v[126:129], v[138:141], v[196:199], v[126:129]
	v_mfma_f32_16x16x32_bf16 v[122:125], v[142:145], v[192:195], v[122:125]
	v_mfma_f32_16x16x32_bf16 v[122:125], v[154:157], v[196:199], v[122:125]
	v_mfma_f32_16x16x32_bf16 v[114:117], v[184:187], v[192:195], v[114:117]
	v_mfma_f32_16x16x32_bf16 v[114:117], v[188:191], v[196:199], v[114:117]
	v_mfma_f32_16x16x32_bf16 v[118:121], v[170:173], v[192:195], v[118:121]
	v_mfma_f32_16x16x32_bf16 v[118:121], v[180:183], v[196:199], v[118:121]
	v_mfma_f32_16x16x32_bf16 v[102:105], v[170:173], v[200:203], v[102:105]
	v_mfma_f32_16x16x32_bf16 v[102:105], v[180:183], v[204:207], v[102:105]
	v_mfma_f32_16x16x32_bf16 v[98:101], v[184:187], v[200:203], v[98:101]
	v_mfma_f32_16x16x32_bf16 v[98:101], v[188:191], v[204:207], v[98:101]
	v_mfma_f32_16x16x32_bf16 v[106:109], v[142:145], v[200:203], v[106:109]
	v_mfma_f32_16x16x32_bf16 v[106:109], v[154:157], v[204:207], v[106:109]
	v_mfma_f32_16x16x32_bf16 v[110:113], v[134:137], v[200:203], v[110:113]
	v_mfma_f32_16x16x32_bf16 v[110:113], v[138:141], v[204:207], v[110:113]
	v_mfma_f32_16x16x32_bf16 v[94:97], v[134:137], v[228:231], v[94:97]
	v_mfma_f32_16x16x32_bf16 v[94:97], v[138:141], v[232:235], v[94:97]
	v_mfma_f32_16x16x32_bf16 v[90:93], v[142:145], v[228:231], v[90:93]
	v_mfma_f32_16x16x32_bf16 v[90:93], v[154:157], v[232:235], v[90:93]
	v_mfma_f32_16x16x32_bf16 v[82:85], v[184:187], v[228:231], v[82:85]
	v_mfma_f32_16x16x32_bf16 v[82:85], v[188:191], v[232:235], v[82:85]
	v_mfma_f32_16x16x32_bf16 v[86:89], v[170:173], v[228:231], v[86:89]
	v_mfma_f32_16x16x32_bf16 v[86:89], v[180:183], v[232:235], v[86:89]
	v_mfma_f32_16x16x32_bf16 v[70:73], v[170:173], v[236:239], v[70:73]
	v_mfma_f32_16x16x32_bf16 v[70:73], v[180:183], v[240:243], v[70:73]
	v_mfma_f32_16x16x32_bf16 v[66:69], v[184:187], v[236:239], v[66:69]
	v_mfma_f32_16x16x32_bf16 v[66:69], v[188:191], v[240:243], v[66:69]
	v_mfma_f32_16x16x32_bf16 v[74:77], v[142:145], v[236:239], v[74:77]
	v_mfma_f32_16x16x32_bf16 v[74:77], v[154:157], v[240:243], v[74:77]
	v_mfma_f32_16x16x32_bf16 v[78:81], v[134:137], v[236:239], v[78:81]
	v_mfma_f32_16x16x32_bf16 v[78:81], v[138:141], v[240:243], v[78:81]
	s_barrier
	s_setprio 0
	s_mov_b32 m0, s36
	s_or_b32 s27, s26, 0x80
	ds_read_b128 v[192:195], v179 offset:49152
	ds_read_b128 v[196:199], v179 offset:50176
	ds_read_b128 v[200:203], v179 offset:51200
	ds_read_b128 v[204:207], v179 offset:52224
	ds_read_b128 v[228:231], v179 offset:53248
	ds_read_b128 v[232:235], v179 offset:54272
	ds_read_b128 v[236:239], v179 offset:55296
	ds_read_b128 v[240:243], v179 offset:56320
	buffer_load_dwordx4 v175, s[60:63], s27 offen lds
	s_mov_b32 m0, s37
	s_add_i32 s26, s26, 0x80080
	buffer_load_dwordx4 v177, s[60:63], s27 offen lds
	s_mov_b32 m0, s48
	s_nop 0
	buffer_load_dwordx4 v175, s[60:63], s26 offen lds
	s_mov_b32 m0, s49
	s_nop 0
	buffer_load_dwordx4 v177, s[60:63], s26 offen lds
	s_mov_b32 m0, s40
	s_nop 0
	buffer_load_dwordx4 v174, s[44:47], s23 offen lds
	s_mov_b32 m0, s41
	s_nop 0
	buffer_load_dwordx4 v176, s[44:47], s23 offen lds
	s_waitcnt vmcnt(8)
	s_waitcnt lgkmcnt(0)
	s_setprio 1
	s_barrier
	v_mfma_f32_16x16x32_bf16 v[62:65], v[134:137], v[192:195], v[62:65]
	v_mfma_f32_16x16x32_bf16 v[62:65], v[138:141], v[196:199], v[62:65]
	v_mfma_f32_16x16x32_bf16 v[58:61], v[142:145], v[192:195], v[58:61]
	v_mfma_f32_16x16x32_bf16 v[58:61], v[154:157], v[196:199], v[58:61]
	v_mfma_f32_16x16x32_bf16 v[50:53], v[184:187], v[192:195], v[50:53]
	v_mfma_f32_16x16x32_bf16 v[50:53], v[188:191], v[196:199], v[50:53]
	v_mfma_f32_16x16x32_bf16 v[54:57], v[170:173], v[192:195], v[54:57]
	v_mfma_f32_16x16x32_bf16 v[54:57], v[180:183], v[196:199], v[54:57]
	v_mfma_f32_16x16x32_bf16 v[38:41], v[170:173], v[200:203], v[38:41]
	v_mfma_f32_16x16x32_bf16 v[38:41], v[180:183], v[204:207], v[38:41]
	v_mfma_f32_16x16x32_bf16 v[34:37], v[184:187], v[200:203], v[34:37]
	v_mfma_f32_16x16x32_bf16 v[34:37], v[188:191], v[204:207], v[34:37]
	v_mfma_f32_16x16x32_bf16 v[42:45], v[142:145], v[200:203], v[42:45]
	v_mfma_f32_16x16x32_bf16 v[42:45], v[154:157], v[204:207], v[42:45]
	v_mfma_f32_16x16x32_bf16 v[46:49], v[134:137], v[200:203], v[46:49]
	v_mfma_f32_16x16x32_bf16 v[46:49], v[138:141], v[204:207], v[46:49]
	v_mfma_f32_16x16x32_bf16 v[30:33], v[134:137], v[228:231], v[30:33]
	v_mfma_f32_16x16x32_bf16 v[30:33], v[138:141], v[232:235], v[30:33]
	v_mfma_f32_16x16x32_bf16 v[26:29], v[142:145], v[228:231], v[26:29]
	v_mfma_f32_16x16x32_bf16 v[26:29], v[154:157], v[232:235], v[26:29]
	v_mfma_f32_16x16x32_bf16 v[18:21], v[184:187], v[228:231], v[18:21]
	v_mfma_f32_16x16x32_bf16 v[18:21], v[188:191], v[232:235], v[18:21]
	v_mfma_f32_16x16x32_bf16 v[22:25], v[170:173], v[228:231], v[22:25]
	v_mfma_f32_16x16x32_bf16 v[22:25], v[180:183], v[232:235], v[22:25]
	v_mfma_f32_16x16x32_bf16 v[6:9], v[170:173], v[236:239], v[6:9]
	v_mfma_f32_16x16x32_bf16 v[6:9], v[180:183], v[240:243], v[6:9]
	v_mfma_f32_16x16x32_bf16 v[2:5], v[184:187], v[236:239], v[2:5]
	v_mfma_f32_16x16x32_bf16 v[2:5], v[188:191], v[240:243], v[2:5]
	v_mfma_f32_16x16x32_bf16 v[10:13], v[142:145], v[236:239], v[10:13]
	v_mfma_f32_16x16x32_bf16 v[10:13], v[154:157], v[240:243], v[10:13]
	v_mfma_f32_16x16x32_bf16 v[14:17], v[134:137], v[236:239], v[14:17]
	v_mfma_f32_16x16x32_bf16 v[14:17], v[138:141], v[240:243], v[14:17]
	s_barrier
	s_setprio 0
	s_add_i32 s22, s22, 2
	s_addk_i32 s13, 0x100
	s_addk_i32 s21, 0x100
	s_cmp_gt_u32 s22, 29
	s_cbranch_scc0 .LBB0_905
	s_and_b64 vcc, exec, s[64:65]
	s_cbranch_vccz .LBB0_908
	s_barrier

.LBB0_1192:
	s_lshl_b32 s12, s70, 22
	s_and_b64 s[8:9], s[26:27], exec
	s_cselect_b32 s8, s12, s30
	s_lshl_b32 s22, s71, 22
	s_and_b64 s[66:67], s[26:27], exec
	s_cselect_b32 s9, s22, s31
	s_add_i32 s30, s30, 0x200080
	s_addk_i32 s31, 0x100
	s_mov_b32 s72, -2
	v_add_u32_e32 v141, 0x10000, v139
	ds_read_b128 v[142:145], v141
	ds_read_b128 v[154:157], v141 offset:1024
	ds_read_b128 v[170:173], v141 offset:2048
	ds_read_b128 v[174:177], v141 offset:3072
	v_add_u32_e32 v141, 0x14000, v139
	ds_read_b128 v[178:181], v141
	ds_read_b128 v[182:185], v141 offset:1024
	ds_read_b128 v[186:189], v141 offset:2048
	ds_read_b128 v[190:193], v141 offset:3072
	s_add_i32 s52, s30, 0xffe00080
	s_cmpk_eq_i32 s72, 0x7c
	s_cselect_b32 s52, s8, s52
	s_cselect_b32 s82, s9, s31
	s_or_b32 s73, s52, 0x80
	s_mov_b32 m0, s69
	ds_read_b128 v[194:197], v140
	ds_read_b128 v[198:201], v140 offset:1024
	ds_read_b128 v[202:205], v140 offset:2048
	ds_read_b128 v[228:231], v140 offset:3072
	ds_read_b128 v[232:235], v140 offset:4096
	ds_read_b128 v[236:239], v140 offset:5120
	ds_read_b128 v[240:243], v140 offset:6144
	ds_read_b128 v[244:247], v140 offset:7168
	buffer_load_dwordx4 v131, s[60:63], s30 offen lds
	s_mov_b32 m0, s46
	s_nop 0
	buffer_load_dwordx4 v135, s[60:63], s30 offen lds
	s_waitcnt vmcnt(8)
	s_waitcnt lgkmcnt(0)
	s_setprio 1
	s_barrier
	v_mfma_f32_16x16x32_bf16 v[126:129], v[142:145], v[194:197], 0
	v_mfma_f32_16x16x32_bf16 v[126:129], v[154:157], v[198:201], v[126:129]
	v_mfma_f32_16x16x32_bf16 v[122:125], v[170:173], v[194:197], 0
	v_mfma_f32_16x16x32_bf16 v[122:125], v[174:177], v[198:201], v[122:125]
	v_mfma_f32_16x16x32_bf16 v[58:61], v[186:189], v[194:197], 0
	v_mfma_f32_16x16x32_bf16 v[58:61], v[190:193], v[198:201], v[58:61]
	v_mfma_f32_16x16x32_bf16 v[62:65], v[178:181], v[194:197], 0
	v_mfma_f32_16x16x32_bf16 v[62:65], v[182:185], v[198:201], v[62:65]
	v_mfma_f32_16x16x32_bf16 v[54:57], v[178:181], v[202:205], 0
	v_mfma_f32_16x16x32_bf16 v[54:57], v[182:185], v[228:231], v[54:57]
	v_mfma_f32_16x16x32_bf16 v[50:53], v[186:189], v[202:205], 0
	v_mfma_f32_16x16x32_bf16 v[50:53], v[190:193], v[228:231], v[50:53]
	v_mfma_f32_16x16x32_bf16 v[114:117], v[170:173], v[202:205], 0
	v_mfma_f32_16x16x32_bf16 v[114:117], v[174:177], v[228:231], v[114:117]
	v_mfma_f32_16x16x32_bf16 v[118:121], v[142:145], v[202:205], 0
	v_mfma_f32_16x16x32_bf16 v[118:121], v[154:157], v[228:231], v[118:121]
	v_mfma_f32_16x16x32_bf16 v[110:113], v[142:145], v[232:235], 0
	v_mfma_f32_16x16x32_bf16 v[110:113], v[154:157], v[236:239], v[110:113]
	v_mfma_f32_16x16x32_bf16 v[106:109], v[170:173], v[232:235], 0
	v_mfma_f32_16x16x32_bf16 v[106:109], v[174:177], v[236:239], v[106:109]
	v_mfma_f32_16x16x32_bf16 v[42:45], v[186:189], v[232:235], 0
	v_mfma_f32_16x16x32_bf16 v[42:45], v[190:193], v[236:239], v[42:45]
	v_mfma_f32_16x16x32_bf16 v[46:49], v[178:181], v[232:235], 0
	v_mfma_f32_16x16x32_bf16 v[46:49], v[182:185], v[236:239], v[46:49]
	v_mfma_f32_16x16x32_bf16 v[38:41], v[178:181], v[240:243], 0
	v_mfma_f32_16x16x32_bf16 v[38:41], v[182:185], v[244:247], v[38:41]
	v_mfma_f32_16x16x32_bf16 v[34:37], v[186:189], v[240:243], 0
	v_mfma_f32_16x16x32_bf16 v[34:37], v[190:193], v[244:247], v[34:37]
	v_mfma_f32_16x16x32_bf16 v[98:101], v[170:173], v[240:243], 0
	v_mfma_f32_16x16x32_bf16 v[98:101], v[174:177], v[244:247], v[98:101]
	v_mfma_f32_16x16x32_bf16 v[102:105], v[142:145], v[240:243], 0
	v_mfma_f32_16x16x32_bf16 v[102:105], v[154:157], v[244:247], v[102:105]
	s_barrier
	s_setprio 0
	s_mov_b32 m0, s15
	s_mov_b32 s66, s62
	s_mov_b32 s67, s63
	ds_read_b128 v[194:197], v140 offset:16384
	ds_read_b128 v[198:201], v140 offset:17408
	ds_read_b128 v[202:205], v140 offset:18432
	ds_read_b128 v[228:231], v140 offset:19456
	ds_read_b128 v[232:235], v140 offset:20480
	ds_read_b128 v[236:239], v140 offset:21504
	ds_read_b128 v[240:243], v140 offset:22528
	ds_read_b128 v[244:247], v140 offset:23552
	buffer_load_dwordx4 v134, s[64:67], s82 offen lds
	s_mov_b32 m0, s16
	s_add_i32 s53, s82, 0x200000
	buffer_load_dwordx4 v136, s[64:67], s82 offen lds
	s_mov_b32 m0, s21
	s_nop 0
	buffer_load_dwordx4 v134, s[64:67], s53 offen lds
	s_mov_b32 m0, s23
	s_nop 0
	buffer_load_dwordx4 v136, s[64:67], s53 offen lds
	s_mov_b32 m0, s2
	s_nop 0
	buffer_load_dwordx4 v131, s[60:63], s52 offen lds
	s_mov_b32 m0, s24
	s_nop 0
	buffer_load_dwordx4 v135, s[60:63], s52 offen lds
	s_waitcnt vmcnt(8)
	s_waitcnt lgkmcnt(0)
	s_setprio 1
	s_barrier
	v_mfma_f32_16x16x32_bf16 v[94:97], v[142:145], v[194:197], 0
	v_mfma_f32_16x16x32_bf16 v[94:97], v[154:157], v[198:201], v[94:97]
	v_mfma_f32_16x16x32_bf16 v[90:93], v[170:173], v[194:197], 0
	v_mfma_f32_16x16x32_bf16 v[90:93], v[174:177], v[198:201], v[90:93]
	v_mfma_f32_16x16x32_bf16 v[26:29], v[186:189], v[194:197], 0
	v_mfma_f32_16x16x32_bf16 v[26:29], v[190:193], v[198:201], v[26:29]
	v_mfma_f32_16x16x32_bf16 v[30:33], v[178:181], v[194:197], 0
	v_mfma_f32_16x16x32_bf16 v[30:33], v[182:185], v[198:201], v[30:33]
	v_mfma_f32_16x16x32_bf16 v[22:25], v[178:181], v[202:205], 0
	v_mfma_f32_16x16x32_bf16 v[22:25], v[182:185], v[228:231], v[22:25]
	v_mfma_f32_16x16x32_bf16 v[18:21], v[186:189], v[202:205], 0
	v_mfma_f32_16x16x32_bf16 v[18:21], v[190:193], v[228:231], v[18:21]
	v_mfma_f32_16x16x32_bf16 v[82:85], v[170:173], v[202:205], 0
	v_mfma_f32_16x16x32_bf16 v[82:85], v[174:177], v[228:231], v[82:85]
	v_mfma_f32_16x16x32_bf16 v[86:89], v[142:145], v[202:205], 0
	v_mfma_f32_16x16x32_bf16 v[86:89], v[154:157], v[228:231], v[86:89]
	v_mfma_f32_16x16x32_bf16 v[78:81], v[142:145], v[232:235], 0
	v_mfma_f32_16x16x32_bf16 v[78:81], v[154:157], v[236:239], v[78:81]
	v_mfma_f32_16x16x32_bf16 v[74:77], v[170:173], v[232:235], 0
	v_mfma_f32_16x16x32_bf16 v[74:77], v[174:177], v[236:239], v[74:77]
	v_mfma_f32_16x16x32_bf16 v[10:13], v[186:189], v[232:235], 0
	v_mfma_f32_16x16x32_bf16 v[10:13], v[190:193], v[236:239], v[10:13]
	v_mfma_f32_16x16x32_bf16 v[14:17], v[178:181], v[232:235], 0
	v_mfma_f32_16x16x32_bf16 v[14:17], v[182:185], v[236:239], v[14:17]
	v_mfma_f32_16x16x32_bf16 v[6:9], v[178:181], v[240:243], 0
	v_mfma_f32_16x16x32_bf16 v[6:9], v[182:185], v[244:247], v[6:9]
	v_mfma_f32_16x16x32_bf16 v[2:5], v[186:189], v[240:243], 0
	v_mfma_f32_16x16x32_bf16 v[2:5], v[190:193], v[244:247], v[2:5]
	v_mfma_f32_16x16x32_bf16 v[66:69], v[170:173], v[240:243], 0
	v_mfma_f32_16x16x32_bf16 v[66:69], v[174:177], v[244:247], v[66:69]
	v_mfma_f32_16x16x32_bf16 v[70:73], v[142:145], v[240:243], 0
	v_mfma_f32_16x16x32_bf16 v[70:73], v[154:157], v[244:247], v[70:73]
	s_barrier
	s_setprio 0
	v_add_u32_e32 v141, 0x18000, v139
	ds_read_b128 v[142:145], v141
	ds_read_b128 v[154:157], v141 offset:1024
	ds_read_b128 v[170:173], v141 offset:2048
	ds_read_b128 v[174:177], v141 offset:3072
	v_add_u32_e32 v141, 0x1c000, v139
	ds_read_b128 v[178:181], v141
	ds_read_b128 v[182:185], v141 offset:1024
	ds_read_b128 v[186:189], v141 offset:2048
	ds_read_b128 v[190:193], v141 offset:3072
	s_add_i32 s52, s52, 0x200000
	s_mov_b32 m0, s25
	ds_read_b128 v[194:197], v140 offset:32768
	ds_read_b128 v[198:201], v140 offset:33792
	ds_read_b128 v[202:205], v140 offset:34816
	ds_read_b128 v[228:231], v140 offset:35840
	ds_read_b128 v[232:235], v140 offset:36864
	ds_read_b128 v[236:239], v140 offset:37888
	ds_read_b128 v[240:243], v140 offset:38912
	ds_read_b128 v[244:247], v140 offset:39936
	buffer_load_dwordx4 v131, s[60:63], s52 offen lds
	s_mov_b32 m0, s33
	s_nop 0
	buffer_load_dwordx4 v135, s[60:63], s52 offen lds
	s_waitcnt vmcnt(8)
	s_waitcnt lgkmcnt(0)
	s_setprio 1
	s_barrier
	v_mfma_f32_16x16x32_bf16 v[126:129], v[142:145], v[194:197], v[126:129]
	v_mfma_f32_16x16x32_bf16 v[126:129], v[154:157], v[198:201], v[126:129]
	v_mfma_f32_16x16x32_bf16 v[122:125], v[170:173], v[194:197], v[122:125]
	v_mfma_f32_16x16x32_bf16 v[122:125], v[174:177], v[198:201], v[122:125]
	v_mfma_f32_16x16x32_bf16 v[58:61], v[186:189], v[194:197], v[58:61]
	v_mfma_f32_16x16x32_bf16 v[58:61], v[190:193], v[198:201], v[58:61]
	v_mfma_f32_16x16x32_bf16 v[62:65], v[178:181], v[194:197], v[62:65]
	v_mfma_f32_16x16x32_bf16 v[62:65], v[182:185], v[198:201], v[62:65]
	v_mfma_f32_16x16x32_bf16 v[54:57], v[178:181], v[202:205], v[54:57]
	v_mfma_f32_16x16x32_bf16 v[54:57], v[182:185], v[228:231], v[54:57]
	v_mfma_f32_16x16x32_bf16 v[50:53], v[186:189], v[202:205], v[50:53]
	v_mfma_f32_16x16x32_bf16 v[50:53], v[190:193], v[228:231], v[50:53]
	v_mfma_f32_16x16x32_bf16 v[114:117], v[170:173], v[202:205], v[114:117]
	v_mfma_f32_16x16x32_bf16 v[114:117], v[174:177], v[228:231], v[114:117]
	v_mfma_f32_16x16x32_bf16 v[118:121], v[142:145], v[202:205], v[118:121]
	v_mfma_f32_16x16x32_bf16 v[118:121], v[154:157], v[228:231], v[118:121]
	v_mfma_f32_16x16x32_bf16 v[110:113], v[142:145], v[232:235], v[110:113]
	v_mfma_f32_16x16x32_bf16 v[110:113], v[154:157], v[236:239], v[110:113]
	v_mfma_f32_16x16x32_bf16 v[106:109], v[170:173], v[232:235], v[106:109]
	v_mfma_f32_16x16x32_bf16 v[106:109], v[174:177], v[236:239], v[106:109]
	v_mfma_f32_16x16x32_bf16 v[42:45], v[186:189], v[232:235], v[42:45]
	v_mfma_f32_16x16x32_bf16 v[42:45], v[190:193], v[236:239], v[42:45]
	v_mfma_f32_16x16x32_bf16 v[46:49], v[178:181], v[232:235], v[46:49]
	v_mfma_f32_16x16x32_bf16 v[46:49], v[182:185], v[236:239], v[46:49]
	v_mfma_f32_16x16x32_bf16 v[38:41], v[178:181], v[240:243], v[38:41]
	v_mfma_f32_16x16x32_bf16 v[38:41], v[182:185], v[244:247], v[38:41]
	v_mfma_f32_16x16x32_bf16 v[34:37], v[186:189], v[240:243], v[34:37]
	v_mfma_f32_16x16x32_bf16 v[34:37], v[190:193], v[244:247], v[34:37]
	v_mfma_f32_16x16x32_bf16 v[98:101], v[170:173], v[240:243], v[98:101]
	v_mfma_f32_16x16x32_bf16 v[98:101], v[174:177], v[244:247], v[98:101]
	v_mfma_f32_16x16x32_bf16 v[102:105], v[142:145], v[240:243], v[102:105]
	v_mfma_f32_16x16x32_bf16 v[102:105], v[154:157], v[244:247], v[102:105]
	s_barrier
	s_setprio 0
	s_mov_b32 m0, s34
	s_or_b32 s52, s82, 0x80
	ds_read_b128 v[194:197], v140 offset:49152
	ds_read_b128 v[198:201], v140 offset:50176
	ds_read_b128 v[202:205], v140 offset:51200
	ds_read_b128 v[228:231], v140 offset:52224
	ds_read_b128 v[232:235], v140 offset:53248
	ds_read_b128 v[236:239], v140 offset:54272
	ds_read_b128 v[240:243], v140 offset:55296
	ds_read_b128 v[244:247], v140 offset:56320
	buffer_load_dwordx4 v134, s[64:67], s52 offen lds
	s_mov_b32 m0, s35
	s_add_i32 s82, s82, 0x200080
	buffer_load_dwordx4 v136, s[64:67], s52 offen lds
	s_mov_b32 m0, s37
	s_nop 0
	buffer_load_dwordx4 v134, s[64:67], s82 offen lds
	s_mov_b32 m0, s44
	s_nop 0
	buffer_load_dwordx4 v136, s[64:67], s82 offen lds
	s_mov_b32 m0, s14
	s_nop 0
	buffer_load_dwordx4 v131, s[60:63], s73 offen lds
	s_mov_b32 m0, s36
	s_nop 0
	buffer_load_dwordx4 v135, s[60:63], s73 offen lds
	s_waitcnt vmcnt(8)
	s_waitcnt lgkmcnt(0)
	s_setprio 1
	s_barrier
	v_mfma_f32_16x16x32_bf16 v[94:97], v[142:145], v[194:197], v[94:97]
	v_mfma_f32_16x16x32_bf16 v[94:97], v[154:157], v[198:201], v[94:97]
	v_mfma_f32_16x16x32_bf16 v[90:93], v[170:173], v[194:197], v[90:93]
	v_mfma_f32_16x16x32_bf16 v[90:93], v[174:177], v[198:201], v[90:93]
	v_mfma_f32_16x16x32_bf16 v[26:29], v[186:189], v[194:197], v[26:29]
	v_mfma_f32_16x16x32_bf16 v[26:29], v[190:193], v[198:201], v[26:29]
	v_mfma_f32_16x16x32_bf16 v[30:33], v[178:181], v[194:197], v[30:33]
	v_mfma_f32_16x16x32_bf16 v[30:33], v[182:185], v[198:201], v[30:33]
	v_mfma_f32_16x16x32_bf16 v[22:25], v[178:181], v[202:205], v[22:25]
	v_mfma_f32_16x16x32_bf16 v[22:25], v[182:185], v[228:231], v[22:25]
	v_mfma_f32_16x16x32_bf16 v[18:21], v[186:189], v[202:205], v[18:21]
	v_mfma_f32_16x16x32_bf16 v[18:21], v[190:193], v[228:231], v[18:21]
	v_mfma_f32_16x16x32_bf16 v[82:85], v[170:173], v[202:205], v[82:85]
	v_mfma_f32_16x16x32_bf16 v[82:85], v[174:177], v[228:231], v[82:85]
	v_mfma_f32_16x16x32_bf16 v[86:89], v[142:145], v[202:205], v[86:89]
	v_mfma_f32_16x16x32_bf16 v[86:89], v[154:157], v[228:231], v[86:89]
	v_mfma_f32_16x16x32_bf16 v[78:81], v[142:145], v[232:235], v[78:81]
	v_mfma_f32_16x16x32_bf16 v[78:81], v[154:157], v[236:239], v[78:81]
	v_mfma_f32_16x16x32_bf16 v[74:77], v[170:173], v[232:235], v[74:77]
	v_mfma_f32_16x16x32_bf16 v[74:77], v[174:177], v[236:239], v[74:77]
	v_mfma_f32_16x16x32_bf16 v[10:13], v[186:189], v[232:235], v[10:13]
	v_mfma_f32_16x16x32_bf16 v[10:13], v[190:193], v[236:239], v[10:13]
	v_mfma_f32_16x16x32_bf16 v[14:17], v[178:181], v[232:235], v[14:17]
	v_mfma_f32_16x16x32_bf16 v[14:17], v[182:185], v[236:239], v[14:17]
	v_mfma_f32_16x16x32_bf16 v[6:9], v[178:181], v[240:243], v[6:9]
	v_mfma_f32_16x16x32_bf16 v[6:9], v[182:185], v[244:247], v[6:9]
	v_mfma_f32_16x16x32_bf16 v[2:5], v[186:189], v[240:243], v[2:5]
	v_mfma_f32_16x16x32_bf16 v[2:5], v[190:193], v[244:247], v[2:5]
	v_mfma_f32_16x16x32_bf16 v[66:69], v[170:173], v[240:243], v[66:69]
	v_mfma_f32_16x16x32_bf16 v[66:69], v[174:177], v[244:247], v[66:69]
	v_mfma_f32_16x16x32_bf16 v[70:73], v[142:145], v[240:243], v[70:73]
	v_mfma_f32_16x16x32_bf16 v[70:73], v[154:157], v[244:247], v[70:73]
	s_barrier
	s_setprio 0
	s_add_i32 s72, s72, 2
	s_addk_i32 s30, 0x100
	s_addk_i32 s31, 0x100
	s_cmpk_gt_u32 s72, 0x7d
.LBB0_1193:
	v_add_u32_e32 v141, 0x10000, v139
	ds_read_b128 v[142:145], v141
	ds_read_b128 v[154:157], v141 offset:1024
	ds_read_b128 v[170:173], v141 offset:2048
	ds_read_b128 v[174:177], v141 offset:3072
	v_add_u32_e32 v141, 0x14000, v139
	ds_read_b128 v[178:181], v141
	ds_read_b128 v[182:185], v141 offset:1024
	ds_read_b128 v[186:189], v141 offset:2048
	ds_read_b128 v[190:193], v141 offset:3072
	s_add_i32 s52, s30, 0xffe00080
	s_cmpk_eq_i32 s72, 0x7c
	s_cselect_b32 s52, s8, s52
	s_cselect_b32 s82, s9, s31
	s_or_b32 s73, s52, 0x80
	s_mov_b32 m0, s69
	ds_read_b128 v[194:197], v140
	ds_read_b128 v[198:201], v140 offset:1024
	ds_read_b128 v[202:205], v140 offset:2048
	ds_read_b128 v[228:231], v140 offset:3072
	ds_read_b128 v[232:235], v140 offset:4096
	ds_read_b128 v[236:239], v140 offset:5120
	ds_read_b128 v[240:243], v140 offset:6144
	ds_read_b128 v[244:247], v140 offset:7168
	buffer_load_dwordx4 v131, s[60:63], s30 offen lds
	s_mov_b32 m0, s46
	s_nop 0
	buffer_load_dwordx4 v135, s[60:63], s30 offen lds
	s_waitcnt vmcnt(8)
	s_waitcnt lgkmcnt(0)
	s_setprio 1
	s_barrier
	v_mfma_f32_16x16x32_bf16 v[126:129], v[142:145], v[194:197], v[126:129]
	v_mfma_f32_16x16x32_bf16 v[126:129], v[154:157], v[198:201], v[126:129]
	v_mfma_f32_16x16x32_bf16 v[122:125], v[170:173], v[194:197], v[122:125]
	v_mfma_f32_16x16x32_bf16 v[122:125], v[174:177], v[198:201], v[122:125]
	v_mfma_f32_16x16x32_bf16 v[58:61], v[186:189], v[194:197], v[58:61]
	v_mfma_f32_16x16x32_bf16 v[58:61], v[190:193], v[198:201], v[58:61]
	v_mfma_f32_16x16x32_bf16 v[62:65], v[178:181], v[194:197], v[62:65]
	v_mfma_f32_16x16x32_bf16 v[62:65], v[182:185], v[198:201], v[62:65]
	v_mfma_f32_16x16x32_bf16 v[54:57], v[178:181], v[202:205], v[54:57]
	v_mfma_f32_16x16x32_bf16 v[54:57], v[182:185], v[228:231], v[54:57]
	v_mfma_f32_16x16x32_bf16 v[50:53], v[186:189], v[202:205], v[50:53]
	v_mfma_f32_16x16x32_bf16 v[50:53], v[190:193], v[228:231], v[50:53]
	v_mfma_f32_16x16x32_bf16 v[114:117], v[170:173], v[202:205], v[114:117]
	v_mfma_f32_16x16x32_bf16 v[114:117], v[174:177], v[228:231], v[114:117]
	v_mfma_f32_16x16x32_bf16 v[118:121], v[142:145], v[202:205], v[118:121]
	v_mfma_f32_16x16x32_bf16 v[118:121], v[154:157], v[228:231], v[118:121]
	v_mfma_f32_16x16x32_bf16 v[110:113], v[142:145], v[232:235], v[110:113]
	v_mfma_f32_16x16x32_bf16 v[110:113], v[154:157], v[236:239], v[110:113]
	v_mfma_f32_16x16x32_bf16 v[106:109], v[170:173], v[232:235], v[106:109]
	v_mfma_f32_16x16x32_bf16 v[106:109], v[174:177], v[236:239], v[106:109]
	v_mfma_f32_16x16x32_bf16 v[42:45], v[186:189], v[232:235], v[42:45]
	v_mfma_f32_16x16x32_bf16 v[42:45], v[190:193], v[236:239], v[42:45]
	v_mfma_f32_16x16x32_bf16 v[46:49], v[178:181], v[232:235], v[46:49]
	v_mfma_f32_16x16x32_bf16 v[46:49], v[182:185], v[236:239], v[46:49]
	v_mfma_f32_16x16x32_bf16 v[38:41], v[178:181], v[240:243], v[38:41]
	v_mfma_f32_16x16x32_bf16 v[38:41], v[182:185], v[244:247], v[38:41]
	v_mfma_f32_16x16x32_bf16 v[34:37], v[186:189], v[240:243], v[34:37]
	v_mfma_f32_16x16x32_bf16 v[34:37], v[190:193], v[244:247], v[34:37]
	v_mfma_f32_16x16x32_bf16 v[98:101], v[170:173], v[240:243], v[98:101]
	v_mfma_f32_16x16x32_bf16 v[98:101], v[174:177], v[244:247], v[98:101]
	v_mfma_f32_16x16x32_bf16 v[102:105], v[142:145], v[240:243], v[102:105]
	v_mfma_f32_16x16x32_bf16 v[102:105], v[154:157], v[244:247], v[102:105]
	s_barrier
	s_setprio 0
	s_mov_b32 m0, s15
	s_mov_b32 s66, s62
	s_mov_b32 s67, s63
	ds_read_b128 v[194:197], v140 offset:16384
	ds_read_b128 v[198:201], v140 offset:17408
	ds_read_b128 v[202:205], v140 offset:18432
	ds_read_b128 v[228:231], v140 offset:19456
	ds_read_b128 v[232:235], v140 offset:20480
	ds_read_b128 v[236:239], v140 offset:21504
	ds_read_b128 v[240:243], v140 offset:22528
	ds_read_b128 v[244:247], v140 offset:23552
	buffer_load_dwordx4 v134, s[64:67], s82 offen lds
	s_mov_b32 m0, s16
	s_add_i32 s53, s82, 0x200000
	buffer_load_dwordx4 v136, s[64:67], s82 offen lds
	s_mov_b32 m0, s21
	s_nop 0
	buffer_load_dwordx4 v134, s[64:67], s53 offen lds
	s_mov_b32 m0, s23
	s_nop 0
	buffer_load_dwordx4 v136, s[64:67], s53 offen lds
	s_mov_b32 m0, s2
	s_nop 0
	buffer_load_dwordx4 v131, s[60:63], s52 offen lds
	s_mov_b32 m0, s24
	s_nop 0
	buffer_load_dwordx4 v135, s[60:63], s52 offen lds
	s_waitcnt vmcnt(8)
	s_waitcnt lgkmcnt(0)
	s_setprio 1
	s_barrier
	v_mfma_f32_16x16x32_bf16 v[94:97], v[142:145], v[194:197], v[94:97]
	v_mfma_f32_16x16x32_bf16 v[94:97], v[154:157], v[198:201], v[94:97]
	v_mfma_f32_16x16x32_bf16 v[90:93], v[170:173], v[194:197], v[90:93]
	v_mfma_f32_16x16x32_bf16 v[90:93], v[174:177], v[198:201], v[90:93]
	v_mfma_f32_16x16x32_bf16 v[26:29], v[186:189], v[194:197], v[26:29]
	v_mfma_f32_16x16x32_bf16 v[26:29], v[190:193], v[198:201], v[26:29]
	v_mfma_f32_16x16x32_bf16 v[30:33], v[178:181], v[194:197], v[30:33]
	v_mfma_f32_16x16x32_bf16 v[30:33], v[182:185], v[198:201], v[30:33]
	v_mfma_f32_16x16x32_bf16 v[22:25], v[178:181], v[202:205], v[22:25]
	v_mfma_f32_16x16x32_bf16 v[22:25], v[182:185], v[228:231], v[22:25]
	v_mfma_f32_16x16x32_bf16 v[18:21], v[186:189], v[202:205], v[18:21]
	v_mfma_f32_16x16x32_bf16 v[18:21], v[190:193], v[228:231], v[18:21]
	v_mfma_f32_16x16x32_bf16 v[82:85], v[170:173], v[202:205], v[82:85]
	v_mfma_f32_16x16x32_bf16 v[82:85], v[174:177], v[228:231], v[82:85]
	v_mfma_f32_16x16x32_bf16 v[86:89], v[142:145], v[202:205], v[86:89]
	v_mfma_f32_16x16x32_bf16 v[86:89], v[154:157], v[228:231], v[86:89]
	v_mfma_f32_16x16x32_bf16 v[78:81], v[142:145], v[232:235], v[78:81]
	v_mfma_f32_16x16x32_bf16 v[78:81], v[154:157], v[236:239], v[78:81]
	v_mfma_f32_16x16x32_bf16 v[74:77], v[170:173], v[232:235], v[74:77]
	v_mfma_f32_16x16x32_bf16 v[74:77], v[174:177], v[236:239], v[74:77]
	v_mfma_f32_16x16x32_bf16 v[10:13], v[186:189], v[232:235], v[10:13]
	v_mfma_f32_16x16x32_bf16 v[10:13], v[190:193], v[236:239], v[10:13]
	v_mfma_f32_16x16x32_bf16 v[14:17], v[178:181], v[232:235], v[14:17]
	v_mfma_f32_16x16x32_bf16 v[14:17], v[182:185], v[236:239], v[14:17]
	v_mfma_f32_16x16x32_bf16 v[6:9], v[178:181], v[240:243], v[6:9]
	v_mfma_f32_16x16x32_bf16 v[6:9], v[182:185], v[244:247], v[6:9]
	v_mfma_f32_16x16x32_bf16 v[2:5], v[186:189], v[240:243], v[2:5]
	v_mfma_f32_16x16x32_bf16 v[2:5], v[190:193], v[244:247], v[2:5]
	v_mfma_f32_16x16x32_bf16 v[66:69], v[170:173], v[240:243], v[66:69]
	v_mfma_f32_16x16x32_bf16 v[66:69], v[174:177], v[244:247], v[66:69]
	v_mfma_f32_16x16x32_bf16 v[70:73], v[142:145], v[240:243], v[70:73]
	v_mfma_f32_16x16x32_bf16 v[70:73], v[154:157], v[244:247], v[70:73]
	s_barrier
	s_setprio 0
	v_add_u32_e32 v141, 0x18000, v139
	ds_read_b128 v[142:145], v141
	ds_read_b128 v[154:157], v141 offset:1024
	ds_read_b128 v[170:173], v141 offset:2048
	ds_read_b128 v[174:177], v141 offset:3072
	v_add_u32_e32 v141, 0x1c000, v139
	ds_read_b128 v[178:181], v141
	ds_read_b128 v[182:185], v141 offset:1024
	ds_read_b128 v[186:189], v141 offset:2048
	ds_read_b128 v[190:193], v141 offset:3072
	s_add_i32 s52, s52, 0x200000
	s_mov_b32 m0, s25
	ds_read_b128 v[194:197], v140 offset:32768
	ds_read_b128 v[198:201], v140 offset:33792
	ds_read_b128 v[202:205], v140 offset:34816
	ds_read_b128 v[228:231], v140 offset:35840
	ds_read_b128 v[232:235], v140 offset:36864
	ds_read_b128 v[236:239], v140 offset:37888
	ds_read_b128 v[240:243], v140 offset:38912
	ds_read_b128 v[244:247], v140 offset:39936
	buffer_load_dwordx4 v131, s[60:63], s52 offen lds
	s_mov_b32 m0, s33
	s_nop 0
	buffer_load_dwordx4 v135, s[60:63], s52 offen lds
	s_waitcnt vmcnt(8)
	s_waitcnt lgkmcnt(0)
	s_setprio 1
	s_barrier
	v_mfma_f32_16x16x32_bf16 v[126:129], v[142:145], v[194:197], v[126:129]
	v_mfma_f32_16x16x32_bf16 v[126:129], v[154:157], v[198:201], v[126:129]
	v_mfma_f32_16x16x32_bf16 v[122:125], v[170:173], v[194:197], v[122:125]
	v_mfma_f32_16x16x32_bf16 v[122:125], v[174:177], v[198:201], v[122:125]
	v_mfma_f32_16x16x32_bf16 v[58:61], v[186:189], v[194:197], v[58:61]
	v_mfma_f32_16x16x32_bf16 v[58:61], v[190:193], v[198:201], v[58:61]
	v_mfma_f32_16x16x32_bf16 v[62:65], v[178:181], v[194:197], v[62:65]
	v_mfma_f32_16x16x32_bf16 v[62:65], v[182:185], v[198:201], v[62:65]
	v_mfma_f32_16x16x32_bf16 v[54:57], v[178:181], v[202:205], v[54:57]
	v_mfma_f32_16x16x32_bf16 v[54:57], v[182:185], v[228:231], v[54:57]
	v_mfma_f32_16x16x32_bf16 v[50:53], v[186:189], v[202:205], v[50:53]
	v_mfma_f32_16x16x32_bf16 v[50:53], v[190:193], v[228:231], v[50:53]
	v_mfma_f32_16x16x32_bf16 v[114:117], v[170:173], v[202:205], v[114:117]
	v_mfma_f32_16x16x32_bf16 v[114:117], v[174:177], v[228:231], v[114:117]
	v_mfma_f32_16x16x32_bf16 v[118:121], v[142:145], v[202:205], v[118:121]
	v_mfma_f32_16x16x32_bf16 v[118:121], v[154:157], v[228:231], v[118:121]
	v_mfma_f32_16x16x32_bf16 v[110:113], v[142:145], v[232:235], v[110:113]
	v_mfma_f32_16x16x32_bf16 v[110:113], v[154:157], v[236:239], v[110:113]
	v_mfma_f32_16x16x32_bf16 v[106:109], v[170:173], v[232:235], v[106:109]
	v_mfma_f32_16x16x32_bf16 v[106:109], v[174:177], v[236:239], v[106:109]
	v_mfma_f32_16x16x32_bf16 v[42:45], v[186:189], v[232:235], v[42:45]
	v_mfma_f32_16x16x32_bf16 v[42:45], v[190:193], v[236:239], v[42:45]
	v_mfma_f32_16x16x32_bf16 v[46:49], v[178:181], v[232:235], v[46:49]
	v_mfma_f32_16x16x32_bf16 v[46:49], v[182:185], v[236:239], v[46:49]
	v_mfma_f32_16x16x32_bf16 v[38:41], v[178:181], v[240:243], v[38:41]
	v_mfma_f32_16x16x32_bf16 v[38:41], v[182:185], v[244:247], v[38:41]
	v_mfma_f32_16x16x32_bf16 v[34:37], v[186:189], v[240:243], v[34:37]
	v_mfma_f32_16x16x32_bf16 v[34:37], v[190:193], v[244:247], v[34:37]
	v_mfma_f32_16x16x32_bf16 v[98:101], v[170:173], v[240:243], v[98:101]
	v_mfma_f32_16x16x32_bf16 v[98:101], v[174:177], v[244:247], v[98:101]
	v_mfma_f32_16x16x32_bf16 v[102:105], v[142:145], v[240:243], v[102:105]
	v_mfma_f32_16x16x32_bf16 v[102:105], v[154:157], v[244:247], v[102:105]
	s_barrier
	s_setprio 0
	s_mov_b32 m0, s34
	s_or_b32 s52, s82, 0x80
	ds_read_b128 v[194:197], v140 offset:49152
	ds_read_b128 v[198:201], v140 offset:50176
	ds_read_b128 v[202:205], v140 offset:51200
	ds_read_b128 v[228:231], v140 offset:52224
	ds_read_b128 v[232:235], v140 offset:53248
	ds_read_b128 v[236:239], v140 offset:54272
	ds_read_b128 v[240:243], v140 offset:55296
	ds_read_b128 v[244:247], v140 offset:56320
	buffer_load_dwordx4 v134, s[64:67], s52 offen lds
	s_mov_b32 m0, s35
	s_add_i32 s82, s82, 0x200080
	buffer_load_dwordx4 v136, s[64:67], s52 offen lds
	s_mov_b32 m0, s37
	s_nop 0
	buffer_load_dwordx4 v134, s[64:67], s82 offen lds
	s_mov_b32 m0, s44
	s_nop 0
	buffer_load_dwordx4 v136, s[64:67], s82 offen lds
	s_mov_b32 m0, s14
	s_nop 0
	buffer_load_dwordx4 v131, s[60:63], s73 offen lds
	s_mov_b32 m0, s36
	s_nop 0
	buffer_load_dwordx4 v135, s[60:63], s73 offen lds
	s_waitcnt vmcnt(8)
	s_waitcnt lgkmcnt(0)
	s_setprio 1
	s_barrier
	v_mfma_f32_16x16x32_bf16 v[94:97], v[142:145], v[194:197], v[94:97]
	v_mfma_f32_16x16x32_bf16 v[94:97], v[154:157], v[198:201], v[94:97]
	v_mfma_f32_16x16x32_bf16 v[90:93], v[170:173], v[194:197], v[90:93]
	v_mfma_f32_16x16x32_bf16 v[90:93], v[174:177], v[198:201], v[90:93]
	v_mfma_f32_16x16x32_bf16 v[26:29], v[186:189], v[194:197], v[26:29]
	v_mfma_f32_16x16x32_bf16 v[26:29], v[190:193], v[198:201], v[26:29]
	v_mfma_f32_16x16x32_bf16 v[30:33], v[178:181], v[194:197], v[30:33]
	v_mfma_f32_16x16x32_bf16 v[30:33], v[182:185], v[198:201], v[30:33]
	v_mfma_f32_16x16x32_bf16 v[22:25], v[178:181], v[202:205], v[22:25]
	v_mfma_f32_16x16x32_bf16 v[22:25], v[182:185], v[228:231], v[22:25]
	v_mfma_f32_16x16x32_bf16 v[18:21], v[186:189], v[202:205], v[18:21]
	v_mfma_f32_16x16x32_bf16 v[18:21], v[190:193], v[228:231], v[18:21]
	v_mfma_f32_16x16x32_bf16 v[82:85], v[170:173], v[202:205], v[82:85]
	v_mfma_f32_16x16x32_bf16 v[82:85], v[174:177], v[228:231], v[82:85]
	v_mfma_f32_16x16x32_bf16 v[86:89], v[142:145], v[202:205], v[86:89]
	v_mfma_f32_16x16x32_bf16 v[86:89], v[154:157], v[228:231], v[86:89]
	v_mfma_f32_16x16x32_bf16 v[78:81], v[142:145], v[232:235], v[78:81]
	v_mfma_f32_16x16x32_bf16 v[78:81], v[154:157], v[236:239], v[78:81]
	v_mfma_f32_16x16x32_bf16 v[74:77], v[170:173], v[232:235], v[74:77]
	v_mfma_f32_16x16x32_bf16 v[74:77], v[174:177], v[236:239], v[74:77]
	v_mfma_f32_16x16x32_bf16 v[10:13], v[186:189], v[232:235], v[10:13]
	v_mfma_f32_16x16x32_bf16 v[10:13], v[190:193], v[236:239], v[10:13]
	v_mfma_f32_16x16x32_bf16 v[14:17], v[178:181], v[232:235], v[14:17]
	v_mfma_f32_16x16x32_bf16 v[14:17], v[182:185], v[236:239], v[14:17]
	v_mfma_f32_16x16x32_bf16 v[6:9], v[178:181], v[240:243], v[6:9]
	v_mfma_f32_16x16x32_bf16 v[6:9], v[182:185], v[244:247], v[6:9]
	v_mfma_f32_16x16x32_bf16 v[2:5], v[186:189], v[240:243], v[2:5]
	v_mfma_f32_16x16x32_bf16 v[2:5], v[190:193], v[244:247], v[2:5]
	v_mfma_f32_16x16x32_bf16 v[66:69], v[170:173], v[240:243], v[66:69]
	v_mfma_f32_16x16x32_bf16 v[66:69], v[174:177], v[244:247], v[66:69]
	v_mfma_f32_16x16x32_bf16 v[70:73], v[142:145], v[240:243], v[70:73]
	v_mfma_f32_16x16x32_bf16 v[70:73], v[154:157], v[244:247], v[70:73]
	s_barrier
	s_setprio 0
	s_add_i32 s72, s72, 2
	s_addk_i32 s30, 0x100
	s_addk_i32 s31, 0x100
	s_cmpk_gt_u32 s72, 0x7d
	s_cbranch_scc0 .LBB0_1193
	s_and_b64 vcc, exec, s[42:43]
	s_cbranch_vccz .LBB0_1196
	s_barrier

.LBB0_1222:
	s_lshl_b32 s14, s82, 22
	s_and_b64 s[8:9], s[44:45], exec
	s_cselect_b32 s8, s14, s19
	s_lshl_b32 s46, s84, 22
	s_and_b64 s[26:27], s[44:45], exec
	s_cselect_b32 s9, s46, s22
	s_add_i32 s19, s19, 0x200080
	s_addk_i32 s22, 0x100
	s_mov_b32 s26, -2
	v_add_u32_e32 v141, 0x10000, v139
	ds_read_b128 v[142:145], v141
	ds_read_b128 v[154:157], v141 offset:1024
	ds_read_b128 v[170:173], v141 offset:2048
	ds_read_b128 v[174:177], v141 offset:3072
	v_add_u32_e32 v141, 0x14000, v139
	ds_read_b128 v[178:181], v141
	ds_read_b128 v[182:185], v141 offset:1024
	ds_read_b128 v[186:189], v141 offset:2048
	ds_read_b128 v[190:193], v141 offset:3072
	s_add_i32 s27, s19, 0xffe00080
	s_cmpk_eq_i32 s26, 0x7c
	s_cselect_b32 s52, s8, s27
	s_cselect_b32 s47, s9, s22
	s_or_b32 s27, s52, 0x80
	s_mov_b32 m0, s71
	ds_read_b128 v[194:197], v140
	ds_read_b128 v[198:201], v140 offset:1024
	ds_read_b128 v[202:205], v140 offset:2048
	ds_read_b128 v[228:231], v140 offset:3072
	ds_read_b128 v[232:235], v140 offset:4096
	ds_read_b128 v[236:239], v140 offset:5120
	ds_read_b128 v[240:243], v140 offset:6144
	ds_read_b128 v[244:247], v140 offset:7168
	buffer_load_dwordx4 v131, s[60:63], s19 offen lds
	s_mov_b32 m0, s72
	s_nop 0
	buffer_load_dwordx4 v135, s[60:63], s19 offen lds
	s_waitcnt vmcnt(8)
	s_waitcnt lgkmcnt(0)
	s_setprio 1
	s_barrier
	v_mfma_f32_16x16x32_bf16 v[126:129], v[142:145], v[194:197], 0
	v_mfma_f32_16x16x32_bf16 v[126:129], v[154:157], v[198:201], v[126:129]
	v_mfma_f32_16x16x32_bf16 v[122:125], v[170:173], v[194:197], 0
	v_mfma_f32_16x16x32_bf16 v[122:125], v[174:177], v[198:201], v[122:125]
	v_mfma_f32_16x16x32_bf16 v[58:61], v[186:189], v[194:197], 0
	v_mfma_f32_16x16x32_bf16 v[58:61], v[190:193], v[198:201], v[58:61]
	v_mfma_f32_16x16x32_bf16 v[62:65], v[178:181], v[194:197], 0
	v_mfma_f32_16x16x32_bf16 v[62:65], v[182:185], v[198:201], v[62:65]
	v_mfma_f32_16x16x32_bf16 v[54:57], v[178:181], v[202:205], 0
	v_mfma_f32_16x16x32_bf16 v[54:57], v[182:185], v[228:231], v[54:57]
	v_mfma_f32_16x16x32_bf16 v[50:53], v[186:189], v[202:205], 0
	v_mfma_f32_16x16x32_bf16 v[50:53], v[190:193], v[228:231], v[50:53]
	v_mfma_f32_16x16x32_bf16 v[114:117], v[170:173], v[202:205], 0
	v_mfma_f32_16x16x32_bf16 v[114:117], v[174:177], v[228:231], v[114:117]
	v_mfma_f32_16x16x32_bf16 v[118:121], v[142:145], v[202:205], 0
	v_mfma_f32_16x16x32_bf16 v[118:121], v[154:157], v[228:231], v[118:121]
	v_mfma_f32_16x16x32_bf16 v[110:113], v[142:145], v[232:235], 0
	v_mfma_f32_16x16x32_bf16 v[110:113], v[154:157], v[236:239], v[110:113]
	v_mfma_f32_16x16x32_bf16 v[106:109], v[170:173], v[232:235], 0
	v_mfma_f32_16x16x32_bf16 v[106:109], v[174:177], v[236:239], v[106:109]
	v_mfma_f32_16x16x32_bf16 v[42:45], v[186:189], v[232:235], 0
	v_mfma_f32_16x16x32_bf16 v[42:45], v[190:193], v[236:239], v[42:45]
	v_mfma_f32_16x16x32_bf16 v[46:49], v[178:181], v[232:235], 0
	v_mfma_f32_16x16x32_bf16 v[46:49], v[182:185], v[236:239], v[46:49]
	v_mfma_f32_16x16x32_bf16 v[38:41], v[178:181], v[240:243], 0
	v_mfma_f32_16x16x32_bf16 v[38:41], v[182:185], v[244:247], v[38:41]
	v_mfma_f32_16x16x32_bf16 v[34:37], v[186:189], v[240:243], 0
	v_mfma_f32_16x16x32_bf16 v[34:37], v[190:193], v[244:247], v[34:37]
	v_mfma_f32_16x16x32_bf16 v[98:101], v[170:173], v[240:243], 0
	v_mfma_f32_16x16x32_bf16 v[98:101], v[174:177], v[244:247], v[98:101]
	v_mfma_f32_16x16x32_bf16 v[102:105], v[142:145], v[240:243], 0
	v_mfma_f32_16x16x32_bf16 v[102:105], v[154:157], v[244:247], v[102:105]
	s_barrier
	s_setprio 0
	s_mov_b32 m0, s2
	s_mov_b32 s66, s62
	s_mov_b32 s67, s63
	ds_read_b128 v[194:197], v140 offset:16384
	ds_read_b128 v[198:201], v140 offset:17408
	ds_read_b128 v[202:205], v140 offset:18432
	ds_read_b128 v[228:231], v140 offset:19456
	ds_read_b128 v[232:235], v140 offset:20480
	ds_read_b128 v[236:239], v140 offset:21504
	ds_read_b128 v[240:243], v140 offset:22528
	ds_read_b128 v[244:247], v140 offset:23552
	buffer_load_dwordx4 v134, s[64:67], s47 offen lds
	s_mov_b32 m0, s21
	s_add_i32 s53, s47, 0x200000
	buffer_load_dwordx4 v136, s[64:67], s47 offen lds
	s_mov_b32 m0, s23
	s_nop 0
	buffer_load_dwordx4 v134, s[64:67], s53 offen lds
	s_mov_b32 m0, s24
	s_nop 0
	buffer_load_dwordx4 v136, s[64:67], s53 offen lds
	s_mov_b32 m0, s16
	s_nop 0
	buffer_load_dwordx4 v131, s[60:63], s52 offen lds
	s_mov_b32 m0, s25
	s_nop 0
	buffer_load_dwordx4 v135, s[60:63], s52 offen lds
	s_waitcnt vmcnt(8)
	s_waitcnt lgkmcnt(0)
	s_setprio 1
	s_barrier
	v_mfma_f32_16x16x32_bf16 v[94:97], v[142:145], v[194:197], 0
	v_mfma_f32_16x16x32_bf16 v[94:97], v[154:157], v[198:201], v[94:97]
	v_mfma_f32_16x16x32_bf16 v[90:93], v[170:173], v[194:197], 0
	v_mfma_f32_16x16x32_bf16 v[90:93], v[174:177], v[198:201], v[90:93]
	v_mfma_f32_16x16x32_bf16 v[26:29], v[186:189], v[194:197], 0
	v_mfma_f32_16x16x32_bf16 v[26:29], v[190:193], v[198:201], v[26:29]
	v_mfma_f32_16x16x32_bf16 v[30:33], v[178:181], v[194:197], 0
	v_mfma_f32_16x16x32_bf16 v[30:33], v[182:185], v[198:201], v[30:33]
	v_mfma_f32_16x16x32_bf16 v[22:25], v[178:181], v[202:205], 0
	v_mfma_f32_16x16x32_bf16 v[22:25], v[182:185], v[228:231], v[22:25]
	v_mfma_f32_16x16x32_bf16 v[18:21], v[186:189], v[202:205], 0
	v_mfma_f32_16x16x32_bf16 v[18:21], v[190:193], v[228:231], v[18:21]
	v_mfma_f32_16x16x32_bf16 v[82:85], v[170:173], v[202:205], 0
	v_mfma_f32_16x16x32_bf16 v[82:85], v[174:177], v[228:231], v[82:85]
	v_mfma_f32_16x16x32_bf16 v[86:89], v[142:145], v[202:205], 0
	v_mfma_f32_16x16x32_bf16 v[86:89], v[154:157], v[228:231], v[86:89]
	v_mfma_f32_16x16x32_bf16 v[78:81], v[142:145], v[232:235], 0
	v_mfma_f32_16x16x32_bf16 v[78:81], v[154:157], v[236:239], v[78:81]
	v_mfma_f32_16x16x32_bf16 v[74:77], v[170:173], v[232:235], 0
	v_mfma_f32_16x16x32_bf16 v[74:77], v[174:177], v[236:239], v[74:77]
	v_mfma_f32_16x16x32_bf16 v[10:13], v[186:189], v[232:235], 0
	v_mfma_f32_16x16x32_bf16 v[10:13], v[190:193], v[236:239], v[10:13]
	v_mfma_f32_16x16x32_bf16 v[14:17], v[178:181], v[232:235], 0
	v_mfma_f32_16x16x32_bf16 v[14:17], v[182:185], v[236:239], v[14:17]
	v_mfma_f32_16x16x32_bf16 v[6:9], v[178:181], v[240:243], 0
	v_mfma_f32_16x16x32_bf16 v[6:9], v[182:185], v[244:247], v[6:9]
	v_mfma_f32_16x16x32_bf16 v[2:5], v[186:189], v[240:243], 0
	v_mfma_f32_16x16x32_bf16 v[2:5], v[190:193], v[244:247], v[2:5]
	v_mfma_f32_16x16x32_bf16 v[66:69], v[170:173], v[240:243], 0
	v_mfma_f32_16x16x32_bf16 v[66:69], v[174:177], v[244:247], v[66:69]
	v_mfma_f32_16x16x32_bf16 v[70:73], v[142:145], v[240:243], 0
	v_mfma_f32_16x16x32_bf16 v[70:73], v[154:157], v[244:247], v[70:73]
	s_barrier
	s_setprio 0
	v_add_u32_e32 v141, 0x18000, v139
	ds_read_b128 v[142:145], v141
	ds_read_b128 v[154:157], v141 offset:1024
	ds_read_b128 v[170:173], v141 offset:2048
	ds_read_b128 v[174:177], v141 offset:3072
	v_add_u32_e32 v141, 0x1c000, v139
	ds_read_b128 v[178:181], v141
	ds_read_b128 v[182:185], v141 offset:1024
	ds_read_b128 v[186:189], v141 offset:2048
	ds_read_b128 v[190:193], v141 offset:3072
	s_add_i32 s52, s52, 0x200000
	s_mov_b32 m0, s30
	ds_read_b128 v[194:197], v140 offset:32768
	ds_read_b128 v[198:201], v140 offset:33792
	ds_read_b128 v[202:205], v140 offset:34816
	ds_read_b128 v[228:231], v140 offset:35840
	ds_read_b128 v[232:235], v140 offset:36864
	ds_read_b128 v[236:239], v140 offset:37888
	ds_read_b128 v[240:243], v140 offset:38912
	ds_read_b128 v[244:247], v140 offset:39936
	buffer_load_dwordx4 v131, s[60:63], s52 offen lds
	s_mov_b32 m0, s31
	s_nop 0
	buffer_load_dwordx4 v135, s[60:63], s52 offen lds
	s_waitcnt vmcnt(8)
	s_waitcnt lgkmcnt(0)
	s_setprio 1
	s_barrier
	v_mfma_f32_16x16x32_bf16 v[126:129], v[142:145], v[194:197], v[126:129]
	v_mfma_f32_16x16x32_bf16 v[126:129], v[154:157], v[198:201], v[126:129]
	v_mfma_f32_16x16x32_bf16 v[122:125], v[170:173], v[194:197], v[122:125]
	v_mfma_f32_16x16x32_bf16 v[122:125], v[174:177], v[198:201], v[122:125]
	v_mfma_f32_16x16x32_bf16 v[58:61], v[186:189], v[194:197], v[58:61]
	v_mfma_f32_16x16x32_bf16 v[58:61], v[190:193], v[198:201], v[58:61]
	v_mfma_f32_16x16x32_bf16 v[62:65], v[178:181], v[194:197], v[62:65]
	v_mfma_f32_16x16x32_bf16 v[62:65], v[182:185], v[198:201], v[62:65]
	v_mfma_f32_16x16x32_bf16 v[54:57], v[178:181], v[202:205], v[54:57]
	v_mfma_f32_16x16x32_bf16 v[54:57], v[182:185], v[228:231], v[54:57]
	v_mfma_f32_16x16x32_bf16 v[50:53], v[186:189], v[202:205], v[50:53]
	v_mfma_f32_16x16x32_bf16 v[50:53], v[190:193], v[228:231], v[50:53]
	v_mfma_f32_16x16x32_bf16 v[114:117], v[170:173], v[202:205], v[114:117]
	v_mfma_f32_16x16x32_bf16 v[114:117], v[174:177], v[228:231], v[114:117]
	v_mfma_f32_16x16x32_bf16 v[118:121], v[142:145], v[202:205], v[118:121]
	v_mfma_f32_16x16x32_bf16 v[118:121], v[154:157], v[228:231], v[118:121]
	v_mfma_f32_16x16x32_bf16 v[110:113], v[142:145], v[232:235], v[110:113]
	v_mfma_f32_16x16x32_bf16 v[110:113], v[154:157], v[236:239], v[110:113]
	v_mfma_f32_16x16x32_bf16 v[106:109], v[170:173], v[232:235], v[106:109]
	v_mfma_f32_16x16x32_bf16 v[106:109], v[174:177], v[236:239], v[106:109]
	v_mfma_f32_16x16x32_bf16 v[42:45], v[186:189], v[232:235], v[42:45]
	v_mfma_f32_16x16x32_bf16 v[42:45], v[190:193], v[236:239], v[42:45]
	v_mfma_f32_16x16x32_bf16 v[46:49], v[178:181], v[232:235], v[46:49]
	v_mfma_f32_16x16x32_bf16 v[46:49], v[182:185], v[236:239], v[46:49]
	v_mfma_f32_16x16x32_bf16 v[38:41], v[178:181], v[240:243], v[38:41]
	v_mfma_f32_16x16x32_bf16 v[38:41], v[182:185], v[244:247], v[38:41]
	v_mfma_f32_16x16x32_bf16 v[34:37], v[186:189], v[240:243], v[34:37]
	v_mfma_f32_16x16x32_bf16 v[34:37], v[190:193], v[244:247], v[34:37]
	v_mfma_f32_16x16x32_bf16 v[98:101], v[170:173], v[240:243], v[98:101]
	v_mfma_f32_16x16x32_bf16 v[98:101], v[174:177], v[244:247], v[98:101]
	v_mfma_f32_16x16x32_bf16 v[102:105], v[142:145], v[240:243], v[102:105]
	v_mfma_f32_16x16x32_bf16 v[102:105], v[154:157], v[244:247], v[102:105]
	s_barrier
	s_setprio 0
	s_mov_b32 m0, s33
	s_or_b32 s52, s47, 0x80
	ds_read_b128 v[194:197], v140 offset:49152
	ds_read_b128 v[198:201], v140 offset:50176
	ds_read_b128 v[202:205], v140 offset:51200
	ds_read_b128 v[228:231], v140 offset:52224
	ds_read_b128 v[232:235], v140 offset:53248
	ds_read_b128 v[236:239], v140 offset:54272
	ds_read_b128 v[240:243], v140 offset:55296
	ds_read_b128 v[244:247], v140 offset:56320
	buffer_load_dwordx4 v134, s[64:67], s52 offen lds
	s_mov_b32 m0, s34
	s_add_i32 s47, s47, 0x200080
	buffer_load_dwordx4 v136, s[64:67], s52 offen lds
	s_mov_b32 m0, s37
	s_nop 0
	buffer_load_dwordx4 v134, s[64:67], s47 offen lds
	s_mov_b32 m0, s68
	s_nop 0
	buffer_load_dwordx4 v136, s[64:67], s47 offen lds
	s_mov_b32 m0, s35
	s_nop 0
	buffer_load_dwordx4 v131, s[60:63], s27 offen lds
	s_mov_b32 m0, s36
	s_nop 0
	buffer_load_dwordx4 v135, s[60:63], s27 offen lds
	s_waitcnt vmcnt(8)
	s_waitcnt lgkmcnt(0)
	s_setprio 1
	s_barrier
	v_mfma_f32_16x16x32_bf16 v[94:97], v[142:145], v[194:197], v[94:97]
	v_mfma_f32_16x16x32_bf16 v[94:97], v[154:157], v[198:201], v[94:97]
	v_mfma_f32_16x16x32_bf16 v[90:93], v[170:173], v[194:197], v[90:93]
	v_mfma_f32_16x16x32_bf16 v[90:93], v[174:177], v[198:201], v[90:93]
	v_mfma_f32_16x16x32_bf16 v[26:29], v[186:189], v[194:197], v[26:29]
	v_mfma_f32_16x16x32_bf16 v[26:29], v[190:193], v[198:201], v[26:29]
	v_mfma_f32_16x16x32_bf16 v[30:33], v[178:181], v[194:197], v[30:33]
	v_mfma_f32_16x16x32_bf16 v[30:33], v[182:185], v[198:201], v[30:33]
	v_mfma_f32_16x16x32_bf16 v[22:25], v[178:181], v[202:205], v[22:25]
	v_mfma_f32_16x16x32_bf16 v[22:25], v[182:185], v[228:231], v[22:25]
	v_mfma_f32_16x16x32_bf16 v[18:21], v[186:189], v[202:205], v[18:21]
	v_mfma_f32_16x16x32_bf16 v[18:21], v[190:193], v[228:231], v[18:21]
	v_mfma_f32_16x16x32_bf16 v[82:85], v[170:173], v[202:205], v[82:85]
	v_mfma_f32_16x16x32_bf16 v[82:85], v[174:177], v[228:231], v[82:85]
	v_mfma_f32_16x16x32_bf16 v[86:89], v[142:145], v[202:205], v[86:89]
	v_mfma_f32_16x16x32_bf16 v[86:89], v[154:157], v[228:231], v[86:89]
	v_mfma_f32_16x16x32_bf16 v[78:81], v[142:145], v[232:235], v[78:81]
	v_mfma_f32_16x16x32_bf16 v[78:81], v[154:157], v[236:239], v[78:81]
	v_mfma_f32_16x16x32_bf16 v[74:77], v[170:173], v[232:235], v[74:77]
	v_mfma_f32_16x16x32_bf16 v[74:77], v[174:177], v[236:239], v[74:77]
	v_mfma_f32_16x16x32_bf16 v[10:13], v[186:189], v[232:235], v[10:13]
	v_mfma_f32_16x16x32_bf16 v[10:13], v[190:193], v[236:239], v[10:13]
	v_mfma_f32_16x16x32_bf16 v[14:17], v[178:181], v[232:235], v[14:17]
	v_mfma_f32_16x16x32_bf16 v[14:17], v[182:185], v[236:239], v[14:17]
	v_mfma_f32_16x16x32_bf16 v[6:9], v[178:181], v[240:243], v[6:9]
	v_mfma_f32_16x16x32_bf16 v[6:9], v[182:185], v[244:247], v[6:9]
	v_mfma_f32_16x16x32_bf16 v[2:5], v[186:189], v[240:243], v[2:5]
	v_mfma_f32_16x16x32_bf16 v[2:5], v[190:193], v[244:247], v[2:5]
	v_mfma_f32_16x16x32_bf16 v[66:69], v[170:173], v[240:243], v[66:69]
	v_mfma_f32_16x16x32_bf16 v[66:69], v[174:177], v[244:247], v[66:69]
	v_mfma_f32_16x16x32_bf16 v[70:73], v[142:145], v[240:243], v[70:73]
	v_mfma_f32_16x16x32_bf16 v[70:73], v[154:157], v[244:247], v[70:73]
	s_barrier
	s_setprio 0
	s_add_i32 s26, s26, 2
	s_addk_i32 s19, 0x100
	s_addk_i32 s22, 0x100
	s_cmpk_gt_u32 s26, 0x7d
.LBB0_1223:
	v_add_u32_e32 v141, 0x10000, v139
	ds_read_b128 v[142:145], v141
	ds_read_b128 v[154:157], v141 offset:1024
	ds_read_b128 v[170:173], v141 offset:2048
	ds_read_b128 v[174:177], v141 offset:3072
	v_add_u32_e32 v141, 0x14000, v139
	ds_read_b128 v[178:181], v141
	ds_read_b128 v[182:185], v141 offset:1024
	ds_read_b128 v[186:189], v141 offset:2048
	ds_read_b128 v[190:193], v141 offset:3072
	s_add_i32 s27, s19, 0xffe00080
	s_cmpk_eq_i32 s26, 0x7c
	s_cselect_b32 s52, s8, s27
	s_cselect_b32 s47, s9, s22
	s_or_b32 s27, s52, 0x80
	s_mov_b32 m0, s71
	ds_read_b128 v[194:197], v140
	ds_read_b128 v[198:201], v140 offset:1024
	ds_read_b128 v[202:205], v140 offset:2048
	ds_read_b128 v[228:231], v140 offset:3072
	ds_read_b128 v[232:235], v140 offset:4096
	ds_read_b128 v[236:239], v140 offset:5120
	ds_read_b128 v[240:243], v140 offset:6144
	ds_read_b128 v[244:247], v140 offset:7168
	buffer_load_dwordx4 v131, s[60:63], s19 offen lds
	s_mov_b32 m0, s72
	s_nop 0
	buffer_load_dwordx4 v135, s[60:63], s19 offen lds
	s_waitcnt vmcnt(8)
	s_waitcnt lgkmcnt(0)
	s_setprio 1
	s_barrier
	v_mfma_f32_16x16x32_bf16 v[126:129], v[142:145], v[194:197], v[126:129]
	v_mfma_f32_16x16x32_bf16 v[126:129], v[154:157], v[198:201], v[126:129]
	v_mfma_f32_16x16x32_bf16 v[122:125], v[170:173], v[194:197], v[122:125]
	v_mfma_f32_16x16x32_bf16 v[122:125], v[174:177], v[198:201], v[122:125]
	v_mfma_f32_16x16x32_bf16 v[58:61], v[186:189], v[194:197], v[58:61]
	v_mfma_f32_16x16x32_bf16 v[58:61], v[190:193], v[198:201], v[58:61]
	v_mfma_f32_16x16x32_bf16 v[62:65], v[178:181], v[194:197], v[62:65]
	v_mfma_f32_16x16x32_bf16 v[62:65], v[182:185], v[198:201], v[62:65]
	v_mfma_f32_16x16x32_bf16 v[54:57], v[178:181], v[202:205], v[54:57]
	v_mfma_f32_16x16x32_bf16 v[54:57], v[182:185], v[228:231], v[54:57]
	v_mfma_f32_16x16x32_bf16 v[50:53], v[186:189], v[202:205], v[50:53]
	v_mfma_f32_16x16x32_bf16 v[50:53], v[190:193], v[228:231], v[50:53]
	v_mfma_f32_16x16x32_bf16 v[114:117], v[170:173], v[202:205], v[114:117]
	v_mfma_f32_16x16x32_bf16 v[114:117], v[174:177], v[228:231], v[114:117]
	v_mfma_f32_16x16x32_bf16 v[118:121], v[142:145], v[202:205], v[118:121]
	v_mfma_f32_16x16x32_bf16 v[118:121], v[154:157], v[228:231], v[118:121]
	v_mfma_f32_16x16x32_bf16 v[110:113], v[142:145], v[232:235], v[110:113]
	v_mfma_f32_16x16x32_bf16 v[110:113], v[154:157], v[236:239], v[110:113]
	v_mfma_f32_16x16x32_bf16 v[106:109], v[170:173], v[232:235], v[106:109]
	v_mfma_f32_16x16x32_bf16 v[106:109], v[174:177], v[236:239], v[106:109]
	v_mfma_f32_16x16x32_bf16 v[42:45], v[186:189], v[232:235], v[42:45]
	v_mfma_f32_16x16x32_bf16 v[42:45], v[190:193], v[236:239], v[42:45]
	v_mfma_f32_16x16x32_bf16 v[46:49], v[178:181], v[232:235], v[46:49]
	v_mfma_f32_16x16x32_bf16 v[46:49], v[182:185], v[236:239], v[46:49]
	v_mfma_f32_16x16x32_bf16 v[38:41], v[178:181], v[240:243], v[38:41]
	v_mfma_f32_16x16x32_bf16 v[38:41], v[182:185], v[244:247], v[38:41]
	v_mfma_f32_16x16x32_bf16 v[34:37], v[186:189], v[240:243], v[34:37]
	v_mfma_f32_16x16x32_bf16 v[34:37], v[190:193], v[244:247], v[34:37]
	v_mfma_f32_16x16x32_bf16 v[98:101], v[170:173], v[240:243], v[98:101]
	v_mfma_f32_16x16x32_bf16 v[98:101], v[174:177], v[244:247], v[98:101]
	v_mfma_f32_16x16x32_bf16 v[102:105], v[142:145], v[240:243], v[102:105]
	v_mfma_f32_16x16x32_bf16 v[102:105], v[154:157], v[244:247], v[102:105]
	s_barrier
	s_setprio 0
	s_mov_b32 m0, s2
	s_mov_b32 s66, s62
	s_mov_b32 s67, s63
	ds_read_b128 v[194:197], v140 offset:16384
	ds_read_b128 v[198:201], v140 offset:17408
	ds_read_b128 v[202:205], v140 offset:18432
	ds_read_b128 v[228:231], v140 offset:19456
	ds_read_b128 v[232:235], v140 offset:20480
	ds_read_b128 v[236:239], v140 offset:21504
	ds_read_b128 v[240:243], v140 offset:22528
	ds_read_b128 v[244:247], v140 offset:23552
	buffer_load_dwordx4 v134, s[64:67], s47 offen lds
	s_mov_b32 m0, s21
	s_add_i32 s53, s47, 0x200000
	buffer_load_dwordx4 v136, s[64:67], s47 offen lds
	s_mov_b32 m0, s23
	s_nop 0
	buffer_load_dwordx4 v134, s[64:67], s53 offen lds
	s_mov_b32 m0, s24
	s_nop 0
	buffer_load_dwordx4 v136, s[64:67], s53 offen lds
	s_mov_b32 m0, s16
	s_nop 0
	buffer_load_dwordx4 v131, s[60:63], s52 offen lds
	s_mov_b32 m0, s25
	s_nop 0
	buffer_load_dwordx4 v135, s[60:63], s52 offen lds
	s_waitcnt vmcnt(8)
	s_waitcnt lgkmcnt(0)
	s_setprio 1
	s_barrier
	v_mfma_f32_16x16x32_bf16 v[94:97], v[142:145], v[194:197], v[94:97]
	v_mfma_f32_16x16x32_bf16 v[94:97], v[154:157], v[198:201], v[94:97]
	v_mfma_f32_16x16x32_bf16 v[90:93], v[170:173], v[194:197], v[90:93]
	v_mfma_f32_16x16x32_bf16 v[90:93], v[174:177], v[198:201], v[90:93]
	v_mfma_f32_16x16x32_bf16 v[26:29], v[186:189], v[194:197], v[26:29]
	v_mfma_f32_16x16x32_bf16 v[26:29], v[190:193], v[198:201], v[26:29]
	v_mfma_f32_16x16x32_bf16 v[30:33], v[178:181], v[194:197], v[30:33]
	v_mfma_f32_16x16x32_bf16 v[30:33], v[182:185], v[198:201], v[30:33]
	v_mfma_f32_16x16x32_bf16 v[22:25], v[178:181], v[202:205], v[22:25]
	v_mfma_f32_16x16x32_bf16 v[22:25], v[182:185], v[228:231], v[22:25]
	v_mfma_f32_16x16x32_bf16 v[18:21], v[186:189], v[202:205], v[18:21]
	v_mfma_f32_16x16x32_bf16 v[18:21], v[190:193], v[228:231], v[18:21]
	v_mfma_f32_16x16x32_bf16 v[82:85], v[170:173], v[202:205], v[82:85]
	v_mfma_f32_16x16x32_bf16 v[82:85], v[174:177], v[228:231], v[82:85]
	v_mfma_f32_16x16x32_bf16 v[86:89], v[142:145], v[202:205], v[86:89]
	v_mfma_f32_16x16x32_bf16 v[86:89], v[154:157], v[228:231], v[86:89]
	v_mfma_f32_16x16x32_bf16 v[78:81], v[142:145], v[232:235], v[78:81]
	v_mfma_f32_16x16x32_bf16 v[78:81], v[154:157], v[236:239], v[78:81]
	v_mfma_f32_16x16x32_bf16 v[74:77], v[170:173], v[232:235], v[74:77]
	v_mfma_f32_16x16x32_bf16 v[74:77], v[174:177], v[236:239], v[74:77]
	v_mfma_f32_16x16x32_bf16 v[10:13], v[186:189], v[232:235], v[10:13]
	v_mfma_f32_16x16x32_bf16 v[10:13], v[190:193], v[236:239], v[10:13]
	v_mfma_f32_16x16x32_bf16 v[14:17], v[178:181], v[232:235], v[14:17]
	v_mfma_f32_16x16x32_bf16 v[14:17], v[182:185], v[236:239], v[14:17]
	v_mfma_f32_16x16x32_bf16 v[6:9], v[178:181], v[240:243], v[6:9]
	v_mfma_f32_16x16x32_bf16 v[6:9], v[182:185], v[244:247], v[6:9]
	v_mfma_f32_16x16x32_bf16 v[2:5], v[186:189], v[240:243], v[2:5]
	v_mfma_f32_16x16x32_bf16 v[2:5], v[190:193], v[244:247], v[2:5]
	v_mfma_f32_16x16x32_bf16 v[66:69], v[170:173], v[240:243], v[66:69]
	v_mfma_f32_16x16x32_bf16 v[66:69], v[174:177], v[244:247], v[66:69]
	v_mfma_f32_16x16x32_bf16 v[70:73], v[142:145], v[240:243], v[70:73]
	v_mfma_f32_16x16x32_bf16 v[70:73], v[154:157], v[244:247], v[70:73]
	s_barrier
	s_setprio 0
	v_add_u32_e32 v141, 0x18000, v139
	ds_read_b128 v[142:145], v141
	ds_read_b128 v[154:157], v141 offset:1024
	ds_read_b128 v[170:173], v141 offset:2048
	ds_read_b128 v[174:177], v141 offset:3072
	v_add_u32_e32 v141, 0x1c000, v139
	ds_read_b128 v[178:181], v141
	ds_read_b128 v[182:185], v141 offset:1024
	ds_read_b128 v[186:189], v141 offset:2048
	ds_read_b128 v[190:193], v141 offset:3072
	s_add_i32 s52, s52, 0x200000
	s_mov_b32 m0, s30
	ds_read_b128 v[194:197], v140 offset:32768
	ds_read_b128 v[198:201], v140 offset:33792
	ds_read_b128 v[202:205], v140 offset:34816
	ds_read_b128 v[228:231], v140 offset:35840
	ds_read_b128 v[232:235], v140 offset:36864
	ds_read_b128 v[236:239], v140 offset:37888
	ds_read_b128 v[240:243], v140 offset:38912
	ds_read_b128 v[244:247], v140 offset:39936
	buffer_load_dwordx4 v131, s[60:63], s52 offen lds
	s_mov_b32 m0, s31
	s_nop 0
	buffer_load_dwordx4 v135, s[60:63], s52 offen lds
	s_waitcnt vmcnt(8)
	s_waitcnt lgkmcnt(0)
	s_setprio 1
	s_barrier
	v_mfma_f32_16x16x32_bf16 v[126:129], v[142:145], v[194:197], v[126:129]
	v_mfma_f32_16x16x32_bf16 v[126:129], v[154:157], v[198:201], v[126:129]
	v_mfma_f32_16x16x32_bf16 v[122:125], v[170:173], v[194:197], v[122:125]
	v_mfma_f32_16x16x32_bf16 v[122:125], v[174:177], v[198:201], v[122:125]
	v_mfma_f32_16x16x32_bf16 v[58:61], v[186:189], v[194:197], v[58:61]
	v_mfma_f32_16x16x32_bf16 v[58:61], v[190:193], v[198:201], v[58:61]
	v_mfma_f32_16x16x32_bf16 v[62:65], v[178:181], v[194:197], v[62:65]
	v_mfma_f32_16x16x32_bf16 v[62:65], v[182:185], v[198:201], v[62:65]
	v_mfma_f32_16x16x32_bf16 v[54:57], v[178:181], v[202:205], v[54:57]
	v_mfma_f32_16x16x32_bf16 v[54:57], v[182:185], v[228:231], v[54:57]
	v_mfma_f32_16x16x32_bf16 v[50:53], v[186:189], v[202:205], v[50:53]
	v_mfma_f32_16x16x32_bf16 v[50:53], v[190:193], v[228:231], v[50:53]
	v_mfma_f32_16x16x32_bf16 v[114:117], v[170:173], v[202:205], v[114:117]
	v_mfma_f32_16x16x32_bf16 v[114:117], v[174:177], v[228:231], v[114:117]
	v_mfma_f32_16x16x32_bf16 v[118:121], v[142:145], v[202:205], v[118:121]
	v_mfma_f32_16x16x32_bf16 v[118:121], v[154:157], v[228:231], v[118:121]
	v_mfma_f32_16x16x32_bf16 v[110:113], v[142:145], v[232:235], v[110:113]
	v_mfma_f32_16x16x32_bf16 v[110:113], v[154:157], v[236:239], v[110:113]
	v_mfma_f32_16x16x32_bf16 v[106:109], v[170:173], v[232:235], v[106:109]
	v_mfma_f32_16x16x32_bf16 v[106:109], v[174:177], v[236:239], v[106:109]
	v_mfma_f32_16x16x32_bf16 v[42:45], v[186:189], v[232:235], v[42:45]
	v_mfma_f32_16x16x32_bf16 v[42:45], v[190:193], v[236:239], v[42:45]
	v_mfma_f32_16x16x32_bf16 v[46:49], v[178:181], v[232:235], v[46:49]
	v_mfma_f32_16x16x32_bf16 v[46:49], v[182:185], v[236:239], v[46:49]
	v_mfma_f32_16x16x32_bf16 v[38:41], v[178:181], v[240:243], v[38:41]
	v_mfma_f32_16x16x32_bf16 v[38:41], v[182:185], v[244:247], v[38:41]
	v_mfma_f32_16x16x32_bf16 v[34:37], v[186:189], v[240:243], v[34:37]
	v_mfma_f32_16x16x32_bf16 v[34:37], v[190:193], v[244:247], v[34:37]
	v_mfma_f32_16x16x32_bf16 v[98:101], v[170:173], v[240:243], v[98:101]
	v_mfma_f32_16x16x32_bf16 v[98:101], v[174:177], v[244:247], v[98:101]
	v_mfma_f32_16x16x32_bf16 v[102:105], v[142:145], v[240:243], v[102:105]
	v_mfma_f32_16x16x32_bf16 v[102:105], v[154:157], v[244:247], v[102:105]
	s_barrier
	s_setprio 0
	s_mov_b32 m0, s33
	s_or_b32 s52, s47, 0x80
	ds_read_b128 v[194:197], v140 offset:49152
	ds_read_b128 v[198:201], v140 offset:50176
	ds_read_b128 v[202:205], v140 offset:51200
	ds_read_b128 v[228:231], v140 offset:52224
	ds_read_b128 v[232:235], v140 offset:53248
	ds_read_b128 v[236:239], v140 offset:54272
	ds_read_b128 v[240:243], v140 offset:55296
	ds_read_b128 v[244:247], v140 offset:56320
	buffer_load_dwordx4 v134, s[64:67], s52 offen lds
	s_mov_b32 m0, s34
	s_add_i32 s47, s47, 0x200080
	buffer_load_dwordx4 v136, s[64:67], s52 offen lds
	s_mov_b32 m0, s37
	s_nop 0
	buffer_load_dwordx4 v134, s[64:67], s47 offen lds
	s_mov_b32 m0, s68
	s_nop 0
	buffer_load_dwordx4 v136, s[64:67], s47 offen lds
	s_mov_b32 m0, s35
	s_nop 0
	buffer_load_dwordx4 v131, s[60:63], s27 offen lds
	s_mov_b32 m0, s36
	s_nop 0
	buffer_load_dwordx4 v135, s[60:63], s27 offen lds
	s_waitcnt vmcnt(8)
	s_waitcnt lgkmcnt(0)
	s_setprio 1
	s_barrier
	v_mfma_f32_16x16x32_bf16 v[94:97], v[142:145], v[194:197], v[94:97]
	v_mfma_f32_16x16x32_bf16 v[94:97], v[154:157], v[198:201], v[94:97]
	v_mfma_f32_16x16x32_bf16 v[90:93], v[170:173], v[194:197], v[90:93]
	v_mfma_f32_16x16x32_bf16 v[90:93], v[174:177], v[198:201], v[90:93]
	v_mfma_f32_16x16x32_bf16 v[26:29], v[186:189], v[194:197], v[26:29]
	v_mfma_f32_16x16x32_bf16 v[26:29], v[190:193], v[198:201], v[26:29]
	v_mfma_f32_16x16x32_bf16 v[30:33], v[178:181], v[194:197], v[30:33]
	v_mfma_f32_16x16x32_bf16 v[30:33], v[182:185], v[198:201], v[30:33]
	v_mfma_f32_16x16x32_bf16 v[22:25], v[178:181], v[202:205], v[22:25]
	v_mfma_f32_16x16x32_bf16 v[22:25], v[182:185], v[228:231], v[22:25]
	v_mfma_f32_16x16x32_bf16 v[18:21], v[186:189], v[202:205], v[18:21]
	v_mfma_f32_16x16x32_bf16 v[18:21], v[190:193], v[228:231], v[18:21]
	v_mfma_f32_16x16x32_bf16 v[82:85], v[170:173], v[202:205], v[82:85]
	v_mfma_f32_16x16x32_bf16 v[82:85], v[174:177], v[228:231], v[82:85]
	v_mfma_f32_16x16x32_bf16 v[86:89], v[142:145], v[202:205], v[86:89]
	v_mfma_f32_16x16x32_bf16 v[86:89], v[154:157], v[228:231], v[86:89]
	v_mfma_f32_16x16x32_bf16 v[78:81], v[142:145], v[232:235], v[78:81]
	v_mfma_f32_16x16x32_bf16 v[78:81], v[154:157], v[236:239], v[78:81]
	v_mfma_f32_16x16x32_bf16 v[74:77], v[170:173], v[232:235], v[74:77]
	v_mfma_f32_16x16x32_bf16 v[74:77], v[174:177], v[236:239], v[74:77]
	v_mfma_f32_16x16x32_bf16 v[10:13], v[186:189], v[232:235], v[10:13]
	v_mfma_f32_16x16x32_bf16 v[10:13], v[190:193], v[236:239], v[10:13]
	v_mfma_f32_16x16x32_bf16 v[14:17], v[178:181], v[232:235], v[14:17]
	v_mfma_f32_16x16x32_bf16 v[14:17], v[182:185], v[236:239], v[14:17]
	v_mfma_f32_16x16x32_bf16 v[6:9], v[178:181], v[240:243], v[6:9]
	v_mfma_f32_16x16x32_bf16 v[6:9], v[182:185], v[244:247], v[6:9]
	v_mfma_f32_16x16x32_bf16 v[2:5], v[186:189], v[240:243], v[2:5]
	v_mfma_f32_16x16x32_bf16 v[2:5], v[190:193], v[244:247], v[2:5]
	v_mfma_f32_16x16x32_bf16 v[66:69], v[170:173], v[240:243], v[66:69]
	v_mfma_f32_16x16x32_bf16 v[66:69], v[174:177], v[244:247], v[66:69]
	v_mfma_f32_16x16x32_bf16 v[70:73], v[142:145], v[240:243], v[70:73]
	v_mfma_f32_16x16x32_bf16 v[70:73], v[154:157], v[244:247], v[70:73]
	s_barrier
	s_setprio 0
	s_add_i32 s26, s26, 2
	s_addk_i32 s19, 0x100
	s_addk_i32 s22, 0x100
	s_cmpk_gt_u32 s26, 0x7d
	s_cbranch_scc0 .LBB0_1223
	s_and_b64 vcc, exec, s[42:43]
	s_cbranch_vccz .LBB0_1226
	s_barrier

.LBB0_1252:
	s_lshl_b32 s12, s73, 20
	s_and_b64 s[8:9], s[40:41], exec
	s_cselect_b32 s8, s12, s26
	s_lshl_b32 s22, s82, 20
	s_and_b64 s[70:71], s[40:41], exec
	s_cselect_b32 s9, s22, s27
	s_add_i32 s26, s26, 0x80080
	s_addk_i32 s27, 0x100
	s_mov_b32 s83, -2
	v_add_u32_e32 v141, 0x10000, v139
	ds_read_b128 v[142:145], v141
	ds_read_b128 v[154:157], v141 offset:1024
	ds_read_b128 v[170:173], v141 offset:2048
	ds_read_b128 v[174:177], v141 offset:3072
	v_add_u32_e32 v141, 0x14000, v139
	ds_read_b128 v[178:181], v141
	ds_read_b128 v[182:185], v141 offset:1024
	ds_read_b128 v[186:189], v141 offset:2048
	ds_read_b128 v[190:193], v141 offset:3072
	s_add_i32 s52, s26, 0xfff80080
	s_cmp_eq_u32 s83, 28
	s_cselect_b32 s52, s8, s52
	s_cselect_b32 s85, s9, s27
	s_or_b32 s84, s52, 0x80
	s_mov_b32 m0, s72
	ds_read_b128 v[194:197], v140
	ds_read_b128 v[198:201], v140 offset:1024
	ds_read_b128 v[202:205], v140 offset:2048
	ds_read_b128 v[228:231], v140 offset:3072
	ds_read_b128 v[232:235], v140 offset:4096
	ds_read_b128 v[236:239], v140 offset:5120
	ds_read_b128 v[240:243], v140 offset:6144
	ds_read_b128 v[244:247], v140 offset:7168
	buffer_load_dwordx4 v131, s[60:63], s26 offen lds
	s_mov_b32 m0, s46
	s_nop 0
	buffer_load_dwordx4 v135, s[60:63], s26 offen lds
	s_waitcnt vmcnt(8)
	s_waitcnt lgkmcnt(0)
	s_setprio 1
	s_barrier
	v_mfma_f32_16x16x32_bf16 v[126:129], v[142:145], v[194:197], 0
	v_mfma_f32_16x16x32_bf16 v[126:129], v[154:157], v[198:201], v[126:129]
	v_mfma_f32_16x16x32_bf16 v[122:125], v[170:173], v[194:197], 0
	v_mfma_f32_16x16x32_bf16 v[122:125], v[174:177], v[198:201], v[122:125]
	v_mfma_f32_16x16x32_bf16 v[58:61], v[186:189], v[194:197], 0
	v_mfma_f32_16x16x32_bf16 v[58:61], v[190:193], v[198:201], v[58:61]
	v_mfma_f32_16x16x32_bf16 v[62:65], v[178:181], v[194:197], 0
	v_mfma_f32_16x16x32_bf16 v[62:65], v[182:185], v[198:201], v[62:65]
	v_mfma_f32_16x16x32_bf16 v[54:57], v[178:181], v[202:205], 0
	v_mfma_f32_16x16x32_bf16 v[54:57], v[182:185], v[228:231], v[54:57]
	v_mfma_f32_16x16x32_bf16 v[50:53], v[186:189], v[202:205], 0
	v_mfma_f32_16x16x32_bf16 v[50:53], v[190:193], v[228:231], v[50:53]
	v_mfma_f32_16x16x32_bf16 v[114:117], v[170:173], v[202:205], 0
	v_mfma_f32_16x16x32_bf16 v[114:117], v[174:177], v[228:231], v[114:117]
	v_mfma_f32_16x16x32_bf16 v[118:121], v[142:145], v[202:205], 0
	v_mfma_f32_16x16x32_bf16 v[118:121], v[154:157], v[228:231], v[118:121]
	v_mfma_f32_16x16x32_bf16 v[110:113], v[142:145], v[232:235], 0
	v_mfma_f32_16x16x32_bf16 v[110:113], v[154:157], v[236:239], v[110:113]
	v_mfma_f32_16x16x32_bf16 v[106:109], v[170:173], v[232:235], 0
	v_mfma_f32_16x16x32_bf16 v[106:109], v[174:177], v[236:239], v[106:109]
	v_mfma_f32_16x16x32_bf16 v[42:45], v[186:189], v[232:235], 0
	v_mfma_f32_16x16x32_bf16 v[42:45], v[190:193], v[236:239], v[42:45]
	v_mfma_f32_16x16x32_bf16 v[46:49], v[178:181], v[232:235], 0
	v_mfma_f32_16x16x32_bf16 v[46:49], v[182:185], v[236:239], v[46:49]
	v_mfma_f32_16x16x32_bf16 v[38:41], v[178:181], v[240:243], 0
	v_mfma_f32_16x16x32_bf16 v[38:41], v[182:185], v[244:247], v[38:41]
	v_mfma_f32_16x16x32_bf16 v[34:37], v[186:189], v[240:243], 0
	v_mfma_f32_16x16x32_bf16 v[34:37], v[190:193], v[244:247], v[34:37]
	v_mfma_f32_16x16x32_bf16 v[98:101], v[170:173], v[240:243], 0
	v_mfma_f32_16x16x32_bf16 v[98:101], v[174:177], v[244:247], v[98:101]
	v_mfma_f32_16x16x32_bf16 v[102:105], v[142:145], v[240:243], 0
	v_mfma_f32_16x16x32_bf16 v[102:105], v[154:157], v[244:247], v[102:105]
	s_barrier
	s_setprio 0
	s_mov_b32 m0, s21
	s_mov_b32 s70, s62
	s_mov_b32 s71, s63
	ds_read_b128 v[194:197], v140 offset:16384
	ds_read_b128 v[198:201], v140 offset:17408
	ds_read_b128 v[202:205], v140 offset:18432
	ds_read_b128 v[228:231], v140 offset:19456
	ds_read_b128 v[232:235], v140 offset:20480
	ds_read_b128 v[236:239], v140 offset:21504
	ds_read_b128 v[240:243], v140 offset:22528
	ds_read_b128 v[244:247], v140 offset:23552
	buffer_load_dwordx4 v134, s[68:71], s85 offen lds
	s_mov_b32 m0, s23
	s_add_i32 s53, s85, 0x80000
	buffer_load_dwordx4 v136, s[68:71], s85 offen lds
	s_mov_b32 m0, s24
	s_nop 0
	buffer_load_dwordx4 v134, s[68:71], s53 offen lds
	s_mov_b32 m0, s25
	s_nop 0
	buffer_load_dwordx4 v136, s[68:71], s53 offen lds
	s_mov_b32 m0, s16
	s_nop 0
	buffer_load_dwordx4 v131, s[60:63], s52 offen lds
	s_mov_b32 m0, s30
	s_nop 0
	buffer_load_dwordx4 v135, s[60:63], s52 offen lds
	s_waitcnt vmcnt(8)
	s_waitcnt lgkmcnt(0)
	s_setprio 1
	s_barrier
	v_mfma_f32_16x16x32_bf16 v[94:97], v[142:145], v[194:197], 0
	v_mfma_f32_16x16x32_bf16 v[94:97], v[154:157], v[198:201], v[94:97]
	v_mfma_f32_16x16x32_bf16 v[90:93], v[170:173], v[194:197], 0
	v_mfma_f32_16x16x32_bf16 v[90:93], v[174:177], v[198:201], v[90:93]
	v_mfma_f32_16x16x32_bf16 v[26:29], v[186:189], v[194:197], 0
	v_mfma_f32_16x16x32_bf16 v[26:29], v[190:193], v[198:201], v[26:29]
	v_mfma_f32_16x16x32_bf16 v[30:33], v[178:181], v[194:197], 0
	v_mfma_f32_16x16x32_bf16 v[30:33], v[182:185], v[198:201], v[30:33]
	v_mfma_f32_16x16x32_bf16 v[22:25], v[178:181], v[202:205], 0
	v_mfma_f32_16x16x32_bf16 v[22:25], v[182:185], v[228:231], v[22:25]
	v_mfma_f32_16x16x32_bf16 v[18:21], v[186:189], v[202:205], 0
	v_mfma_f32_16x16x32_bf16 v[18:21], v[190:193], v[228:231], v[18:21]
	v_mfma_f32_16x16x32_bf16 v[82:85], v[170:173], v[202:205], 0
	v_mfma_f32_16x16x32_bf16 v[82:85], v[174:177], v[228:231], v[82:85]
	v_mfma_f32_16x16x32_bf16 v[86:89], v[142:145], v[202:205], 0
	v_mfma_f32_16x16x32_bf16 v[86:89], v[154:157], v[228:231], v[86:89]
	v_mfma_f32_16x16x32_bf16 v[78:81], v[142:145], v[232:235], 0
	v_mfma_f32_16x16x32_bf16 v[78:81], v[154:157], v[236:239], v[78:81]
	v_mfma_f32_16x16x32_bf16 v[74:77], v[170:173], v[232:235], 0
	v_mfma_f32_16x16x32_bf16 v[74:77], v[174:177], v[236:239], v[74:77]
	v_mfma_f32_16x16x32_bf16 v[10:13], v[186:189], v[232:235], 0
	v_mfma_f32_16x16x32_bf16 v[10:13], v[190:193], v[236:239], v[10:13]
	v_mfma_f32_16x16x32_bf16 v[14:17], v[178:181], v[232:235], 0
	v_mfma_f32_16x16x32_bf16 v[14:17], v[182:185], v[236:239], v[14:17]
	v_mfma_f32_16x16x32_bf16 v[6:9], v[178:181], v[240:243], 0
	v_mfma_f32_16x16x32_bf16 v[6:9], v[182:185], v[244:247], v[6:9]
	v_mfma_f32_16x16x32_bf16 v[2:5], v[186:189], v[240:243], 0
	v_mfma_f32_16x16x32_bf16 v[2:5], v[190:193], v[244:247], v[2:5]
	v_mfma_f32_16x16x32_bf16 v[66:69], v[170:173], v[240:243], 0
	v_mfma_f32_16x16x32_bf16 v[66:69], v[174:177], v[244:247], v[66:69]
	v_mfma_f32_16x16x32_bf16 v[70:73], v[142:145], v[240:243], 0
	v_mfma_f32_16x16x32_bf16 v[70:73], v[154:157], v[244:247], v[70:73]
	s_barrier
	s_setprio 0
	v_add_u32_e32 v141, 0x18000, v139
	ds_read_b128 v[142:145], v141
	ds_read_b128 v[154:157], v141 offset:1024
	ds_read_b128 v[170:173], v141 offset:2048
	ds_read_b128 v[174:177], v141 offset:3072
	v_add_u32_e32 v141, 0x1c000, v139
	ds_read_b128 v[178:181], v141
	ds_read_b128 v[182:185], v141 offset:1024
	ds_read_b128 v[186:189], v141 offset:2048
	ds_read_b128 v[190:193], v141 offset:3072
	s_add_i32 s52, s52, 0x80000
	s_mov_b32 m0, s31
	ds_read_b128 v[194:197], v140 offset:32768
	ds_read_b128 v[198:201], v140 offset:33792
	ds_read_b128 v[202:205], v140 offset:34816
	ds_read_b128 v[228:231], v140 offset:35840
	ds_read_b128 v[232:235], v140 offset:36864
	ds_read_b128 v[236:239], v140 offset:37888
	ds_read_b128 v[240:243], v140 offset:38912
	ds_read_b128 v[244:247], v140 offset:39936
	buffer_load_dwordx4 v131, s[60:63], s52 offen lds
	s_mov_b32 m0, s33
	s_nop 0
	buffer_load_dwordx4 v135, s[60:63], s52 offen lds
	s_waitcnt vmcnt(8)
	s_waitcnt lgkmcnt(0)
	s_setprio 1
	s_barrier
	v_mfma_f32_16x16x32_bf16 v[126:129], v[142:145], v[194:197], v[126:129]
	v_mfma_f32_16x16x32_bf16 v[126:129], v[154:157], v[198:201], v[126:129]
	v_mfma_f32_16x16x32_bf16 v[122:125], v[170:173], v[194:197], v[122:125]
	v_mfma_f32_16x16x32_bf16 v[122:125], v[174:177], v[198:201], v[122:125]
	v_mfma_f32_16x16x32_bf16 v[58:61], v[186:189], v[194:197], v[58:61]
	v_mfma_f32_16x16x32_bf16 v[58:61], v[190:193], v[198:201], v[58:61]
	v_mfma_f32_16x16x32_bf16 v[62:65], v[178:181], v[194:197], v[62:65]
	v_mfma_f32_16x16x32_bf16 v[62:65], v[182:185], v[198:201], v[62:65]
	v_mfma_f32_16x16x32_bf16 v[54:57], v[178:181], v[202:205], v[54:57]
	v_mfma_f32_16x16x32_bf16 v[54:57], v[182:185], v[228:231], v[54:57]
	v_mfma_f32_16x16x32_bf16 v[50:53], v[186:189], v[202:205], v[50:53]
	v_mfma_f32_16x16x32_bf16 v[50:53], v[190:193], v[228:231], v[50:53]
	v_mfma_f32_16x16x32_bf16 v[114:117], v[170:173], v[202:205], v[114:117]
	v_mfma_f32_16x16x32_bf16 v[114:117], v[174:177], v[228:231], v[114:117]
	v_mfma_f32_16x16x32_bf16 v[118:121], v[142:145], v[202:205], v[118:121]
	v_mfma_f32_16x16x32_bf16 v[118:121], v[154:157], v[228:231], v[118:121]
	v_mfma_f32_16x16x32_bf16 v[110:113], v[142:145], v[232:235], v[110:113]
	v_mfma_f32_16x16x32_bf16 v[110:113], v[154:157], v[236:239], v[110:113]
	v_mfma_f32_16x16x32_bf16 v[106:109], v[170:173], v[232:235], v[106:109]
	v_mfma_f32_16x16x32_bf16 v[106:109], v[174:177], v[236:239], v[106:109]
	v_mfma_f32_16x16x32_bf16 v[42:45], v[186:189], v[232:235], v[42:45]
	v_mfma_f32_16x16x32_bf16 v[42:45], v[190:193], v[236:239], v[42:45]
	v_mfma_f32_16x16x32_bf16 v[46:49], v[178:181], v[232:235], v[46:49]
	v_mfma_f32_16x16x32_bf16 v[46:49], v[182:185], v[236:239], v[46:49]
	v_mfma_f32_16x16x32_bf16 v[38:41], v[178:181], v[240:243], v[38:41]
	v_mfma_f32_16x16x32_bf16 v[38:41], v[182:185], v[244:247], v[38:41]
	v_mfma_f32_16x16x32_bf16 v[34:37], v[186:189], v[240:243], v[34:37]
	v_mfma_f32_16x16x32_bf16 v[34:37], v[190:193], v[244:247], v[34:37]
	v_mfma_f32_16x16x32_bf16 v[98:101], v[170:173], v[240:243], v[98:101]
	v_mfma_f32_16x16x32_bf16 v[98:101], v[174:177], v[244:247], v[98:101]
	v_mfma_f32_16x16x32_bf16 v[102:105], v[142:145], v[240:243], v[102:105]
	v_mfma_f32_16x16x32_bf16 v[102:105], v[154:157], v[244:247], v[102:105]
	s_barrier
	s_setprio 0
	s_mov_b32 m0, s34
	s_or_b32 s52, s85, 0x80
	ds_read_b128 v[194:197], v140 offset:49152
	ds_read_b128 v[198:201], v140 offset:50176
	ds_read_b128 v[202:205], v140 offset:51200
	ds_read_b128 v[228:231], v140 offset:52224
	ds_read_b128 v[232:235], v140 offset:53248
	ds_read_b128 v[236:239], v140 offset:54272
	ds_read_b128 v[240:243], v140 offset:55296
	ds_read_b128 v[244:247], v140 offset:56320
	buffer_load_dwordx4 v134, s[68:71], s52 offen lds
	s_mov_b32 m0, s35
	s_add_i32 s85, s85, 0x80080
	buffer_load_dwordx4 v136, s[68:71], s52 offen lds
	s_mov_b32 m0, s37
	s_nop 0
	buffer_load_dwordx4 v134, s[68:71], s85 offen lds
	s_mov_b32 m0, s65
	s_nop 0
	buffer_load_dwordx4 v136, s[68:71], s85 offen lds
	s_mov_b32 m0, s14
	s_nop 0
	buffer_load_dwordx4 v131, s[60:63], s84 offen lds
	s_mov_b32 m0, s36
	s_nop 0
	buffer_load_dwordx4 v135, s[60:63], s84 offen lds
	s_waitcnt vmcnt(8)
	s_waitcnt lgkmcnt(0)
	s_setprio 1
	s_barrier
	v_mfma_f32_16x16x32_bf16 v[94:97], v[142:145], v[194:197], v[94:97]
	v_mfma_f32_16x16x32_bf16 v[94:97], v[154:157], v[198:201], v[94:97]
	v_mfma_f32_16x16x32_bf16 v[90:93], v[170:173], v[194:197], v[90:93]
	v_mfma_f32_16x16x32_bf16 v[90:93], v[174:177], v[198:201], v[90:93]
	v_mfma_f32_16x16x32_bf16 v[26:29], v[186:189], v[194:197], v[26:29]
	v_mfma_f32_16x16x32_bf16 v[26:29], v[190:193], v[198:201], v[26:29]
	v_mfma_f32_16x16x32_bf16 v[30:33], v[178:181], v[194:197], v[30:33]
	v_mfma_f32_16x16x32_bf16 v[30:33], v[182:185], v[198:201], v[30:33]
	v_mfma_f32_16x16x32_bf16 v[22:25], v[178:181], v[202:205], v[22:25]
	v_mfma_f32_16x16x32_bf16 v[22:25], v[182:185], v[228:231], v[22:25]
	v_mfma_f32_16x16x32_bf16 v[18:21], v[186:189], v[202:205], v[18:21]
	v_mfma_f32_16x16x32_bf16 v[18:21], v[190:193], v[228:231], v[18:21]
	v_mfma_f32_16x16x32_bf16 v[82:85], v[170:173], v[202:205], v[82:85]
	v_mfma_f32_16x16x32_bf16 v[82:85], v[174:177], v[228:231], v[82:85]
	v_mfma_f32_16x16x32_bf16 v[86:89], v[142:145], v[202:205], v[86:89]
	v_mfma_f32_16x16x32_bf16 v[86:89], v[154:157], v[228:231], v[86:89]
	v_mfma_f32_16x16x32_bf16 v[78:81], v[142:145], v[232:235], v[78:81]
	v_mfma_f32_16x16x32_bf16 v[78:81], v[154:157], v[236:239], v[78:81]
	v_mfma_f32_16x16x32_bf16 v[74:77], v[170:173], v[232:235], v[74:77]
	v_mfma_f32_16x16x32_bf16 v[74:77], v[174:177], v[236:239], v[74:77]
	v_mfma_f32_16x16x32_bf16 v[10:13], v[186:189], v[232:235], v[10:13]
	v_mfma_f32_16x16x32_bf16 v[10:13], v[190:193], v[236:239], v[10:13]
	v_mfma_f32_16x16x32_bf16 v[14:17], v[178:181], v[232:235], v[14:17]
	v_mfma_f32_16x16x32_bf16 v[14:17], v[182:185], v[236:239], v[14:17]
	v_mfma_f32_16x16x32_bf16 v[6:9], v[178:181], v[240:243], v[6:9]
	v_mfma_f32_16x16x32_bf16 v[6:9], v[182:185], v[244:247], v[6:9]
	v_mfma_f32_16x16x32_bf16 v[2:5], v[186:189], v[240:243], v[2:5]
	v_mfma_f32_16x16x32_bf16 v[2:5], v[190:193], v[244:247], v[2:5]
	v_mfma_f32_16x16x32_bf16 v[66:69], v[170:173], v[240:243], v[66:69]
	v_mfma_f32_16x16x32_bf16 v[66:69], v[174:177], v[244:247], v[66:69]
	v_mfma_f32_16x16x32_bf16 v[70:73], v[142:145], v[240:243], v[70:73]
	v_mfma_f32_16x16x32_bf16 v[70:73], v[154:157], v[244:247], v[70:73]
	s_barrier
	s_setprio 0
	s_add_i32 s83, s83, 2
	s_addk_i32 s26, 0x100
	s_addk_i32 s27, 0x100
	s_cmp_gt_u32 s83, 29
.LBB0_1253:
	v_add_u32_e32 v141, 0x10000, v139
	ds_read_b128 v[142:145], v141
	ds_read_b128 v[154:157], v141 offset:1024
	ds_read_b128 v[170:173], v141 offset:2048
	ds_read_b128 v[174:177], v141 offset:3072
	v_add_u32_e32 v141, 0x14000, v139
	ds_read_b128 v[178:181], v141
	ds_read_b128 v[182:185], v141 offset:1024
	ds_read_b128 v[186:189], v141 offset:2048
	ds_read_b128 v[190:193], v141 offset:3072
	s_add_i32 s52, s26, 0xfff80080
	s_cmp_eq_u32 s83, 28
	s_cselect_b32 s52, s8, s52
	s_cselect_b32 s85, s9, s27
	s_or_b32 s84, s52, 0x80
	s_mov_b32 m0, s72
	ds_read_b128 v[194:197], v140
	ds_read_b128 v[198:201], v140 offset:1024
	ds_read_b128 v[202:205], v140 offset:2048
	ds_read_b128 v[228:231], v140 offset:3072
	ds_read_b128 v[232:235], v140 offset:4096
	ds_read_b128 v[236:239], v140 offset:5120
	ds_read_b128 v[240:243], v140 offset:6144
	ds_read_b128 v[244:247], v140 offset:7168
	buffer_load_dwordx4 v131, s[60:63], s26 offen lds
	s_mov_b32 m0, s46
	s_nop 0
	buffer_load_dwordx4 v135, s[60:63], s26 offen lds
	s_waitcnt vmcnt(8)
	s_waitcnt lgkmcnt(0)
	s_setprio 1
	s_barrier
	v_mfma_f32_16x16x32_bf16 v[126:129], v[142:145], v[194:197], v[126:129]
	v_mfma_f32_16x16x32_bf16 v[126:129], v[154:157], v[198:201], v[126:129]
	v_mfma_f32_16x16x32_bf16 v[122:125], v[170:173], v[194:197], v[122:125]
	v_mfma_f32_16x16x32_bf16 v[122:125], v[174:177], v[198:201], v[122:125]
	v_mfma_f32_16x16x32_bf16 v[58:61], v[186:189], v[194:197], v[58:61]
	v_mfma_f32_16x16x32_bf16 v[58:61], v[190:193], v[198:201], v[58:61]
	v_mfma_f32_16x16x32_bf16 v[62:65], v[178:181], v[194:197], v[62:65]
	v_mfma_f32_16x16x32_bf16 v[62:65], v[182:185], v[198:201], v[62:65]
	v_mfma_f32_16x16x32_bf16 v[54:57], v[178:181], v[202:205], v[54:57]
	v_mfma_f32_16x16x32_bf16 v[54:57], v[182:185], v[228:231], v[54:57]
	v_mfma_f32_16x16x32_bf16 v[50:53], v[186:189], v[202:205], v[50:53]
	v_mfma_f32_16x16x32_bf16 v[50:53], v[190:193], v[228:231], v[50:53]
	v_mfma_f32_16x16x32_bf16 v[114:117], v[170:173], v[202:205], v[114:117]
	v_mfma_f32_16x16x32_bf16 v[114:117], v[174:177], v[228:231], v[114:117]
	v_mfma_f32_16x16x32_bf16 v[118:121], v[142:145], v[202:205], v[118:121]
	v_mfma_f32_16x16x32_bf16 v[118:121], v[154:157], v[228:231], v[118:121]
	v_mfma_f32_16x16x32_bf16 v[110:113], v[142:145], v[232:235], v[110:113]
	v_mfma_f32_16x16x32_bf16 v[110:113], v[154:157], v[236:239], v[110:113]
	v_mfma_f32_16x16x32_bf16 v[106:109], v[170:173], v[232:235], v[106:109]
	v_mfma_f32_16x16x32_bf16 v[106:109], v[174:177], v[236:239], v[106:109]
	v_mfma_f32_16x16x32_bf16 v[42:45], v[186:189], v[232:235], v[42:45]
	v_mfma_f32_16x16x32_bf16 v[42:45], v[190:193], v[236:239], v[42:45]
	v_mfma_f32_16x16x32_bf16 v[46:49], v[178:181], v[232:235], v[46:49]
	v_mfma_f32_16x16x32_bf16 v[46:49], v[182:185], v[236:239], v[46:49]
	v_mfma_f32_16x16x32_bf16 v[38:41], v[178:181], v[240:243], v[38:41]
	v_mfma_f32_16x16x32_bf16 v[38:41], v[182:185], v[244:247], v[38:41]
	v_mfma_f32_16x16x32_bf16 v[34:37], v[186:189], v[240:243], v[34:37]
	v_mfma_f32_16x16x32_bf16 v[34:37], v[190:193], v[244:247], v[34:37]
	v_mfma_f32_16x16x32_bf16 v[98:101], v[170:173], v[240:243], v[98:101]
	v_mfma_f32_16x16x32_bf16 v[98:101], v[174:177], v[244:247], v[98:101]
	v_mfma_f32_16x16x32_bf16 v[102:105], v[142:145], v[240:243], v[102:105]
	v_mfma_f32_16x16x32_bf16 v[102:105], v[154:157], v[244:247], v[102:105]
	s_barrier
	s_setprio 0
	s_mov_b32 m0, s21
	s_mov_b32 s70, s62
	s_mov_b32 s71, s63
	ds_read_b128 v[194:197], v140 offset:16384
	ds_read_b128 v[198:201], v140 offset:17408
	ds_read_b128 v[202:205], v140 offset:18432
	ds_read_b128 v[228:231], v140 offset:19456
	ds_read_b128 v[232:235], v140 offset:20480
	ds_read_b128 v[236:239], v140 offset:21504
	ds_read_b128 v[240:243], v140 offset:22528
	ds_read_b128 v[244:247], v140 offset:23552
	buffer_load_dwordx4 v134, s[68:71], s85 offen lds
	s_mov_b32 m0, s23
	s_add_i32 s53, s85, 0x80000
	buffer_load_dwordx4 v136, s[68:71], s85 offen lds
	s_mov_b32 m0, s24
	s_nop 0
	buffer_load_dwordx4 v134, s[68:71], s53 offen lds
	s_mov_b32 m0, s25
	s_nop 0
	buffer_load_dwordx4 v136, s[68:71], s53 offen lds
	s_mov_b32 m0, s16
	s_nop 0
	buffer_load_dwordx4 v131, s[60:63], s52 offen lds
	s_mov_b32 m0, s30
	s_nop 0
	buffer_load_dwordx4 v135, s[60:63], s52 offen lds
	s_waitcnt vmcnt(8)
	s_waitcnt lgkmcnt(0)
	s_setprio 1
	s_barrier
	v_mfma_f32_16x16x32_bf16 v[94:97], v[142:145], v[194:197], v[94:97]
	v_mfma_f32_16x16x32_bf16 v[94:97], v[154:157], v[198:201], v[94:97]
	v_mfma_f32_16x16x32_bf16 v[90:93], v[170:173], v[194:197], v[90:93]
	v_mfma_f32_16x16x32_bf16 v[90:93], v[174:177], v[198:201], v[90:93]
	v_mfma_f32_16x16x32_bf16 v[26:29], v[186:189], v[194:197], v[26:29]
	v_mfma_f32_16x16x32_bf16 v[26:29], v[190:193], v[198:201], v[26:29]
	v_mfma_f32_16x16x32_bf16 v[30:33], v[178:181], v[194:197], v[30:33]
	v_mfma_f32_16x16x32_bf16 v[30:33], v[182:185], v[198:201], v[30:33]
	v_mfma_f32_16x16x32_bf16 v[22:25], v[178:181], v[202:205], v[22:25]
	v_mfma_f32_16x16x32_bf16 v[22:25], v[182:185], v[228:231], v[22:25]
	v_mfma_f32_16x16x32_bf16 v[18:21], v[186:189], v[202:205], v[18:21]
	v_mfma_f32_16x16x32_bf16 v[18:21], v[190:193], v[228:231], v[18:21]
	v_mfma_f32_16x16x32_bf16 v[82:85], v[170:173], v[202:205], v[82:85]
	v_mfma_f32_16x16x32_bf16 v[82:85], v[174:177], v[228:231], v[82:85]
	v_mfma_f32_16x16x32_bf16 v[86:89], v[142:145], v[202:205], v[86:89]
	v_mfma_f32_16x16x32_bf16 v[86:89], v[154:157], v[228:231], v[86:89]
	v_mfma_f32_16x16x32_bf16 v[78:81], v[142:145], v[232:235], v[78:81]
	v_mfma_f32_16x16x32_bf16 v[78:81], v[154:157], v[236:239], v[78:81]
	v_mfma_f32_16x16x32_bf16 v[74:77], v[170:173], v[232:235], v[74:77]
	v_mfma_f32_16x16x32_bf16 v[74:77], v[174:177], v[236:239], v[74:77]
	v_mfma_f32_16x16x32_bf16 v[10:13], v[186:189], v[232:235], v[10:13]
	v_mfma_f32_16x16x32_bf16 v[10:13], v[190:193], v[236:239], v[10:13]
	v_mfma_f32_16x16x32_bf16 v[14:17], v[178:181], v[232:235], v[14:17]
	v_mfma_f32_16x16x32_bf16 v[14:17], v[182:185], v[236:239], v[14:17]
	v_mfma_f32_16x16x32_bf16 v[6:9], v[178:181], v[240:243], v[6:9]
	v_mfma_f32_16x16x32_bf16 v[6:9], v[182:185], v[244:247], v[6:9]
	v_mfma_f32_16x16x32_bf16 v[2:5], v[186:189], v[240:243], v[2:5]
	v_mfma_f32_16x16x32_bf16 v[2:5], v[190:193], v[244:247], v[2:5]
	v_mfma_f32_16x16x32_bf16 v[66:69], v[170:173], v[240:243], v[66:69]
	v_mfma_f32_16x16x32_bf16 v[66:69], v[174:177], v[244:247], v[66:69]
	v_mfma_f32_16x16x32_bf16 v[70:73], v[142:145], v[240:243], v[70:73]
	v_mfma_f32_16x16x32_bf16 v[70:73], v[154:157], v[244:247], v[70:73]
	s_barrier
	s_setprio 0
	v_add_u32_e32 v141, 0x18000, v139
	ds_read_b128 v[142:145], v141
	ds_read_b128 v[154:157], v141 offset:1024
	ds_read_b128 v[170:173], v141 offset:2048
	ds_read_b128 v[174:177], v141 offset:3072
	v_add_u32_e32 v141, 0x1c000, v139
	ds_read_b128 v[178:181], v141
	ds_read_b128 v[182:185], v141 offset:1024
	ds_read_b128 v[186:189], v141 offset:2048
	ds_read_b128 v[190:193], v141 offset:3072
	s_add_i32 s52, s52, 0x80000
	s_mov_b32 m0, s31
	ds_read_b128 v[194:197], v140 offset:32768
	ds_read_b128 v[198:201], v140 offset:33792
	ds_read_b128 v[202:205], v140 offset:34816
	ds_read_b128 v[228:231], v140 offset:35840
	ds_read_b128 v[232:235], v140 offset:36864
	ds_read_b128 v[236:239], v140 offset:37888
	ds_read_b128 v[240:243], v140 offset:38912
	ds_read_b128 v[244:247], v140 offset:39936
	buffer_load_dwordx4 v131, s[60:63], s52 offen lds
	s_mov_b32 m0, s33
	s_nop 0
	buffer_load_dwordx4 v135, s[60:63], s52 offen lds
	s_waitcnt vmcnt(8)
	s_waitcnt lgkmcnt(0)
	s_setprio 1
	s_barrier
	v_mfma_f32_16x16x32_bf16 v[126:129], v[142:145], v[194:197], v[126:129]
	v_mfma_f32_16x16x32_bf16 v[126:129], v[154:157], v[198:201], v[126:129]
	v_mfma_f32_16x16x32_bf16 v[122:125], v[170:173], v[194:197], v[122:125]
	v_mfma_f32_16x16x32_bf16 v[122:125], v[174:177], v[198:201], v[122:125]
	v_mfma_f32_16x16x32_bf16 v[58:61], v[186:189], v[194:197], v[58:61]
	v_mfma_f32_16x16x32_bf16 v[58:61], v[190:193], v[198:201], v[58:61]
	v_mfma_f32_16x16x32_bf16 v[62:65], v[178:181], v[194:197], v[62:65]
	v_mfma_f32_16x16x32_bf16 v[62:65], v[182:185], v[198:201], v[62:65]
	v_mfma_f32_16x16x32_bf16 v[54:57], v[178:181], v[202:205], v[54:57]
	v_mfma_f32_16x16x32_bf16 v[54:57], v[182:185], v[228:231], v[54:57]
	v_mfma_f32_16x16x32_bf16 v[50:53], v[186:189], v[202:205], v[50:53]
	v_mfma_f32_16x16x32_bf16 v[50:53], v[190:193], v[228:231], v[50:53]
	v_mfma_f32_16x16x32_bf16 v[114:117], v[170:173], v[202:205], v[114:117]
	v_mfma_f32_16x16x32_bf16 v[114:117], v[174:177], v[228:231], v[114:117]
	v_mfma_f32_16x16x32_bf16 v[118:121], v[142:145], v[202:205], v[118:121]
	v_mfma_f32_16x16x32_bf16 v[118:121], v[154:157], v[228:231], v[118:121]
	v_mfma_f32_16x16x32_bf16 v[110:113], v[142:145], v[232:235], v[110:113]
	v_mfma_f32_16x16x32_bf16 v[110:113], v[154:157], v[236:239], v[110:113]
	v_mfma_f32_16x16x32_bf16 v[106:109], v[170:173], v[232:235], v[106:109]
	v_mfma_f32_16x16x32_bf16 v[106:109], v[174:177], v[236:239], v[106:109]
	v_mfma_f32_16x16x32_bf16 v[42:45], v[186:189], v[232:235], v[42:45]
	v_mfma_f32_16x16x32_bf16 v[42:45], v[190:193], v[236:239], v[42:45]
	v_mfma_f32_16x16x32_bf16 v[46:49], v[178:181], v[232:235], v[46:49]
	v_mfma_f32_16x16x32_bf16 v[46:49], v[182:185], v[236:239], v[46:49]
	v_mfma_f32_16x16x32_bf16 v[38:41], v[178:181], v[240:243], v[38:41]
	v_mfma_f32_16x16x32_bf16 v[38:41], v[182:185], v[244:247], v[38:41]
	v_mfma_f32_16x16x32_bf16 v[34:37], v[186:189], v[240:243], v[34:37]
	v_mfma_f32_16x16x32_bf16 v[34:37], v[190:193], v[244:247], v[34:37]
	v_mfma_f32_16x16x32_bf16 v[98:101], v[170:173], v[240:243], v[98:101]
	v_mfma_f32_16x16x32_bf16 v[98:101], v[174:177], v[244:247], v[98:101]
	v_mfma_f32_16x16x32_bf16 v[102:105], v[142:145], v[240:243], v[102:105]
	v_mfma_f32_16x16x32_bf16 v[102:105], v[154:157], v[244:247], v[102:105]
	s_barrier
	s_setprio 0
	s_mov_b32 m0, s34
	s_or_b32 s52, s85, 0x80
	ds_read_b128 v[194:197], v140 offset:49152
	ds_read_b128 v[198:201], v140 offset:50176
	ds_read_b128 v[202:205], v140 offset:51200
	ds_read_b128 v[228:231], v140 offset:52224
	ds_read_b128 v[232:235], v140 offset:53248
	ds_read_b128 v[236:239], v140 offset:54272
	ds_read_b128 v[240:243], v140 offset:55296
	ds_read_b128 v[244:247], v140 offset:56320
	buffer_load_dwordx4 v134, s[68:71], s52 offen lds
	s_mov_b32 m0, s35
	s_add_i32 s85, s85, 0x80080
	buffer_load_dwordx4 v136, s[68:71], s52 offen lds
	s_mov_b32 m0, s37
	s_nop 0
	buffer_load_dwordx4 v134, s[68:71], s85 offen lds
	s_mov_b32 m0, s65
	s_nop 0
	buffer_load_dwordx4 v136, s[68:71], s85 offen lds
	s_mov_b32 m0, s14
	s_nop 0
	buffer_load_dwordx4 v131, s[60:63], s84 offen lds
	s_mov_b32 m0, s36
	s_nop 0
	buffer_load_dwordx4 v135, s[60:63], s84 offen lds
	s_waitcnt vmcnt(8)
	s_waitcnt lgkmcnt(0)
	s_setprio 1
	s_barrier
	v_mfma_f32_16x16x32_bf16 v[94:97], v[142:145], v[194:197], v[94:97]
	v_mfma_f32_16x16x32_bf16 v[94:97], v[154:157], v[198:201], v[94:97]
	v_mfma_f32_16x16x32_bf16 v[90:93], v[170:173], v[194:197], v[90:93]
	v_mfma_f32_16x16x32_bf16 v[90:93], v[174:177], v[198:201], v[90:93]
	v_mfma_f32_16x16x32_bf16 v[26:29], v[186:189], v[194:197], v[26:29]
	v_mfma_f32_16x16x32_bf16 v[26:29], v[190:193], v[198:201], v[26:29]
	v_mfma_f32_16x16x32_bf16 v[30:33], v[178:181], v[194:197], v[30:33]
	v_mfma_f32_16x16x32_bf16 v[30:33], v[182:185], v[198:201], v[30:33]
	v_mfma_f32_16x16x32_bf16 v[22:25], v[178:181], v[202:205], v[22:25]
	v_mfma_f32_16x16x32_bf16 v[22:25], v[182:185], v[228:231], v[22:25]
	v_mfma_f32_16x16x32_bf16 v[18:21], v[186:189], v[202:205], v[18:21]
	v_mfma_f32_16x16x32_bf16 v[18:21], v[190:193], v[228:231], v[18:21]
	v_mfma_f32_16x16x32_bf16 v[82:85], v[170:173], v[202:205], v[82:85]
	v_mfma_f32_16x16x32_bf16 v[82:85], v[174:177], v[228:231], v[82:85]
	v_mfma_f32_16x16x32_bf16 v[86:89], v[142:145], v[202:205], v[86:89]
	v_mfma_f32_16x16x32_bf16 v[86:89], v[154:157], v[228:231], v[86:89]
	v_mfma_f32_16x16x32_bf16 v[78:81], v[142:145], v[232:235], v[78:81]
	v_mfma_f32_16x16x32_bf16 v[78:81], v[154:157], v[236:239], v[78:81]
	v_mfma_f32_16x16x32_bf16 v[74:77], v[170:173], v[232:235], v[74:77]
	v_mfma_f32_16x16x32_bf16 v[74:77], v[174:177], v[236:239], v[74:77]
	v_mfma_f32_16x16x32_bf16 v[10:13], v[186:189], v[232:235], v[10:13]
	v_mfma_f32_16x16x32_bf16 v[10:13], v[190:193], v[236:239], v[10:13]
	v_mfma_f32_16x16x32_bf16 v[14:17], v[178:181], v[232:235], v[14:17]
	v_mfma_f32_16x16x32_bf16 v[14:17], v[182:185], v[236:239], v[14:17]
	v_mfma_f32_16x16x32_bf16 v[6:9], v[178:181], v[240:243], v[6:9]
	v_mfma_f32_16x16x32_bf16 v[6:9], v[182:185], v[244:247], v[6:9]
	v_mfma_f32_16x16x32_bf16 v[2:5], v[186:189], v[240:243], v[2:5]
	v_mfma_f32_16x16x32_bf16 v[2:5], v[190:193], v[244:247], v[2:5]
	v_mfma_f32_16x16x32_bf16 v[66:69], v[170:173], v[240:243], v[66:69]
	v_mfma_f32_16x16x32_bf16 v[66:69], v[174:177], v[244:247], v[66:69]
	v_mfma_f32_16x16x32_bf16 v[70:73], v[142:145], v[240:243], v[70:73]
	v_mfma_f32_16x16x32_bf16 v[70:73], v[154:157], v[244:247], v[70:73]
	s_barrier
	s_setprio 0
	s_add_i32 s83, s83, 2
	s_addk_i32 s26, 0x100
	s_addk_i32 s27, 0x100
	s_cmp_gt_u32 s83, 29
	s_cbranch_scc0 .LBB0_1253
	s_and_b64 vcc, exec, s[44:45]
	s_cbranch_vccz .LBB0_1256
	s_barrier

.LBB0_1282:
	s_lshl_b32 s46, s85, 20
	s_and_b64 s[8:9], s[40:41], exec
	s_cselect_b32 s8, s46, s19
	s_lshl_b32 s47, s14, 20
	s_and_b64 s[26:27], s[40:41], exec
	s_cselect_b32 s9, s47, s22
	s_add_i32 s19, s19, 0x80080
	s_addk_i32 s22, 0x100
	s_mov_b32 s26, -2
	v_add_u32_e32 v141, 0x10000, v139
	ds_read_b128 v[142:145], v141
	ds_read_b128 v[154:157], v141 offset:1024
	ds_read_b128 v[170:173], v141 offset:2048
	ds_read_b128 v[174:177], v141 offset:3072
	v_add_u32_e32 v141, 0x14000, v139
	ds_read_b128 v[178:181], v141
	ds_read_b128 v[182:185], v141 offset:1024
	ds_read_b128 v[186:189], v141 offset:2048
	ds_read_b128 v[190:193], v141 offset:3072
	s_add_i32 s27, s19, 0xfff80080
	s_cmp_eq_u32 s26, 28
	s_cselect_b32 s52, s8, s27
	s_cselect_b32 s83, s9, s22
	s_or_b32 s27, s52, 0x80
	s_mov_b32 m0, s73
	ds_read_b128 v[194:197], v140
	ds_read_b128 v[198:201], v140 offset:1024
	ds_read_b128 v[202:205], v140 offset:2048
	ds_read_b128 v[228:231], v140 offset:3072
	ds_read_b128 v[232:235], v140 offset:4096
	ds_read_b128 v[236:239], v140 offset:5120
	ds_read_b128 v[240:243], v140 offset:6144
	ds_read_b128 v[244:247], v140 offset:7168
	buffer_load_dwordx4 v131, s[60:63], s19 offen lds
	s_mov_b32 m0, s82
	s_nop 0
	buffer_load_dwordx4 v135, s[60:63], s19 offen lds
	s_waitcnt vmcnt(8)
	s_waitcnt lgkmcnt(0)
	s_setprio 1
	s_barrier
	v_mfma_f32_16x16x32_bf16 v[126:129], v[142:145], v[194:197], 0
	v_mfma_f32_16x16x32_bf16 v[126:129], v[154:157], v[198:201], v[126:129]
	v_mfma_f32_16x16x32_bf16 v[122:125], v[170:173], v[194:197], 0
	v_mfma_f32_16x16x32_bf16 v[122:125], v[174:177], v[198:201], v[122:125]
	v_mfma_f32_16x16x32_bf16 v[58:61], v[186:189], v[194:197], 0
	v_mfma_f32_16x16x32_bf16 v[58:61], v[190:193], v[198:201], v[58:61]
	v_mfma_f32_16x16x32_bf16 v[62:65], v[178:181], v[194:197], 0
	v_mfma_f32_16x16x32_bf16 v[62:65], v[182:185], v[198:201], v[62:65]
	v_mfma_f32_16x16x32_bf16 v[54:57], v[178:181], v[202:205], 0
	v_mfma_f32_16x16x32_bf16 v[54:57], v[182:185], v[228:231], v[54:57]
	v_mfma_f32_16x16x32_bf16 v[50:53], v[186:189], v[202:205], 0
	v_mfma_f32_16x16x32_bf16 v[50:53], v[190:193], v[228:231], v[50:53]
	v_mfma_f32_16x16x32_bf16 v[114:117], v[170:173], v[202:205], 0
	v_mfma_f32_16x16x32_bf16 v[114:117], v[174:177], v[228:231], v[114:117]
	v_mfma_f32_16x16x32_bf16 v[118:121], v[142:145], v[202:205], 0
	v_mfma_f32_16x16x32_bf16 v[118:121], v[154:157], v[228:231], v[118:121]
	v_mfma_f32_16x16x32_bf16 v[110:113], v[142:145], v[232:235], 0
	v_mfma_f32_16x16x32_bf16 v[110:113], v[154:157], v[236:239], v[110:113]
	v_mfma_f32_16x16x32_bf16 v[106:109], v[170:173], v[232:235], 0
	v_mfma_f32_16x16x32_bf16 v[106:109], v[174:177], v[236:239], v[106:109]
	v_mfma_f32_16x16x32_bf16 v[42:45], v[186:189], v[232:235], 0
	v_mfma_f32_16x16x32_bf16 v[42:45], v[190:193], v[236:239], v[42:45]
	v_mfma_f32_16x16x32_bf16 v[46:49], v[178:181], v[232:235], 0
	v_mfma_f32_16x16x32_bf16 v[46:49], v[182:185], v[236:239], v[46:49]
	v_mfma_f32_16x16x32_bf16 v[38:41], v[178:181], v[240:243], 0
	v_mfma_f32_16x16x32_bf16 v[38:41], v[182:185], v[244:247], v[38:41]
	v_mfma_f32_16x16x32_bf16 v[34:37], v[186:189], v[240:243], 0
	v_mfma_f32_16x16x32_bf16 v[34:37], v[190:193], v[244:247], v[34:37]
	v_mfma_f32_16x16x32_bf16 v[98:101], v[170:173], v[240:243], 0
	v_mfma_f32_16x16x32_bf16 v[98:101], v[174:177], v[244:247], v[98:101]
	v_mfma_f32_16x16x32_bf16 v[102:105], v[142:145], v[240:243], 0
	v_mfma_f32_16x16x32_bf16 v[102:105], v[154:157], v[244:247], v[102:105]
	s_barrier
	s_setprio 0
	s_mov_b32 m0, s21
	s_mov_b32 s70, s62
	s_mov_b32 s71, s63
	ds_read_b128 v[194:197], v140 offset:16384
	ds_read_b128 v[198:201], v140 offset:17408
	ds_read_b128 v[202:205], v140 offset:18432
	ds_read_b128 v[228:231], v140 offset:19456
	ds_read_b128 v[232:235], v140 offset:20480
	ds_read_b128 v[236:239], v140 offset:21504
	ds_read_b128 v[240:243], v140 offset:22528
	ds_read_b128 v[244:247], v140 offset:23552
	buffer_load_dwordx4 v134, s[68:71], s83 offen lds
	s_mov_b32 m0, s23
	s_add_i32 s53, s83, 0x80000
	buffer_load_dwordx4 v136, s[68:71], s83 offen lds
	s_mov_b32 m0, s24
	s_nop 0
	buffer_load_dwordx4 v134, s[68:71], s53 offen lds
	s_mov_b32 m0, s25
	s_nop 0
	buffer_load_dwordx4 v136, s[68:71], s53 offen lds
	s_mov_b32 m0, s2
	s_nop 0
	buffer_load_dwordx4 v131, s[60:63], s52 offen lds
	s_mov_b32 m0, s30
	s_nop 0
	buffer_load_dwordx4 v135, s[60:63], s52 offen lds
	s_waitcnt vmcnt(8)
	s_waitcnt lgkmcnt(0)
	s_setprio 1
	s_barrier
	v_mfma_f32_16x16x32_bf16 v[94:97], v[142:145], v[194:197], 0
	v_mfma_f32_16x16x32_bf16 v[94:97], v[154:157], v[198:201], v[94:97]
	v_mfma_f32_16x16x32_bf16 v[90:93], v[170:173], v[194:197], 0
	v_mfma_f32_16x16x32_bf16 v[90:93], v[174:177], v[198:201], v[90:93]
	v_mfma_f32_16x16x32_bf16 v[26:29], v[186:189], v[194:197], 0
	v_mfma_f32_16x16x32_bf16 v[26:29], v[190:193], v[198:201], v[26:29]
	v_mfma_f32_16x16x32_bf16 v[30:33], v[178:181], v[194:197], 0
	v_mfma_f32_16x16x32_bf16 v[30:33], v[182:185], v[198:201], v[30:33]
	v_mfma_f32_16x16x32_bf16 v[22:25], v[178:181], v[202:205], 0
	v_mfma_f32_16x16x32_bf16 v[22:25], v[182:185], v[228:231], v[22:25]
	v_mfma_f32_16x16x32_bf16 v[18:21], v[186:189], v[202:205], 0
	v_mfma_f32_16x16x32_bf16 v[18:21], v[190:193], v[228:231], v[18:21]
	v_mfma_f32_16x16x32_bf16 v[82:85], v[170:173], v[202:205], 0
	v_mfma_f32_16x16x32_bf16 v[82:85], v[174:177], v[228:231], v[82:85]
	v_mfma_f32_16x16x32_bf16 v[86:89], v[142:145], v[202:205], 0
	v_mfma_f32_16x16x32_bf16 v[86:89], v[154:157], v[228:231], v[86:89]
	v_mfma_f32_16x16x32_bf16 v[78:81], v[142:145], v[232:235], 0
	v_mfma_f32_16x16x32_bf16 v[78:81], v[154:157], v[236:239], v[78:81]
	v_mfma_f32_16x16x32_bf16 v[74:77], v[170:173], v[232:235], 0
	v_mfma_f32_16x16x32_bf16 v[74:77], v[174:177], v[236:239], v[74:77]
	v_mfma_f32_16x16x32_bf16 v[10:13], v[186:189], v[232:235], 0
	v_mfma_f32_16x16x32_bf16 v[10:13], v[190:193], v[236:239], v[10:13]
	v_mfma_f32_16x16x32_bf16 v[14:17], v[178:181], v[232:235], 0
	v_mfma_f32_16x16x32_bf16 v[14:17], v[182:185], v[236:239], v[14:17]
	v_mfma_f32_16x16x32_bf16 v[6:9], v[178:181], v[240:243], 0
	v_mfma_f32_16x16x32_bf16 v[6:9], v[182:185], v[244:247], v[6:9]
	v_mfma_f32_16x16x32_bf16 v[2:5], v[186:189], v[240:243], 0
	v_mfma_f32_16x16x32_bf16 v[2:5], v[190:193], v[244:247], v[2:5]
	v_mfma_f32_16x16x32_bf16 v[66:69], v[170:173], v[240:243], 0
	v_mfma_f32_16x16x32_bf16 v[66:69], v[174:177], v[244:247], v[66:69]
	v_mfma_f32_16x16x32_bf16 v[70:73], v[142:145], v[240:243], 0
	v_mfma_f32_16x16x32_bf16 v[70:73], v[154:157], v[244:247], v[70:73]
	s_barrier
	s_setprio 0
	v_add_u32_e32 v141, 0x18000, v139
	ds_read_b128 v[142:145], v141
	ds_read_b128 v[154:157], v141 offset:1024
	ds_read_b128 v[170:173], v141 offset:2048
	ds_read_b128 v[174:177], v141 offset:3072
	v_add_u32_e32 v141, 0x1c000, v139
	ds_read_b128 v[178:181], v141
	ds_read_b128 v[182:185], v141 offset:1024
	ds_read_b128 v[186:189], v141 offset:2048
	ds_read_b128 v[190:193], v141 offset:3072
	s_add_i32 s52, s52, 0x80000
	s_mov_b32 m0, s31
	ds_read_b128 v[194:197], v140 offset:32768
	ds_read_b128 v[198:201], v140 offset:33792
	ds_read_b128 v[202:205], v140 offset:34816
	ds_read_b128 v[228:231], v140 offset:35840
	ds_read_b128 v[232:235], v140 offset:36864
	ds_read_b128 v[236:239], v140 offset:37888
	ds_read_b128 v[240:243], v140 offset:38912
	ds_read_b128 v[244:247], v140 offset:39936
	buffer_load_dwordx4 v131, s[60:63], s52 offen lds
	s_mov_b32 m0, s33
	s_nop 0
	buffer_load_dwordx4 v135, s[60:63], s52 offen lds
	s_waitcnt vmcnt(8)
	s_waitcnt lgkmcnt(0)
	s_setprio 1
	s_barrier
	v_mfma_f32_16x16x32_bf16 v[126:129], v[142:145], v[194:197], v[126:129]
	v_mfma_f32_16x16x32_bf16 v[126:129], v[154:157], v[198:201], v[126:129]
	v_mfma_f32_16x16x32_bf16 v[122:125], v[170:173], v[194:197], v[122:125]
	v_mfma_f32_16x16x32_bf16 v[122:125], v[174:177], v[198:201], v[122:125]
	v_mfma_f32_16x16x32_bf16 v[58:61], v[186:189], v[194:197], v[58:61]
	v_mfma_f32_16x16x32_bf16 v[58:61], v[190:193], v[198:201], v[58:61]
	v_mfma_f32_16x16x32_bf16 v[62:65], v[178:181], v[194:197], v[62:65]
	v_mfma_f32_16x16x32_bf16 v[62:65], v[182:185], v[198:201], v[62:65]
	v_mfma_f32_16x16x32_bf16 v[54:57], v[178:181], v[202:205], v[54:57]
	v_mfma_f32_16x16x32_bf16 v[54:57], v[182:185], v[228:231], v[54:57]
	v_mfma_f32_16x16x32_bf16 v[50:53], v[186:189], v[202:205], v[50:53]
	v_mfma_f32_16x16x32_bf16 v[50:53], v[190:193], v[228:231], v[50:53]
	v_mfma_f32_16x16x32_bf16 v[114:117], v[170:173], v[202:205], v[114:117]
	v_mfma_f32_16x16x32_bf16 v[114:117], v[174:177], v[228:231], v[114:117]
	v_mfma_f32_16x16x32_bf16 v[118:121], v[142:145], v[202:205], v[118:121]
	v_mfma_f32_16x16x32_bf16 v[118:121], v[154:157], v[228:231], v[118:121]
	v_mfma_f32_16x16x32_bf16 v[110:113], v[142:145], v[232:235], v[110:113]
	v_mfma_f32_16x16x32_bf16 v[110:113], v[154:157], v[236:239], v[110:113]
	v_mfma_f32_16x16x32_bf16 v[106:109], v[170:173], v[232:235], v[106:109]
	v_mfma_f32_16x16x32_bf16 v[106:109], v[174:177], v[236:239], v[106:109]
	v_mfma_f32_16x16x32_bf16 v[42:45], v[186:189], v[232:235], v[42:45]
	v_mfma_f32_16x16x32_bf16 v[42:45], v[190:193], v[236:239], v[42:45]
	v_mfma_f32_16x16x32_bf16 v[46:49], v[178:181], v[232:235], v[46:49]
	v_mfma_f32_16x16x32_bf16 v[46:49], v[182:185], v[236:239], v[46:49]
	v_mfma_f32_16x16x32_bf16 v[38:41], v[178:181], v[240:243], v[38:41]
	v_mfma_f32_16x16x32_bf16 v[38:41], v[182:185], v[244:247], v[38:41]
	v_mfma_f32_16x16x32_bf16 v[34:37], v[186:189], v[240:243], v[34:37]
	v_mfma_f32_16x16x32_bf16 v[34:37], v[190:193], v[244:247], v[34:37]
	v_mfma_f32_16x16x32_bf16 v[98:101], v[170:173], v[240:243], v[98:101]
	v_mfma_f32_16x16x32_bf16 v[98:101], v[174:177], v[244:247], v[98:101]
	v_mfma_f32_16x16x32_bf16 v[102:105], v[142:145], v[240:243], v[102:105]
	v_mfma_f32_16x16x32_bf16 v[102:105], v[154:157], v[244:247], v[102:105]
	s_barrier
	s_setprio 0
	s_mov_b32 m0, s34
	s_or_b32 s52, s83, 0x80
	ds_read_b128 v[194:197], v140 offset:49152
	ds_read_b128 v[198:201], v140 offset:50176
	ds_read_b128 v[202:205], v140 offset:51200
	ds_read_b128 v[228:231], v140 offset:52224
	ds_read_b128 v[232:235], v140 offset:53248
	ds_read_b128 v[236:239], v140 offset:54272
	ds_read_b128 v[240:243], v140 offset:55296
	ds_read_b128 v[244:247], v140 offset:56320
	buffer_load_dwordx4 v134, s[68:71], s52 offen lds
	s_mov_b32 m0, s35
	s_add_i32 s83, s83, 0x80080
	buffer_load_dwordx4 v136, s[68:71], s52 offen lds
	s_mov_b32 m0, s65
	s_nop 0
	buffer_load_dwordx4 v134, s[68:71], s83 offen lds
	s_mov_b32 m0, s66
	s_nop 0
	buffer_load_dwordx4 v136, s[68:71], s83 offen lds
	s_mov_b32 m0, s36
	s_nop 0
	buffer_load_dwordx4 v131, s[60:63], s27 offen lds
	s_mov_b32 m0, s37
	s_nop 0
	buffer_load_dwordx4 v135, s[60:63], s27 offen lds
	s_waitcnt vmcnt(8)
	s_waitcnt lgkmcnt(0)
	s_setprio 1
	s_barrier
	v_mfma_f32_16x16x32_bf16 v[94:97], v[142:145], v[194:197], v[94:97]
	v_mfma_f32_16x16x32_bf16 v[94:97], v[154:157], v[198:201], v[94:97]
	v_mfma_f32_16x16x32_bf16 v[90:93], v[170:173], v[194:197], v[90:93]
	v_mfma_f32_16x16x32_bf16 v[90:93], v[174:177], v[198:201], v[90:93]
	v_mfma_f32_16x16x32_bf16 v[26:29], v[186:189], v[194:197], v[26:29]
	v_mfma_f32_16x16x32_bf16 v[26:29], v[190:193], v[198:201], v[26:29]
	v_mfma_f32_16x16x32_bf16 v[30:33], v[178:181], v[194:197], v[30:33]
	v_mfma_f32_16x16x32_bf16 v[30:33], v[182:185], v[198:201], v[30:33]
	v_mfma_f32_16x16x32_bf16 v[22:25], v[178:181], v[202:205], v[22:25]
	v_mfma_f32_16x16x32_bf16 v[22:25], v[182:185], v[228:231], v[22:25]
	v_mfma_f32_16x16x32_bf16 v[18:21], v[186:189], v[202:205], v[18:21]
	v_mfma_f32_16x16x32_bf16 v[18:21], v[190:193], v[228:231], v[18:21]
	v_mfma_f32_16x16x32_bf16 v[82:85], v[170:173], v[202:205], v[82:85]
	v_mfma_f32_16x16x32_bf16 v[82:85], v[174:177], v[228:231], v[82:85]
	v_mfma_f32_16x16x32_bf16 v[86:89], v[142:145], v[202:205], v[86:89]
	v_mfma_f32_16x16x32_bf16 v[86:89], v[154:157], v[228:231], v[86:89]
	v_mfma_f32_16x16x32_bf16 v[78:81], v[142:145], v[232:235], v[78:81]
	v_mfma_f32_16x16x32_bf16 v[78:81], v[154:157], v[236:239], v[78:81]
	v_mfma_f32_16x16x32_bf16 v[74:77], v[170:173], v[232:235], v[74:77]
	v_mfma_f32_16x16x32_bf16 v[74:77], v[174:177], v[236:239], v[74:77]
	v_mfma_f32_16x16x32_bf16 v[10:13], v[186:189], v[232:235], v[10:13]
	v_mfma_f32_16x16x32_bf16 v[10:13], v[190:193], v[236:239], v[10:13]
	v_mfma_f32_16x16x32_bf16 v[14:17], v[178:181], v[232:235], v[14:17]
	v_mfma_f32_16x16x32_bf16 v[14:17], v[182:185], v[236:239], v[14:17]
	v_mfma_f32_16x16x32_bf16 v[6:9], v[178:181], v[240:243], v[6:9]
	v_mfma_f32_16x16x32_bf16 v[6:9], v[182:185], v[244:247], v[6:9]
	v_mfma_f32_16x16x32_bf16 v[2:5], v[186:189], v[240:243], v[2:5]
	v_mfma_f32_16x16x32_bf16 v[2:5], v[190:193], v[244:247], v[2:5]
	v_mfma_f32_16x16x32_bf16 v[66:69], v[170:173], v[240:243], v[66:69]
	v_mfma_f32_16x16x32_bf16 v[66:69], v[174:177], v[244:247], v[66:69]
	v_mfma_f32_16x16x32_bf16 v[70:73], v[142:145], v[240:243], v[70:73]
	v_mfma_f32_16x16x32_bf16 v[70:73], v[154:157], v[244:247], v[70:73]
	s_barrier
	s_setprio 0
	s_add_i32 s26, s26, 2
	s_addk_i32 s19, 0x100
	s_addk_i32 s22, 0x100
	s_cmp_gt_u32 s26, 29
.LBB0_1283:
	v_add_u32_e32 v141, 0x10000, v139
	ds_read_b128 v[142:145], v141
	ds_read_b128 v[154:157], v141 offset:1024
	ds_read_b128 v[170:173], v141 offset:2048
	ds_read_b128 v[174:177], v141 offset:3072
	v_add_u32_e32 v141, 0x14000, v139
	ds_read_b128 v[178:181], v141
	ds_read_b128 v[182:185], v141 offset:1024
	ds_read_b128 v[186:189], v141 offset:2048
	ds_read_b128 v[190:193], v141 offset:3072
	s_add_i32 s27, s19, 0xfff80080
	s_cmp_eq_u32 s26, 28
	s_cselect_b32 s52, s8, s27
	s_cselect_b32 s83, s9, s22
	s_or_b32 s27, s52, 0x80
	s_mov_b32 m0, s73
	ds_read_b128 v[194:197], v140
	ds_read_b128 v[198:201], v140 offset:1024
	ds_read_b128 v[202:205], v140 offset:2048
	ds_read_b128 v[228:231], v140 offset:3072
	ds_read_b128 v[232:235], v140 offset:4096
	ds_read_b128 v[236:239], v140 offset:5120
	ds_read_b128 v[240:243], v140 offset:6144
	ds_read_b128 v[244:247], v140 offset:7168
	buffer_load_dwordx4 v131, s[60:63], s19 offen lds
	s_mov_b32 m0, s82
	s_nop 0
	buffer_load_dwordx4 v135, s[60:63], s19 offen lds
	s_waitcnt vmcnt(8)
	s_waitcnt lgkmcnt(0)
	s_setprio 1
	s_barrier
	v_mfma_f32_16x16x32_bf16 v[126:129], v[142:145], v[194:197], v[126:129]
	v_mfma_f32_16x16x32_bf16 v[126:129], v[154:157], v[198:201], v[126:129]
	v_mfma_f32_16x16x32_bf16 v[122:125], v[170:173], v[194:197], v[122:125]
	v_mfma_f32_16x16x32_bf16 v[122:125], v[174:177], v[198:201], v[122:125]
	v_mfma_f32_16x16x32_bf16 v[58:61], v[186:189], v[194:197], v[58:61]
	v_mfma_f32_16x16x32_bf16 v[58:61], v[190:193], v[198:201], v[58:61]
	v_mfma_f32_16x16x32_bf16 v[62:65], v[178:181], v[194:197], v[62:65]
	v_mfma_f32_16x16x32_bf16 v[62:65], v[182:185], v[198:201], v[62:65]
	v_mfma_f32_16x16x32_bf16 v[54:57], v[178:181], v[202:205], v[54:57]
	v_mfma_f32_16x16x32_bf16 v[54:57], v[182:185], v[228:231], v[54:57]
	v_mfma_f32_16x16x32_bf16 v[50:53], v[186:189], v[202:205], v[50:53]
	v_mfma_f32_16x16x32_bf16 v[50:53], v[190:193], v[228:231], v[50:53]
	v_mfma_f32_16x16x32_bf16 v[114:117], v[170:173], v[202:205], v[114:117]
	v_mfma_f32_16x16x32_bf16 v[114:117], v[174:177], v[228:231], v[114:117]
	v_mfma_f32_16x16x32_bf16 v[118:121], v[142:145], v[202:205], v[118:121]
	v_mfma_f32_16x16x32_bf16 v[118:121], v[154:157], v[228:231], v[118:121]
	v_mfma_f32_16x16x32_bf16 v[110:113], v[142:145], v[232:235], v[110:113]
	v_mfma_f32_16x16x32_bf16 v[110:113], v[154:157], v[236:239], v[110:113]
	v_mfma_f32_16x16x32_bf16 v[106:109], v[170:173], v[232:235], v[106:109]
	v_mfma_f32_16x16x32_bf16 v[106:109], v[174:177], v[236:239], v[106:109]
	v_mfma_f32_16x16x32_bf16 v[42:45], v[186:189], v[232:235], v[42:45]
	v_mfma_f32_16x16x32_bf16 v[42:45], v[190:193], v[236:239], v[42:45]
	v_mfma_f32_16x16x32_bf16 v[46:49], v[178:181], v[232:235], v[46:49]
	v_mfma_f32_16x16x32_bf16 v[46:49], v[182:185], v[236:239], v[46:49]
	v_mfma_f32_16x16x32_bf16 v[38:41], v[178:181], v[240:243], v[38:41]
	v_mfma_f32_16x16x32_bf16 v[38:41], v[182:185], v[244:247], v[38:41]
	v_mfma_f32_16x16x32_bf16 v[34:37], v[186:189], v[240:243], v[34:37]
	v_mfma_f32_16x16x32_bf16 v[34:37], v[190:193], v[244:247], v[34:37]
	v_mfma_f32_16x16x32_bf16 v[98:101], v[170:173], v[240:243], v[98:101]
	v_mfma_f32_16x16x32_bf16 v[98:101], v[174:177], v[244:247], v[98:101]
	v_mfma_f32_16x16x32_bf16 v[102:105], v[142:145], v[240:243], v[102:105]
	v_mfma_f32_16x16x32_bf16 v[102:105], v[154:157], v[244:247], v[102:105]
	s_barrier
	s_setprio 0
	s_mov_b32 m0, s21
	s_mov_b32 s70, s62
	s_mov_b32 s71, s63
	ds_read_b128 v[194:197], v140 offset:16384
	ds_read_b128 v[198:201], v140 offset:17408
	ds_read_b128 v[202:205], v140 offset:18432
	ds_read_b128 v[228:231], v140 offset:19456
	ds_read_b128 v[232:235], v140 offset:20480
	ds_read_b128 v[236:239], v140 offset:21504
	ds_read_b128 v[240:243], v140 offset:22528
	ds_read_b128 v[244:247], v140 offset:23552
	buffer_load_dwordx4 v134, s[68:71], s83 offen lds
	s_mov_b32 m0, s23
	s_add_i32 s53, s83, 0x80000
	buffer_load_dwordx4 v136, s[68:71], s83 offen lds
	s_mov_b32 m0, s24
	s_nop 0
	buffer_load_dwordx4 v134, s[68:71], s53 offen lds
	s_mov_b32 m0, s25
	s_nop 0
	buffer_load_dwordx4 v136, s[68:71], s53 offen lds
	s_mov_b32 m0, s2
	s_nop 0
	buffer_load_dwordx4 v131, s[60:63], s52 offen lds
	s_mov_b32 m0, s30
	s_nop 0
	buffer_load_dwordx4 v135, s[60:63], s52 offen lds
	s_waitcnt vmcnt(8)
	s_waitcnt lgkmcnt(0)
	s_setprio 1
	s_barrier
	v_mfma_f32_16x16x32_bf16 v[94:97], v[142:145], v[194:197], v[94:97]
	v_mfma_f32_16x16x32_bf16 v[94:97], v[154:157], v[198:201], v[94:97]
	v_mfma_f32_16x16x32_bf16 v[90:93], v[170:173], v[194:197], v[90:93]
	v_mfma_f32_16x16x32_bf16 v[90:93], v[174:177], v[198:201], v[90:93]
	v_mfma_f32_16x16x32_bf16 v[26:29], v[186:189], v[194:197], v[26:29]
	v_mfma_f32_16x16x32_bf16 v[26:29], v[190:193], v[198:201], v[26:29]
	v_mfma_f32_16x16x32_bf16 v[30:33], v[178:181], v[194:197], v[30:33]
	v_mfma_f32_16x16x32_bf16 v[30:33], v[182:185], v[198:201], v[30:33]
	v_mfma_f32_16x16x32_bf16 v[22:25], v[178:181], v[202:205], v[22:25]
	v_mfma_f32_16x16x32_bf16 v[22:25], v[182:185], v[228:231], v[22:25]
	v_mfma_f32_16x16x32_bf16 v[18:21], v[186:189], v[202:205], v[18:21]
	v_mfma_f32_16x16x32_bf16 v[18:21], v[190:193], v[228:231], v[18:21]
	v_mfma_f32_16x16x32_bf16 v[82:85], v[170:173], v[202:205], v[82:85]
	v_mfma_f32_16x16x32_bf16 v[82:85], v[174:177], v[228:231], v[82:85]
	v_mfma_f32_16x16x32_bf16 v[86:89], v[142:145], v[202:205], v[86:89]
	v_mfma_f32_16x16x32_bf16 v[86:89], v[154:157], v[228:231], v[86:89]
	v_mfma_f32_16x16x32_bf16 v[78:81], v[142:145], v[232:235], v[78:81]
	v_mfma_f32_16x16x32_bf16 v[78:81], v[154:157], v[236:239], v[78:81]
	v_mfma_f32_16x16x32_bf16 v[74:77], v[170:173], v[232:235], v[74:77]
	v_mfma_f32_16x16x32_bf16 v[74:77], v[174:177], v[236:239], v[74:77]
	v_mfma_f32_16x16x32_bf16 v[10:13], v[186:189], v[232:235], v[10:13]
	v_mfma_f32_16x16x32_bf16 v[10:13], v[190:193], v[236:239], v[10:13]
	v_mfma_f32_16x16x32_bf16 v[14:17], v[178:181], v[232:235], v[14:17]
	v_mfma_f32_16x16x32_bf16 v[14:17], v[182:185], v[236:239], v[14:17]
	v_mfma_f32_16x16x32_bf16 v[6:9], v[178:181], v[240:243], v[6:9]
	v_mfma_f32_16x16x32_bf16 v[6:9], v[182:185], v[244:247], v[6:9]
	v_mfma_f32_16x16x32_bf16 v[2:5], v[186:189], v[240:243], v[2:5]
	v_mfma_f32_16x16x32_bf16 v[2:5], v[190:193], v[244:247], v[2:5]
	v_mfma_f32_16x16x32_bf16 v[66:69], v[170:173], v[240:243], v[66:69]
	v_mfma_f32_16x16x32_bf16 v[66:69], v[174:177], v[244:247], v[66:69]
	v_mfma_f32_16x16x32_bf16 v[70:73], v[142:145], v[240:243], v[70:73]
	v_mfma_f32_16x16x32_bf16 v[70:73], v[154:157], v[244:247], v[70:73]
	s_barrier
	s_setprio 0
	v_add_u32_e32 v141, 0x18000, v139
	ds_read_b128 v[142:145], v141
	ds_read_b128 v[154:157], v141 offset:1024
	ds_read_b128 v[170:173], v141 offset:2048
	ds_read_b128 v[174:177], v141 offset:3072
	v_add_u32_e32 v141, 0x1c000, v139
	ds_read_b128 v[178:181], v141
	ds_read_b128 v[182:185], v141 offset:1024
	ds_read_b128 v[186:189], v141 offset:2048
	ds_read_b128 v[190:193], v141 offset:3072
	s_add_i32 s52, s52, 0x80000
	s_mov_b32 m0, s31
	ds_read_b128 v[194:197], v140 offset:32768
	ds_read_b128 v[198:201], v140 offset:33792
	ds_read_b128 v[202:205], v140 offset:34816
	ds_read_b128 v[228:231], v140 offset:35840
	ds_read_b128 v[232:235], v140 offset:36864
	ds_read_b128 v[236:239], v140 offset:37888
	ds_read_b128 v[240:243], v140 offset:38912
	ds_read_b128 v[244:247], v140 offset:39936
	buffer_load_dwordx4 v131, s[60:63], s52 offen lds
	s_mov_b32 m0, s33
	s_nop 0
	buffer_load_dwordx4 v135, s[60:63], s52 offen lds
	s_waitcnt vmcnt(8)
	s_waitcnt lgkmcnt(0)
	s_setprio 1
	s_barrier
	v_mfma_f32_16x16x32_bf16 v[126:129], v[142:145], v[194:197], v[126:129]
	v_mfma_f32_16x16x32_bf16 v[126:129], v[154:157], v[198:201], v[126:129]
	v_mfma_f32_16x16x32_bf16 v[122:125], v[170:173], v[194:197], v[122:125]
	v_mfma_f32_16x16x32_bf16 v[122:125], v[174:177], v[198:201], v[122:125]
	v_mfma_f32_16x16x32_bf16 v[58:61], v[186:189], v[194:197], v[58:61]
	v_mfma_f32_16x16x32_bf16 v[58:61], v[190:193], v[198:201], v[58:61]
	v_mfma_f32_16x16x32_bf16 v[62:65], v[178:181], v[194:197], v[62:65]
	v_mfma_f32_16x16x32_bf16 v[62:65], v[182:185], v[198:201], v[62:65]
	v_mfma_f32_16x16x32_bf16 v[54:57], v[178:181], v[202:205], v[54:57]
	v_mfma_f32_16x16x32_bf16 v[54:57], v[182:185], v[228:231], v[54:57]
	v_mfma_f32_16x16x32_bf16 v[50:53], v[186:189], v[202:205], v[50:53]
	v_mfma_f32_16x16x32_bf16 v[50:53], v[190:193], v[228:231], v[50:53]
	v_mfma_f32_16x16x32_bf16 v[114:117], v[170:173], v[202:205], v[114:117]
	v_mfma_f32_16x16x32_bf16 v[114:117], v[174:177], v[228:231], v[114:117]
	v_mfma_f32_16x16x32_bf16 v[118:121], v[142:145], v[202:205], v[118:121]
	v_mfma_f32_16x16x32_bf16 v[118:121], v[154:157], v[228:231], v[118:121]
	v_mfma_f32_16x16x32_bf16 v[110:113], v[142:145], v[232:235], v[110:113]
	v_mfma_f32_16x16x32_bf16 v[110:113], v[154:157], v[236:239], v[110:113]
	v_mfma_f32_16x16x32_bf16 v[106:109], v[170:173], v[232:235], v[106:109]
	v_mfma_f32_16x16x32_bf16 v[106:109], v[174:177], v[236:239], v[106:109]
	v_mfma_f32_16x16x32_bf16 v[42:45], v[186:189], v[232:235], v[42:45]
	v_mfma_f32_16x16x32_bf16 v[42:45], v[190:193], v[236:239], v[42:45]
	v_mfma_f32_16x16x32_bf16 v[46:49], v[178:181], v[232:235], v[46:49]
	v_mfma_f32_16x16x32_bf16 v[46:49], v[182:185], v[236:239], v[46:49]
	v_mfma_f32_16x16x32_bf16 v[38:41], v[178:181], v[240:243], v[38:41]
	v_mfma_f32_16x16x32_bf16 v[38:41], v[182:185], v[244:247], v[38:41]
	v_mfma_f32_16x16x32_bf16 v[34:37], v[186:189], v[240:243], v[34:37]
	v_mfma_f32_16x16x32_bf16 v[34:37], v[190:193], v[244:247], v[34:37]
	v_mfma_f32_16x16x32_bf16 v[98:101], v[170:173], v[240:243], v[98:101]
	v_mfma_f32_16x16x32_bf16 v[98:101], v[174:177], v[244:247], v[98:101]
	v_mfma_f32_16x16x32_bf16 v[102:105], v[142:145], v[240:243], v[102:105]
	v_mfma_f32_16x16x32_bf16 v[102:105], v[154:157], v[244:247], v[102:105]
	s_barrier
	s_setprio 0
	s_mov_b32 m0, s34
	s_or_b32 s52, s83, 0x80
	ds_read_b128 v[194:197], v140 offset:49152
	ds_read_b128 v[198:201], v140 offset:50176
	ds_read_b128 v[202:205], v140 offset:51200
	ds_read_b128 v[228:231], v140 offset:52224
	ds_read_b128 v[232:235], v140 offset:53248
	ds_read_b128 v[236:239], v140 offset:54272
	ds_read_b128 v[240:243], v140 offset:55296
	ds_read_b128 v[244:247], v140 offset:56320
	buffer_load_dwordx4 v134, s[68:71], s52 offen lds
	s_mov_b32 m0, s35
	s_add_i32 s83, s83, 0x80080
	buffer_load_dwordx4 v136, s[68:71], s52 offen lds
	s_mov_b32 m0, s65
	s_nop 0
	buffer_load_dwordx4 v134, s[68:71], s83 offen lds
	s_mov_b32 m0, s66
	s_nop 0
	buffer_load_dwordx4 v136, s[68:71], s83 offen lds
	s_mov_b32 m0, s36
	s_nop 0
	buffer_load_dwordx4 v131, s[60:63], s27 offen lds
	s_mov_b32 m0, s37
	s_nop 0
	buffer_load_dwordx4 v135, s[60:63], s27 offen lds
	s_waitcnt vmcnt(8)
	s_waitcnt lgkmcnt(0)
	s_setprio 1
	s_barrier
	v_mfma_f32_16x16x32_bf16 v[94:97], v[142:145], v[194:197], v[94:97]
	v_mfma_f32_16x16x32_bf16 v[94:97], v[154:157], v[198:201], v[94:97]
	v_mfma_f32_16x16x32_bf16 v[90:93], v[170:173], v[194:197], v[90:93]
	v_mfma_f32_16x16x32_bf16 v[90:93], v[174:177], v[198:201], v[90:93]
	v_mfma_f32_16x16x32_bf16 v[26:29], v[186:189], v[194:197], v[26:29]
	v_mfma_f32_16x16x32_bf16 v[26:29], v[190:193], v[198:201], v[26:29]
	v_mfma_f32_16x16x32_bf16 v[30:33], v[178:181], v[194:197], v[30:33]
	v_mfma_f32_16x16x32_bf16 v[30:33], v[182:185], v[198:201], v[30:33]
	v_mfma_f32_16x16x32_bf16 v[22:25], v[178:181], v[202:205], v[22:25]
	v_mfma_f32_16x16x32_bf16 v[22:25], v[182:185], v[228:231], v[22:25]
	v_mfma_f32_16x16x32_bf16 v[18:21], v[186:189], v[202:205], v[18:21]
	v_mfma_f32_16x16x32_bf16 v[18:21], v[190:193], v[228:231], v[18:21]
	v_mfma_f32_16x16x32_bf16 v[82:85], v[170:173], v[202:205], v[82:85]
	v_mfma_f32_16x16x32_bf16 v[82:85], v[174:177], v[228:231], v[82:85]
	v_mfma_f32_16x16x32_bf16 v[86:89], v[142:145], v[202:205], v[86:89]
	v_mfma_f32_16x16x32_bf16 v[86:89], v[154:157], v[228:231], v[86:89]
	v_mfma_f32_16x16x32_bf16 v[78:81], v[142:145], v[232:235], v[78:81]
	v_mfma_f32_16x16x32_bf16 v[78:81], v[154:157], v[236:239], v[78:81]
	v_mfma_f32_16x16x32_bf16 v[74:77], v[170:173], v[232:235], v[74:77]
	v_mfma_f32_16x16x32_bf16 v[74:77], v[174:177], v[236:239], v[74:77]
	v_mfma_f32_16x16x32_bf16 v[10:13], v[186:189], v[232:235], v[10:13]
	v_mfma_f32_16x16x32_bf16 v[10:13], v[190:193], v[236:239], v[10:13]
	v_mfma_f32_16x16x32_bf16 v[14:17], v[178:181], v[232:235], v[14:17]
	v_mfma_f32_16x16x32_bf16 v[14:17], v[182:185], v[236:239], v[14:17]
	v_mfma_f32_16x16x32_bf16 v[6:9], v[178:181], v[240:243], v[6:9]
	v_mfma_f32_16x16x32_bf16 v[6:9], v[182:185], v[244:247], v[6:9]
	v_mfma_f32_16x16x32_bf16 v[2:5], v[186:189], v[240:243], v[2:5]
	v_mfma_f32_16x16x32_bf16 v[2:5], v[190:193], v[244:247], v[2:5]
	v_mfma_f32_16x16x32_bf16 v[66:69], v[170:173], v[240:243], v[66:69]
	v_mfma_f32_16x16x32_bf16 v[66:69], v[174:177], v[244:247], v[66:69]
	v_mfma_f32_16x16x32_bf16 v[70:73], v[142:145], v[240:243], v[70:73]
	v_mfma_f32_16x16x32_bf16 v[70:73], v[154:157], v[244:247], v[70:73]
	s_barrier
	s_setprio 0
	s_add_i32 s26, s26, 2
	s_addk_i32 s19, 0x100
	s_addk_i32 s22, 0x100
	s_cmp_gt_u32 s26, 29
	s_cbranch_scc0 .LBB0_1283
	s_and_b64 vcc, exec, s[44:45]
	s_cbranch_vccz .LBB0_1286
	s_barrier

.LBB0_1588:
	s_lshl_b32 s85, s84, 20
	s_and_b64 s[8:9], s[42:43], exec
	s_cselect_b32 s8, s85, s13
	s_lshl_b32 s48, s73, 20
	s_and_b64 s[22:23], s[42:43], exec
	s_cselect_b32 s9, s48, s21
	s_add_i32 s13, s13, 0x80080
	s_addk_i32 s21, 0x100
	s_mov_b32 s22, -2
	s_waitcnt lgkmcnt(0)
	v_add_u32_e32 v170, 0x10000, v140
	v_add_u32_e32 v186, 0x14000, v140
	ds_read_b128 v[132:135], v170
	ds_read_b128 v[142:145], v170 offset:1024
	ds_read_b128 v[154:157], v170 offset:2048
	ds_read_b128 v[170:173], v170 offset:3072
	ds_read_b128 v[174:177], v186
	ds_read_b128 v[178:181], v186 offset:1024
	ds_read_b128 v[182:185], v186 offset:2048
	ds_read_b128 v[186:189], v186 offset:3072
	s_add_i32 s23, s13, 0xfff80080
	s_cmp_eq_u32 s22, 28
	s_cselect_b32 s27, s8, s23
	s_cselect_b32 s26, s9, s21
	s_or_b32 s23, s27, 0x80
	s_mov_b32 m0, s70
	ds_read_b128 v[190:193], v141
	ds_read_b128 v[194:197], v141 offset:1024
	ds_read_b128 v[198:201], v141 offset:2048
	ds_read_b128 v[202:205], v141 offset:3072
	ds_read_b128 v[228:231], v141 offset:4096
	ds_read_b128 v[232:235], v141 offset:5120
	ds_read_b128 v[236:239], v141 offset:6144
	ds_read_b128 v[240:243], v141 offset:7168
	buffer_load_dwordx4 v136, s[60:63], s13 offen lds
	s_mov_b32 m0, s72
	s_nop 0
	buffer_load_dwordx4 v138, s[60:63], s13 offen lds
	s_waitcnt vmcnt(8)
	s_waitcnt lgkmcnt(0)
	s_setprio 1
	s_barrier
	v_mfma_f32_16x16x32_bf16 v[126:129], v[132:135], v[190:193], 0
	v_mfma_f32_16x16x32_bf16 v[126:129], v[142:145], v[194:197], v[126:129]
	v_mfma_f32_16x16x32_bf16 v[106:109], v[154:157], v[190:193], 0
	v_mfma_f32_16x16x32_bf16 v[106:109], v[170:173], v[194:197], v[106:109]
	v_mfma_f32_16x16x32_bf16 v[110:113], v[182:185], v[190:193], 0
	v_mfma_f32_16x16x32_bf16 v[110:113], v[186:189], v[194:197], v[110:113]
	v_mfma_f32_16x16x32_bf16 v[122:125], v[174:177], v[190:193], 0
	v_mfma_f32_16x16x32_bf16 v[122:125], v[178:181], v[194:197], v[122:125]
	v_mfma_f32_16x16x32_bf16 v[102:105], v[174:177], v[198:201], 0
	v_mfma_f32_16x16x32_bf16 v[102:105], v[178:181], v[202:205], v[102:105]
	v_mfma_f32_16x16x32_bf16 v[98:101], v[182:185], v[198:201], 0
	v_mfma_f32_16x16x32_bf16 v[98:101], v[186:189], v[202:205], v[98:101]
	v_mfma_f32_16x16x32_bf16 v[114:117], v[154:157], v[198:201], 0
	v_mfma_f32_16x16x32_bf16 v[114:117], v[170:173], v[202:205], v[114:117]
	v_mfma_f32_16x16x32_bf16 v[118:121], v[132:135], v[198:201], 0
	v_mfma_f32_16x16x32_bf16 v[118:121], v[142:145], v[202:205], v[118:121]
	v_mfma_f32_16x16x32_bf16 v[94:97], v[132:135], v[228:231], 0
	v_mfma_f32_16x16x32_bf16 v[94:97], v[142:145], v[232:235], v[94:97]
	v_mfma_f32_16x16x32_bf16 v[90:93], v[154:157], v[228:231], 0
	v_mfma_f32_16x16x32_bf16 v[90:93], v[170:173], v[232:235], v[90:93]
	v_mfma_f32_16x16x32_bf16 v[82:85], v[182:185], v[228:231], 0
	v_mfma_f32_16x16x32_bf16 v[82:85], v[186:189], v[232:235], v[82:85]
	v_mfma_f32_16x16x32_bf16 v[86:89], v[174:177], v[228:231], 0
	v_mfma_f32_16x16x32_bf16 v[86:89], v[178:181], v[232:235], v[86:89]
	v_mfma_f32_16x16x32_bf16 v[70:73], v[174:177], v[236:239], 0
	v_mfma_f32_16x16x32_bf16 v[70:73], v[178:181], v[240:243], v[70:73]
	v_mfma_f32_16x16x32_bf16 v[66:69], v[182:185], v[236:239], 0
	v_mfma_f32_16x16x32_bf16 v[66:69], v[186:189], v[240:243], v[66:69]
	v_mfma_f32_16x16x32_bf16 v[74:77], v[154:157], v[236:239], 0
	v_mfma_f32_16x16x32_bf16 v[74:77], v[170:173], v[240:243], v[74:77]
	v_mfma_f32_16x16x32_bf16 v[78:81], v[132:135], v[236:239], 0
	v_mfma_f32_16x16x32_bf16 v[78:81], v[142:145], v[240:243], v[78:81]
	s_barrier
	s_setprio 0
	s_mov_b32 m0, s15
	s_mov_b32 s46, s62
	s_mov_b32 s47, s63
	ds_read_b128 v[190:193], v141 offset:16384
	ds_read_b128 v[194:197], v141 offset:17408
	ds_read_b128 v[198:201], v141 offset:18432
	ds_read_b128 v[202:205], v141 offset:19456
	ds_read_b128 v[228:231], v141 offset:20480
	ds_read_b128 v[232:235], v141 offset:21504
	ds_read_b128 v[236:239], v141 offset:22528
	ds_read_b128 v[240:243], v141 offset:23552
	buffer_load_dwordx4 v137, s[44:47], s26 offen lds
	s_mov_b32 m0, s16
	s_add_i32 s49, s26, 0x80000
	buffer_load_dwordx4 v139, s[44:47], s26 offen lds
	s_mov_b32 m0, s18
	s_nop 0
	buffer_load_dwordx4 v137, s[44:47], s49 offen lds
	s_mov_b32 m0, s19
	s_nop 0
	buffer_load_dwordx4 v139, s[44:47], s49 offen lds
	s_mov_b32 m0, s14
	s_nop 0
	buffer_load_dwordx4 v136, s[60:63], s27 offen lds
	s_mov_b32 m0, s24
	s_nop 0
	buffer_load_dwordx4 v138, s[60:63], s27 offen lds
	s_waitcnt vmcnt(8)
	s_waitcnt lgkmcnt(0)
	s_setprio 1
	s_barrier
	v_mfma_f32_16x16x32_bf16 v[62:65], v[132:135], v[190:193], 0
	v_mfma_f32_16x16x32_bf16 v[62:65], v[142:145], v[194:197], v[62:65]
	v_mfma_f32_16x16x32_bf16 v[58:61], v[154:157], v[190:193], 0
	v_mfma_f32_16x16x32_bf16 v[58:61], v[170:173], v[194:197], v[58:61]
	v_mfma_f32_16x16x32_bf16 v[50:53], v[182:185], v[190:193], 0
	v_mfma_f32_16x16x32_bf16 v[50:53], v[186:189], v[194:197], v[50:53]
	v_mfma_f32_16x16x32_bf16 v[54:57], v[174:177], v[190:193], 0
	v_mfma_f32_16x16x32_bf16 v[54:57], v[178:181], v[194:197], v[54:57]
	v_mfma_f32_16x16x32_bf16 v[38:41], v[174:177], v[198:201], 0
	v_mfma_f32_16x16x32_bf16 v[38:41], v[178:181], v[202:205], v[38:41]
	v_mfma_f32_16x16x32_bf16 v[34:37], v[182:185], v[198:201], 0
	v_mfma_f32_16x16x32_bf16 v[34:37], v[186:189], v[202:205], v[34:37]
	v_mfma_f32_16x16x32_bf16 v[42:45], v[154:157], v[198:201], 0
	v_mfma_f32_16x16x32_bf16 v[42:45], v[170:173], v[202:205], v[42:45]
	v_mfma_f32_16x16x32_bf16 v[46:49], v[132:135], v[198:201], 0
	v_mfma_f32_16x16x32_bf16 v[46:49], v[142:145], v[202:205], v[46:49]
	v_mfma_f32_16x16x32_bf16 v[30:33], v[132:135], v[228:231], 0
	v_mfma_f32_16x16x32_bf16 v[30:33], v[142:145], v[232:235], v[30:33]
	v_mfma_f32_16x16x32_bf16 v[26:29], v[154:157], v[228:231], 0
	v_mfma_f32_16x16x32_bf16 v[26:29], v[170:173], v[232:235], v[26:29]
	v_mfma_f32_16x16x32_bf16 v[18:21], v[182:185], v[228:231], 0
	v_mfma_f32_16x16x32_bf16 v[18:21], v[186:189], v[232:235], v[18:21]
	v_mfma_f32_16x16x32_bf16 v[22:25], v[174:177], v[228:231], 0
	v_mfma_f32_16x16x32_bf16 v[22:25], v[178:181], v[232:235], v[22:25]
	v_mfma_f32_16x16x32_bf16 v[6:9], v[174:177], v[236:239], 0
	v_mfma_f32_16x16x32_bf16 v[6:9], v[178:181], v[240:243], v[6:9]
	v_mfma_f32_16x16x32_bf16 v[2:5], v[182:185], v[236:239], 0
	v_mfma_f32_16x16x32_bf16 v[2:5], v[186:189], v[240:243], v[2:5]
	v_mfma_f32_16x16x32_bf16 v[10:13], v[154:157], v[236:239], 0
	v_mfma_f32_16x16x32_bf16 v[10:13], v[170:173], v[240:243], v[10:13]
	v_mfma_f32_16x16x32_bf16 v[14:17], v[132:135], v[236:239], 0
	v_mfma_f32_16x16x32_bf16 v[14:17], v[142:145], v[240:243], v[14:17]
	s_barrier
	s_setprio 0
	v_add_u32_e32 v170, 0x18000, v140
	v_add_u32_e32 v186, 0x1c000, v140
	ds_read_b128 v[132:135], v170
	ds_read_b128 v[142:145], v170 offset:1024
	ds_read_b128 v[154:157], v170 offset:2048
	ds_read_b128 v[170:173], v170 offset:3072
	ds_read_b128 v[174:177], v186
	ds_read_b128 v[178:181], v186 offset:1024
	ds_read_b128 v[182:185], v186 offset:2048
	ds_read_b128 v[186:189], v186 offset:3072
	s_add_i32 s27, s27, 0x80000
	s_mov_b32 m0, s25
	ds_read_b128 v[190:193], v141 offset:32768
	ds_read_b128 v[194:197], v141 offset:33792
	ds_read_b128 v[198:201], v141 offset:34816
	ds_read_b128 v[202:205], v141 offset:35840
	ds_read_b128 v[228:231], v141 offset:36864
	ds_read_b128 v[232:235], v141 offset:37888
	ds_read_b128 v[236:239], v141 offset:38912
	ds_read_b128 v[240:243], v141 offset:39936
	buffer_load_dwordx4 v136, s[60:63], s27 offen lds
	s_mov_b32 m0, s30
	s_nop 0
	buffer_load_dwordx4 v138, s[60:63], s27 offen lds
	s_waitcnt vmcnt(8)
	s_waitcnt lgkmcnt(0)
	s_setprio 1
	s_barrier
	v_mfma_f32_16x16x32_bf16 v[126:129], v[132:135], v[190:193], v[126:129]
	v_mfma_f32_16x16x32_bf16 v[126:129], v[142:145], v[194:197], v[126:129]
	v_mfma_f32_16x16x32_bf16 v[106:109], v[154:157], v[190:193], v[106:109]
	v_mfma_f32_16x16x32_bf16 v[106:109], v[170:173], v[194:197], v[106:109]
	v_mfma_f32_16x16x32_bf16 v[110:113], v[182:185], v[190:193], v[110:113]
	v_mfma_f32_16x16x32_bf16 v[110:113], v[186:189], v[194:197], v[110:113]
	v_mfma_f32_16x16x32_bf16 v[122:125], v[174:177], v[190:193], v[122:125]
	v_mfma_f32_16x16x32_bf16 v[122:125], v[178:181], v[194:197], v[122:125]
	v_mfma_f32_16x16x32_bf16 v[102:105], v[174:177], v[198:201], v[102:105]
	v_mfma_f32_16x16x32_bf16 v[102:105], v[178:181], v[202:205], v[102:105]
	v_mfma_f32_16x16x32_bf16 v[98:101], v[182:185], v[198:201], v[98:101]
	v_mfma_f32_16x16x32_bf16 v[98:101], v[186:189], v[202:205], v[98:101]
	v_mfma_f32_16x16x32_bf16 v[114:117], v[154:157], v[198:201], v[114:117]
	v_mfma_f32_16x16x32_bf16 v[114:117], v[170:173], v[202:205], v[114:117]
	v_mfma_f32_16x16x32_bf16 v[118:121], v[132:135], v[198:201], v[118:121]
	v_mfma_f32_16x16x32_bf16 v[118:121], v[142:145], v[202:205], v[118:121]
	v_mfma_f32_16x16x32_bf16 v[94:97], v[132:135], v[228:231], v[94:97]
	v_mfma_f32_16x16x32_bf16 v[94:97], v[142:145], v[232:235], v[94:97]
	v_mfma_f32_16x16x32_bf16 v[90:93], v[154:157], v[228:231], v[90:93]
	v_mfma_f32_16x16x32_bf16 v[90:93], v[170:173], v[232:235], v[90:93]
	v_mfma_f32_16x16x32_bf16 v[82:85], v[182:185], v[228:231], v[82:85]
	v_mfma_f32_16x16x32_bf16 v[82:85], v[186:189], v[232:235], v[82:85]
	v_mfma_f32_16x16x32_bf16 v[86:89], v[174:177], v[228:231], v[86:89]
	v_mfma_f32_16x16x32_bf16 v[86:89], v[178:181], v[232:235], v[86:89]
	v_mfma_f32_16x16x32_bf16 v[70:73], v[174:177], v[236:239], v[70:73]
	v_mfma_f32_16x16x32_bf16 v[70:73], v[178:181], v[240:243], v[70:73]
	v_mfma_f32_16x16x32_bf16 v[66:69], v[182:185], v[236:239], v[66:69]
	v_mfma_f32_16x16x32_bf16 v[66:69], v[186:189], v[240:243], v[66:69]
	v_mfma_f32_16x16x32_bf16 v[74:77], v[154:157], v[236:239], v[74:77]
	v_mfma_f32_16x16x32_bf16 v[74:77], v[170:173], v[240:243], v[74:77]
	v_mfma_f32_16x16x32_bf16 v[78:81], v[132:135], v[236:239], v[78:81]
	v_mfma_f32_16x16x32_bf16 v[78:81], v[142:145], v[240:243], v[78:81]
	s_barrier
	s_setprio 0
	s_mov_b32 m0, s36
	s_or_b32 s27, s26, 0x80
	ds_read_b128 v[190:193], v141 offset:49152
	ds_read_b128 v[194:197], v141 offset:50176
	ds_read_b128 v[198:201], v141 offset:51200
	ds_read_b128 v[202:205], v141 offset:52224
	ds_read_b128 v[228:231], v141 offset:53248
	ds_read_b128 v[232:235], v141 offset:54272
	ds_read_b128 v[236:239], v141 offset:55296
	ds_read_b128 v[240:243], v141 offset:56320
	buffer_load_dwordx4 v137, s[44:47], s27 offen lds
	s_mov_b32 m0, s37
	s_add_i32 s26, s26, 0x80080
	buffer_load_dwordx4 v139, s[44:47], s27 offen lds
	s_mov_b32 m0, s68
	s_nop 0
	buffer_load_dwordx4 v137, s[44:47], s26 offen lds
	s_mov_b32 m0, s69
	s_nop 0
	buffer_load_dwordx4 v139, s[44:47], s26 offen lds
	s_mov_b32 m0, s66
	s_nop 0
	buffer_load_dwordx4 v136, s[60:63], s23 offen lds
	s_mov_b32 m0, s67
	s_nop 0
	buffer_load_dwordx4 v138, s[60:63], s23 offen lds
	s_waitcnt vmcnt(8)
	s_waitcnt lgkmcnt(0)
	s_setprio 1
	s_barrier
	v_mfma_f32_16x16x32_bf16 v[62:65], v[132:135], v[190:193], v[62:65]
	v_mfma_f32_16x16x32_bf16 v[62:65], v[142:145], v[194:197], v[62:65]
	v_mfma_f32_16x16x32_bf16 v[58:61], v[154:157], v[190:193], v[58:61]
	v_mfma_f32_16x16x32_bf16 v[58:61], v[170:173], v[194:197], v[58:61]
	v_mfma_f32_16x16x32_bf16 v[50:53], v[182:185], v[190:193], v[50:53]
	v_mfma_f32_16x16x32_bf16 v[50:53], v[186:189], v[194:197], v[50:53]
	v_mfma_f32_16x16x32_bf16 v[54:57], v[174:177], v[190:193], v[54:57]
	v_mfma_f32_16x16x32_bf16 v[54:57], v[178:181], v[194:197], v[54:57]
	v_mfma_f32_16x16x32_bf16 v[38:41], v[174:177], v[198:201], v[38:41]
	v_mfma_f32_16x16x32_bf16 v[38:41], v[178:181], v[202:205], v[38:41]
	v_mfma_f32_16x16x32_bf16 v[34:37], v[182:185], v[198:201], v[34:37]
	v_mfma_f32_16x16x32_bf16 v[34:37], v[186:189], v[202:205], v[34:37]
	v_mfma_f32_16x16x32_bf16 v[42:45], v[154:157], v[198:201], v[42:45]
	v_mfma_f32_16x16x32_bf16 v[42:45], v[170:173], v[202:205], v[42:45]
	v_mfma_f32_16x16x32_bf16 v[46:49], v[132:135], v[198:201], v[46:49]
	v_mfma_f32_16x16x32_bf16 v[46:49], v[142:145], v[202:205], v[46:49]
	v_mfma_f32_16x16x32_bf16 v[30:33], v[132:135], v[228:231], v[30:33]
	v_mfma_f32_16x16x32_bf16 v[30:33], v[142:145], v[232:235], v[30:33]
	v_mfma_f32_16x16x32_bf16 v[26:29], v[154:157], v[228:231], v[26:29]
	v_mfma_f32_16x16x32_bf16 v[26:29], v[170:173], v[232:235], v[26:29]
	v_mfma_f32_16x16x32_bf16 v[18:21], v[182:185], v[228:231], v[18:21]
	v_mfma_f32_16x16x32_bf16 v[18:21], v[186:189], v[232:235], v[18:21]
	v_mfma_f32_16x16x32_bf16 v[22:25], v[174:177], v[228:231], v[22:25]
	v_mfma_f32_16x16x32_bf16 v[22:25], v[178:181], v[232:235], v[22:25]
	v_mfma_f32_16x16x32_bf16 v[6:9], v[174:177], v[236:239], v[6:9]
	v_mfma_f32_16x16x32_bf16 v[6:9], v[178:181], v[240:243], v[6:9]
	v_mfma_f32_16x16x32_bf16 v[2:5], v[182:185], v[236:239], v[2:5]
	v_mfma_f32_16x16x32_bf16 v[2:5], v[186:189], v[240:243], v[2:5]
	v_mfma_f32_16x16x32_bf16 v[10:13], v[154:157], v[236:239], v[10:13]
	v_mfma_f32_16x16x32_bf16 v[10:13], v[170:173], v[240:243], v[10:13]
	v_mfma_f32_16x16x32_bf16 v[14:17], v[132:135], v[236:239], v[14:17]
	v_mfma_f32_16x16x32_bf16 v[14:17], v[142:145], v[240:243], v[14:17]
	s_barrier
	s_setprio 0
	s_add_i32 s22, s22, 2
	s_addk_i32 s13, 0x100
	s_addk_i32 s21, 0x100
	s_cmp_gt_u32 s22, 29
.LBB0_1589:
	v_add_u32_e32 v170, 0x10000, v140
	v_add_u32_e32 v186, 0x14000, v140
	ds_read_b128 v[132:135], v170
	ds_read_b128 v[142:145], v170 offset:1024
	ds_read_b128 v[154:157], v170 offset:2048
	ds_read_b128 v[170:173], v170 offset:3072
	ds_read_b128 v[174:177], v186
	ds_read_b128 v[178:181], v186 offset:1024
	ds_read_b128 v[182:185], v186 offset:2048
	ds_read_b128 v[186:189], v186 offset:3072
	s_add_i32 s23, s13, 0xfff80080
	s_cmp_eq_u32 s22, 28
	s_cselect_b32 s27, s8, s23
	s_cselect_b32 s26, s9, s21
	s_or_b32 s23, s27, 0x80
	s_mov_b32 m0, s70
	ds_read_b128 v[190:193], v141
	ds_read_b128 v[194:197], v141 offset:1024
	ds_read_b128 v[198:201], v141 offset:2048
	ds_read_b128 v[202:205], v141 offset:3072
	ds_read_b128 v[228:231], v141 offset:4096
	ds_read_b128 v[232:235], v141 offset:5120
	ds_read_b128 v[236:239], v141 offset:6144
	ds_read_b128 v[240:243], v141 offset:7168
	buffer_load_dwordx4 v136, s[60:63], s13 offen lds
	s_mov_b32 m0, s72
	s_nop 0
	buffer_load_dwordx4 v138, s[60:63], s13 offen lds
	s_waitcnt vmcnt(8)
	s_waitcnt lgkmcnt(0)
	s_setprio 1
	s_barrier
	v_mfma_f32_16x16x32_bf16 v[126:129], v[132:135], v[190:193], v[126:129]
	v_mfma_f32_16x16x32_bf16 v[126:129], v[142:145], v[194:197], v[126:129]
	v_mfma_f32_16x16x32_bf16 v[106:109], v[154:157], v[190:193], v[106:109]
	v_mfma_f32_16x16x32_bf16 v[106:109], v[170:173], v[194:197], v[106:109]
	v_mfma_f32_16x16x32_bf16 v[110:113], v[182:185], v[190:193], v[110:113]
	v_mfma_f32_16x16x32_bf16 v[110:113], v[186:189], v[194:197], v[110:113]
	v_mfma_f32_16x16x32_bf16 v[122:125], v[174:177], v[190:193], v[122:125]
	v_mfma_f32_16x16x32_bf16 v[122:125], v[178:181], v[194:197], v[122:125]
	v_mfma_f32_16x16x32_bf16 v[102:105], v[174:177], v[198:201], v[102:105]
	v_mfma_f32_16x16x32_bf16 v[102:105], v[178:181], v[202:205], v[102:105]
	v_mfma_f32_16x16x32_bf16 v[98:101], v[182:185], v[198:201], v[98:101]
	v_mfma_f32_16x16x32_bf16 v[98:101], v[186:189], v[202:205], v[98:101]
	v_mfma_f32_16x16x32_bf16 v[114:117], v[154:157], v[198:201], v[114:117]
	v_mfma_f32_16x16x32_bf16 v[114:117], v[170:173], v[202:205], v[114:117]
	v_mfma_f32_16x16x32_bf16 v[118:121], v[132:135], v[198:201], v[118:121]
	v_mfma_f32_16x16x32_bf16 v[118:121], v[142:145], v[202:205], v[118:121]
	v_mfma_f32_16x16x32_bf16 v[94:97], v[132:135], v[228:231], v[94:97]
	v_mfma_f32_16x16x32_bf16 v[94:97], v[142:145], v[232:235], v[94:97]
	v_mfma_f32_16x16x32_bf16 v[90:93], v[154:157], v[228:231], v[90:93]
	v_mfma_f32_16x16x32_bf16 v[90:93], v[170:173], v[232:235], v[90:93]
	v_mfma_f32_16x16x32_bf16 v[82:85], v[182:185], v[228:231], v[82:85]
	v_mfma_f32_16x16x32_bf16 v[82:85], v[186:189], v[232:235], v[82:85]
	v_mfma_f32_16x16x32_bf16 v[86:89], v[174:177], v[228:231], v[86:89]
	v_mfma_f32_16x16x32_bf16 v[86:89], v[178:181], v[232:235], v[86:89]
	v_mfma_f32_16x16x32_bf16 v[70:73], v[174:177], v[236:239], v[70:73]
	v_mfma_f32_16x16x32_bf16 v[70:73], v[178:181], v[240:243], v[70:73]
	v_mfma_f32_16x16x32_bf16 v[66:69], v[182:185], v[236:239], v[66:69]
	v_mfma_f32_16x16x32_bf16 v[66:69], v[186:189], v[240:243], v[66:69]
	v_mfma_f32_16x16x32_bf16 v[74:77], v[154:157], v[236:239], v[74:77]
	v_mfma_f32_16x16x32_bf16 v[74:77], v[170:173], v[240:243], v[74:77]
	v_mfma_f32_16x16x32_bf16 v[78:81], v[132:135], v[236:239], v[78:81]
	v_mfma_f32_16x16x32_bf16 v[78:81], v[142:145], v[240:243], v[78:81]
	s_barrier
	s_setprio 0
	s_mov_b32 m0, s15
	s_mov_b32 s46, s62
	s_mov_b32 s47, s63
	ds_read_b128 v[190:193], v141 offset:16384
	ds_read_b128 v[194:197], v141 offset:17408
	ds_read_b128 v[198:201], v141 offset:18432
	ds_read_b128 v[202:205], v141 offset:19456
	ds_read_b128 v[228:231], v141 offset:20480
	ds_read_b128 v[232:235], v141 offset:21504
	ds_read_b128 v[236:239], v141 offset:22528
	ds_read_b128 v[240:243], v141 offset:23552
	buffer_load_dwordx4 v137, s[44:47], s26 offen lds
	s_mov_b32 m0, s16
	s_add_i32 s49, s26, 0x80000
	buffer_load_dwordx4 v139, s[44:47], s26 offen lds
	s_mov_b32 m0, s18
	s_nop 0
	buffer_load_dwordx4 v137, s[44:47], s49 offen lds
	s_mov_b32 m0, s19
	s_nop 0
	buffer_load_dwordx4 v139, s[44:47], s49 offen lds
	s_mov_b32 m0, s14
	s_nop 0
	buffer_load_dwordx4 v136, s[60:63], s27 offen lds
	s_mov_b32 m0, s24
	s_nop 0
	buffer_load_dwordx4 v138, s[60:63], s27 offen lds
	s_waitcnt vmcnt(8)
	s_waitcnt lgkmcnt(0)
	s_setprio 1
	s_barrier
	v_mfma_f32_16x16x32_bf16 v[62:65], v[132:135], v[190:193], v[62:65]
	v_mfma_f32_16x16x32_bf16 v[62:65], v[142:145], v[194:197], v[62:65]
	v_mfma_f32_16x16x32_bf16 v[58:61], v[154:157], v[190:193], v[58:61]
	v_mfma_f32_16x16x32_bf16 v[58:61], v[170:173], v[194:197], v[58:61]
	v_mfma_f32_16x16x32_bf16 v[50:53], v[182:185], v[190:193], v[50:53]
	v_mfma_f32_16x16x32_bf16 v[50:53], v[186:189], v[194:197], v[50:53]
	v_mfma_f32_16x16x32_bf16 v[54:57], v[174:177], v[190:193], v[54:57]
	v_mfma_f32_16x16x32_bf16 v[54:57], v[178:181], v[194:197], v[54:57]
	v_mfma_f32_16x16x32_bf16 v[38:41], v[174:177], v[198:201], v[38:41]
	v_mfma_f32_16x16x32_bf16 v[38:41], v[178:181], v[202:205], v[38:41]
	v_mfma_f32_16x16x32_bf16 v[34:37], v[182:185], v[198:201], v[34:37]
	v_mfma_f32_16x16x32_bf16 v[34:37], v[186:189], v[202:205], v[34:37]
	v_mfma_f32_16x16x32_bf16 v[42:45], v[154:157], v[198:201], v[42:45]
	v_mfma_f32_16x16x32_bf16 v[42:45], v[170:173], v[202:205], v[42:45]
	v_mfma_f32_16x16x32_bf16 v[46:49], v[132:135], v[198:201], v[46:49]
	v_mfma_f32_16x16x32_bf16 v[46:49], v[142:145], v[202:205], v[46:49]
	v_mfma_f32_16x16x32_bf16 v[30:33], v[132:135], v[228:231], v[30:33]
	v_mfma_f32_16x16x32_bf16 v[30:33], v[142:145], v[232:235], v[30:33]
	v_mfma_f32_16x16x32_bf16 v[26:29], v[154:157], v[228:231], v[26:29]
	v_mfma_f32_16x16x32_bf16 v[26:29], v[170:173], v[232:235], v[26:29]
	v_mfma_f32_16x16x32_bf16 v[18:21], v[182:185], v[228:231], v[18:21]
	v_mfma_f32_16x16x32_bf16 v[18:21], v[186:189], v[232:235], v[18:21]
	v_mfma_f32_16x16x32_bf16 v[22:25], v[174:177], v[228:231], v[22:25]
	v_mfma_f32_16x16x32_bf16 v[22:25], v[178:181], v[232:235], v[22:25]
	v_mfma_f32_16x16x32_bf16 v[6:9], v[174:177], v[236:239], v[6:9]
	v_mfma_f32_16x16x32_bf16 v[6:9], v[178:181], v[240:243], v[6:9]
	v_mfma_f32_16x16x32_bf16 v[2:5], v[182:185], v[236:239], v[2:5]
	v_mfma_f32_16x16x32_bf16 v[2:5], v[186:189], v[240:243], v[2:5]
	v_mfma_f32_16x16x32_bf16 v[10:13], v[154:157], v[236:239], v[10:13]
	v_mfma_f32_16x16x32_bf16 v[10:13], v[170:173], v[240:243], v[10:13]
	v_mfma_f32_16x16x32_bf16 v[14:17], v[132:135], v[236:239], v[14:17]
	v_mfma_f32_16x16x32_bf16 v[14:17], v[142:145], v[240:243], v[14:17]
	s_barrier
	s_setprio 0
	v_add_u32_e32 v170, 0x18000, v140
	v_add_u32_e32 v186, 0x1c000, v140
	ds_read_b128 v[132:135], v170
	ds_read_b128 v[142:145], v170 offset:1024
	ds_read_b128 v[154:157], v170 offset:2048
	ds_read_b128 v[170:173], v170 offset:3072
	ds_read_b128 v[174:177], v186
	ds_read_b128 v[178:181], v186 offset:1024
	ds_read_b128 v[182:185], v186 offset:2048
	ds_read_b128 v[186:189], v186 offset:3072
	s_add_i32 s27, s27, 0x80000
	s_mov_b32 m0, s25
	ds_read_b128 v[190:193], v141 offset:32768
	ds_read_b128 v[194:197], v141 offset:33792
	ds_read_b128 v[198:201], v141 offset:34816
	ds_read_b128 v[202:205], v141 offset:35840
	ds_read_b128 v[228:231], v141 offset:36864
	ds_read_b128 v[232:235], v141 offset:37888
	ds_read_b128 v[236:239], v141 offset:38912
	ds_read_b128 v[240:243], v141 offset:39936
	buffer_load_dwordx4 v136, s[60:63], s27 offen lds
	s_mov_b32 m0, s30
	s_nop 0
	buffer_load_dwordx4 v138, s[60:63], s27 offen lds
	s_waitcnt vmcnt(8)
	s_waitcnt lgkmcnt(0)
	s_setprio 1
	s_barrier
	v_mfma_f32_16x16x32_bf16 v[126:129], v[132:135], v[190:193], v[126:129]
	v_mfma_f32_16x16x32_bf16 v[126:129], v[142:145], v[194:197], v[126:129]
	v_mfma_f32_16x16x32_bf16 v[106:109], v[154:157], v[190:193], v[106:109]
	v_mfma_f32_16x16x32_bf16 v[106:109], v[170:173], v[194:197], v[106:109]
	v_mfma_f32_16x16x32_bf16 v[110:113], v[182:185], v[190:193], v[110:113]
	v_mfma_f32_16x16x32_bf16 v[110:113], v[186:189], v[194:197], v[110:113]
	v_mfma_f32_16x16x32_bf16 v[122:125], v[174:177], v[190:193], v[122:125]
	v_mfma_f32_16x16x32_bf16 v[122:125], v[178:181], v[194:197], v[122:125]
	v_mfma_f32_16x16x32_bf16 v[102:105], v[174:177], v[198:201], v[102:105]
	v_mfma_f32_16x16x32_bf16 v[102:105], v[178:181], v[202:205], v[102:105]
	v_mfma_f32_16x16x32_bf16 v[98:101], v[182:185], v[198:201], v[98:101]
	v_mfma_f32_16x16x32_bf16 v[98:101], v[186:189], v[202:205], v[98:101]
	v_mfma_f32_16x16x32_bf16 v[114:117], v[154:157], v[198:201], v[114:117]
	v_mfma_f32_16x16x32_bf16 v[114:117], v[170:173], v[202:205], v[114:117]
	v_mfma_f32_16x16x32_bf16 v[118:121], v[132:135], v[198:201], v[118:121]
	v_mfma_f32_16x16x32_bf16 v[118:121], v[142:145], v[202:205], v[118:121]
	v_mfma_f32_16x16x32_bf16 v[94:97], v[132:135], v[228:231], v[94:97]
	v_mfma_f32_16x16x32_bf16 v[94:97], v[142:145], v[232:235], v[94:97]
	v_mfma_f32_16x16x32_bf16 v[90:93], v[154:157], v[228:231], v[90:93]
	v_mfma_f32_16x16x32_bf16 v[90:93], v[170:173], v[232:235], v[90:93]
	v_mfma_f32_16x16x32_bf16 v[82:85], v[182:185], v[228:231], v[82:85]
	v_mfma_f32_16x16x32_bf16 v[82:85], v[186:189], v[232:235], v[82:85]
	v_mfma_f32_16x16x32_bf16 v[86:89], v[174:177], v[228:231], v[86:89]
	v_mfma_f32_16x16x32_bf16 v[86:89], v[178:181], v[232:235], v[86:89]
	v_mfma_f32_16x16x32_bf16 v[70:73], v[174:177], v[236:239], v[70:73]
	v_mfma_f32_16x16x32_bf16 v[70:73], v[178:181], v[240:243], v[70:73]
	v_mfma_f32_16x16x32_bf16 v[66:69], v[182:185], v[236:239], v[66:69]
	v_mfma_f32_16x16x32_bf16 v[66:69], v[186:189], v[240:243], v[66:69]
	v_mfma_f32_16x16x32_bf16 v[74:77], v[154:157], v[236:239], v[74:77]
	v_mfma_f32_16x16x32_bf16 v[74:77], v[170:173], v[240:243], v[74:77]
	v_mfma_f32_16x16x32_bf16 v[78:81], v[132:135], v[236:239], v[78:81]
	v_mfma_f32_16x16x32_bf16 v[78:81], v[142:145], v[240:243], v[78:81]
	s_barrier
	s_setprio 0
	s_mov_b32 m0, s36
	s_or_b32 s27, s26, 0x80
	ds_read_b128 v[190:193], v141 offset:49152
	ds_read_b128 v[194:197], v141 offset:50176
	ds_read_b128 v[198:201], v141 offset:51200
	ds_read_b128 v[202:205], v141 offset:52224
	ds_read_b128 v[228:231], v141 offset:53248
	ds_read_b128 v[232:235], v141 offset:54272
	ds_read_b128 v[236:239], v141 offset:55296
	ds_read_b128 v[240:243], v141 offset:56320
	buffer_load_dwordx4 v137, s[44:47], s27 offen lds
	s_mov_b32 m0, s37
	s_add_i32 s26, s26, 0x80080
	buffer_load_dwordx4 v139, s[44:47], s27 offen lds
	s_mov_b32 m0, s68
	s_nop 0
	buffer_load_dwordx4 v137, s[44:47], s26 offen lds
	s_mov_b32 m0, s69
	s_nop 0
	buffer_load_dwordx4 v139, s[44:47], s26 offen lds
	s_mov_b32 m0, s66
	s_nop 0
	buffer_load_dwordx4 v136, s[60:63], s23 offen lds
	s_mov_b32 m0, s67
	s_nop 0
	buffer_load_dwordx4 v138, s[60:63], s23 offen lds
	s_waitcnt vmcnt(8)
	s_waitcnt lgkmcnt(0)
	s_setprio 1
	s_barrier
	v_mfma_f32_16x16x32_bf16 v[62:65], v[132:135], v[190:193], v[62:65]
	v_mfma_f32_16x16x32_bf16 v[62:65], v[142:145], v[194:197], v[62:65]
	v_mfma_f32_16x16x32_bf16 v[58:61], v[154:157], v[190:193], v[58:61]
	v_mfma_f32_16x16x32_bf16 v[58:61], v[170:173], v[194:197], v[58:61]
	v_mfma_f32_16x16x32_bf16 v[50:53], v[182:185], v[190:193], v[50:53]
	v_mfma_f32_16x16x32_bf16 v[50:53], v[186:189], v[194:197], v[50:53]
	v_mfma_f32_16x16x32_bf16 v[54:57], v[174:177], v[190:193], v[54:57]
	v_mfma_f32_16x16x32_bf16 v[54:57], v[178:181], v[194:197], v[54:57]
	v_mfma_f32_16x16x32_bf16 v[38:41], v[174:177], v[198:201], v[38:41]
	v_mfma_f32_16x16x32_bf16 v[38:41], v[178:181], v[202:205], v[38:41]
	v_mfma_f32_16x16x32_bf16 v[34:37], v[182:185], v[198:201], v[34:37]
	v_mfma_f32_16x16x32_bf16 v[34:37], v[186:189], v[202:205], v[34:37]
	v_mfma_f32_16x16x32_bf16 v[42:45], v[154:157], v[198:201], v[42:45]
	v_mfma_f32_16x16x32_bf16 v[42:45], v[170:173], v[202:205], v[42:45]
	v_mfma_f32_16x16x32_bf16 v[46:49], v[132:135], v[198:201], v[46:49]
	v_mfma_f32_16x16x32_bf16 v[46:49], v[142:145], v[202:205], v[46:49]
	v_mfma_f32_16x16x32_bf16 v[30:33], v[132:135], v[228:231], v[30:33]
	v_mfma_f32_16x16x32_bf16 v[30:33], v[142:145], v[232:235], v[30:33]
	v_mfma_f32_16x16x32_bf16 v[26:29], v[154:157], v[228:231], v[26:29]
	v_mfma_f32_16x16x32_bf16 v[26:29], v[170:173], v[232:235], v[26:29]
	v_mfma_f32_16x16x32_bf16 v[18:21], v[182:185], v[228:231], v[18:21]
	v_mfma_f32_16x16x32_bf16 v[18:21], v[186:189], v[232:235], v[18:21]
	v_mfma_f32_16x16x32_bf16 v[22:25], v[174:177], v[228:231], v[22:25]
	v_mfma_f32_16x16x32_bf16 v[22:25], v[178:181], v[232:235], v[22:25]
	v_mfma_f32_16x16x32_bf16 v[6:9], v[174:177], v[236:239], v[6:9]
	v_mfma_f32_16x16x32_bf16 v[6:9], v[178:181], v[240:243], v[6:9]
	v_mfma_f32_16x16x32_bf16 v[2:5], v[182:185], v[236:239], v[2:5]
	v_mfma_f32_16x16x32_bf16 v[2:5], v[186:189], v[240:243], v[2:5]
	v_mfma_f32_16x16x32_bf16 v[10:13], v[154:157], v[236:239], v[10:13]
	v_mfma_f32_16x16x32_bf16 v[10:13], v[170:173], v[240:243], v[10:13]
	v_mfma_f32_16x16x32_bf16 v[14:17], v[132:135], v[236:239], v[14:17]
	v_mfma_f32_16x16x32_bf16 v[14:17], v[142:145], v[240:243], v[14:17]
	s_barrier
	s_setprio 0
	s_add_i32 s22, s22, 2
	s_addk_i32 s13, 0x100
	s_addk_i32 s21, 0x100
	s_cmp_gt_u32 s22, 29
	s_cbranch_scc0 .LBB0_1589
	s_and_b64 vcc, exec, s[64:65]
	s_cbranch_vccz .LBB0_1592
	s_barrier

.LBB0_1879:
	s_lshl_b32 s18, s91, 20
	s_and_b64 s[8:9], s[48:49], exec
	s_cselect_b32 s8, s18, s95
	s_lshl_b32 s19, s92, 20
	s_and_b64 s[42:43], s[48:49], exec
	s_cselect_b32 s9, s19, s94
	s_add_i32 vcc_lo, s95, 0x80080
	s_add_i32 vcc_hi, s94, 0x100
	s_mov_b32 s94, -2
	v_add_u32_e32 v139, 0x10000, v136
	ds_read_b128 v[140:143], v139
	ds_read_b128 v[154:157], v139 offset:1024
	ds_read_b128 v[170:173], v139 offset:2048
	ds_read_b128 v[174:177], v139 offset:3072
	v_add_u32_e32 v139, 0x14000, v136
	ds_read_b128 v[178:181], v139
	ds_read_b128 v[182:185], v139 offset:1024
	ds_read_b128 v[186:189], v139 offset:2048
	ds_read_b128 v[190:193], v139 offset:3072
	s_add_i32 s42, vcc_lo, 0xfff80080
	s_cmp_eq_u32 s94, 28
	s_cselect_b32 s52, s8, s42
	s_cselect_b32 s96, s9, vcc_hi
	s_or_b32 s95, s52, 0x80
	s_mov_b32 m0, s72
	ds_read_b128 v[194:197], v137
	ds_read_b128 v[198:201], v137 offset:1024
	ds_read_b128 v[202:205], v137 offset:2048
	ds_read_b128 v[228:231], v137 offset:3072
	ds_read_b128 v[232:235], v137 offset:4096
	ds_read_b128 v[236:239], v137 offset:5120
	ds_read_b128 v[240:243], v137 offset:6144
	ds_read_b128 v[244:247], v137 offset:7168
	buffer_load_dwordx4 v132, s[60:63], vcc_lo offen lds
	s_mov_b32 m0, s47
	s_nop 0
	buffer_load_dwordx4 v134, s[60:63], vcc_lo offen lds
	s_waitcnt vmcnt(8)
	s_waitcnt lgkmcnt(0)
	s_setprio 1
	s_barrier
	v_mfma_f32_16x16x32_bf16 v[114:117], v[140:143], v[194:197], 0
	v_mfma_f32_16x16x32_bf16 v[114:117], v[154:157], v[198:201], v[114:117]
	v_mfma_f32_16x16x32_bf16 v[110:113], v[170:173], v[194:197], 0
	v_mfma_f32_16x16x32_bf16 v[110:113], v[174:177], v[198:201], v[110:113]
	v_mfma_f32_16x16x32_bf16 v[122:125], v[186:189], v[194:197], 0
	v_mfma_f32_16x16x32_bf16 v[122:125], v[190:193], v[198:201], v[122:125]
	v_mfma_f32_16x16x32_bf16 v[126:129], v[178:181], v[194:197], 0
	v_mfma_f32_16x16x32_bf16 v[126:129], v[182:185], v[198:201], v[126:129]
	v_mfma_f32_16x16x32_bf16 v[118:121], v[178:181], v[202:205], 0
	v_mfma_f32_16x16x32_bf16 v[118:121], v[182:185], v[228:231], v[118:121]
	v_mfma_f32_16x16x32_bf16 v[98:101], v[186:189], v[202:205], 0
	v_mfma_f32_16x16x32_bf16 v[98:101], v[190:193], v[228:231], v[98:101]
	v_mfma_f32_16x16x32_bf16 v[102:105], v[170:173], v[202:205], 0
	v_mfma_f32_16x16x32_bf16 v[102:105], v[174:177], v[228:231], v[102:105]
	v_mfma_f32_16x16x32_bf16 v[106:109], v[140:143], v[202:205], 0
	v_mfma_f32_16x16x32_bf16 v[106:109], v[154:157], v[228:231], v[106:109]
	v_mfma_f32_16x16x32_bf16 v[94:97], v[140:143], v[232:235], 0
	v_mfma_f32_16x16x32_bf16 v[94:97], v[154:157], v[236:239], v[94:97]
	v_mfma_f32_16x16x32_bf16 v[86:89], v[170:173], v[232:235], 0
	v_mfma_f32_16x16x32_bf16 v[86:89], v[174:177], v[236:239], v[86:89]
	v_mfma_f32_16x16x32_bf16 v[82:85], v[186:189], v[232:235], 0
	v_mfma_f32_16x16x32_bf16 v[82:85], v[190:193], v[236:239], v[82:85]
	v_mfma_f32_16x16x32_bf16 v[90:93], v[178:181], v[232:235], 0
	v_mfma_f32_16x16x32_bf16 v[90:93], v[182:185], v[236:239], v[90:93]
	v_mfma_f32_16x16x32_bf16 v[74:77], v[178:181], v[240:243], 0
	v_mfma_f32_16x16x32_bf16 v[74:77], v[182:185], v[244:247], v[74:77]
	v_mfma_f32_16x16x32_bf16 v[66:69], v[186:189], v[240:243], 0
	v_mfma_f32_16x16x32_bf16 v[66:69], v[190:193], v[244:247], v[66:69]
	v_mfma_f32_16x16x32_bf16 v[70:73], v[170:173], v[240:243], 0
	v_mfma_f32_16x16x32_bf16 v[70:73], v[174:177], v[244:247], v[70:73]
	v_mfma_f32_16x16x32_bf16 v[78:81], v[140:143], v[240:243], 0
	v_mfma_f32_16x16x32_bf16 v[78:81], v[154:157], v[244:247], v[78:81]
	s_barrier
	s_setprio 0
	s_mov_b32 m0, s13
	s_mov_b32 s42, s62
	s_mov_b32 s43, s63
	ds_read_b128 v[194:197], v137 offset:16384
	ds_read_b128 v[198:201], v137 offset:17408
	ds_read_b128 v[202:205], v137 offset:18432
	ds_read_b128 v[228:231], v137 offset:19456
	ds_read_b128 v[232:235], v137 offset:20480
	ds_read_b128 v[236:239], v137 offset:21504
	ds_read_b128 v[240:243], v137 offset:22528
	ds_read_b128 v[244:247], v137 offset:23552
	buffer_load_dwordx4 v133, s[40:43], s96 offen lds
	s_mov_b32 m0, s14
	s_add_i32 s53, s96, 0x80000
	buffer_load_dwordx4 v135, s[40:43], s96 offen lds
	s_mov_b32 m0, s15
	s_nop 0
	buffer_load_dwordx4 v133, s[40:43], s53 offen lds
	s_mov_b32 m0, s16
	s_nop 0
	buffer_load_dwordx4 v135, s[40:43], s53 offen lds
	s_mov_b32 m0, s2
	s_nop 0
	buffer_load_dwordx4 v132, s[60:63], s52 offen lds
	s_mov_b32 m0, s21
	s_nop 0
	buffer_load_dwordx4 v134, s[60:63], s52 offen lds
	s_waitcnt vmcnt(8)
	s_waitcnt lgkmcnt(0)
	s_setprio 1
	s_barrier
	v_mfma_f32_16x16x32_bf16 v[62:65], v[140:143], v[194:197], 0
	v_mfma_f32_16x16x32_bf16 v[62:65], v[154:157], v[198:201], v[62:65]
	v_mfma_f32_16x16x32_bf16 v[54:57], v[170:173], v[194:197], 0
	v_mfma_f32_16x16x32_bf16 v[54:57], v[174:177], v[198:201], v[54:57]
	v_mfma_f32_16x16x32_bf16 v[50:53], v[186:189], v[194:197], 0
	v_mfma_f32_16x16x32_bf16 v[50:53], v[190:193], v[198:201], v[50:53]
	v_mfma_f32_16x16x32_bf16 v[58:61], v[178:181], v[194:197], 0
	v_mfma_f32_16x16x32_bf16 v[58:61], v[182:185], v[198:201], v[58:61]
	v_mfma_f32_16x16x32_bf16 v[42:45], v[178:181], v[202:205], 0
	v_mfma_f32_16x16x32_bf16 v[42:45], v[182:185], v[228:231], v[42:45]
	v_mfma_f32_16x16x32_bf16 v[34:37], v[186:189], v[202:205], 0
	v_mfma_f32_16x16x32_bf16 v[34:37], v[190:193], v[228:231], v[34:37]
	v_mfma_f32_16x16x32_bf16 v[38:41], v[170:173], v[202:205], 0
	v_mfma_f32_16x16x32_bf16 v[38:41], v[174:177], v[228:231], v[38:41]
	v_mfma_f32_16x16x32_bf16 v[46:49], v[140:143], v[202:205], 0
	v_mfma_f32_16x16x32_bf16 v[46:49], v[154:157], v[228:231], v[46:49]
	v_mfma_f32_16x16x32_bf16 v[30:33], v[140:143], v[232:235], 0
	v_mfma_f32_16x16x32_bf16 v[30:33], v[154:157], v[236:239], v[30:33]
	v_mfma_f32_16x16x32_bf16 v[22:25], v[170:173], v[232:235], 0
	v_mfma_f32_16x16x32_bf16 v[22:25], v[174:177], v[236:239], v[22:25]
	v_mfma_f32_16x16x32_bf16 v[18:21], v[186:189], v[232:235], 0
	v_mfma_f32_16x16x32_bf16 v[18:21], v[190:193], v[236:239], v[18:21]
	v_mfma_f32_16x16x32_bf16 v[26:29], v[178:181], v[232:235], 0
	v_mfma_f32_16x16x32_bf16 v[26:29], v[182:185], v[236:239], v[26:29]
	v_mfma_f32_16x16x32_bf16 v[10:13], v[178:181], v[240:243], 0
	v_mfma_f32_16x16x32_bf16 v[10:13], v[182:185], v[244:247], v[10:13]
	v_mfma_f32_16x16x32_bf16 v[2:5], v[186:189], v[240:243], 0
	v_mfma_f32_16x16x32_bf16 v[2:5], v[190:193], v[244:247], v[2:5]
	v_mfma_f32_16x16x32_bf16 v[6:9], v[170:173], v[240:243], 0
	v_mfma_f32_16x16x32_bf16 v[6:9], v[174:177], v[244:247], v[6:9]
	v_mfma_f32_16x16x32_bf16 v[14:17], v[140:143], v[240:243], 0
	v_mfma_f32_16x16x32_bf16 v[14:17], v[154:157], v[244:247], v[14:17]
	s_barrier
	s_setprio 0
	v_add_u32_e32 v139, 0x18000, v136
	ds_read_b128 v[140:143], v139
	ds_read_b128 v[154:157], v139 offset:1024
	ds_read_b128 v[170:173], v139 offset:2048
	ds_read_b128 v[174:177], v139 offset:3072
	v_add_u32_e32 v139, 0x1c000, v136
	ds_read_b128 v[178:181], v139
	ds_read_b128 v[182:185], v139 offset:1024
	ds_read_b128 v[186:189], v139 offset:2048
	ds_read_b128 v[190:193], v139 offset:3072
	s_add_i32 s52, s52, 0x80000
	s_mov_b32 m0, s23
	ds_read_b128 v[194:197], v137 offset:32768
	ds_read_b128 v[198:201], v137 offset:33792
	ds_read_b128 v[202:205], v137 offset:34816
	ds_read_b128 v[228:231], v137 offset:35840
	ds_read_b128 v[232:235], v137 offset:36864
	ds_read_b128 v[236:239], v137 offset:37888
	ds_read_b128 v[240:243], v137 offset:38912
	ds_read_b128 v[244:247], v137 offset:39936
	buffer_load_dwordx4 v132, s[60:63], s52 offen lds
	s_mov_b32 m0, s24
	s_nop 0
	buffer_load_dwordx4 v134, s[60:63], s52 offen lds
	s_waitcnt vmcnt(8)
	s_waitcnt lgkmcnt(0)
	s_setprio 1
	s_barrier
	v_mfma_f32_16x16x32_bf16 v[114:117], v[140:143], v[194:197], v[114:117]
	v_mfma_f32_16x16x32_bf16 v[114:117], v[154:157], v[198:201], v[114:117]
	v_mfma_f32_16x16x32_bf16 v[110:113], v[170:173], v[194:197], v[110:113]
	v_mfma_f32_16x16x32_bf16 v[110:113], v[174:177], v[198:201], v[110:113]
	v_mfma_f32_16x16x32_bf16 v[122:125], v[186:189], v[194:197], v[122:125]
	v_mfma_f32_16x16x32_bf16 v[122:125], v[190:193], v[198:201], v[122:125]
	v_mfma_f32_16x16x32_bf16 v[126:129], v[178:181], v[194:197], v[126:129]
	v_mfma_f32_16x16x32_bf16 v[126:129], v[182:185], v[198:201], v[126:129]
	v_mfma_f32_16x16x32_bf16 v[118:121], v[178:181], v[202:205], v[118:121]
	v_mfma_f32_16x16x32_bf16 v[118:121], v[182:185], v[228:231], v[118:121]
	v_mfma_f32_16x16x32_bf16 v[98:101], v[186:189], v[202:205], v[98:101]
	v_mfma_f32_16x16x32_bf16 v[98:101], v[190:193], v[228:231], v[98:101]
	v_mfma_f32_16x16x32_bf16 v[102:105], v[170:173], v[202:205], v[102:105]
	v_mfma_f32_16x16x32_bf16 v[102:105], v[174:177], v[228:231], v[102:105]
	v_mfma_f32_16x16x32_bf16 v[106:109], v[140:143], v[202:205], v[106:109]
	v_mfma_f32_16x16x32_bf16 v[106:109], v[154:157], v[228:231], v[106:109]
	v_mfma_f32_16x16x32_bf16 v[94:97], v[140:143], v[232:235], v[94:97]
	v_mfma_f32_16x16x32_bf16 v[94:97], v[154:157], v[236:239], v[94:97]
	v_mfma_f32_16x16x32_bf16 v[86:89], v[170:173], v[232:235], v[86:89]
	v_mfma_f32_16x16x32_bf16 v[86:89], v[174:177], v[236:239], v[86:89]
	v_mfma_f32_16x16x32_bf16 v[82:85], v[186:189], v[232:235], v[82:85]
	v_mfma_f32_16x16x32_bf16 v[82:85], v[190:193], v[236:239], v[82:85]
	v_mfma_f32_16x16x32_bf16 v[90:93], v[178:181], v[232:235], v[90:93]
	v_mfma_f32_16x16x32_bf16 v[90:93], v[182:185], v[236:239], v[90:93]
	v_mfma_f32_16x16x32_bf16 v[74:77], v[178:181], v[240:243], v[74:77]
	v_mfma_f32_16x16x32_bf16 v[74:77], v[182:185], v[244:247], v[74:77]
	v_mfma_f32_16x16x32_bf16 v[66:69], v[186:189], v[240:243], v[66:69]
	v_mfma_f32_16x16x32_bf16 v[66:69], v[190:193], v[244:247], v[66:69]
	v_mfma_f32_16x16x32_bf16 v[70:73], v[170:173], v[240:243], v[70:73]
	v_mfma_f32_16x16x32_bf16 v[70:73], v[174:177], v[244:247], v[70:73]
	v_mfma_f32_16x16x32_bf16 v[78:81], v[140:143], v[240:243], v[78:81]
	v_mfma_f32_16x16x32_bf16 v[78:81], v[154:157], v[244:247], v[78:81]
	s_barrier
	s_setprio 0
	s_mov_b32 m0, s31
	s_or_b32 s52, s96, 0x80
	ds_read_b128 v[194:197], v137 offset:49152
	ds_read_b128 v[198:201], v137 offset:50176
	ds_read_b128 v[202:205], v137 offset:51200
	ds_read_b128 v[228:231], v137 offset:52224
	ds_read_b128 v[232:235], v137 offset:53248
	ds_read_b128 v[236:239], v137 offset:54272
	ds_read_b128 v[240:243], v137 offset:55296
	ds_read_b128 v[244:247], v137 offset:56320
	buffer_load_dwordx4 v133, s[40:43], s52 offen lds
	s_mov_b32 m0, s33
	s_add_i32 s96, s96, 0x80080
	buffer_load_dwordx4 v135, s[40:43], s52 offen lds
	s_mov_b32 m0, s36
	s_nop 0
	buffer_load_dwordx4 v133, s[40:43], s96 offen lds
	s_mov_b32 m0, s37
	s_nop 0
	buffer_load_dwordx4 v135, s[40:43], s96 offen lds
	s_mov_b32 m0, s34
	s_nop 0
	buffer_load_dwordx4 v132, s[60:63], s95 offen lds
	s_mov_b32 m0, s35
	s_nop 0
	buffer_load_dwordx4 v134, s[60:63], s95 offen lds
	s_waitcnt vmcnt(8)
	s_waitcnt lgkmcnt(0)
	s_setprio 1
	s_barrier
	v_mfma_f32_16x16x32_bf16 v[62:65], v[140:143], v[194:197], v[62:65]
	v_mfma_f32_16x16x32_bf16 v[62:65], v[154:157], v[198:201], v[62:65]
	v_mfma_f32_16x16x32_bf16 v[54:57], v[170:173], v[194:197], v[54:57]
	v_mfma_f32_16x16x32_bf16 v[54:57], v[174:177], v[198:201], v[54:57]
	v_mfma_f32_16x16x32_bf16 v[50:53], v[186:189], v[194:197], v[50:53]
	v_mfma_f32_16x16x32_bf16 v[50:53], v[190:193], v[198:201], v[50:53]
	v_mfma_f32_16x16x32_bf16 v[58:61], v[178:181], v[194:197], v[58:61]
	v_mfma_f32_16x16x32_bf16 v[58:61], v[182:185], v[198:201], v[58:61]
	v_mfma_f32_16x16x32_bf16 v[42:45], v[178:181], v[202:205], v[42:45]
	v_mfma_f32_16x16x32_bf16 v[42:45], v[182:185], v[228:231], v[42:45]
	v_mfma_f32_16x16x32_bf16 v[34:37], v[186:189], v[202:205], v[34:37]
	v_mfma_f32_16x16x32_bf16 v[34:37], v[190:193], v[228:231], v[34:37]
	v_mfma_f32_16x16x32_bf16 v[38:41], v[170:173], v[202:205], v[38:41]
	v_mfma_f32_16x16x32_bf16 v[38:41], v[174:177], v[228:231], v[38:41]
	v_mfma_f32_16x16x32_bf16 v[46:49], v[140:143], v[202:205], v[46:49]
	v_mfma_f32_16x16x32_bf16 v[46:49], v[154:157], v[228:231], v[46:49]
	v_mfma_f32_16x16x32_bf16 v[30:33], v[140:143], v[232:235], v[30:33]
	v_mfma_f32_16x16x32_bf16 v[30:33], v[154:157], v[236:239], v[30:33]
	v_mfma_f32_16x16x32_bf16 v[22:25], v[170:173], v[232:235], v[22:25]
	v_mfma_f32_16x16x32_bf16 v[22:25], v[174:177], v[236:239], v[22:25]
	v_mfma_f32_16x16x32_bf16 v[18:21], v[186:189], v[232:235], v[18:21]
	v_mfma_f32_16x16x32_bf16 v[18:21], v[190:193], v[236:239], v[18:21]
	v_mfma_f32_16x16x32_bf16 v[26:29], v[178:181], v[232:235], v[26:29]
	v_mfma_f32_16x16x32_bf16 v[26:29], v[182:185], v[236:239], v[26:29]
	v_mfma_f32_16x16x32_bf16 v[10:13], v[178:181], v[240:243], v[10:13]
	v_mfma_f32_16x16x32_bf16 v[10:13], v[182:185], v[244:247], v[10:13]
	v_mfma_f32_16x16x32_bf16 v[2:5], v[186:189], v[240:243], v[2:5]
	v_mfma_f32_16x16x32_bf16 v[2:5], v[190:193], v[244:247], v[2:5]
	v_mfma_f32_16x16x32_bf16 v[6:9], v[170:173], v[240:243], v[6:9]
	v_mfma_f32_16x16x32_bf16 v[6:9], v[174:177], v[244:247], v[6:9]
	v_mfma_f32_16x16x32_bf16 v[14:17], v[140:143], v[240:243], v[14:17]
	v_mfma_f32_16x16x32_bf16 v[14:17], v[154:157], v[244:247], v[14:17]
	s_barrier
	s_setprio 0
	s_add_i32 s94, s94, 2
	s_addk_i32 vcc_lo, 0x100
	s_addk_i32 vcc_hi, 0x100
	s_cmp_gt_u32 s94, 29
.LBB0_1880:
	v_add_u32_e32 v139, 0x10000, v136
	ds_read_b128 v[140:143], v139
	ds_read_b128 v[154:157], v139 offset:1024
	ds_read_b128 v[170:173], v139 offset:2048
	ds_read_b128 v[174:177], v139 offset:3072
	v_add_u32_e32 v139, 0x14000, v136
	ds_read_b128 v[178:181], v139
	ds_read_b128 v[182:185], v139 offset:1024
	ds_read_b128 v[186:189], v139 offset:2048
	ds_read_b128 v[190:193], v139 offset:3072
	s_add_i32 s42, vcc_lo, 0xfff80080
	s_cmp_eq_u32 s94, 28
	s_cselect_b32 s52, s8, s42
	s_cselect_b32 s96, s9, vcc_hi
	s_or_b32 s95, s52, 0x80
	s_mov_b32 m0, s72
	ds_read_b128 v[194:197], v137
	ds_read_b128 v[198:201], v137 offset:1024
	ds_read_b128 v[202:205], v137 offset:2048
	ds_read_b128 v[228:231], v137 offset:3072
	ds_read_b128 v[232:235], v137 offset:4096
	ds_read_b128 v[236:239], v137 offset:5120
	ds_read_b128 v[240:243], v137 offset:6144
	ds_read_b128 v[244:247], v137 offset:7168
	buffer_load_dwordx4 v132, s[60:63], vcc_lo offen lds
	s_mov_b32 m0, s47
	s_nop 0
	buffer_load_dwordx4 v134, s[60:63], vcc_lo offen lds
	s_waitcnt vmcnt(8)
	s_waitcnt lgkmcnt(0)
	s_setprio 1
	s_barrier
	v_mfma_f32_16x16x32_bf16 v[114:117], v[140:143], v[194:197], v[114:117]
	v_mfma_f32_16x16x32_bf16 v[114:117], v[154:157], v[198:201], v[114:117]
	v_mfma_f32_16x16x32_bf16 v[110:113], v[170:173], v[194:197], v[110:113]
	v_mfma_f32_16x16x32_bf16 v[110:113], v[174:177], v[198:201], v[110:113]
	v_mfma_f32_16x16x32_bf16 v[122:125], v[186:189], v[194:197], v[122:125]
	v_mfma_f32_16x16x32_bf16 v[122:125], v[190:193], v[198:201], v[122:125]
	v_mfma_f32_16x16x32_bf16 v[126:129], v[178:181], v[194:197], v[126:129]
	v_mfma_f32_16x16x32_bf16 v[126:129], v[182:185], v[198:201], v[126:129]
	v_mfma_f32_16x16x32_bf16 v[118:121], v[178:181], v[202:205], v[118:121]
	v_mfma_f32_16x16x32_bf16 v[118:121], v[182:185], v[228:231], v[118:121]
	v_mfma_f32_16x16x32_bf16 v[98:101], v[186:189], v[202:205], v[98:101]
	v_mfma_f32_16x16x32_bf16 v[98:101], v[190:193], v[228:231], v[98:101]
	v_mfma_f32_16x16x32_bf16 v[102:105], v[170:173], v[202:205], v[102:105]
	v_mfma_f32_16x16x32_bf16 v[102:105], v[174:177], v[228:231], v[102:105]
	v_mfma_f32_16x16x32_bf16 v[106:109], v[140:143], v[202:205], v[106:109]
	v_mfma_f32_16x16x32_bf16 v[106:109], v[154:157], v[228:231], v[106:109]
	v_mfma_f32_16x16x32_bf16 v[94:97], v[140:143], v[232:235], v[94:97]
	v_mfma_f32_16x16x32_bf16 v[94:97], v[154:157], v[236:239], v[94:97]
	v_mfma_f32_16x16x32_bf16 v[86:89], v[170:173], v[232:235], v[86:89]
	v_mfma_f32_16x16x32_bf16 v[86:89], v[174:177], v[236:239], v[86:89]
	v_mfma_f32_16x16x32_bf16 v[82:85], v[186:189], v[232:235], v[82:85]
	v_mfma_f32_16x16x32_bf16 v[82:85], v[190:193], v[236:239], v[82:85]
	v_mfma_f32_16x16x32_bf16 v[90:93], v[178:181], v[232:235], v[90:93]
	v_mfma_f32_16x16x32_bf16 v[90:93], v[182:185], v[236:239], v[90:93]
	v_mfma_f32_16x16x32_bf16 v[74:77], v[178:181], v[240:243], v[74:77]
	v_mfma_f32_16x16x32_bf16 v[74:77], v[182:185], v[244:247], v[74:77]
	v_mfma_f32_16x16x32_bf16 v[66:69], v[186:189], v[240:243], v[66:69]
	v_mfma_f32_16x16x32_bf16 v[66:69], v[190:193], v[244:247], v[66:69]
	v_mfma_f32_16x16x32_bf16 v[70:73], v[170:173], v[240:243], v[70:73]
	v_mfma_f32_16x16x32_bf16 v[70:73], v[174:177], v[244:247], v[70:73]
	v_mfma_f32_16x16x32_bf16 v[78:81], v[140:143], v[240:243], v[78:81]
	v_mfma_f32_16x16x32_bf16 v[78:81], v[154:157], v[244:247], v[78:81]
	s_barrier
	s_setprio 0
	s_mov_b32 m0, s13
	s_mov_b32 s42, s62
	s_mov_b32 s43, s63
	ds_read_b128 v[194:197], v137 offset:16384
	ds_read_b128 v[198:201], v137 offset:17408
	ds_read_b128 v[202:205], v137 offset:18432
	ds_read_b128 v[228:231], v137 offset:19456
	ds_read_b128 v[232:235], v137 offset:20480
	ds_read_b128 v[236:239], v137 offset:21504
	ds_read_b128 v[240:243], v137 offset:22528
	ds_read_b128 v[244:247], v137 offset:23552
	buffer_load_dwordx4 v133, s[40:43], s96 offen lds
	s_mov_b32 m0, s14
	s_add_i32 s53, s96, 0x80000
	buffer_load_dwordx4 v135, s[40:43], s96 offen lds
	s_mov_b32 m0, s15
	s_nop 0
	buffer_load_dwordx4 v133, s[40:43], s53 offen lds
	s_mov_b32 m0, s16
	s_nop 0
	buffer_load_dwordx4 v135, s[40:43], s53 offen lds
	s_mov_b32 m0, s2
	s_nop 0
	buffer_load_dwordx4 v132, s[60:63], s52 offen lds
	s_mov_b32 m0, s21
	s_nop 0
	buffer_load_dwordx4 v134, s[60:63], s52 offen lds
	s_waitcnt vmcnt(8)
	s_waitcnt lgkmcnt(0)
	s_setprio 1
	s_barrier
	v_mfma_f32_16x16x32_bf16 v[62:65], v[140:143], v[194:197], v[62:65]
	v_mfma_f32_16x16x32_bf16 v[62:65], v[154:157], v[198:201], v[62:65]
	v_mfma_f32_16x16x32_bf16 v[54:57], v[170:173], v[194:197], v[54:57]
	v_mfma_f32_16x16x32_bf16 v[54:57], v[174:177], v[198:201], v[54:57]
	v_mfma_f32_16x16x32_bf16 v[50:53], v[186:189], v[194:197], v[50:53]
	v_mfma_f32_16x16x32_bf16 v[50:53], v[190:193], v[198:201], v[50:53]
	v_mfma_f32_16x16x32_bf16 v[58:61], v[178:181], v[194:197], v[58:61]
	v_mfma_f32_16x16x32_bf16 v[58:61], v[182:185], v[198:201], v[58:61]
	v_mfma_f32_16x16x32_bf16 v[42:45], v[178:181], v[202:205], v[42:45]
	v_mfma_f32_16x16x32_bf16 v[42:45], v[182:185], v[228:231], v[42:45]
	v_mfma_f32_16x16x32_bf16 v[34:37], v[186:189], v[202:205], v[34:37]
	v_mfma_f32_16x16x32_bf16 v[34:37], v[190:193], v[228:231], v[34:37]
	v_mfma_f32_16x16x32_bf16 v[38:41], v[170:173], v[202:205], v[38:41]
	v_mfma_f32_16x16x32_bf16 v[38:41], v[174:177], v[228:231], v[38:41]
	v_mfma_f32_16x16x32_bf16 v[46:49], v[140:143], v[202:205], v[46:49]
	v_mfma_f32_16x16x32_bf16 v[46:49], v[154:157], v[228:231], v[46:49]
	v_mfma_f32_16x16x32_bf16 v[30:33], v[140:143], v[232:235], v[30:33]
	v_mfma_f32_16x16x32_bf16 v[30:33], v[154:157], v[236:239], v[30:33]
	v_mfma_f32_16x16x32_bf16 v[22:25], v[170:173], v[232:235], v[22:25]
	v_mfma_f32_16x16x32_bf16 v[22:25], v[174:177], v[236:239], v[22:25]
	v_mfma_f32_16x16x32_bf16 v[18:21], v[186:189], v[232:235], v[18:21]
	v_mfma_f32_16x16x32_bf16 v[18:21], v[190:193], v[236:239], v[18:21]
	v_mfma_f32_16x16x32_bf16 v[26:29], v[178:181], v[232:235], v[26:29]
	v_mfma_f32_16x16x32_bf16 v[26:29], v[182:185], v[236:239], v[26:29]
	v_mfma_f32_16x16x32_bf16 v[10:13], v[178:181], v[240:243], v[10:13]
	v_mfma_f32_16x16x32_bf16 v[10:13], v[182:185], v[244:247], v[10:13]
	v_mfma_f32_16x16x32_bf16 v[2:5], v[186:189], v[240:243], v[2:5]
	v_mfma_f32_16x16x32_bf16 v[2:5], v[190:193], v[244:247], v[2:5]
	v_mfma_f32_16x16x32_bf16 v[6:9], v[170:173], v[240:243], v[6:9]
	v_mfma_f32_16x16x32_bf16 v[6:9], v[174:177], v[244:247], v[6:9]
	v_mfma_f32_16x16x32_bf16 v[14:17], v[140:143], v[240:243], v[14:17]
	v_mfma_f32_16x16x32_bf16 v[14:17], v[154:157], v[244:247], v[14:17]
	s_barrier
	s_setprio 0
	v_add_u32_e32 v139, 0x18000, v136
	ds_read_b128 v[140:143], v139
	ds_read_b128 v[154:157], v139 offset:1024
	ds_read_b128 v[170:173], v139 offset:2048
	ds_read_b128 v[174:177], v139 offset:3072
	v_add_u32_e32 v139, 0x1c000, v136
	ds_read_b128 v[178:181], v139
	ds_read_b128 v[182:185], v139 offset:1024
	ds_read_b128 v[186:189], v139 offset:2048
	ds_read_b128 v[190:193], v139 offset:3072
	s_add_i32 s52, s52, 0x80000
	s_mov_b32 m0, s23
	ds_read_b128 v[194:197], v137 offset:32768
	ds_read_b128 v[198:201], v137 offset:33792
	ds_read_b128 v[202:205], v137 offset:34816
	ds_read_b128 v[228:231], v137 offset:35840
	ds_read_b128 v[232:235], v137 offset:36864
	ds_read_b128 v[236:239], v137 offset:37888
	ds_read_b128 v[240:243], v137 offset:38912
	ds_read_b128 v[244:247], v137 offset:39936
	buffer_load_dwordx4 v132, s[60:63], s52 offen lds
	s_mov_b32 m0, s24
	s_nop 0
	buffer_load_dwordx4 v134, s[60:63], s52 offen lds
	s_waitcnt vmcnt(8)
	s_waitcnt lgkmcnt(0)
	s_setprio 1
	s_barrier
	v_mfma_f32_16x16x32_bf16 v[114:117], v[140:143], v[194:197], v[114:117]
	v_mfma_f32_16x16x32_bf16 v[114:117], v[154:157], v[198:201], v[114:117]
	v_mfma_f32_16x16x32_bf16 v[110:113], v[170:173], v[194:197], v[110:113]
	v_mfma_f32_16x16x32_bf16 v[110:113], v[174:177], v[198:201], v[110:113]
	v_mfma_f32_16x16x32_bf16 v[122:125], v[186:189], v[194:197], v[122:125]
	v_mfma_f32_16x16x32_bf16 v[122:125], v[190:193], v[198:201], v[122:125]
	v_mfma_f32_16x16x32_bf16 v[126:129], v[178:181], v[194:197], v[126:129]
	v_mfma_f32_16x16x32_bf16 v[126:129], v[182:185], v[198:201], v[126:129]
	v_mfma_f32_16x16x32_bf16 v[118:121], v[178:181], v[202:205], v[118:121]
	v_mfma_f32_16x16x32_bf16 v[118:121], v[182:185], v[228:231], v[118:121]
	v_mfma_f32_16x16x32_bf16 v[98:101], v[186:189], v[202:205], v[98:101]
	v_mfma_f32_16x16x32_bf16 v[98:101], v[190:193], v[228:231], v[98:101]
	v_mfma_f32_16x16x32_bf16 v[102:105], v[170:173], v[202:205], v[102:105]
	v_mfma_f32_16x16x32_bf16 v[102:105], v[174:177], v[228:231], v[102:105]
	v_mfma_f32_16x16x32_bf16 v[106:109], v[140:143], v[202:205], v[106:109]
	v_mfma_f32_16x16x32_bf16 v[106:109], v[154:157], v[228:231], v[106:109]
	v_mfma_f32_16x16x32_bf16 v[94:97], v[140:143], v[232:235], v[94:97]
	v_mfma_f32_16x16x32_bf16 v[94:97], v[154:157], v[236:239], v[94:97]
	v_mfma_f32_16x16x32_bf16 v[86:89], v[170:173], v[232:235], v[86:89]
	v_mfma_f32_16x16x32_bf16 v[86:89], v[174:177], v[236:239], v[86:89]
	v_mfma_f32_16x16x32_bf16 v[82:85], v[186:189], v[232:235], v[82:85]
	v_mfma_f32_16x16x32_bf16 v[82:85], v[190:193], v[236:239], v[82:85]
	v_mfma_f32_16x16x32_bf16 v[90:93], v[178:181], v[232:235], v[90:93]
	v_mfma_f32_16x16x32_bf16 v[90:93], v[182:185], v[236:239], v[90:93]
	v_mfma_f32_16x16x32_bf16 v[74:77], v[178:181], v[240:243], v[74:77]
	v_mfma_f32_16x16x32_bf16 v[74:77], v[182:185], v[244:247], v[74:77]
	v_mfma_f32_16x16x32_bf16 v[66:69], v[186:189], v[240:243], v[66:69]
	v_mfma_f32_16x16x32_bf16 v[66:69], v[190:193], v[244:247], v[66:69]
	v_mfma_f32_16x16x32_bf16 v[70:73], v[170:173], v[240:243], v[70:73]
	v_mfma_f32_16x16x32_bf16 v[70:73], v[174:177], v[244:247], v[70:73]
	v_mfma_f32_16x16x32_bf16 v[78:81], v[140:143], v[240:243], v[78:81]
	v_mfma_f32_16x16x32_bf16 v[78:81], v[154:157], v[244:247], v[78:81]
	s_barrier
	s_setprio 0
	s_mov_b32 m0, s31
	s_or_b32 s52, s96, 0x80
	ds_read_b128 v[194:197], v137 offset:49152
	ds_read_b128 v[198:201], v137 offset:50176
	ds_read_b128 v[202:205], v137 offset:51200
	ds_read_b128 v[228:231], v137 offset:52224
	ds_read_b128 v[232:235], v137 offset:53248
	ds_read_b128 v[236:239], v137 offset:54272
	ds_read_b128 v[240:243], v137 offset:55296
	ds_read_b128 v[244:247], v137 offset:56320
	buffer_load_dwordx4 v133, s[40:43], s52 offen lds
	s_mov_b32 m0, s33
	s_add_i32 s96, s96, 0x80080
	buffer_load_dwordx4 v135, s[40:43], s52 offen lds
	s_mov_b32 m0, s36
	s_nop 0
	buffer_load_dwordx4 v133, s[40:43], s96 offen lds
	s_mov_b32 m0, s37
	s_nop 0
	buffer_load_dwordx4 v135, s[40:43], s96 offen lds
	s_mov_b32 m0, s34
	s_nop 0
	buffer_load_dwordx4 v132, s[60:63], s95 offen lds
	s_mov_b32 m0, s35
	s_nop 0
	buffer_load_dwordx4 v134, s[60:63], s95 offen lds
	s_waitcnt vmcnt(8)
	s_waitcnt lgkmcnt(0)
	s_setprio 1
	s_barrier
	v_mfma_f32_16x16x32_bf16 v[62:65], v[140:143], v[194:197], v[62:65]
	v_mfma_f32_16x16x32_bf16 v[62:65], v[154:157], v[198:201], v[62:65]
	v_mfma_f32_16x16x32_bf16 v[54:57], v[170:173], v[194:197], v[54:57]
	v_mfma_f32_16x16x32_bf16 v[54:57], v[174:177], v[198:201], v[54:57]
	v_mfma_f32_16x16x32_bf16 v[50:53], v[186:189], v[194:197], v[50:53]
	v_mfma_f32_16x16x32_bf16 v[50:53], v[190:193], v[198:201], v[50:53]
	v_mfma_f32_16x16x32_bf16 v[58:61], v[178:181], v[194:197], v[58:61]
	v_mfma_f32_16x16x32_bf16 v[58:61], v[182:185], v[198:201], v[58:61]
	v_mfma_f32_16x16x32_bf16 v[42:45], v[178:181], v[202:205], v[42:45]
	v_mfma_f32_16x16x32_bf16 v[42:45], v[182:185], v[228:231], v[42:45]
	v_mfma_f32_16x16x32_bf16 v[34:37], v[186:189], v[202:205], v[34:37]
	v_mfma_f32_16x16x32_bf16 v[34:37], v[190:193], v[228:231], v[34:37]
	v_mfma_f32_16x16x32_bf16 v[38:41], v[170:173], v[202:205], v[38:41]
	v_mfma_f32_16x16x32_bf16 v[38:41], v[174:177], v[228:231], v[38:41]
	v_mfma_f32_16x16x32_bf16 v[46:49], v[140:143], v[202:205], v[46:49]
	v_mfma_f32_16x16x32_bf16 v[46:49], v[154:157], v[228:231], v[46:49]
	v_mfma_f32_16x16x32_bf16 v[30:33], v[140:143], v[232:235], v[30:33]
	v_mfma_f32_16x16x32_bf16 v[30:33], v[154:157], v[236:239], v[30:33]
	v_mfma_f32_16x16x32_bf16 v[22:25], v[170:173], v[232:235], v[22:25]
	v_mfma_f32_16x16x32_bf16 v[22:25], v[174:177], v[236:239], v[22:25]
	v_mfma_f32_16x16x32_bf16 v[18:21], v[186:189], v[232:235], v[18:21]
	v_mfma_f32_16x16x32_bf16 v[18:21], v[190:193], v[236:239], v[18:21]
	v_mfma_f32_16x16x32_bf16 v[26:29], v[178:181], v[232:235], v[26:29]
	v_mfma_f32_16x16x32_bf16 v[26:29], v[182:185], v[236:239], v[26:29]
	v_mfma_f32_16x16x32_bf16 v[10:13], v[178:181], v[240:243], v[10:13]
	v_mfma_f32_16x16x32_bf16 v[10:13], v[182:185], v[244:247], v[10:13]
	v_mfma_f32_16x16x32_bf16 v[2:5], v[186:189], v[240:243], v[2:5]
	v_mfma_f32_16x16x32_bf16 v[2:5], v[190:193], v[244:247], v[2:5]
	v_mfma_f32_16x16x32_bf16 v[6:9], v[170:173], v[240:243], v[6:9]
	v_mfma_f32_16x16x32_bf16 v[6:9], v[174:177], v[244:247], v[6:9]
	v_mfma_f32_16x16x32_bf16 v[14:17], v[140:143], v[240:243], v[14:17]
	v_mfma_f32_16x16x32_bf16 v[14:17], v[154:157], v[244:247], v[14:17]
	s_barrier
	s_setprio 0
	s_add_i32 s94, s94, 2
	s_addk_i32 vcc_lo, 0x100
	s_addk_i32 vcc_hi, 0x100
	s_cmp_gt_u32 s94, 29
	s_cbranch_scc0 .LBB0_1880
	s_and_b64 vcc, exec, s[64:65]
	s_cbranch_vccz .LBB0_1883
	s_barrier

.LBB0_2155:
	s_mul_i32 s49, s48, 0x2c0000
	s_and_b64 s[8:9], s[42:43], exec
	s_mul_i32 s23, s15, 0x2c0000
	s_cselect_b32 s8, s49, s21
	s_cselect_b32 s9, s23, s13
	s_addk_i32 s13, 0x100
	s_add_i32 s21, s21, 0xc000
	s_mov_b32 s22, -2
	s_waitcnt lgkmcnt(0)
	v_add_u32_e32 v170, 0x10000, v140
	v_add_u32_e32 v186, 0x14000, v140
	ds_read_b128 v[132:135], v170
	ds_read_b128 v[142:145], v170 offset:1024
	ds_read_b128 v[154:157], v170 offset:2048
	ds_read_b128 v[170:173], v170 offset:3072
	ds_read_b128 v[174:177], v186
	ds_read_b128 v[178:181], v186 offset:1024
	ds_read_b128 v[182:185], v186 offset:2048
	ds_read_b128 v[186:189], v186 offset:3072
	s_add_i32 s26, s21, 0x4000
	s_cmpk_eq_i32 s22, 0x54
	s_cselect_b32 s52, s8, s26
	s_cselect_b32 s27, s9, s13
	s_or_b32 s26, s52, 0x8000
	s_mov_b32 m0, s84
	ds_read_b128 v[190:193], v141
	ds_read_b128 v[194:197], v141 offset:1024
	ds_read_b128 v[198:201], v141 offset:2048
	ds_read_b128 v[202:205], v141 offset:3072
	ds_read_b128 v[228:231], v141 offset:4096
	ds_read_b128 v[232:235], v141 offset:5120
	ds_read_b128 v[236:239], v141 offset:6144
	ds_read_b128 v[240:243], v141 offset:7168
	buffer_load_dwordx4 v136, s[60:63], s21 offen lds
	s_mov_b32 m0, s16
	s_nop 0
	buffer_load_dwordx4 v138, s[60:63], s21 offen lds
	s_waitcnt vmcnt(8)
	s_waitcnt lgkmcnt(0)
	s_setprio 1
	s_barrier
	v_mfma_f32_16x16x32_bf16 v[126:129], v[132:135], v[190:193], 0
	v_mfma_f32_16x16x32_bf16 v[126:129], v[142:145], v[194:197], v[126:129]
	v_mfma_f32_16x16x32_bf16 v[106:109], v[154:157], v[190:193], 0
	v_mfma_f32_16x16x32_bf16 v[106:109], v[170:173], v[194:197], v[106:109]
	v_mfma_f32_16x16x32_bf16 v[110:113], v[182:185], v[190:193], 0
	v_mfma_f32_16x16x32_bf16 v[110:113], v[186:189], v[194:197], v[110:113]
	v_mfma_f32_16x16x32_bf16 v[122:125], v[174:177], v[190:193], 0
	v_mfma_f32_16x16x32_bf16 v[122:125], v[178:181], v[194:197], v[122:125]
	v_mfma_f32_16x16x32_bf16 v[102:105], v[174:177], v[198:201], 0
	v_mfma_f32_16x16x32_bf16 v[102:105], v[178:181], v[202:205], v[102:105]
	v_mfma_f32_16x16x32_bf16 v[98:101], v[182:185], v[198:201], 0
	v_mfma_f32_16x16x32_bf16 v[98:101], v[186:189], v[202:205], v[98:101]
	v_mfma_f32_16x16x32_bf16 v[114:117], v[154:157], v[198:201], 0
	v_mfma_f32_16x16x32_bf16 v[114:117], v[170:173], v[202:205], v[114:117]
	v_mfma_f32_16x16x32_bf16 v[118:121], v[132:135], v[198:201], 0
	v_mfma_f32_16x16x32_bf16 v[118:121], v[142:145], v[202:205], v[118:121]
	v_mfma_f32_16x16x32_bf16 v[94:97], v[132:135], v[228:231], 0
	v_mfma_f32_16x16x32_bf16 v[94:97], v[142:145], v[232:235], v[94:97]
	v_mfma_f32_16x16x32_bf16 v[90:93], v[154:157], v[228:231], 0
	v_mfma_f32_16x16x32_bf16 v[90:93], v[170:173], v[232:235], v[90:93]
	v_mfma_f32_16x16x32_bf16 v[82:85], v[182:185], v[228:231], 0
	v_mfma_f32_16x16x32_bf16 v[82:85], v[186:189], v[232:235], v[82:85]
	v_mfma_f32_16x16x32_bf16 v[86:89], v[174:177], v[228:231], 0
	v_mfma_f32_16x16x32_bf16 v[86:89], v[178:181], v[232:235], v[86:89]
	v_mfma_f32_16x16x32_bf16 v[70:73], v[174:177], v[236:239], 0
	v_mfma_f32_16x16x32_bf16 v[70:73], v[178:181], v[240:243], v[70:73]
	v_mfma_f32_16x16x32_bf16 v[66:69], v[182:185], v[236:239], 0
	v_mfma_f32_16x16x32_bf16 v[66:69], v[186:189], v[240:243], v[66:69]
	v_mfma_f32_16x16x32_bf16 v[74:77], v[154:157], v[236:239], 0
	v_mfma_f32_16x16x32_bf16 v[74:77], v[170:173], v[240:243], v[74:77]
	v_mfma_f32_16x16x32_bf16 v[78:81], v[132:135], v[236:239], 0
	v_mfma_f32_16x16x32_bf16 v[78:81], v[142:145], v[240:243], v[78:81]
	s_barrier
	s_setprio 0
	s_mov_b32 m0, s18
	s_mov_b32 s46, s62
	s_mov_b32 s47, s63
	ds_read_b128 v[190:193], v141 offset:16384
	ds_read_b128 v[194:197], v141 offset:17408
	ds_read_b128 v[198:201], v141 offset:18432
	ds_read_b128 v[202:205], v141 offset:19456
	ds_read_b128 v[228:231], v141 offset:20480
	ds_read_b128 v[232:235], v141 offset:21504
	ds_read_b128 v[236:239], v141 offset:22528
	ds_read_b128 v[240:243], v141 offset:23552
	buffer_load_dwordx4 v137, s[44:47], s27 offen lds
	s_mov_b32 m0, s19
	s_add_i32 s53, s27, 0x160000
	buffer_load_dwordx4 v139, s[44:47], s27 offen lds
	s_mov_b32 m0, s24
	s_nop 0
	buffer_load_dwordx4 v137, s[44:47], s53 offen lds
	s_mov_b32 m0, s25
	s_nop 0
	buffer_load_dwordx4 v139, s[44:47], s53 offen lds
	s_mov_b32 m0, s14
	s_nop 0
	buffer_load_dwordx4 v136, s[60:63], s52 offen lds
	s_mov_b32 m0, s30
	s_nop 0
	buffer_load_dwordx4 v138, s[60:63], s52 offen lds
	s_waitcnt vmcnt(8)
	s_waitcnt lgkmcnt(0)
	s_setprio 1
	s_barrier
	v_mfma_f32_16x16x32_bf16 v[62:65], v[132:135], v[190:193], 0
	v_mfma_f32_16x16x32_bf16 v[62:65], v[142:145], v[194:197], v[62:65]
	v_mfma_f32_16x16x32_bf16 v[58:61], v[154:157], v[190:193], 0
	v_mfma_f32_16x16x32_bf16 v[58:61], v[170:173], v[194:197], v[58:61]
	v_mfma_f32_16x16x32_bf16 v[50:53], v[182:185], v[190:193], 0
	v_mfma_f32_16x16x32_bf16 v[50:53], v[186:189], v[194:197], v[50:53]
	v_mfma_f32_16x16x32_bf16 v[54:57], v[174:177], v[190:193], 0
	v_mfma_f32_16x16x32_bf16 v[54:57], v[178:181], v[194:197], v[54:57]
	v_mfma_f32_16x16x32_bf16 v[38:41], v[174:177], v[198:201], 0
	v_mfma_f32_16x16x32_bf16 v[38:41], v[178:181], v[202:205], v[38:41]
	v_mfma_f32_16x16x32_bf16 v[34:37], v[182:185], v[198:201], 0
	v_mfma_f32_16x16x32_bf16 v[34:37], v[186:189], v[202:205], v[34:37]
	v_mfma_f32_16x16x32_bf16 v[42:45], v[154:157], v[198:201], 0
	v_mfma_f32_16x16x32_bf16 v[42:45], v[170:173], v[202:205], v[42:45]
	v_mfma_f32_16x16x32_bf16 v[46:49], v[132:135], v[198:201], 0
	v_mfma_f32_16x16x32_bf16 v[46:49], v[142:145], v[202:205], v[46:49]
	v_mfma_f32_16x16x32_bf16 v[30:33], v[132:135], v[228:231], 0
	v_mfma_f32_16x16x32_bf16 v[30:33], v[142:145], v[232:235], v[30:33]
	v_mfma_f32_16x16x32_bf16 v[26:29], v[154:157], v[228:231], 0
	v_mfma_f32_16x16x32_bf16 v[26:29], v[170:173], v[232:235], v[26:29]
	v_mfma_f32_16x16x32_bf16 v[18:21], v[182:185], v[228:231], 0
	v_mfma_f32_16x16x32_bf16 v[18:21], v[186:189], v[232:235], v[18:21]
	v_mfma_f32_16x16x32_bf16 v[22:25], v[174:177], v[228:231], 0
	v_mfma_f32_16x16x32_bf16 v[22:25], v[178:181], v[232:235], v[22:25]
	v_mfma_f32_16x16x32_bf16 v[6:9], v[174:177], v[236:239], 0
	v_mfma_f32_16x16x32_bf16 v[6:9], v[178:181], v[240:243], v[6:9]
	v_mfma_f32_16x16x32_bf16 v[2:5], v[182:185], v[236:239], 0
	v_mfma_f32_16x16x32_bf16 v[2:5], v[186:189], v[240:243], v[2:5]
	v_mfma_f32_16x16x32_bf16 v[10:13], v[154:157], v[236:239], 0
	v_mfma_f32_16x16x32_bf16 v[10:13], v[170:173], v[240:243], v[10:13]
	v_mfma_f32_16x16x32_bf16 v[14:17], v[132:135], v[236:239], 0
	v_mfma_f32_16x16x32_bf16 v[14:17], v[142:145], v[240:243], v[14:17]
	s_barrier
	s_setprio 0
	v_add_u32_e32 v170, 0x18000, v140
	v_add_u32_e32 v186, 0x1c000, v140
	ds_read_b128 v[132:135], v170
	ds_read_b128 v[142:145], v170 offset:1024
	ds_read_b128 v[154:157], v170 offset:2048
	ds_read_b128 v[170:173], v170 offset:3072
	ds_read_b128 v[174:177], v186
	ds_read_b128 v[178:181], v186 offset:1024
	ds_read_b128 v[182:185], v186 offset:2048
	ds_read_b128 v[186:189], v186 offset:3072
	s_bitset1_b32 s52, 14
	s_mov_b32 m0, s31
	ds_read_b128 v[190:193], v141 offset:32768
	ds_read_b128 v[194:197], v141 offset:33792
	ds_read_b128 v[198:201], v141 offset:34816
	ds_read_b128 v[202:205], v141 offset:35840
	ds_read_b128 v[228:231], v141 offset:36864
	ds_read_b128 v[232:235], v141 offset:37888
	ds_read_b128 v[236:239], v141 offset:38912
	ds_read_b128 v[240:243], v141 offset:39936
	buffer_load_dwordx4 v136, s[60:63], s52 offen lds
	s_mov_b32 m0, s33
	s_nop 0
	buffer_load_dwordx4 v138, s[60:63], s52 offen lds
	s_waitcnt vmcnt(8)
	s_waitcnt lgkmcnt(0)
	s_setprio 1
	s_barrier
	v_mfma_f32_16x16x32_bf16 v[126:129], v[132:135], v[190:193], v[126:129]
	v_mfma_f32_16x16x32_bf16 v[126:129], v[142:145], v[194:197], v[126:129]
	v_mfma_f32_16x16x32_bf16 v[106:109], v[154:157], v[190:193], v[106:109]
	v_mfma_f32_16x16x32_bf16 v[106:109], v[170:173], v[194:197], v[106:109]
	v_mfma_f32_16x16x32_bf16 v[110:113], v[182:185], v[190:193], v[110:113]
	v_mfma_f32_16x16x32_bf16 v[110:113], v[186:189], v[194:197], v[110:113]
	v_mfma_f32_16x16x32_bf16 v[122:125], v[174:177], v[190:193], v[122:125]
	v_mfma_f32_16x16x32_bf16 v[122:125], v[178:181], v[194:197], v[122:125]
	v_mfma_f32_16x16x32_bf16 v[102:105], v[174:177], v[198:201], v[102:105]
	v_mfma_f32_16x16x32_bf16 v[102:105], v[178:181], v[202:205], v[102:105]
	v_mfma_f32_16x16x32_bf16 v[98:101], v[182:185], v[198:201], v[98:101]
	v_mfma_f32_16x16x32_bf16 v[98:101], v[186:189], v[202:205], v[98:101]
	v_mfma_f32_16x16x32_bf16 v[114:117], v[154:157], v[198:201], v[114:117]
	v_mfma_f32_16x16x32_bf16 v[114:117], v[170:173], v[202:205], v[114:117]
	v_mfma_f32_16x16x32_bf16 v[118:121], v[132:135], v[198:201], v[118:121]
	v_mfma_f32_16x16x32_bf16 v[118:121], v[142:145], v[202:205], v[118:121]
	v_mfma_f32_16x16x32_bf16 v[94:97], v[132:135], v[228:231], v[94:97]
	v_mfma_f32_16x16x32_bf16 v[94:97], v[142:145], v[232:235], v[94:97]
	v_mfma_f32_16x16x32_bf16 v[90:93], v[154:157], v[228:231], v[90:93]
	v_mfma_f32_16x16x32_bf16 v[90:93], v[170:173], v[232:235], v[90:93]
	v_mfma_f32_16x16x32_bf16 v[82:85], v[182:185], v[228:231], v[82:85]
	v_mfma_f32_16x16x32_bf16 v[82:85], v[186:189], v[232:235], v[82:85]
	v_mfma_f32_16x16x32_bf16 v[86:89], v[174:177], v[228:231], v[86:89]
	v_mfma_f32_16x16x32_bf16 v[86:89], v[178:181], v[232:235], v[86:89]
	v_mfma_f32_16x16x32_bf16 v[70:73], v[174:177], v[236:239], v[70:73]
	v_mfma_f32_16x16x32_bf16 v[70:73], v[178:181], v[240:243], v[70:73]
	v_mfma_f32_16x16x32_bf16 v[66:69], v[182:185], v[236:239], v[66:69]
	v_mfma_f32_16x16x32_bf16 v[66:69], v[186:189], v[240:243], v[66:69]
	v_mfma_f32_16x16x32_bf16 v[74:77], v[154:157], v[236:239], v[74:77]
	v_mfma_f32_16x16x32_bf16 v[74:77], v[170:173], v[240:243], v[74:77]
	v_mfma_f32_16x16x32_bf16 v[78:81], v[132:135], v[236:239], v[78:81]
	v_mfma_f32_16x16x32_bf16 v[78:81], v[142:145], v[240:243], v[78:81]
	s_barrier
	s_setprio 0
	s_mov_b32 m0, s68
	s_or_b32 s52, s27, 0x80
	ds_read_b128 v[190:193], v141 offset:49152
	ds_read_b128 v[194:197], v141 offset:50176
	ds_read_b128 v[198:201], v141 offset:51200
	ds_read_b128 v[202:205], v141 offset:52224
	ds_read_b128 v[228:231], v141 offset:53248
	ds_read_b128 v[232:235], v141 offset:54272
	ds_read_b128 v[236:239], v141 offset:55296
	ds_read_b128 v[240:243], v141 offset:56320
	buffer_load_dwordx4 v137, s[44:47], s52 offen lds
	s_mov_b32 m0, s69
	s_add_i32 s27, s27, 0x160080
	buffer_load_dwordx4 v139, s[44:47], s52 offen lds
	s_mov_b32 m0, s72
	s_nop 0
	buffer_load_dwordx4 v137, s[44:47], s27 offen lds
	s_mov_b32 m0, s73
	s_nop 0
	buffer_load_dwordx4 v139, s[44:47], s27 offen lds
	s_mov_b32 m0, s70
	s_nop 0
	buffer_load_dwordx4 v136, s[60:63], s26 offen lds
	s_mov_b32 m0, s71
	s_nop 0
	buffer_load_dwordx4 v138, s[60:63], s26 offen lds
	s_waitcnt vmcnt(8)
	s_waitcnt lgkmcnt(0)
	s_setprio 1
	s_barrier
	v_mfma_f32_16x16x32_bf16 v[62:65], v[132:135], v[190:193], v[62:65]
	v_mfma_f32_16x16x32_bf16 v[62:65], v[142:145], v[194:197], v[62:65]
	v_mfma_f32_16x16x32_bf16 v[58:61], v[154:157], v[190:193], v[58:61]
	v_mfma_f32_16x16x32_bf16 v[58:61], v[170:173], v[194:197], v[58:61]
	v_mfma_f32_16x16x32_bf16 v[50:53], v[182:185], v[190:193], v[50:53]
	v_mfma_f32_16x16x32_bf16 v[50:53], v[186:189], v[194:197], v[50:53]
	v_mfma_f32_16x16x32_bf16 v[54:57], v[174:177], v[190:193], v[54:57]
	v_mfma_f32_16x16x32_bf16 v[54:57], v[178:181], v[194:197], v[54:57]
	v_mfma_f32_16x16x32_bf16 v[38:41], v[174:177], v[198:201], v[38:41]
	v_mfma_f32_16x16x32_bf16 v[38:41], v[178:181], v[202:205], v[38:41]
	v_mfma_f32_16x16x32_bf16 v[34:37], v[182:185], v[198:201], v[34:37]
	v_mfma_f32_16x16x32_bf16 v[34:37], v[186:189], v[202:205], v[34:37]
	v_mfma_f32_16x16x32_bf16 v[42:45], v[154:157], v[198:201], v[42:45]
	v_mfma_f32_16x16x32_bf16 v[42:45], v[170:173], v[202:205], v[42:45]
	v_mfma_f32_16x16x32_bf16 v[46:49], v[132:135], v[198:201], v[46:49]
	v_mfma_f32_16x16x32_bf16 v[46:49], v[142:145], v[202:205], v[46:49]
	v_mfma_f32_16x16x32_bf16 v[30:33], v[132:135], v[228:231], v[30:33]
	v_mfma_f32_16x16x32_bf16 v[30:33], v[142:145], v[232:235], v[30:33]
	v_mfma_f32_16x16x32_bf16 v[26:29], v[154:157], v[228:231], v[26:29]
	v_mfma_f32_16x16x32_bf16 v[26:29], v[170:173], v[232:235], v[26:29]
	v_mfma_f32_16x16x32_bf16 v[18:21], v[182:185], v[228:231], v[18:21]
	v_mfma_f32_16x16x32_bf16 v[18:21], v[186:189], v[232:235], v[18:21]
	v_mfma_f32_16x16x32_bf16 v[22:25], v[174:177], v[228:231], v[22:25]
	v_mfma_f32_16x16x32_bf16 v[22:25], v[178:181], v[232:235], v[22:25]
	v_mfma_f32_16x16x32_bf16 v[6:9], v[174:177], v[236:239], v[6:9]
	v_mfma_f32_16x16x32_bf16 v[6:9], v[178:181], v[240:243], v[6:9]
	v_mfma_f32_16x16x32_bf16 v[2:5], v[182:185], v[236:239], v[2:5]
	v_mfma_f32_16x16x32_bf16 v[2:5], v[186:189], v[240:243], v[2:5]
	v_mfma_f32_16x16x32_bf16 v[10:13], v[154:157], v[236:239], v[10:13]
	v_mfma_f32_16x16x32_bf16 v[10:13], v[170:173], v[240:243], v[10:13]
	v_mfma_f32_16x16x32_bf16 v[14:17], v[132:135], v[236:239], v[14:17]
	v_mfma_f32_16x16x32_bf16 v[14:17], v[142:145], v[240:243], v[14:17]
	s_barrier
	s_setprio 0
	s_addk_i32 s13, 0x100
	s_add_i32 s22, s22, 2
	s_add_i32 s21, s21, 0x10000
	s_cmpk_gt_u32 s22, 0x55
.LBB0_2156:
	v_add_u32_e32 v170, 0x10000, v140
	v_add_u32_e32 v186, 0x14000, v140
	ds_read_b128 v[132:135], v170
	ds_read_b128 v[142:145], v170 offset:1024
	ds_read_b128 v[154:157], v170 offset:2048
	ds_read_b128 v[170:173], v170 offset:3072
	ds_read_b128 v[174:177], v186
	ds_read_b128 v[178:181], v186 offset:1024
	ds_read_b128 v[182:185], v186 offset:2048
	ds_read_b128 v[186:189], v186 offset:3072
	s_add_i32 s26, s21, 0x4000
	s_cmpk_eq_i32 s22, 0x54
	s_cselect_b32 s52, s8, s26
	s_cselect_b32 s27, s9, s13
	s_or_b32 s26, s52, 0x8000
	s_mov_b32 m0, s84
	ds_read_b128 v[190:193], v141
	ds_read_b128 v[194:197], v141 offset:1024
	ds_read_b128 v[198:201], v141 offset:2048
	ds_read_b128 v[202:205], v141 offset:3072
	ds_read_b128 v[228:231], v141 offset:4096
	ds_read_b128 v[232:235], v141 offset:5120
	ds_read_b128 v[236:239], v141 offset:6144
	ds_read_b128 v[240:243], v141 offset:7168
	buffer_load_dwordx4 v136, s[60:63], s21 offen lds
	s_mov_b32 m0, s16
	s_nop 0
	buffer_load_dwordx4 v138, s[60:63], s21 offen lds
	s_waitcnt vmcnt(8)
	s_waitcnt lgkmcnt(0)
	s_setprio 1
	s_barrier
	v_mfma_f32_16x16x32_bf16 v[126:129], v[132:135], v[190:193], v[126:129]
	v_mfma_f32_16x16x32_bf16 v[126:129], v[142:145], v[194:197], v[126:129]
	v_mfma_f32_16x16x32_bf16 v[106:109], v[154:157], v[190:193], v[106:109]
	v_mfma_f32_16x16x32_bf16 v[106:109], v[170:173], v[194:197], v[106:109]
	v_mfma_f32_16x16x32_bf16 v[110:113], v[182:185], v[190:193], v[110:113]
	v_mfma_f32_16x16x32_bf16 v[110:113], v[186:189], v[194:197], v[110:113]
	v_mfma_f32_16x16x32_bf16 v[122:125], v[174:177], v[190:193], v[122:125]
	v_mfma_f32_16x16x32_bf16 v[122:125], v[178:181], v[194:197], v[122:125]
	v_mfma_f32_16x16x32_bf16 v[102:105], v[174:177], v[198:201], v[102:105]
	v_mfma_f32_16x16x32_bf16 v[102:105], v[178:181], v[202:205], v[102:105]
	v_mfma_f32_16x16x32_bf16 v[98:101], v[182:185], v[198:201], v[98:101]
	v_mfma_f32_16x16x32_bf16 v[98:101], v[186:189], v[202:205], v[98:101]
	v_mfma_f32_16x16x32_bf16 v[114:117], v[154:157], v[198:201], v[114:117]
	v_mfma_f32_16x16x32_bf16 v[114:117], v[170:173], v[202:205], v[114:117]
	v_mfma_f32_16x16x32_bf16 v[118:121], v[132:135], v[198:201], v[118:121]
	v_mfma_f32_16x16x32_bf16 v[118:121], v[142:145], v[202:205], v[118:121]
	v_mfma_f32_16x16x32_bf16 v[94:97], v[132:135], v[228:231], v[94:97]
	v_mfma_f32_16x16x32_bf16 v[94:97], v[142:145], v[232:235], v[94:97]
	v_mfma_f32_16x16x32_bf16 v[90:93], v[154:157], v[228:231], v[90:93]
	v_mfma_f32_16x16x32_bf16 v[90:93], v[170:173], v[232:235], v[90:93]
	v_mfma_f32_16x16x32_bf16 v[82:85], v[182:185], v[228:231], v[82:85]
	v_mfma_f32_16x16x32_bf16 v[82:85], v[186:189], v[232:235], v[82:85]
	v_mfma_f32_16x16x32_bf16 v[86:89], v[174:177], v[228:231], v[86:89]
	v_mfma_f32_16x16x32_bf16 v[86:89], v[178:181], v[232:235], v[86:89]
	v_mfma_f32_16x16x32_bf16 v[70:73], v[174:177], v[236:239], v[70:73]
	v_mfma_f32_16x16x32_bf16 v[70:73], v[178:181], v[240:243], v[70:73]
	v_mfma_f32_16x16x32_bf16 v[66:69], v[182:185], v[236:239], v[66:69]
	v_mfma_f32_16x16x32_bf16 v[66:69], v[186:189], v[240:243], v[66:69]
	v_mfma_f32_16x16x32_bf16 v[74:77], v[154:157], v[236:239], v[74:77]
	v_mfma_f32_16x16x32_bf16 v[74:77], v[170:173], v[240:243], v[74:77]
	v_mfma_f32_16x16x32_bf16 v[78:81], v[132:135], v[236:239], v[78:81]
	v_mfma_f32_16x16x32_bf16 v[78:81], v[142:145], v[240:243], v[78:81]
	s_barrier
	s_setprio 0
	s_mov_b32 m0, s18
	s_mov_b32 s46, s62
	s_mov_b32 s47, s63
	ds_read_b128 v[190:193], v141 offset:16384
	ds_read_b128 v[194:197], v141 offset:17408
	ds_read_b128 v[198:201], v141 offset:18432
	ds_read_b128 v[202:205], v141 offset:19456
	ds_read_b128 v[228:231], v141 offset:20480
	ds_read_b128 v[232:235], v141 offset:21504
	ds_read_b128 v[236:239], v141 offset:22528
	ds_read_b128 v[240:243], v141 offset:23552
	buffer_load_dwordx4 v137, s[44:47], s27 offen lds
	s_mov_b32 m0, s19
	s_add_i32 s53, s27, 0x160000
	buffer_load_dwordx4 v139, s[44:47], s27 offen lds
	s_mov_b32 m0, s24
	s_nop 0
	buffer_load_dwordx4 v137, s[44:47], s53 offen lds
	s_mov_b32 m0, s25
	s_nop 0
	buffer_load_dwordx4 v139, s[44:47], s53 offen lds
	s_mov_b32 m0, s14
	s_nop 0
	buffer_load_dwordx4 v136, s[60:63], s52 offen lds
	s_mov_b32 m0, s30
	s_nop 0
	buffer_load_dwordx4 v138, s[60:63], s52 offen lds
	s_waitcnt vmcnt(8)
	s_waitcnt lgkmcnt(0)
	s_setprio 1
	s_barrier
	v_mfma_f32_16x16x32_bf16 v[62:65], v[132:135], v[190:193], v[62:65]
	v_mfma_f32_16x16x32_bf16 v[62:65], v[142:145], v[194:197], v[62:65]
	v_mfma_f32_16x16x32_bf16 v[58:61], v[154:157], v[190:193], v[58:61]
	v_mfma_f32_16x16x32_bf16 v[58:61], v[170:173], v[194:197], v[58:61]
	v_mfma_f32_16x16x32_bf16 v[50:53], v[182:185], v[190:193], v[50:53]
	v_mfma_f32_16x16x32_bf16 v[50:53], v[186:189], v[194:197], v[50:53]
	v_mfma_f32_16x16x32_bf16 v[54:57], v[174:177], v[190:193], v[54:57]
	v_mfma_f32_16x16x32_bf16 v[54:57], v[178:181], v[194:197], v[54:57]
	v_mfma_f32_16x16x32_bf16 v[38:41], v[174:177], v[198:201], v[38:41]
	v_mfma_f32_16x16x32_bf16 v[38:41], v[178:181], v[202:205], v[38:41]
	v_mfma_f32_16x16x32_bf16 v[34:37], v[182:185], v[198:201], v[34:37]
	v_mfma_f32_16x16x32_bf16 v[34:37], v[186:189], v[202:205], v[34:37]
	v_mfma_f32_16x16x32_bf16 v[42:45], v[154:157], v[198:201], v[42:45]
	v_mfma_f32_16x16x32_bf16 v[42:45], v[170:173], v[202:205], v[42:45]
	v_mfma_f32_16x16x32_bf16 v[46:49], v[132:135], v[198:201], v[46:49]
	v_mfma_f32_16x16x32_bf16 v[46:49], v[142:145], v[202:205], v[46:49]
	v_mfma_f32_16x16x32_bf16 v[30:33], v[132:135], v[228:231], v[30:33]
	v_mfma_f32_16x16x32_bf16 v[30:33], v[142:145], v[232:235], v[30:33]
	v_mfma_f32_16x16x32_bf16 v[26:29], v[154:157], v[228:231], v[26:29]
	v_mfma_f32_16x16x32_bf16 v[26:29], v[170:173], v[232:235], v[26:29]
	v_mfma_f32_16x16x32_bf16 v[18:21], v[182:185], v[228:231], v[18:21]
	v_mfma_f32_16x16x32_bf16 v[18:21], v[186:189], v[232:235], v[18:21]
	v_mfma_f32_16x16x32_bf16 v[22:25], v[174:177], v[228:231], v[22:25]
	v_mfma_f32_16x16x32_bf16 v[22:25], v[178:181], v[232:235], v[22:25]
	v_mfma_f32_16x16x32_bf16 v[6:9], v[174:177], v[236:239], v[6:9]
	v_mfma_f32_16x16x32_bf16 v[6:9], v[178:181], v[240:243], v[6:9]
	v_mfma_f32_16x16x32_bf16 v[2:5], v[182:185], v[236:239], v[2:5]
	v_mfma_f32_16x16x32_bf16 v[2:5], v[186:189], v[240:243], v[2:5]
	v_mfma_f32_16x16x32_bf16 v[10:13], v[154:157], v[236:239], v[10:13]
	v_mfma_f32_16x16x32_bf16 v[10:13], v[170:173], v[240:243], v[10:13]
	v_mfma_f32_16x16x32_bf16 v[14:17], v[132:135], v[236:239], v[14:17]
	v_mfma_f32_16x16x32_bf16 v[14:17], v[142:145], v[240:243], v[14:17]
	s_barrier
	s_setprio 0
	v_add_u32_e32 v170, 0x18000, v140
	v_add_u32_e32 v186, 0x1c000, v140
	ds_read_b128 v[132:135], v170
	ds_read_b128 v[142:145], v170 offset:1024
	ds_read_b128 v[154:157], v170 offset:2048
	ds_read_b128 v[170:173], v170 offset:3072
	ds_read_b128 v[174:177], v186
	ds_read_b128 v[178:181], v186 offset:1024
	ds_read_b128 v[182:185], v186 offset:2048
	ds_read_b128 v[186:189], v186 offset:3072
	s_bitset1_b32 s52, 14
	s_mov_b32 m0, s31
	ds_read_b128 v[190:193], v141 offset:32768
	ds_read_b128 v[194:197], v141 offset:33792
	ds_read_b128 v[198:201], v141 offset:34816
	ds_read_b128 v[202:205], v141 offset:35840
	ds_read_b128 v[228:231], v141 offset:36864
	ds_read_b128 v[232:235], v141 offset:37888
	ds_read_b128 v[236:239], v141 offset:38912
	ds_read_b128 v[240:243], v141 offset:39936
	buffer_load_dwordx4 v136, s[60:63], s52 offen lds
	s_mov_b32 m0, s33
	s_nop 0
	buffer_load_dwordx4 v138, s[60:63], s52 offen lds
	s_waitcnt vmcnt(8)
	s_waitcnt lgkmcnt(0)
	s_setprio 1
	s_barrier
	v_mfma_f32_16x16x32_bf16 v[126:129], v[132:135], v[190:193], v[126:129]
	v_mfma_f32_16x16x32_bf16 v[126:129], v[142:145], v[194:197], v[126:129]
	v_mfma_f32_16x16x32_bf16 v[106:109], v[154:157], v[190:193], v[106:109]
	v_mfma_f32_16x16x32_bf16 v[106:109], v[170:173], v[194:197], v[106:109]
	v_mfma_f32_16x16x32_bf16 v[110:113], v[182:185], v[190:193], v[110:113]
	v_mfma_f32_16x16x32_bf16 v[110:113], v[186:189], v[194:197], v[110:113]
	v_mfma_f32_16x16x32_bf16 v[122:125], v[174:177], v[190:193], v[122:125]
	v_mfma_f32_16x16x32_bf16 v[122:125], v[178:181], v[194:197], v[122:125]
	v_mfma_f32_16x16x32_bf16 v[102:105], v[174:177], v[198:201], v[102:105]
	v_mfma_f32_16x16x32_bf16 v[102:105], v[178:181], v[202:205], v[102:105]
	v_mfma_f32_16x16x32_bf16 v[98:101], v[182:185], v[198:201], v[98:101]
	v_mfma_f32_16x16x32_bf16 v[98:101], v[186:189], v[202:205], v[98:101]
	v_mfma_f32_16x16x32_bf16 v[114:117], v[154:157], v[198:201], v[114:117]
	v_mfma_f32_16x16x32_bf16 v[114:117], v[170:173], v[202:205], v[114:117]
	v_mfma_f32_16x16x32_bf16 v[118:121], v[132:135], v[198:201], v[118:121]
	v_mfma_f32_16x16x32_bf16 v[118:121], v[142:145], v[202:205], v[118:121]
	v_mfma_f32_16x16x32_bf16 v[94:97], v[132:135], v[228:231], v[94:97]
	v_mfma_f32_16x16x32_bf16 v[94:97], v[142:145], v[232:235], v[94:97]
	v_mfma_f32_16x16x32_bf16 v[90:93], v[154:157], v[228:231], v[90:93]
	v_mfma_f32_16x16x32_bf16 v[90:93], v[170:173], v[232:235], v[90:93]
	v_mfma_f32_16x16x32_bf16 v[82:85], v[182:185], v[228:231], v[82:85]
	v_mfma_f32_16x16x32_bf16 v[82:85], v[186:189], v[232:235], v[82:85]
	v_mfma_f32_16x16x32_bf16 v[86:89], v[174:177], v[228:231], v[86:89]
	v_mfma_f32_16x16x32_bf16 v[86:89], v[178:181], v[232:235], v[86:89]
	v_mfma_f32_16x16x32_bf16 v[70:73], v[174:177], v[236:239], v[70:73]
	v_mfma_f32_16x16x32_bf16 v[70:73], v[178:181], v[240:243], v[70:73]
	v_mfma_f32_16x16x32_bf16 v[66:69], v[182:185], v[236:239], v[66:69]
	v_mfma_f32_16x16x32_bf16 v[66:69], v[186:189], v[240:243], v[66:69]
	v_mfma_f32_16x16x32_bf16 v[74:77], v[154:157], v[236:239], v[74:77]
	v_mfma_f32_16x16x32_bf16 v[74:77], v[170:173], v[240:243], v[74:77]
	v_mfma_f32_16x16x32_bf16 v[78:81], v[132:135], v[236:239], v[78:81]
	v_mfma_f32_16x16x32_bf16 v[78:81], v[142:145], v[240:243], v[78:81]
	s_barrier
	s_setprio 0
	s_mov_b32 m0, s68
	s_or_b32 s52, s27, 0x80
	ds_read_b128 v[190:193], v141 offset:49152
	ds_read_b128 v[194:197], v141 offset:50176
	ds_read_b128 v[198:201], v141 offset:51200
	ds_read_b128 v[202:205], v141 offset:52224
	ds_read_b128 v[228:231], v141 offset:53248
	ds_read_b128 v[232:235], v141 offset:54272
	ds_read_b128 v[236:239], v141 offset:55296
	ds_read_b128 v[240:243], v141 offset:56320
	buffer_load_dwordx4 v137, s[44:47], s52 offen lds
	s_mov_b32 m0, s69
	s_add_i32 s27, s27, 0x160080
	buffer_load_dwordx4 v139, s[44:47], s52 offen lds
	s_mov_b32 m0, s72
	s_nop 0
	buffer_load_dwordx4 v137, s[44:47], s27 offen lds
	s_mov_b32 m0, s73
	s_nop 0
	buffer_load_dwordx4 v139, s[44:47], s27 offen lds
	s_mov_b32 m0, s70
	s_nop 0
	buffer_load_dwordx4 v136, s[60:63], s26 offen lds
	s_mov_b32 m0, s71
	s_nop 0
	buffer_load_dwordx4 v138, s[60:63], s26 offen lds
	s_waitcnt vmcnt(8)
	s_waitcnt lgkmcnt(0)
	s_setprio 1
	s_barrier
	v_mfma_f32_16x16x32_bf16 v[62:65], v[132:135], v[190:193], v[62:65]
	v_mfma_f32_16x16x32_bf16 v[62:65], v[142:145], v[194:197], v[62:65]
	v_mfma_f32_16x16x32_bf16 v[58:61], v[154:157], v[190:193], v[58:61]
	v_mfma_f32_16x16x32_bf16 v[58:61], v[170:173], v[194:197], v[58:61]
	v_mfma_f32_16x16x32_bf16 v[50:53], v[182:185], v[190:193], v[50:53]
	v_mfma_f32_16x16x32_bf16 v[50:53], v[186:189], v[194:197], v[50:53]
	v_mfma_f32_16x16x32_bf16 v[54:57], v[174:177], v[190:193], v[54:57]
	v_mfma_f32_16x16x32_bf16 v[54:57], v[178:181], v[194:197], v[54:57]
	v_mfma_f32_16x16x32_bf16 v[38:41], v[174:177], v[198:201], v[38:41]
	v_mfma_f32_16x16x32_bf16 v[38:41], v[178:181], v[202:205], v[38:41]
	v_mfma_f32_16x16x32_bf16 v[34:37], v[182:185], v[198:201], v[34:37]
	v_mfma_f32_16x16x32_bf16 v[34:37], v[186:189], v[202:205], v[34:37]
	v_mfma_f32_16x16x32_bf16 v[42:45], v[154:157], v[198:201], v[42:45]
	v_mfma_f32_16x16x32_bf16 v[42:45], v[170:173], v[202:205], v[42:45]
	v_mfma_f32_16x16x32_bf16 v[46:49], v[132:135], v[198:201], v[46:49]
	v_mfma_f32_16x16x32_bf16 v[46:49], v[142:145], v[202:205], v[46:49]
	v_mfma_f32_16x16x32_bf16 v[30:33], v[132:135], v[228:231], v[30:33]
	v_mfma_f32_16x16x32_bf16 v[30:33], v[142:145], v[232:235], v[30:33]
	v_mfma_f32_16x16x32_bf16 v[26:29], v[154:157], v[228:231], v[26:29]
	v_mfma_f32_16x16x32_bf16 v[26:29], v[170:173], v[232:235], v[26:29]
	v_mfma_f32_16x16x32_bf16 v[18:21], v[182:185], v[228:231], v[18:21]
	v_mfma_f32_16x16x32_bf16 v[18:21], v[186:189], v[232:235], v[18:21]
	v_mfma_f32_16x16x32_bf16 v[22:25], v[174:177], v[228:231], v[22:25]
	v_mfma_f32_16x16x32_bf16 v[22:25], v[178:181], v[232:235], v[22:25]
	v_mfma_f32_16x16x32_bf16 v[6:9], v[174:177], v[236:239], v[6:9]
	v_mfma_f32_16x16x32_bf16 v[6:9], v[178:181], v[240:243], v[6:9]
	v_mfma_f32_16x16x32_bf16 v[2:5], v[182:185], v[236:239], v[2:5]
	v_mfma_f32_16x16x32_bf16 v[2:5], v[186:189], v[240:243], v[2:5]
	v_mfma_f32_16x16x32_bf16 v[10:13], v[154:157], v[236:239], v[10:13]
	v_mfma_f32_16x16x32_bf16 v[10:13], v[170:173], v[240:243], v[10:13]
	v_mfma_f32_16x16x32_bf16 v[14:17], v[132:135], v[236:239], v[14:17]
	v_mfma_f32_16x16x32_bf16 v[14:17], v[142:145], v[240:243], v[14:17]
	s_barrier
	s_setprio 0
	s_addk_i32 s13, 0x100
	s_add_i32 s22, s22, 2
	s_add_i32 s21, s21, 0x10000
	s_cmpk_gt_u32 s22, 0x55
	s_cbranch_scc0 .LBB0_2156
	s_and_b64 vcc, exec, s[66:67]
	s_cbranch_vccz .LBB0_2159
	s_barrier

.LBB0_2173:
	v_mov_b32_e32 v125, 0
	s_mul_i32 s69, s68, s12
	s_mul_i32 s70, s67, s12
	s_andn2_b64 vcc, exec, s[34:35]
	v_mov_b32_e32 v124, v125
	v_mov_b32_e32 v123, v125
	v_mov_b32_e32 v122, v125
	v_mov_b32_e32 v129, v125
	v_mov_b32_e32 v128, v125
	v_mov_b32_e32 v127, v125
	v_mov_b32_e32 v126, v125
	v_mov_b32_e32 v113, v125
	v_mov_b32_e32 v112, v125
	v_mov_b32_e32 v111, v125
	v_mov_b32_e32 v110, v125
	v_mov_b32_e32 v109, v125
	v_mov_b32_e32 v108, v125
	v_mov_b32_e32 v107, v125
	v_mov_b32_e32 v106, v125
	v_mov_b32_e32 v97, v125
	v_mov_b32_e32 v96, v125
	v_mov_b32_e32 v95, v125
	v_mov_b32_e32 v94, v125
	v_mov_b32_e32 v93, v125
	v_mov_b32_e32 v92, v125
	v_mov_b32_e32 v91, v125
	v_mov_b32_e32 v90, v125
	v_mov_b32_e32 v81, v125
	v_mov_b32_e32 v80, v125
	v_mov_b32_e32 v79, v125
	v_mov_b32_e32 v78, v125
	v_mov_b32_e32 v77, v125
	v_mov_b32_e32 v76, v125
	v_mov_b32_e32 v75, v125
	v_mov_b32_e32 v74, v125
	v_mov_b32_e32 v121, v125
	v_mov_b32_e32 v120, v125
	v_mov_b32_e32 v119, v125
	v_mov_b32_e32 v118, v125
	v_mov_b32_e32 v117, v125
	v_mov_b32_e32 v116, v125
	v_mov_b32_e32 v115, v125
	v_mov_b32_e32 v114, v125
	v_mov_b32_e32 v105, v125
	v_mov_b32_e32 v104, v125
	v_mov_b32_e32 v103, v125
	v_mov_b32_e32 v102, v125
	v_mov_b32_e32 v101, v125
	v_mov_b32_e32 v100, v125
	v_mov_b32_e32 v99, v125
	v_mov_b32_e32 v98, v125
	v_mov_b32_e32 v89, v125
	v_mov_b32_e32 v88, v125
	v_mov_b32_e32 v87, v125
	v_mov_b32_e32 v86, v125
	v_mov_b32_e32 v85, v125
	v_mov_b32_e32 v84, v125
	v_mov_b32_e32 v83, v125
	v_mov_b32_e32 v82, v125
	v_mov_b32_e32 v73, v125
	v_mov_b32_e32 v72, v125
	v_mov_b32_e32 v71, v125
	v_mov_b32_e32 v70, v125
	v_mov_b32_e32 v69, v125
	v_mov_b32_e32 v68, v125
	v_mov_b32_e32 v67, v125
	v_mov_b32_e32 v66, v125
	v_mov_b32_e32 v65, v125
	v_mov_b32_e32 v64, v125
	v_mov_b32_e32 v63, v125
	v_mov_b32_e32 v62, v125
	v_mov_b32_e32 v61, v125
	v_mov_b32_e32 v60, v125
	v_mov_b32_e32 v59, v125
	v_mov_b32_e32 v58, v125
	v_mov_b32_e32 v49, v125
	v_mov_b32_e32 v48, v125
	v_mov_b32_e32 v47, v125
	v_mov_b32_e32 v46, v125
	v_mov_b32_e32 v45, v125
	v_mov_b32_e32 v44, v125
	v_mov_b32_e32 v43, v125
	v_mov_b32_e32 v42, v125
	v_mov_b32_e32 v33, v125
	v_mov_b32_e32 v32, v125
	v_mov_b32_e32 v31, v125
	v_mov_b32_e32 v30, v125
	v_mov_b32_e32 v29, v125
	v_mov_b32_e32 v28, v125
	v_mov_b32_e32 v27, v125
	v_mov_b32_e32 v26, v125
	v_mov_b32_e32 v17, v125
	v_mov_b32_e32 v16, v125
	v_mov_b32_e32 v15, v125
	v_mov_b32_e32 v14, v125
	v_mov_b32_e32 v13, v125
	v_mov_b32_e32 v12, v125
	v_mov_b32_e32 v11, v125
	v_mov_b32_e32 v10, v125
	v_mov_b32_e32 v57, v125
	v_mov_b32_e32 v56, v125
	v_mov_b32_e32 v55, v125
	v_mov_b32_e32 v54, v125
	v_mov_b32_e32 v53, v125
	v_mov_b32_e32 v52, v125
	v_mov_b32_e32 v51, v125
	v_mov_b32_e32 v50, v125
	v_mov_b32_e32 v41, v125
	v_mov_b32_e32 v40, v125
	v_mov_b32_e32 v39, v125
	v_mov_b32_e32 v38, v125
	v_mov_b32_e32 v37, v125
	v_mov_b32_e32 v36, v125
	v_mov_b32_e32 v35, v125
	v_mov_b32_e32 v34, v125
	v_mov_b32_e32 v25, v125
	v_mov_b32_e32 v24, v125
	v_mov_b32_e32 v23, v125
	v_mov_b32_e32 v22, v125
	v_mov_b32_e32 v21, v125
	v_mov_b32_e32 v20, v125
	v_mov_b32_e32 v19, v125
	v_mov_b32_e32 v18, v125
	v_mov_b32_e32 v9, v125
	v_mov_b32_e32 v8, v125
	v_mov_b32_e32 v7, v125
	v_mov_b32_e32 v6, v125
	v_mov_b32_e32 v5, v125
	v_mov_b32_e32 v4, v125
	v_mov_b32_e32 v3, v125
	v_mov_b32_e32 v2, v125
	s_cbranch_vccnz .LBB0_2177
	s_and_b64 s[8:9], s[40:41], exec
	s_cselect_b32 s8, s69, s73
	s_cselect_b32 s9, s70, s82
	s_addk_i32 s73, 0x80
	s_addk_i32 s82, 0x100
	s_mov_b32 s83, 0
	v_add_u32_e32 v144, 0x10000, v134
	ds_read_b128 v[136:139], v144
	ds_read_b128 v[140:143], v144 offset:1024
	ds_read_b128 v[154:157], v144 offset:2048
	ds_read_b128 v[170:173], v144 offset:3072
	v_add_u32_e32 v144, 0x14000, v134
	ds_read_b128 v[174:177], v144
	ds_read_b128 v[178:181], v144 offset:1024
	ds_read_b128 v[182:185], v144 offset:2048
	ds_read_b128 v[186:189], v144 offset:3072
	s_add_i32 s46, s73, 0x80
	s_cmp_eq_u32 s49, s83
	s_cselect_b32 s52, s8, s46
	s_cselect_b32 s85, s9, s82
	s_add_i32 s84, s52, 0x80
	s_add_i32 s46, s2, s73
	s_mov_b32 m0, s64
	ds_read_b128 v[190:193], v135
	ds_read_b128 v[194:197], v135 offset:1024
	ds_read_b128 v[198:201], v135 offset:2048
	ds_read_b128 v[202:205], v135 offset:3072
	ds_read_b128 v[228:231], v135 offset:4096
	ds_read_b128 v[232:235], v135 offset:5120
	ds_read_b128 v[236:239], v135 offset:6144
	ds_read_b128 v[240:243], v135 offset:7168
	buffer_load_dwordx4 v130, s[60:63], s46 offen lds
	s_mov_b32 m0, s65
	s_nop 0
	buffer_load_dwordx4 v132, s[60:63], s46 offen lds
	s_waitcnt vmcnt(8)
	s_waitcnt lgkmcnt(0)
	s_setprio 1
	s_barrier
	v_mfma_f32_16x16x32_bf16 v[122:125], v[136:139], v[190:193], 0
	v_mfma_f32_16x16x32_bf16 v[122:125], v[140:143], v[194:197], v[122:125]
	v_mfma_f32_16x16x32_bf16 v[126:129], v[154:157], v[190:193], 0
	v_mfma_f32_16x16x32_bf16 v[126:129], v[170:173], v[194:197], v[126:129]
	v_mfma_f32_16x16x32_bf16 v[114:117], v[182:185], v[190:193], 0
	v_mfma_f32_16x16x32_bf16 v[114:117], v[186:189], v[194:197], v[114:117]
	v_mfma_f32_16x16x32_bf16 v[118:121], v[174:177], v[190:193], 0
	v_mfma_f32_16x16x32_bf16 v[118:121], v[178:181], v[194:197], v[118:121]
	v_mfma_f32_16x16x32_bf16 v[102:105], v[174:177], v[198:201], 0
	v_mfma_f32_16x16x32_bf16 v[102:105], v[178:181], v[202:205], v[102:105]
	v_mfma_f32_16x16x32_bf16 v[98:101], v[182:185], v[198:201], 0
	v_mfma_f32_16x16x32_bf16 v[98:101], v[186:189], v[202:205], v[98:101]
	v_mfma_f32_16x16x32_bf16 v[106:109], v[154:157], v[198:201], 0
	v_mfma_f32_16x16x32_bf16 v[106:109], v[170:173], v[202:205], v[106:109]
	v_mfma_f32_16x16x32_bf16 v[110:113], v[136:139], v[198:201], 0
	v_mfma_f32_16x16x32_bf16 v[110:113], v[140:143], v[202:205], v[110:113]
	v_mfma_f32_16x16x32_bf16 v[94:97], v[136:139], v[228:231], 0
	v_mfma_f32_16x16x32_bf16 v[94:97], v[140:143], v[232:235], v[94:97]
	v_mfma_f32_16x16x32_bf16 v[90:93], v[154:157], v[228:231], 0
	v_mfma_f32_16x16x32_bf16 v[90:93], v[170:173], v[232:235], v[90:93]
	v_mfma_f32_16x16x32_bf16 v[82:85], v[182:185], v[228:231], 0
	v_mfma_f32_16x16x32_bf16 v[82:85], v[186:189], v[232:235], v[82:85]
	v_mfma_f32_16x16x32_bf16 v[86:89], v[174:177], v[228:231], 0
	v_mfma_f32_16x16x32_bf16 v[86:89], v[178:181], v[232:235], v[86:89]
	v_mfma_f32_16x16x32_bf16 v[70:73], v[174:177], v[236:239], 0
	v_mfma_f32_16x16x32_bf16 v[70:73], v[178:181], v[240:243], v[70:73]
	v_mfma_f32_16x16x32_bf16 v[66:69], v[182:185], v[236:239], 0
	v_mfma_f32_16x16x32_bf16 v[66:69], v[186:189], v[240:243], v[66:69]
	v_mfma_f32_16x16x32_bf16 v[74:77], v[154:157], v[236:239], 0
	v_mfma_f32_16x16x32_bf16 v[74:77], v[170:173], v[240:243], v[74:77]
	v_mfma_f32_16x16x32_bf16 v[78:81], v[136:139], v[236:239], 0
	v_mfma_f32_16x16x32_bf16 v[78:81], v[140:143], v[240:243], v[78:81]
	s_barrier
	s_setprio 0
	s_mov_b32 m0, s14
	s_mov_b32 s46, s62
	s_mov_b32 s47, s63
	ds_read_b128 v[190:193], v135 offset:16384
	ds_read_b128 v[194:197], v135 offset:17408
	ds_read_b128 v[198:201], v135 offset:18432
	ds_read_b128 v[202:205], v135 offset:19456
	ds_read_b128 v[228:231], v135 offset:20480
	ds_read_b128 v[232:235], v135 offset:21504
	ds_read_b128 v[236:239], v135 offset:22528
	ds_read_b128 v[240:243], v135 offset:23552
	buffer_load_dwordx4 v131, s[44:47], s85 offen lds
	s_mov_b32 m0, s15
	s_add_i32 s53, s85, s2
	buffer_load_dwordx4 v133, s[44:47], s85 offen lds
	s_mov_b32 m0, s16
	s_nop 0
	buffer_load_dwordx4 v131, s[44:47], s53 offen lds
	s_mov_b32 m0, s18
	s_nop 0
	buffer_load_dwordx4 v133, s[44:47], s53 offen lds
	s_mov_b32 m0, s13
	s_nop 0
	buffer_load_dwordx4 v130, s[60:63], s52 offen lds
	s_mov_b32 m0, s19
	s_nop 0
	buffer_load_dwordx4 v132, s[60:63], s52 offen lds
	s_waitcnt vmcnt(8)
	s_waitcnt lgkmcnt(0)
	s_setprio 1
	s_barrier
	v_mfma_f32_16x16x32_bf16 v[62:65], v[136:139], v[190:193], 0
	v_mfma_f32_16x16x32_bf16 v[62:65], v[140:143], v[194:197], v[62:65]
	v_mfma_f32_16x16x32_bf16 v[58:61], v[154:157], v[190:193], 0
	v_mfma_f32_16x16x32_bf16 v[58:61], v[170:173], v[194:197], v[58:61]
	v_mfma_f32_16x16x32_bf16 v[50:53], v[182:185], v[190:193], 0
	v_mfma_f32_16x16x32_bf16 v[50:53], v[186:189], v[194:197], v[50:53]
	v_mfma_f32_16x16x32_bf16 v[54:57], v[174:177], v[190:193], 0
	v_mfma_f32_16x16x32_bf16 v[54:57], v[178:181], v[194:197], v[54:57]
	v_mfma_f32_16x16x32_bf16 v[38:41], v[174:177], v[198:201], 0
	v_mfma_f32_16x16x32_bf16 v[38:41], v[178:181], v[202:205], v[38:41]
	v_mfma_f32_16x16x32_bf16 v[34:37], v[182:185], v[198:201], 0
	v_mfma_f32_16x16x32_bf16 v[34:37], v[186:189], v[202:205], v[34:37]
	v_mfma_f32_16x16x32_bf16 v[42:45], v[154:157], v[198:201], 0
	v_mfma_f32_16x16x32_bf16 v[42:45], v[170:173], v[202:205], v[42:45]
	v_mfma_f32_16x16x32_bf16 v[46:49], v[136:139], v[198:201], 0
	v_mfma_f32_16x16x32_bf16 v[46:49], v[140:143], v[202:205], v[46:49]
	v_mfma_f32_16x16x32_bf16 v[30:33], v[136:139], v[228:231], 0
	v_mfma_f32_16x16x32_bf16 v[30:33], v[140:143], v[232:235], v[30:33]
	v_mfma_f32_16x16x32_bf16 v[26:29], v[154:157], v[228:231], 0
	v_mfma_f32_16x16x32_bf16 v[26:29], v[170:173], v[232:235], v[26:29]
	v_mfma_f32_16x16x32_bf16 v[18:21], v[182:185], v[228:231], 0
	v_mfma_f32_16x16x32_bf16 v[18:21], v[186:189], v[232:235], v[18:21]
	v_mfma_f32_16x16x32_bf16 v[22:25], v[174:177], v[228:231], 0
	v_mfma_f32_16x16x32_bf16 v[22:25], v[178:181], v[232:235], v[22:25]
	v_mfma_f32_16x16x32_bf16 v[6:9], v[174:177], v[236:239], 0
	v_mfma_f32_16x16x32_bf16 v[6:9], v[178:181], v[240:243], v[6:9]
	v_mfma_f32_16x16x32_bf16 v[2:5], v[182:185], v[236:239], 0
	v_mfma_f32_16x16x32_bf16 v[2:5], v[186:189], v[240:243], v[2:5]
	v_mfma_f32_16x16x32_bf16 v[10:13], v[154:157], v[236:239], 0
	v_mfma_f32_16x16x32_bf16 v[10:13], v[170:173], v[240:243], v[10:13]
	v_mfma_f32_16x16x32_bf16 v[14:17], v[136:139], v[236:239], 0
	v_mfma_f32_16x16x32_bf16 v[14:17], v[140:143], v[240:243], v[14:17]
	s_barrier
	s_setprio 0
	v_add_u32_e32 v144, 0x18000, v134
	ds_read_b128 v[136:139], v144
	ds_read_b128 v[140:143], v144 offset:1024
	ds_read_b128 v[154:157], v144 offset:2048
	ds_read_b128 v[170:173], v144 offset:3072
	v_add_u32_e32 v144, 0x1c000, v134
	ds_read_b128 v[174:177], v144
	ds_read_b128 v[178:181], v144 offset:1024
	ds_read_b128 v[182:185], v144 offset:2048
	ds_read_b128 v[186:189], v144 offset:3072
	s_add_i32 s52, s52, s2
	s_mov_b32 m0, s21
	ds_read_b128 v[190:193], v135 offset:32768
	ds_read_b128 v[194:197], v135 offset:33792
	ds_read_b128 v[198:201], v135 offset:34816
	ds_read_b128 v[202:205], v135 offset:35840
	ds_read_b128 v[228:231], v135 offset:36864
	ds_read_b128 v[232:235], v135 offset:37888
	ds_read_b128 v[236:239], v135 offset:38912
	ds_read_b128 v[240:243], v135 offset:39936
	buffer_load_dwordx4 v130, s[60:63], s52 offen lds
	s_mov_b32 m0, s22
	s_nop 0
	buffer_load_dwordx4 v132, s[60:63], s52 offen lds
	s_waitcnt vmcnt(8)
	s_waitcnt lgkmcnt(0)
	s_setprio 1
	s_barrier
	v_mfma_f32_16x16x32_bf16 v[122:125], v[136:139], v[190:193], v[122:125]
	v_mfma_f32_16x16x32_bf16 v[122:125], v[140:143], v[194:197], v[122:125]
	v_mfma_f32_16x16x32_bf16 v[126:129], v[154:157], v[190:193], v[126:129]
	v_mfma_f32_16x16x32_bf16 v[126:129], v[170:173], v[194:197], v[126:129]
	v_mfma_f32_16x16x32_bf16 v[114:117], v[182:185], v[190:193], v[114:117]
	v_mfma_f32_16x16x32_bf16 v[114:117], v[186:189], v[194:197], v[114:117]
	v_mfma_f32_16x16x32_bf16 v[118:121], v[174:177], v[190:193], v[118:121]
	v_mfma_f32_16x16x32_bf16 v[118:121], v[178:181], v[194:197], v[118:121]
	v_mfma_f32_16x16x32_bf16 v[102:105], v[174:177], v[198:201], v[102:105]
	v_mfma_f32_16x16x32_bf16 v[102:105], v[178:181], v[202:205], v[102:105]
	v_mfma_f32_16x16x32_bf16 v[98:101], v[182:185], v[198:201], v[98:101]
	v_mfma_f32_16x16x32_bf16 v[98:101], v[186:189], v[202:205], v[98:101]
	v_mfma_f32_16x16x32_bf16 v[106:109], v[154:157], v[198:201], v[106:109]
	v_mfma_f32_16x16x32_bf16 v[106:109], v[170:173], v[202:205], v[106:109]
	v_mfma_f32_16x16x32_bf16 v[110:113], v[136:139], v[198:201], v[110:113]
	v_mfma_f32_16x16x32_bf16 v[110:113], v[140:143], v[202:205], v[110:113]
	v_mfma_f32_16x16x32_bf16 v[94:97], v[136:139], v[228:231], v[94:97]
	v_mfma_f32_16x16x32_bf16 v[94:97], v[140:143], v[232:235], v[94:97]
	v_mfma_f32_16x16x32_bf16 v[90:93], v[154:157], v[228:231], v[90:93]
	v_mfma_f32_16x16x32_bf16 v[90:93], v[170:173], v[232:235], v[90:93]
	v_mfma_f32_16x16x32_bf16 v[82:85], v[182:185], v[228:231], v[82:85]
	v_mfma_f32_16x16x32_bf16 v[82:85], v[186:189], v[232:235], v[82:85]
	v_mfma_f32_16x16x32_bf16 v[86:89], v[174:177], v[228:231], v[86:89]
	v_mfma_f32_16x16x32_bf16 v[86:89], v[178:181], v[232:235], v[86:89]
	v_mfma_f32_16x16x32_bf16 v[70:73], v[174:177], v[236:239], v[70:73]
	v_mfma_f32_16x16x32_bf16 v[70:73], v[178:181], v[240:243], v[70:73]
	v_mfma_f32_16x16x32_bf16 v[66:69], v[182:185], v[236:239], v[66:69]
	v_mfma_f32_16x16x32_bf16 v[66:69], v[186:189], v[240:243], v[66:69]
	v_mfma_f32_16x16x32_bf16 v[74:77], v[154:157], v[236:239], v[74:77]
	v_mfma_f32_16x16x32_bf16 v[74:77], v[170:173], v[240:243], v[74:77]
	v_mfma_f32_16x16x32_bf16 v[78:81], v[136:139], v[236:239], v[78:81]
	v_mfma_f32_16x16x32_bf16 v[78:81], v[140:143], v[240:243], v[78:81]
	s_barrier
	s_setprio 0
	s_mov_b32 m0, s33
	s_add_i32 s52, s85, 0x80
	ds_read_b128 v[190:193], v135 offset:49152
	ds_read_b128 v[194:197], v135 offset:50176
	ds_read_b128 v[198:201], v135 offset:51200
	ds_read_b128 v[202:205], v135 offset:52224
	ds_read_b128 v[228:231], v135 offset:53248
	ds_read_b128 v[232:235], v135 offset:54272
	ds_read_b128 v[236:239], v135 offset:55296
	ds_read_b128 v[240:243], v135 offset:56320
	buffer_load_dwordx4 v131, s[44:47], s52 offen lds
	s_mov_b32 m0, s36
	s_nop 0
	buffer_load_dwordx4 v133, s[44:47], s52 offen lds
	s_add_i32 s52, s52, s2
	s_mov_b32 m0, s43
	s_nop 0
	buffer_load_dwordx4 v131, s[44:47], s52 offen lds
	s_mov_b32 m0, s48
	s_nop 0
	buffer_load_dwordx4 v133, s[44:47], s52 offen lds
	s_mov_b32 m0, s37
	s_nop 0
	buffer_load_dwordx4 v130, s[60:63], s84 offen lds
	s_mov_b32 m0, s42
	s_nop 0
	buffer_load_dwordx4 v132, s[60:63], s84 offen lds
	s_waitcnt vmcnt(8)
	s_waitcnt lgkmcnt(0)
	s_setprio 1
	s_barrier
	v_mfma_f32_16x16x32_bf16 v[62:65], v[136:139], v[190:193], v[62:65]
	v_mfma_f32_16x16x32_bf16 v[62:65], v[140:143], v[194:197], v[62:65]
	v_mfma_f32_16x16x32_bf16 v[58:61], v[154:157], v[190:193], v[58:61]
	v_mfma_f32_16x16x32_bf16 v[58:61], v[170:173], v[194:197], v[58:61]
	v_mfma_f32_16x16x32_bf16 v[50:53], v[182:185], v[190:193], v[50:53]
	v_mfma_f32_16x16x32_bf16 v[50:53], v[186:189], v[194:197], v[50:53]
	v_mfma_f32_16x16x32_bf16 v[54:57], v[174:177], v[190:193], v[54:57]
	v_mfma_f32_16x16x32_bf16 v[54:57], v[178:181], v[194:197], v[54:57]
	v_mfma_f32_16x16x32_bf16 v[38:41], v[174:177], v[198:201], v[38:41]
	v_mfma_f32_16x16x32_bf16 v[38:41], v[178:181], v[202:205], v[38:41]
	v_mfma_f32_16x16x32_bf16 v[34:37], v[182:185], v[198:201], v[34:37]
	v_mfma_f32_16x16x32_bf16 v[34:37], v[186:189], v[202:205], v[34:37]
	v_mfma_f32_16x16x32_bf16 v[42:45], v[154:157], v[198:201], v[42:45]
	v_mfma_f32_16x16x32_bf16 v[42:45], v[170:173], v[202:205], v[42:45]
	v_mfma_f32_16x16x32_bf16 v[46:49], v[136:139], v[198:201], v[46:49]
	v_mfma_f32_16x16x32_bf16 v[46:49], v[140:143], v[202:205], v[46:49]
	v_mfma_f32_16x16x32_bf16 v[30:33], v[136:139], v[228:231], v[30:33]
	v_mfma_f32_16x16x32_bf16 v[30:33], v[140:143], v[232:235], v[30:33]
	v_mfma_f32_16x16x32_bf16 v[26:29], v[154:157], v[228:231], v[26:29]
	v_mfma_f32_16x16x32_bf16 v[26:29], v[170:173], v[232:235], v[26:29]
	v_mfma_f32_16x16x32_bf16 v[18:21], v[182:185], v[228:231], v[18:21]
	v_mfma_f32_16x16x32_bf16 v[18:21], v[186:189], v[232:235], v[18:21]
	v_mfma_f32_16x16x32_bf16 v[22:25], v[174:177], v[228:231], v[22:25]
	v_mfma_f32_16x16x32_bf16 v[22:25], v[178:181], v[232:235], v[22:25]
	v_mfma_f32_16x16x32_bf16 v[6:9], v[174:177], v[236:239], v[6:9]
	v_mfma_f32_16x16x32_bf16 v[6:9], v[178:181], v[240:243], v[6:9]
	v_mfma_f32_16x16x32_bf16 v[2:5], v[182:185], v[236:239], v[2:5]
	v_mfma_f32_16x16x32_bf16 v[2:5], v[186:189], v[240:243], v[2:5]
	v_mfma_f32_16x16x32_bf16 v[10:13], v[154:157], v[236:239], v[10:13]
	v_mfma_f32_16x16x32_bf16 v[10:13], v[170:173], v[240:243], v[10:13]
	v_mfma_f32_16x16x32_bf16 v[14:17], v[136:139], v[236:239], v[14:17]
	v_mfma_f32_16x16x32_bf16 v[14:17], v[140:143], v[240:243], v[14:17]
	s_barrier
	s_setprio 0
	s_add_i32 s83, s83, 2
	s_addk_i32 s73, 0x100
	s_addk_i32 s82, 0x100
	s_cmp_ge_i32 s83, s23
.LBB0_2175:
	v_add_u32_e32 v144, 0x10000, v134
	ds_read_b128 v[136:139], v144
	ds_read_b128 v[140:143], v144 offset:1024
	ds_read_b128 v[154:157], v144 offset:2048
	ds_read_b128 v[170:173], v144 offset:3072
	v_add_u32_e32 v144, 0x14000, v134
	ds_read_b128 v[174:177], v144
	ds_read_b128 v[178:181], v144 offset:1024
	ds_read_b128 v[182:185], v144 offset:2048
	ds_read_b128 v[186:189], v144 offset:3072
	s_add_i32 s46, s73, 0x80
	s_cmp_eq_u32 s49, s83
	s_cselect_b32 s52, s8, s46
	s_cselect_b32 s85, s9, s82
	s_add_i32 s84, s52, 0x80
	s_add_i32 s46, s2, s73
	s_mov_b32 m0, s64
	ds_read_b128 v[190:193], v135
	ds_read_b128 v[194:197], v135 offset:1024
	ds_read_b128 v[198:201], v135 offset:2048
	ds_read_b128 v[202:205], v135 offset:3072
	ds_read_b128 v[228:231], v135 offset:4096
	ds_read_b128 v[232:235], v135 offset:5120
	ds_read_b128 v[236:239], v135 offset:6144
	ds_read_b128 v[240:243], v135 offset:7168
	buffer_load_dwordx4 v130, s[60:63], s46 offen lds
	s_mov_b32 m0, s65
	s_nop 0
	buffer_load_dwordx4 v132, s[60:63], s46 offen lds
	s_waitcnt vmcnt(8)
	s_waitcnt lgkmcnt(0)
	s_setprio 1
	s_barrier
	v_mfma_f32_16x16x32_bf16 v[122:125], v[136:139], v[190:193], v[122:125]
	v_mfma_f32_16x16x32_bf16 v[122:125], v[140:143], v[194:197], v[122:125]
	v_mfma_f32_16x16x32_bf16 v[126:129], v[154:157], v[190:193], v[126:129]
	v_mfma_f32_16x16x32_bf16 v[126:129], v[170:173], v[194:197], v[126:129]
	v_mfma_f32_16x16x32_bf16 v[114:117], v[182:185], v[190:193], v[114:117]
	v_mfma_f32_16x16x32_bf16 v[114:117], v[186:189], v[194:197], v[114:117]
	v_mfma_f32_16x16x32_bf16 v[118:121], v[174:177], v[190:193], v[118:121]
	v_mfma_f32_16x16x32_bf16 v[118:121], v[178:181], v[194:197], v[118:121]
	v_mfma_f32_16x16x32_bf16 v[102:105], v[174:177], v[198:201], v[102:105]
	v_mfma_f32_16x16x32_bf16 v[102:105], v[178:181], v[202:205], v[102:105]
	v_mfma_f32_16x16x32_bf16 v[98:101], v[182:185], v[198:201], v[98:101]
	v_mfma_f32_16x16x32_bf16 v[98:101], v[186:189], v[202:205], v[98:101]
	v_mfma_f32_16x16x32_bf16 v[106:109], v[154:157], v[198:201], v[106:109]
	v_mfma_f32_16x16x32_bf16 v[106:109], v[170:173], v[202:205], v[106:109]
	v_mfma_f32_16x16x32_bf16 v[110:113], v[136:139], v[198:201], v[110:113]
	v_mfma_f32_16x16x32_bf16 v[110:113], v[140:143], v[202:205], v[110:113]
	v_mfma_f32_16x16x32_bf16 v[94:97], v[136:139], v[228:231], v[94:97]
	v_mfma_f32_16x16x32_bf16 v[94:97], v[140:143], v[232:235], v[94:97]
	v_mfma_f32_16x16x32_bf16 v[90:93], v[154:157], v[228:231], v[90:93]
	v_mfma_f32_16x16x32_bf16 v[90:93], v[170:173], v[232:235], v[90:93]
	v_mfma_f32_16x16x32_bf16 v[82:85], v[182:185], v[228:231], v[82:85]
	v_mfma_f32_16x16x32_bf16 v[82:85], v[186:189], v[232:235], v[82:85]
	v_mfma_f32_16x16x32_bf16 v[86:89], v[174:177], v[228:231], v[86:89]
	v_mfma_f32_16x16x32_bf16 v[86:89], v[178:181], v[232:235], v[86:89]
	v_mfma_f32_16x16x32_bf16 v[70:73], v[174:177], v[236:239], v[70:73]
	v_mfma_f32_16x16x32_bf16 v[70:73], v[178:181], v[240:243], v[70:73]
	v_mfma_f32_16x16x32_bf16 v[66:69], v[182:185], v[236:239], v[66:69]
	v_mfma_f32_16x16x32_bf16 v[66:69], v[186:189], v[240:243], v[66:69]
	v_mfma_f32_16x16x32_bf16 v[74:77], v[154:157], v[236:239], v[74:77]
	v_mfma_f32_16x16x32_bf16 v[74:77], v[170:173], v[240:243], v[74:77]
	v_mfma_f32_16x16x32_bf16 v[78:81], v[136:139], v[236:239], v[78:81]
	v_mfma_f32_16x16x32_bf16 v[78:81], v[140:143], v[240:243], v[78:81]
	s_barrier
	s_setprio 0
	s_mov_b32 m0, s14
	s_mov_b32 s46, s62
	s_mov_b32 s47, s63
	ds_read_b128 v[190:193], v135 offset:16384
	ds_read_b128 v[194:197], v135 offset:17408
	ds_read_b128 v[198:201], v135 offset:18432
	ds_read_b128 v[202:205], v135 offset:19456
	ds_read_b128 v[228:231], v135 offset:20480
	ds_read_b128 v[232:235], v135 offset:21504
	ds_read_b128 v[236:239], v135 offset:22528
	ds_read_b128 v[240:243], v135 offset:23552
	buffer_load_dwordx4 v131, s[44:47], s85 offen lds
	s_mov_b32 m0, s15
	s_add_i32 s53, s85, s2
	buffer_load_dwordx4 v133, s[44:47], s85 offen lds
	s_mov_b32 m0, s16
	s_nop 0
	buffer_load_dwordx4 v131, s[44:47], s53 offen lds
	s_mov_b32 m0, s18
	s_nop 0
	buffer_load_dwordx4 v133, s[44:47], s53 offen lds
	s_mov_b32 m0, s13
	s_nop 0
	buffer_load_dwordx4 v130, s[60:63], s52 offen lds
	s_mov_b32 m0, s19
	s_nop 0
	buffer_load_dwordx4 v132, s[60:63], s52 offen lds
	s_waitcnt vmcnt(8)
	s_waitcnt lgkmcnt(0)
	s_setprio 1
	s_barrier
	v_mfma_f32_16x16x32_bf16 v[62:65], v[136:139], v[190:193], v[62:65]
	v_mfma_f32_16x16x32_bf16 v[62:65], v[140:143], v[194:197], v[62:65]
	v_mfma_f32_16x16x32_bf16 v[58:61], v[154:157], v[190:193], v[58:61]
	v_mfma_f32_16x16x32_bf16 v[58:61], v[170:173], v[194:197], v[58:61]
	v_mfma_f32_16x16x32_bf16 v[50:53], v[182:185], v[190:193], v[50:53]
	v_mfma_f32_16x16x32_bf16 v[50:53], v[186:189], v[194:197], v[50:53]
	v_mfma_f32_16x16x32_bf16 v[54:57], v[174:177], v[190:193], v[54:57]
	v_mfma_f32_16x16x32_bf16 v[54:57], v[178:181], v[194:197], v[54:57]
	v_mfma_f32_16x16x32_bf16 v[38:41], v[174:177], v[198:201], v[38:41]
	v_mfma_f32_16x16x32_bf16 v[38:41], v[178:181], v[202:205], v[38:41]
	v_mfma_f32_16x16x32_bf16 v[34:37], v[182:185], v[198:201], v[34:37]
	v_mfma_f32_16x16x32_bf16 v[34:37], v[186:189], v[202:205], v[34:37]
	v_mfma_f32_16x16x32_bf16 v[42:45], v[154:157], v[198:201], v[42:45]
	v_mfma_f32_16x16x32_bf16 v[42:45], v[170:173], v[202:205], v[42:45]
	v_mfma_f32_16x16x32_bf16 v[46:49], v[136:139], v[198:201], v[46:49]
	v_mfma_f32_16x16x32_bf16 v[46:49], v[140:143], v[202:205], v[46:49]
	v_mfma_f32_16x16x32_bf16 v[30:33], v[136:139], v[228:231], v[30:33]
	v_mfma_f32_16x16x32_bf16 v[30:33], v[140:143], v[232:235], v[30:33]
	v_mfma_f32_16x16x32_bf16 v[26:29], v[154:157], v[228:231], v[26:29]
	v_mfma_f32_16x16x32_bf16 v[26:29], v[170:173], v[232:235], v[26:29]
	v_mfma_f32_16x16x32_bf16 v[18:21], v[182:185], v[228:231], v[18:21]
	v_mfma_f32_16x16x32_bf16 v[18:21], v[186:189], v[232:235], v[18:21]
	v_mfma_f32_16x16x32_bf16 v[22:25], v[174:177], v[228:231], v[22:25]
	v_mfma_f32_16x16x32_bf16 v[22:25], v[178:181], v[232:235], v[22:25]
	v_mfma_f32_16x16x32_bf16 v[6:9], v[174:177], v[236:239], v[6:9]
	v_mfma_f32_16x16x32_bf16 v[6:9], v[178:181], v[240:243], v[6:9]
	v_mfma_f32_16x16x32_bf16 v[2:5], v[182:185], v[236:239], v[2:5]
	v_mfma_f32_16x16x32_bf16 v[2:5], v[186:189], v[240:243], v[2:5]
	v_mfma_f32_16x16x32_bf16 v[10:13], v[154:157], v[236:239], v[10:13]
	v_mfma_f32_16x16x32_bf16 v[10:13], v[170:173], v[240:243], v[10:13]
	v_mfma_f32_16x16x32_bf16 v[14:17], v[136:139], v[236:239], v[14:17]
	v_mfma_f32_16x16x32_bf16 v[14:17], v[140:143], v[240:243], v[14:17]
	s_barrier
	s_setprio 0
	v_add_u32_e32 v144, 0x18000, v134
	ds_read_b128 v[136:139], v144
	ds_read_b128 v[140:143], v144 offset:1024
	ds_read_b128 v[154:157], v144 offset:2048
	ds_read_b128 v[170:173], v144 offset:3072
	v_add_u32_e32 v144, 0x1c000, v134
	ds_read_b128 v[174:177], v144
	ds_read_b128 v[178:181], v144 offset:1024
	ds_read_b128 v[182:185], v144 offset:2048
	ds_read_b128 v[186:189], v144 offset:3072
	s_add_i32 s52, s52, s2
	s_mov_b32 m0, s21
	ds_read_b128 v[190:193], v135 offset:32768
	ds_read_b128 v[194:197], v135 offset:33792
	ds_read_b128 v[198:201], v135 offset:34816
	ds_read_b128 v[202:205], v135 offset:35840
	ds_read_b128 v[228:231], v135 offset:36864
	ds_read_b128 v[232:235], v135 offset:37888
	ds_read_b128 v[236:239], v135 offset:38912
	ds_read_b128 v[240:243], v135 offset:39936
	buffer_load_dwordx4 v130, s[60:63], s52 offen lds
	s_mov_b32 m0, s22
	s_nop 0
	buffer_load_dwordx4 v132, s[60:63], s52 offen lds
	s_waitcnt vmcnt(8)
	s_waitcnt lgkmcnt(0)
	s_setprio 1
	s_barrier
	v_mfma_f32_16x16x32_bf16 v[122:125], v[136:139], v[190:193], v[122:125]
	v_mfma_f32_16x16x32_bf16 v[122:125], v[140:143], v[194:197], v[122:125]
	v_mfma_f32_16x16x32_bf16 v[126:129], v[154:157], v[190:193], v[126:129]
	v_mfma_f32_16x16x32_bf16 v[126:129], v[170:173], v[194:197], v[126:129]
	v_mfma_f32_16x16x32_bf16 v[114:117], v[182:185], v[190:193], v[114:117]
	v_mfma_f32_16x16x32_bf16 v[114:117], v[186:189], v[194:197], v[114:117]
	v_mfma_f32_16x16x32_bf16 v[118:121], v[174:177], v[190:193], v[118:121]
	v_mfma_f32_16x16x32_bf16 v[118:121], v[178:181], v[194:197], v[118:121]
	v_mfma_f32_16x16x32_bf16 v[102:105], v[174:177], v[198:201], v[102:105]
	v_mfma_f32_16x16x32_bf16 v[102:105], v[178:181], v[202:205], v[102:105]
	v_mfma_f32_16x16x32_bf16 v[98:101], v[182:185], v[198:201], v[98:101]
	v_mfma_f32_16x16x32_bf16 v[98:101], v[186:189], v[202:205], v[98:101]
	v_mfma_f32_16x16x32_bf16 v[106:109], v[154:157], v[198:201], v[106:109]
	v_mfma_f32_16x16x32_bf16 v[106:109], v[170:173], v[202:205], v[106:109]
	v_mfma_f32_16x16x32_bf16 v[110:113], v[136:139], v[198:201], v[110:113]
	v_mfma_f32_16x16x32_bf16 v[110:113], v[140:143], v[202:205], v[110:113]
	v_mfma_f32_16x16x32_bf16 v[94:97], v[136:139], v[228:231], v[94:97]
	v_mfma_f32_16x16x32_bf16 v[94:97], v[140:143], v[232:235], v[94:97]
	v_mfma_f32_16x16x32_bf16 v[90:93], v[154:157], v[228:231], v[90:93]
	v_mfma_f32_16x16x32_bf16 v[90:93], v[170:173], v[232:235], v[90:93]
	v_mfma_f32_16x16x32_bf16 v[82:85], v[182:185], v[228:231], v[82:85]
	v_mfma_f32_16x16x32_bf16 v[82:85], v[186:189], v[232:235], v[82:85]
	v_mfma_f32_16x16x32_bf16 v[86:89], v[174:177], v[228:231], v[86:89]
	v_mfma_f32_16x16x32_bf16 v[86:89], v[178:181], v[232:235], v[86:89]
	v_mfma_f32_16x16x32_bf16 v[70:73], v[174:177], v[236:239], v[70:73]
	v_mfma_f32_16x16x32_bf16 v[70:73], v[178:181], v[240:243], v[70:73]
	v_mfma_f32_16x16x32_bf16 v[66:69], v[182:185], v[236:239], v[66:69]
	v_mfma_f32_16x16x32_bf16 v[66:69], v[186:189], v[240:243], v[66:69]
	v_mfma_f32_16x16x32_bf16 v[74:77], v[154:157], v[236:239], v[74:77]
	v_mfma_f32_16x16x32_bf16 v[74:77], v[170:173], v[240:243], v[74:77]
	v_mfma_f32_16x16x32_bf16 v[78:81], v[136:139], v[236:239], v[78:81]
	v_mfma_f32_16x16x32_bf16 v[78:81], v[140:143], v[240:243], v[78:81]
	s_barrier
	s_setprio 0
	s_mov_b32 m0, s33
	s_add_i32 s52, s85, 0x80
	ds_read_b128 v[190:193], v135 offset:49152
	ds_read_b128 v[194:197], v135 offset:50176
	ds_read_b128 v[198:201], v135 offset:51200
	ds_read_b128 v[202:205], v135 offset:52224
	ds_read_b128 v[228:231], v135 offset:53248
	ds_read_b128 v[232:235], v135 offset:54272
	ds_read_b128 v[236:239], v135 offset:55296
	ds_read_b128 v[240:243], v135 offset:56320
	buffer_load_dwordx4 v131, s[44:47], s52 offen lds
	s_mov_b32 m0, s36
	s_nop 0
	buffer_load_dwordx4 v133, s[44:47], s52 offen lds
	s_add_i32 s52, s52, s2
	s_mov_b32 m0, s43
	s_nop 0
	buffer_load_dwordx4 v131, s[44:47], s52 offen lds
	s_mov_b32 m0, s48
	s_nop 0
	buffer_load_dwordx4 v133, s[44:47], s52 offen lds
	s_mov_b32 m0, s37
	s_nop 0
	buffer_load_dwordx4 v130, s[60:63], s84 offen lds
	s_mov_b32 m0, s42
	s_nop 0
	buffer_load_dwordx4 v132, s[60:63], s84 offen lds
	s_waitcnt vmcnt(8)
	s_waitcnt lgkmcnt(0)
	s_setprio 1
	s_barrier
	v_mfma_f32_16x16x32_bf16 v[62:65], v[136:139], v[190:193], v[62:65]
	v_mfma_f32_16x16x32_bf16 v[62:65], v[140:143], v[194:197], v[62:65]
	v_mfma_f32_16x16x32_bf16 v[58:61], v[154:157], v[190:193], v[58:61]
	v_mfma_f32_16x16x32_bf16 v[58:61], v[170:173], v[194:197], v[58:61]
	v_mfma_f32_16x16x32_bf16 v[50:53], v[182:185], v[190:193], v[50:53]
	v_mfma_f32_16x16x32_bf16 v[50:53], v[186:189], v[194:197], v[50:53]
	v_mfma_f32_16x16x32_bf16 v[54:57], v[174:177], v[190:193], v[54:57]
	v_mfma_f32_16x16x32_bf16 v[54:57], v[178:181], v[194:197], v[54:57]
	v_mfma_f32_16x16x32_bf16 v[38:41], v[174:177], v[198:201], v[38:41]
	v_mfma_f32_16x16x32_bf16 v[38:41], v[178:181], v[202:205], v[38:41]
	v_mfma_f32_16x16x32_bf16 v[34:37], v[182:185], v[198:201], v[34:37]
	v_mfma_f32_16x16x32_bf16 v[34:37], v[186:189], v[202:205], v[34:37]
	v_mfma_f32_16x16x32_bf16 v[42:45], v[154:157], v[198:201], v[42:45]
	v_mfma_f32_16x16x32_bf16 v[42:45], v[170:173], v[202:205], v[42:45]
	v_mfma_f32_16x16x32_bf16 v[46:49], v[136:139], v[198:201], v[46:49]
	v_mfma_f32_16x16x32_bf16 v[46:49], v[140:143], v[202:205], v[46:49]
	v_mfma_f32_16x16x32_bf16 v[30:33], v[136:139], v[228:231], v[30:33]
	v_mfma_f32_16x16x32_bf16 v[30:33], v[140:143], v[232:235], v[30:33]
	v_mfma_f32_16x16x32_bf16 v[26:29], v[154:157], v[228:231], v[26:29]
	v_mfma_f32_16x16x32_bf16 v[26:29], v[170:173], v[232:235], v[26:29]
	v_mfma_f32_16x16x32_bf16 v[18:21], v[182:185], v[228:231], v[18:21]
	v_mfma_f32_16x16x32_bf16 v[18:21], v[186:189], v[232:235], v[18:21]
	v_mfma_f32_16x16x32_bf16 v[22:25], v[174:177], v[228:231], v[22:25]
	v_mfma_f32_16x16x32_bf16 v[22:25], v[178:181], v[232:235], v[22:25]
	v_mfma_f32_16x16x32_bf16 v[6:9], v[174:177], v[236:239], v[6:9]
	v_mfma_f32_16x16x32_bf16 v[6:9], v[178:181], v[240:243], v[6:9]
	v_mfma_f32_16x16x32_bf16 v[2:5], v[182:185], v[236:239], v[2:5]
	v_mfma_f32_16x16x32_bf16 v[2:5], v[186:189], v[240:243], v[2:5]
	v_mfma_f32_16x16x32_bf16 v[10:13], v[154:157], v[236:239], v[10:13]
	v_mfma_f32_16x16x32_bf16 v[10:13], v[170:173], v[240:243], v[10:13]
	v_mfma_f32_16x16x32_bf16 v[14:17], v[136:139], v[236:239], v[14:17]
	v_mfma_f32_16x16x32_bf16 v[14:17], v[140:143], v[240:243], v[14:17]
	s_barrier
	s_setprio 0
	s_add_i32 s83, s83, 2
	s_addk_i32 s73, 0x100
	s_addk_i32 s82, 0x100
	s_cmp_ge_i32 s83, s23
	s_cbranch_scc0 .LBB0_2175
	v_readlane_b32 s83, v252, 30

.LBB0_2449:
	s_lshl_b32 s73, s72, 20
	s_and_b64 s[8:9], s[40:41], exec
	s_cselect_b32 s8, s73, s13
	s_lshl_b32 s84, s71, 20
	s_and_b64 s[24:25], s[40:41], exec
	s_cselect_b32 s9, s84, s21
	s_add_i32 s13, s13, 0x80080
	s_addk_i32 s21, 0x100
	s_mov_b32 s22, -2
	s_waitcnt lgkmcnt(0)
	v_add_u32_e32 v142, 0x10000, v188
	v_add_u32_e32 v182, 0x14000, v188
	ds_read_b128 v[130:133], v142
	ds_read_b128 v[134:137], v142 offset:1024
	ds_read_b128 v[138:141], v142 offset:2048
	ds_read_b128 v[142:145], v142 offset:3072
	ds_read_b128 v[154:157], v182
	ds_read_b128 v[174:177], v182 offset:1024
	ds_read_b128 v[178:181], v182 offset:2048
	ds_read_b128 v[190:193], v182 offset:3072
	s_add_i32 s24, s13, 0xfff80080
	s_cmp_eq_u32 s22, 28
	s_cselect_b32 s52, s8, s24
	s_cselect_b32 s25, s9, s21
	s_or_b32 s24, s52, 0x80
	s_mov_b32 m0, s68
	ds_read_b128 v[194:197], v189
	ds_read_b128 v[198:201], v189 offset:1024
	ds_read_b128 v[202:205], v189 offset:2048
	ds_read_b128 v[228:231], v189 offset:3072
	ds_read_b128 v[232:235], v189 offset:4096
	ds_read_b128 v[236:239], v189 offset:5120
	ds_read_b128 v[240:243], v189 offset:6144
	ds_read_b128 v[244:247], v189 offset:7168
	buffer_load_dwordx4 v184, s[60:63], s13 offen lds
	s_mov_b32 m0, s70
	s_nop 0
	buffer_load_dwordx4 v186, s[60:63], s13 offen lds
	s_waitcnt vmcnt(8)
	s_waitcnt lgkmcnt(0)
	s_setprio 1
	s_barrier
	v_mfma_f32_16x16x32_bf16 v[126:129], v[130:133], v[194:197], 0
	v_mfma_f32_16x16x32_bf16 v[126:129], v[134:137], v[198:201], v[126:129]
	v_mfma_f32_16x16x32_bf16 v[122:125], v[138:141], v[194:197], 0
	v_mfma_f32_16x16x32_bf16 v[122:125], v[142:145], v[198:201], v[122:125]
	v_mfma_f32_16x16x32_bf16 v[114:117], v[178:181], v[194:197], 0
	v_mfma_f32_16x16x32_bf16 v[114:117], v[190:193], v[198:201], v[114:117]
	v_mfma_f32_16x16x32_bf16 v[118:121], v[154:157], v[194:197], 0
	v_mfma_f32_16x16x32_bf16 v[118:121], v[174:177], v[198:201], v[118:121]
	v_mfma_f32_16x16x32_bf16 v[102:105], v[154:157], v[202:205], 0
	v_mfma_f32_16x16x32_bf16 v[102:105], v[174:177], v[228:231], v[102:105]
	v_mfma_f32_16x16x32_bf16 v[98:101], v[178:181], v[202:205], 0
	v_mfma_f32_16x16x32_bf16 v[98:101], v[190:193], v[228:231], v[98:101]
	v_mfma_f32_16x16x32_bf16 v[106:109], v[138:141], v[202:205], 0
	v_mfma_f32_16x16x32_bf16 v[106:109], v[142:145], v[228:231], v[106:109]
	v_mfma_f32_16x16x32_bf16 v[110:113], v[130:133], v[202:205], 0
	v_mfma_f32_16x16x32_bf16 v[110:113], v[134:137], v[228:231], v[110:113]
	v_mfma_f32_16x16x32_bf16 v[94:97], v[130:133], v[232:235], 0
	v_mfma_f32_16x16x32_bf16 v[94:97], v[134:137], v[236:239], v[94:97]
	v_mfma_f32_16x16x32_bf16 v[90:93], v[138:141], v[232:235], 0
	v_mfma_f32_16x16x32_bf16 v[90:93], v[142:145], v[236:239], v[90:93]
	v_mfma_f32_16x16x32_bf16 v[82:85], v[178:181], v[232:235], 0
	v_mfma_f32_16x16x32_bf16 v[82:85], v[190:193], v[236:239], v[82:85]
	v_mfma_f32_16x16x32_bf16 v[86:89], v[154:157], v[232:235], 0
	v_mfma_f32_16x16x32_bf16 v[86:89], v[174:177], v[236:239], v[86:89]
	v_mfma_f32_16x16x32_bf16 v[70:73], v[154:157], v[240:243], 0
	v_mfma_f32_16x16x32_bf16 v[70:73], v[174:177], v[244:247], v[70:73]
	v_mfma_f32_16x16x32_bf16 v[66:69], v[178:181], v[240:243], 0
	v_mfma_f32_16x16x32_bf16 v[66:69], v[190:193], v[244:247], v[66:69]
	v_mfma_f32_16x16x32_bf16 v[74:77], v[138:141], v[240:243], 0
	v_mfma_f32_16x16x32_bf16 v[74:77], v[142:145], v[244:247], v[74:77]
	v_mfma_f32_16x16x32_bf16 v[78:81], v[130:133], v[240:243], 0
	v_mfma_f32_16x16x32_bf16 v[78:81], v[134:137], v[244:247], v[78:81]
	s_barrier
	s_setprio 0
	s_mov_b32 m0, s16
	s_mov_b32 s46, s62
	s_mov_b32 s47, s63
	ds_read_b128 v[194:197], v189 offset:16384
	ds_read_b128 v[198:201], v189 offset:17408
	ds_read_b128 v[202:205], v189 offset:18432
	ds_read_b128 v[228:231], v189 offset:19456
	ds_read_b128 v[232:235], v189 offset:20480
	ds_read_b128 v[236:239], v189 offset:21504
	ds_read_b128 v[240:243], v189 offset:22528
	ds_read_b128 v[244:247], v189 offset:23552
	buffer_load_dwordx4 v185, s[44:47], s25 offen lds
	s_mov_b32 m0, s18
	s_add_i32 s53, s25, 0x80000
	buffer_load_dwordx4 v187, s[44:47], s25 offen lds
	s_mov_b32 m0, s19
	s_nop 0
	buffer_load_dwordx4 v185, s[44:47], s53 offen lds
	s_mov_b32 m0, s23
	s_nop 0
	buffer_load_dwordx4 v187, s[44:47], s53 offen lds
	s_mov_b32 m0, s15
	s_nop 0
	buffer_load_dwordx4 v184, s[60:63], s52 offen lds
	s_mov_b32 m0, s26
	s_nop 0
	buffer_load_dwordx4 v186, s[60:63], s52 offen lds
	s_waitcnt vmcnt(8)
	s_waitcnt lgkmcnt(0)
	s_setprio 1
	s_barrier
	v_mfma_f32_16x16x32_bf16 v[62:65], v[130:133], v[194:197], 0
	v_mfma_f32_16x16x32_bf16 v[62:65], v[134:137], v[198:201], v[62:65]
	v_mfma_f32_16x16x32_bf16 v[58:61], v[138:141], v[194:197], 0
	v_mfma_f32_16x16x32_bf16 v[58:61], v[142:145], v[198:201], v[58:61]
	v_mfma_f32_16x16x32_bf16 v[50:53], v[178:181], v[194:197], 0
	v_mfma_f32_16x16x32_bf16 v[50:53], v[190:193], v[198:201], v[50:53]
	v_mfma_f32_16x16x32_bf16 v[54:57], v[154:157], v[194:197], 0
	v_mfma_f32_16x16x32_bf16 v[54:57], v[174:177], v[198:201], v[54:57]
	v_mfma_f32_16x16x32_bf16 v[38:41], v[154:157], v[202:205], 0
	v_mfma_f32_16x16x32_bf16 v[38:41], v[174:177], v[228:231], v[38:41]
	v_mfma_f32_16x16x32_bf16 v[34:37], v[178:181], v[202:205], 0
	v_mfma_f32_16x16x32_bf16 v[34:37], v[190:193], v[228:231], v[34:37]
	v_mfma_f32_16x16x32_bf16 v[42:45], v[138:141], v[202:205], 0
	v_mfma_f32_16x16x32_bf16 v[42:45], v[142:145], v[228:231], v[42:45]
	v_mfma_f32_16x16x32_bf16 v[46:49], v[130:133], v[202:205], 0
	v_mfma_f32_16x16x32_bf16 v[46:49], v[134:137], v[228:231], v[46:49]
	v_mfma_f32_16x16x32_bf16 v[30:33], v[130:133], v[232:235], 0
	v_mfma_f32_16x16x32_bf16 v[30:33], v[134:137], v[236:239], v[30:33]
	v_mfma_f32_16x16x32_bf16 v[26:29], v[138:141], v[232:235], 0
	v_mfma_f32_16x16x32_bf16 v[26:29], v[142:145], v[236:239], v[26:29]
	v_mfma_f32_16x16x32_bf16 v[18:21], v[178:181], v[232:235], 0
	v_mfma_f32_16x16x32_bf16 v[18:21], v[190:193], v[236:239], v[18:21]
	v_mfma_f32_16x16x32_bf16 v[22:25], v[154:157], v[232:235], 0
	v_mfma_f32_16x16x32_bf16 v[22:25], v[174:177], v[236:239], v[22:25]
	v_mfma_f32_16x16x32_bf16 v[6:9], v[154:157], v[240:243], 0
	v_mfma_f32_16x16x32_bf16 v[6:9], v[174:177], v[244:247], v[6:9]
	v_mfma_f32_16x16x32_bf16 v[2:5], v[178:181], v[240:243], 0
	v_mfma_f32_16x16x32_bf16 v[2:5], v[190:193], v[244:247], v[2:5]
	v_mfma_f32_16x16x32_bf16 v[10:13], v[138:141], v[240:243], 0
	v_mfma_f32_16x16x32_bf16 v[10:13], v[142:145], v[244:247], v[10:13]
	v_mfma_f32_16x16x32_bf16 v[14:17], v[130:133], v[240:243], 0
	v_mfma_f32_16x16x32_bf16 v[14:17], v[134:137], v[244:247], v[14:17]
	s_barrier
	s_setprio 0
	v_add_u32_e32 v142, 0x18000, v188
	v_add_u32_e32 v182, 0x1c000, v188
	ds_read_b128 v[130:133], v142
	ds_read_b128 v[134:137], v142 offset:1024
	ds_read_b128 v[138:141], v142 offset:2048
	ds_read_b128 v[142:145], v142 offset:3072
	ds_read_b128 v[154:157], v182
	ds_read_b128 v[174:177], v182 offset:1024
	ds_read_b128 v[178:181], v182 offset:2048
	ds_read_b128 v[190:193], v182 offset:3072
	s_add_i32 s52, s52, 0x80000
	s_mov_b32 m0, s27
	ds_read_b128 v[194:197], v189 offset:32768
	ds_read_b128 v[198:201], v189 offset:33792
	ds_read_b128 v[202:205], v189 offset:34816
	ds_read_b128 v[228:231], v189 offset:35840
	ds_read_b128 v[232:235], v189 offset:36864
	ds_read_b128 v[236:239], v189 offset:37888
	ds_read_b128 v[240:243], v189 offset:38912
	ds_read_b128 v[244:247], v189 offset:39936
	buffer_load_dwordx4 v184, s[60:63], s52 offen lds
	s_mov_b32 m0, s30
	s_nop 0
	buffer_load_dwordx4 v186, s[60:63], s52 offen lds
	s_waitcnt vmcnt(8)
	s_waitcnt lgkmcnt(0)
	s_setprio 1
	s_barrier
	v_mfma_f32_16x16x32_bf16 v[126:129], v[130:133], v[194:197], v[126:129]
	v_mfma_f32_16x16x32_bf16 v[126:129], v[134:137], v[198:201], v[126:129]
	v_mfma_f32_16x16x32_bf16 v[122:125], v[138:141], v[194:197], v[122:125]
	v_mfma_f32_16x16x32_bf16 v[122:125], v[142:145], v[198:201], v[122:125]
	v_mfma_f32_16x16x32_bf16 v[114:117], v[178:181], v[194:197], v[114:117]
	v_mfma_f32_16x16x32_bf16 v[114:117], v[190:193], v[198:201], v[114:117]
	v_mfma_f32_16x16x32_bf16 v[118:121], v[154:157], v[194:197], v[118:121]
	v_mfma_f32_16x16x32_bf16 v[118:121], v[174:177], v[198:201], v[118:121]
	v_mfma_f32_16x16x32_bf16 v[102:105], v[154:157], v[202:205], v[102:105]
	v_mfma_f32_16x16x32_bf16 v[102:105], v[174:177], v[228:231], v[102:105]
	v_mfma_f32_16x16x32_bf16 v[98:101], v[178:181], v[202:205], v[98:101]
	v_mfma_f32_16x16x32_bf16 v[98:101], v[190:193], v[228:231], v[98:101]
	v_mfma_f32_16x16x32_bf16 v[106:109], v[138:141], v[202:205], v[106:109]
	v_mfma_f32_16x16x32_bf16 v[106:109], v[142:145], v[228:231], v[106:109]
	v_mfma_f32_16x16x32_bf16 v[110:113], v[130:133], v[202:205], v[110:113]
	v_mfma_f32_16x16x32_bf16 v[110:113], v[134:137], v[228:231], v[110:113]
	v_mfma_f32_16x16x32_bf16 v[94:97], v[130:133], v[232:235], v[94:97]
	v_mfma_f32_16x16x32_bf16 v[94:97], v[134:137], v[236:239], v[94:97]
	v_mfma_f32_16x16x32_bf16 v[90:93], v[138:141], v[232:235], v[90:93]
	v_mfma_f32_16x16x32_bf16 v[90:93], v[142:145], v[236:239], v[90:93]
	v_mfma_f32_16x16x32_bf16 v[82:85], v[178:181], v[232:235], v[82:85]
	v_mfma_f32_16x16x32_bf16 v[82:85], v[190:193], v[236:239], v[82:85]
	v_mfma_f32_16x16x32_bf16 v[86:89], v[154:157], v[232:235], v[86:89]
	v_mfma_f32_16x16x32_bf16 v[86:89], v[174:177], v[236:239], v[86:89]
	v_mfma_f32_16x16x32_bf16 v[70:73], v[154:157], v[240:243], v[70:73]
	v_mfma_f32_16x16x32_bf16 v[70:73], v[174:177], v[244:247], v[70:73]
	v_mfma_f32_16x16x32_bf16 v[66:69], v[178:181], v[240:243], v[66:69]
	v_mfma_f32_16x16x32_bf16 v[66:69], v[190:193], v[244:247], v[66:69]
	v_mfma_f32_16x16x32_bf16 v[74:77], v[138:141], v[240:243], v[74:77]
	v_mfma_f32_16x16x32_bf16 v[74:77], v[142:145], v[244:247], v[74:77]
	v_mfma_f32_16x16x32_bf16 v[78:81], v[130:133], v[240:243], v[78:81]
	v_mfma_f32_16x16x32_bf16 v[78:81], v[134:137], v[244:247], v[78:81]
	s_barrier
	s_setprio 0
	s_mov_b32 m0, s36
	s_or_b32 s52, s25, 0x80
	ds_read_b128 v[194:197], v189 offset:49152
	ds_read_b128 v[198:201], v189 offset:50176
	ds_read_b128 v[202:205], v189 offset:51200
	ds_read_b128 v[228:231], v189 offset:52224
	ds_read_b128 v[232:235], v189 offset:53248
	ds_read_b128 v[236:239], v189 offset:54272
	ds_read_b128 v[240:243], v189 offset:55296
	ds_read_b128 v[244:247], v189 offset:56320
	buffer_load_dwordx4 v185, s[44:47], s52 offen lds
	s_mov_b32 m0, s37
	s_add_i32 s25, s25, 0x80080
	buffer_load_dwordx4 v187, s[44:47], s52 offen lds
	s_mov_b32 m0, s66
	s_nop 0
	buffer_load_dwordx4 v185, s[44:47], s25 offen lds
	s_mov_b32 m0, s67
	s_nop 0
	buffer_load_dwordx4 v187, s[44:47], s25 offen lds
	s_mov_b32 m0, s48
	s_nop 0
	buffer_load_dwordx4 v184, s[60:63], s24 offen lds
	s_mov_b32 m0, s49
	s_nop 0
	buffer_load_dwordx4 v186, s[60:63], s24 offen lds
	s_waitcnt vmcnt(8)
	s_waitcnt lgkmcnt(0)
	s_setprio 1
	s_barrier
	v_mfma_f32_16x16x32_bf16 v[62:65], v[130:133], v[194:197], v[62:65]
	v_mfma_f32_16x16x32_bf16 v[62:65], v[134:137], v[198:201], v[62:65]
	v_mfma_f32_16x16x32_bf16 v[58:61], v[138:141], v[194:197], v[58:61]
	v_mfma_f32_16x16x32_bf16 v[58:61], v[142:145], v[198:201], v[58:61]
	v_mfma_f32_16x16x32_bf16 v[50:53], v[178:181], v[194:197], v[50:53]
	v_mfma_f32_16x16x32_bf16 v[50:53], v[190:193], v[198:201], v[50:53]
	v_mfma_f32_16x16x32_bf16 v[54:57], v[154:157], v[194:197], v[54:57]
	v_mfma_f32_16x16x32_bf16 v[54:57], v[174:177], v[198:201], v[54:57]
	v_mfma_f32_16x16x32_bf16 v[38:41], v[154:157], v[202:205], v[38:41]
	v_mfma_f32_16x16x32_bf16 v[38:41], v[174:177], v[228:231], v[38:41]
	v_mfma_f32_16x16x32_bf16 v[34:37], v[178:181], v[202:205], v[34:37]
	v_mfma_f32_16x16x32_bf16 v[34:37], v[190:193], v[228:231], v[34:37]
	v_mfma_f32_16x16x32_bf16 v[42:45], v[138:141], v[202:205], v[42:45]
	v_mfma_f32_16x16x32_bf16 v[42:45], v[142:145], v[228:231], v[42:45]
	v_mfma_f32_16x16x32_bf16 v[46:49], v[130:133], v[202:205], v[46:49]
	v_mfma_f32_16x16x32_bf16 v[46:49], v[134:137], v[228:231], v[46:49]
	v_mfma_f32_16x16x32_bf16 v[30:33], v[130:133], v[232:235], v[30:33]
	v_mfma_f32_16x16x32_bf16 v[30:33], v[134:137], v[236:239], v[30:33]
	v_mfma_f32_16x16x32_bf16 v[26:29], v[138:141], v[232:235], v[26:29]
	v_mfma_f32_16x16x32_bf16 v[26:29], v[142:145], v[236:239], v[26:29]
	v_mfma_f32_16x16x32_bf16 v[18:21], v[178:181], v[232:235], v[18:21]
	v_mfma_f32_16x16x32_bf16 v[18:21], v[190:193], v[236:239], v[18:21]
	v_mfma_f32_16x16x32_bf16 v[22:25], v[154:157], v[232:235], v[22:25]
	v_mfma_f32_16x16x32_bf16 v[22:25], v[174:177], v[236:239], v[22:25]
	v_mfma_f32_16x16x32_bf16 v[6:9], v[154:157], v[240:243], v[6:9]
	v_mfma_f32_16x16x32_bf16 v[6:9], v[174:177], v[244:247], v[6:9]
	v_mfma_f32_16x16x32_bf16 v[2:5], v[178:181], v[240:243], v[2:5]
	v_mfma_f32_16x16x32_bf16 v[2:5], v[190:193], v[244:247], v[2:5]
	v_mfma_f32_16x16x32_bf16 v[10:13], v[138:141], v[240:243], v[10:13]
	v_mfma_f32_16x16x32_bf16 v[10:13], v[142:145], v[244:247], v[10:13]
	v_mfma_f32_16x16x32_bf16 v[14:17], v[130:133], v[240:243], v[14:17]
	v_mfma_f32_16x16x32_bf16 v[14:17], v[134:137], v[244:247], v[14:17]
	s_barrier
	s_setprio 0
	s_add_i32 s22, s22, 2
	s_addk_i32 s13, 0x100
	s_addk_i32 s21, 0x100
	s_cmp_gt_u32 s22, 29
.LBB0_2450:
	v_add_u32_e32 v142, 0x10000, v188
	v_add_u32_e32 v182, 0x14000, v188
	ds_read_b128 v[130:133], v142
	ds_read_b128 v[134:137], v142 offset:1024
	ds_read_b128 v[138:141], v142 offset:2048
	ds_read_b128 v[142:145], v142 offset:3072
	ds_read_b128 v[154:157], v182
	ds_read_b128 v[174:177], v182 offset:1024
	ds_read_b128 v[178:181], v182 offset:2048
	ds_read_b128 v[190:193], v182 offset:3072
	s_add_i32 s24, s13, 0xfff80080
	s_cmp_eq_u32 s22, 28
	s_cselect_b32 s52, s8, s24
	s_cselect_b32 s25, s9, s21
	s_or_b32 s24, s52, 0x80
	s_mov_b32 m0, s68
	ds_read_b128 v[194:197], v189
	ds_read_b128 v[198:201], v189 offset:1024
	ds_read_b128 v[202:205], v189 offset:2048
	ds_read_b128 v[228:231], v189 offset:3072
	ds_read_b128 v[232:235], v189 offset:4096
	ds_read_b128 v[236:239], v189 offset:5120
	ds_read_b128 v[240:243], v189 offset:6144
	ds_read_b128 v[244:247], v189 offset:7168
	buffer_load_dwordx4 v184, s[60:63], s13 offen lds
	s_mov_b32 m0, s70
	s_nop 0
	buffer_load_dwordx4 v186, s[60:63], s13 offen lds
	s_waitcnt vmcnt(8)
	s_waitcnt lgkmcnt(0)
	s_setprio 1
	s_barrier
	v_mfma_f32_16x16x32_bf16 v[126:129], v[130:133], v[194:197], v[126:129]
	v_mfma_f32_16x16x32_bf16 v[126:129], v[134:137], v[198:201], v[126:129]
	v_mfma_f32_16x16x32_bf16 v[122:125], v[138:141], v[194:197], v[122:125]
	v_mfma_f32_16x16x32_bf16 v[122:125], v[142:145], v[198:201], v[122:125]
	v_mfma_f32_16x16x32_bf16 v[114:117], v[178:181], v[194:197], v[114:117]
	v_mfma_f32_16x16x32_bf16 v[114:117], v[190:193], v[198:201], v[114:117]
	v_mfma_f32_16x16x32_bf16 v[118:121], v[154:157], v[194:197], v[118:121]
	v_mfma_f32_16x16x32_bf16 v[118:121], v[174:177], v[198:201], v[118:121]
	v_mfma_f32_16x16x32_bf16 v[102:105], v[154:157], v[202:205], v[102:105]
	v_mfma_f32_16x16x32_bf16 v[102:105], v[174:177], v[228:231], v[102:105]
	v_mfma_f32_16x16x32_bf16 v[98:101], v[178:181], v[202:205], v[98:101]
	v_mfma_f32_16x16x32_bf16 v[98:101], v[190:193], v[228:231], v[98:101]
	v_mfma_f32_16x16x32_bf16 v[106:109], v[138:141], v[202:205], v[106:109]
	v_mfma_f32_16x16x32_bf16 v[106:109], v[142:145], v[228:231], v[106:109]
	v_mfma_f32_16x16x32_bf16 v[110:113], v[130:133], v[202:205], v[110:113]
	v_mfma_f32_16x16x32_bf16 v[110:113], v[134:137], v[228:231], v[110:113]
	v_mfma_f32_16x16x32_bf16 v[94:97], v[130:133], v[232:235], v[94:97]
	v_mfma_f32_16x16x32_bf16 v[94:97], v[134:137], v[236:239], v[94:97]
	v_mfma_f32_16x16x32_bf16 v[90:93], v[138:141], v[232:235], v[90:93]
	v_mfma_f32_16x16x32_bf16 v[90:93], v[142:145], v[236:239], v[90:93]
	v_mfma_f32_16x16x32_bf16 v[82:85], v[178:181], v[232:235], v[82:85]
	v_mfma_f32_16x16x32_bf16 v[82:85], v[190:193], v[236:239], v[82:85]
	v_mfma_f32_16x16x32_bf16 v[86:89], v[154:157], v[232:235], v[86:89]
	v_mfma_f32_16x16x32_bf16 v[86:89], v[174:177], v[236:239], v[86:89]
	v_mfma_f32_16x16x32_bf16 v[70:73], v[154:157], v[240:243], v[70:73]
	v_mfma_f32_16x16x32_bf16 v[70:73], v[174:177], v[244:247], v[70:73]
	v_mfma_f32_16x16x32_bf16 v[66:69], v[178:181], v[240:243], v[66:69]
	v_mfma_f32_16x16x32_bf16 v[66:69], v[190:193], v[244:247], v[66:69]
	v_mfma_f32_16x16x32_bf16 v[74:77], v[138:141], v[240:243], v[74:77]
	v_mfma_f32_16x16x32_bf16 v[74:77], v[142:145], v[244:247], v[74:77]
	v_mfma_f32_16x16x32_bf16 v[78:81], v[130:133], v[240:243], v[78:81]
	v_mfma_f32_16x16x32_bf16 v[78:81], v[134:137], v[244:247], v[78:81]
	s_barrier
	s_setprio 0
	s_mov_b32 m0, s16
	s_mov_b32 s46, s62
	s_mov_b32 s47, s63
	ds_read_b128 v[194:197], v189 offset:16384
	ds_read_b128 v[198:201], v189 offset:17408
	ds_read_b128 v[202:205], v189 offset:18432
	ds_read_b128 v[228:231], v189 offset:19456
	ds_read_b128 v[232:235], v189 offset:20480
	ds_read_b128 v[236:239], v189 offset:21504
	ds_read_b128 v[240:243], v189 offset:22528
	ds_read_b128 v[244:247], v189 offset:23552
	buffer_load_dwordx4 v185, s[44:47], s25 offen lds
	s_mov_b32 m0, s18
	s_add_i32 s53, s25, 0x80000
	buffer_load_dwordx4 v187, s[44:47], s25 offen lds
	s_mov_b32 m0, s19
	s_nop 0
	buffer_load_dwordx4 v185, s[44:47], s53 offen lds
	s_mov_b32 m0, s23
	s_nop 0
	buffer_load_dwordx4 v187, s[44:47], s53 offen lds
	s_mov_b32 m0, s15
	s_nop 0
	buffer_load_dwordx4 v184, s[60:63], s52 offen lds
	s_mov_b32 m0, s26
	s_nop 0
	buffer_load_dwordx4 v186, s[60:63], s52 offen lds
	s_waitcnt vmcnt(8)
	s_waitcnt lgkmcnt(0)
	s_setprio 1
	s_barrier
	v_mfma_f32_16x16x32_bf16 v[62:65], v[130:133], v[194:197], v[62:65]
	v_mfma_f32_16x16x32_bf16 v[62:65], v[134:137], v[198:201], v[62:65]
	v_mfma_f32_16x16x32_bf16 v[58:61], v[138:141], v[194:197], v[58:61]
	v_mfma_f32_16x16x32_bf16 v[58:61], v[142:145], v[198:201], v[58:61]
	v_mfma_f32_16x16x32_bf16 v[50:53], v[178:181], v[194:197], v[50:53]
	v_mfma_f32_16x16x32_bf16 v[50:53], v[190:193], v[198:201], v[50:53]
	v_mfma_f32_16x16x32_bf16 v[54:57], v[154:157], v[194:197], v[54:57]
	v_mfma_f32_16x16x32_bf16 v[54:57], v[174:177], v[198:201], v[54:57]
	v_mfma_f32_16x16x32_bf16 v[38:41], v[154:157], v[202:205], v[38:41]
	v_mfma_f32_16x16x32_bf16 v[38:41], v[174:177], v[228:231], v[38:41]
	v_mfma_f32_16x16x32_bf16 v[34:37], v[178:181], v[202:205], v[34:37]
	v_mfma_f32_16x16x32_bf16 v[34:37], v[190:193], v[228:231], v[34:37]
	v_mfma_f32_16x16x32_bf16 v[42:45], v[138:141], v[202:205], v[42:45]
	v_mfma_f32_16x16x32_bf16 v[42:45], v[142:145], v[228:231], v[42:45]
	v_mfma_f32_16x16x32_bf16 v[46:49], v[130:133], v[202:205], v[46:49]
	v_mfma_f32_16x16x32_bf16 v[46:49], v[134:137], v[228:231], v[46:49]
	v_mfma_f32_16x16x32_bf16 v[30:33], v[130:133], v[232:235], v[30:33]
	v_mfma_f32_16x16x32_bf16 v[30:33], v[134:137], v[236:239], v[30:33]
	v_mfma_f32_16x16x32_bf16 v[26:29], v[138:141], v[232:235], v[26:29]
	v_mfma_f32_16x16x32_bf16 v[26:29], v[142:145], v[236:239], v[26:29]
	v_mfma_f32_16x16x32_bf16 v[18:21], v[178:181], v[232:235], v[18:21]
	v_mfma_f32_16x16x32_bf16 v[18:21], v[190:193], v[236:239], v[18:21]
	v_mfma_f32_16x16x32_bf16 v[22:25], v[154:157], v[232:235], v[22:25]
	v_mfma_f32_16x16x32_bf16 v[22:25], v[174:177], v[236:239], v[22:25]
	v_mfma_f32_16x16x32_bf16 v[6:9], v[154:157], v[240:243], v[6:9]
	v_mfma_f32_16x16x32_bf16 v[6:9], v[174:177], v[244:247], v[6:9]
	v_mfma_f32_16x16x32_bf16 v[2:5], v[178:181], v[240:243], v[2:5]
	v_mfma_f32_16x16x32_bf16 v[2:5], v[190:193], v[244:247], v[2:5]
	v_mfma_f32_16x16x32_bf16 v[10:13], v[138:141], v[240:243], v[10:13]
	v_mfma_f32_16x16x32_bf16 v[10:13], v[142:145], v[244:247], v[10:13]
	v_mfma_f32_16x16x32_bf16 v[14:17], v[130:133], v[240:243], v[14:17]
	v_mfma_f32_16x16x32_bf16 v[14:17], v[134:137], v[244:247], v[14:17]
	s_barrier
	s_setprio 0
	v_add_u32_e32 v142, 0x18000, v188
	v_add_u32_e32 v182, 0x1c000, v188
	ds_read_b128 v[130:133], v142
	ds_read_b128 v[134:137], v142 offset:1024
	ds_read_b128 v[138:141], v142 offset:2048
	ds_read_b128 v[142:145], v142 offset:3072
	ds_read_b128 v[154:157], v182
	ds_read_b128 v[174:177], v182 offset:1024
	ds_read_b128 v[178:181], v182 offset:2048
	ds_read_b128 v[190:193], v182 offset:3072
	s_add_i32 s52, s52, 0x80000
	s_mov_b32 m0, s27
	ds_read_b128 v[194:197], v189 offset:32768
	ds_read_b128 v[198:201], v189 offset:33792
	ds_read_b128 v[202:205], v189 offset:34816
	ds_read_b128 v[228:231], v189 offset:35840
	ds_read_b128 v[232:235], v189 offset:36864
	ds_read_b128 v[236:239], v189 offset:37888
	ds_read_b128 v[240:243], v189 offset:38912
	ds_read_b128 v[244:247], v189 offset:39936
	buffer_load_dwordx4 v184, s[60:63], s52 offen lds
	s_mov_b32 m0, s30
	s_nop 0
	buffer_load_dwordx4 v186, s[60:63], s52 offen lds
	s_waitcnt vmcnt(8)
	s_waitcnt lgkmcnt(0)
	s_setprio 1
	s_barrier
	v_mfma_f32_16x16x32_bf16 v[126:129], v[130:133], v[194:197], v[126:129]
	v_mfma_f32_16x16x32_bf16 v[126:129], v[134:137], v[198:201], v[126:129]
	v_mfma_f32_16x16x32_bf16 v[122:125], v[138:141], v[194:197], v[122:125]
	v_mfma_f32_16x16x32_bf16 v[122:125], v[142:145], v[198:201], v[122:125]
	v_mfma_f32_16x16x32_bf16 v[114:117], v[178:181], v[194:197], v[114:117]
	v_mfma_f32_16x16x32_bf16 v[114:117], v[190:193], v[198:201], v[114:117]
	v_mfma_f32_16x16x32_bf16 v[118:121], v[154:157], v[194:197], v[118:121]
	v_mfma_f32_16x16x32_bf16 v[118:121], v[174:177], v[198:201], v[118:121]
	v_mfma_f32_16x16x32_bf16 v[102:105], v[154:157], v[202:205], v[102:105]
	v_mfma_f32_16x16x32_bf16 v[102:105], v[174:177], v[228:231], v[102:105]
	v_mfma_f32_16x16x32_bf16 v[98:101], v[178:181], v[202:205], v[98:101]
	v_mfma_f32_16x16x32_bf16 v[98:101], v[190:193], v[228:231], v[98:101]
	v_mfma_f32_16x16x32_bf16 v[106:109], v[138:141], v[202:205], v[106:109]
	v_mfma_f32_16x16x32_bf16 v[106:109], v[142:145], v[228:231], v[106:109]
	v_mfma_f32_16x16x32_bf16 v[110:113], v[130:133], v[202:205], v[110:113]
	v_mfma_f32_16x16x32_bf16 v[110:113], v[134:137], v[228:231], v[110:113]
	v_mfma_f32_16x16x32_bf16 v[94:97], v[130:133], v[232:235], v[94:97]
	v_mfma_f32_16x16x32_bf16 v[94:97], v[134:137], v[236:239], v[94:97]
	v_mfma_f32_16x16x32_bf16 v[90:93], v[138:141], v[232:235], v[90:93]
	v_mfma_f32_16x16x32_bf16 v[90:93], v[142:145], v[236:239], v[90:93]
	v_mfma_f32_16x16x32_bf16 v[82:85], v[178:181], v[232:235], v[82:85]
	v_mfma_f32_16x16x32_bf16 v[82:85], v[190:193], v[236:239], v[82:85]
	v_mfma_f32_16x16x32_bf16 v[86:89], v[154:157], v[232:235], v[86:89]
	v_mfma_f32_16x16x32_bf16 v[86:89], v[174:177], v[236:239], v[86:89]
	v_mfma_f32_16x16x32_bf16 v[70:73], v[154:157], v[240:243], v[70:73]
	v_mfma_f32_16x16x32_bf16 v[70:73], v[174:177], v[244:247], v[70:73]
	v_mfma_f32_16x16x32_bf16 v[66:69], v[178:181], v[240:243], v[66:69]
	v_mfma_f32_16x16x32_bf16 v[66:69], v[190:193], v[244:247], v[66:69]
	v_mfma_f32_16x16x32_bf16 v[74:77], v[138:141], v[240:243], v[74:77]
	v_mfma_f32_16x16x32_bf16 v[74:77], v[142:145], v[244:247], v[74:77]
	v_mfma_f32_16x16x32_bf16 v[78:81], v[130:133], v[240:243], v[78:81]
	v_mfma_f32_16x16x32_bf16 v[78:81], v[134:137], v[244:247], v[78:81]
	s_barrier
	s_setprio 0
	s_mov_b32 m0, s36
	s_or_b32 s52, s25, 0x80
	ds_read_b128 v[194:197], v189 offset:49152
	ds_read_b128 v[198:201], v189 offset:50176
	ds_read_b128 v[202:205], v189 offset:51200
	ds_read_b128 v[228:231], v189 offset:52224
	ds_read_b128 v[232:235], v189 offset:53248
	ds_read_b128 v[236:239], v189 offset:54272
	ds_read_b128 v[240:243], v189 offset:55296
	ds_read_b128 v[244:247], v189 offset:56320
	buffer_load_dwordx4 v185, s[44:47], s52 offen lds
	s_mov_b32 m0, s37
	s_add_i32 s25, s25, 0x80080
	buffer_load_dwordx4 v187, s[44:47], s52 offen lds
	s_mov_b32 m0, s66
	s_nop 0
	buffer_load_dwordx4 v185, s[44:47], s25 offen lds
	s_mov_b32 m0, s67
	s_nop 0
	buffer_load_dwordx4 v187, s[44:47], s25 offen lds
	s_mov_b32 m0, s48
	s_nop 0
	buffer_load_dwordx4 v184, s[60:63], s24 offen lds
	s_mov_b32 m0, s49
	s_nop 0
	buffer_load_dwordx4 v186, s[60:63], s24 offen lds
	s_waitcnt vmcnt(8)
	s_waitcnt lgkmcnt(0)
	s_setprio 1
	s_barrier
	v_mfma_f32_16x16x32_bf16 v[62:65], v[130:133], v[194:197], v[62:65]
	v_mfma_f32_16x16x32_bf16 v[62:65], v[134:137], v[198:201], v[62:65]
	v_mfma_f32_16x16x32_bf16 v[58:61], v[138:141], v[194:197], v[58:61]
	v_mfma_f32_16x16x32_bf16 v[58:61], v[142:145], v[198:201], v[58:61]
	v_mfma_f32_16x16x32_bf16 v[50:53], v[178:181], v[194:197], v[50:53]
	v_mfma_f32_16x16x32_bf16 v[50:53], v[190:193], v[198:201], v[50:53]
	v_mfma_f32_16x16x32_bf16 v[54:57], v[154:157], v[194:197], v[54:57]
	v_mfma_f32_16x16x32_bf16 v[54:57], v[174:177], v[198:201], v[54:57]
	v_mfma_f32_16x16x32_bf16 v[38:41], v[154:157], v[202:205], v[38:41]
	v_mfma_f32_16x16x32_bf16 v[38:41], v[174:177], v[228:231], v[38:41]
	v_mfma_f32_16x16x32_bf16 v[34:37], v[178:181], v[202:205], v[34:37]
	v_mfma_f32_16x16x32_bf16 v[34:37], v[190:193], v[228:231], v[34:37]
	v_mfma_f32_16x16x32_bf16 v[42:45], v[138:141], v[202:205], v[42:45]
	v_mfma_f32_16x16x32_bf16 v[42:45], v[142:145], v[228:231], v[42:45]
	v_mfma_f32_16x16x32_bf16 v[46:49], v[130:133], v[202:205], v[46:49]
	v_mfma_f32_16x16x32_bf16 v[46:49], v[134:137], v[228:231], v[46:49]
	v_mfma_f32_16x16x32_bf16 v[30:33], v[130:133], v[232:235], v[30:33]
	v_mfma_f32_16x16x32_bf16 v[30:33], v[134:137], v[236:239], v[30:33]
	v_mfma_f32_16x16x32_bf16 v[26:29], v[138:141], v[232:235], v[26:29]
	v_mfma_f32_16x16x32_bf16 v[26:29], v[142:145], v[236:239], v[26:29]
	v_mfma_f32_16x16x32_bf16 v[18:21], v[178:181], v[232:235], v[18:21]
	v_mfma_f32_16x16x32_bf16 v[18:21], v[190:193], v[236:239], v[18:21]
	v_mfma_f32_16x16x32_bf16 v[22:25], v[154:157], v[232:235], v[22:25]
	v_mfma_f32_16x16x32_bf16 v[22:25], v[174:177], v[236:239], v[22:25]
	v_mfma_f32_16x16x32_bf16 v[6:9], v[154:157], v[240:243], v[6:9]
	v_mfma_f32_16x16x32_bf16 v[6:9], v[174:177], v[244:247], v[6:9]
	v_mfma_f32_16x16x32_bf16 v[2:5], v[178:181], v[240:243], v[2:5]
	v_mfma_f32_16x16x32_bf16 v[2:5], v[190:193], v[244:247], v[2:5]
	v_mfma_f32_16x16x32_bf16 v[10:13], v[138:141], v[240:243], v[10:13]
	v_mfma_f32_16x16x32_bf16 v[10:13], v[142:145], v[244:247], v[10:13]
	v_mfma_f32_16x16x32_bf16 v[14:17], v[130:133], v[240:243], v[14:17]
	v_mfma_f32_16x16x32_bf16 v[14:17], v[134:137], v[244:247], v[14:17]
	s_barrier
	s_setprio 0
	s_add_i32 s22, s22, 2
	s_addk_i32 s13, 0x100
	s_addk_i32 s21, 0x100
	s_cmp_gt_u32 s22, 29
	s_cbranch_scc0 .LBB0_2450
	s_and_b64 vcc, exec, s[64:65]
	s_cbranch_vccz .LBB0_2453
	s_barrier
